# v38 plus dead shuffle-address arithmetic in the GEMM epilogues replaced by equal wait states
# speedup vs baseline: 1.0029x; 1.0029x over previous
; __device__ __forceinline__ float row_part(const float* ss, int row, int fq) { const f32x4 a = ((const f32x4*)(ss + (size_t)row * 16))[fq]; return (a[0] + a[1]) + (a[2] + a[3]); }
; __device__ __forceinline__ float row_finish(float t) { t += shx(t, 16); t += shx(t, 32); return __builtin_amdgcn_rsqf(t * (1.0f / 1024.0f) + RMS_EPS); }
; __device__ __forceinline__ float sq4(f32x4 v) { return (v[0] * v[0] + v[1] * v[1]) + (v[2] * v[2] + v[3] * v[3]); }
;     __device__ __forceinline__ void operator()(const f32x4 (&acc)[2][2][4][2], const Unit& u, int wr, int wc, int fr, int fq) const {
;         const int g = u.pn * 4 + wc;
;         int mode = 0; const float* w = mqw; float sc = 1.f, nsc = 1.f;
;         if (g >= 36) { mode = 2; w = mqw; nsc = qscale; }
;         else if (diff) { if (g < 12) { mode = 2; w = qw; nsc = qscale; } else if (g < 24) { mode = 2; w = kw; } }
;         else { if (g >= 6 && g < 12) sc = 0.125f; else if (g >= 24) mode = 1; }
;         f32x4 wv[2][2];
; #pragma unroll
;         for (int bj = 0; bj < 2; ++bj)
; #pragma unroll
;             for (int n = 0; n < 2; ++n) wv[bj][n] = *(const f32x4*)(w + 32 * bj + 8 * fq + 4 * n) * nsc;
;         const int lcol = u.pn * 256 + 64 * wc + 8 * fq;
;         float rs[2][4];
; #pragma unroll
;         for (int ai = 0; ai < 2; ++ai)
; #pragma unroll
;             for (int m = 0; m < 4; ++m) rs[ai][m] = row_part(ss, u.pm * BM + ai * HALF + wr * 64 + m * 16 + fr, fq);
; #pragma unroll
;         for (int ai = 0; ai < 2; ++ai)
; #pragma unroll
;             for (int m = 0; m < 4; ++m) rs[ai][m] = row_finish(rs[ai][m]);
; #pragma unroll
;         for (int ai = 0; ai < 2; ++ai)
; #pragma unroll
;             for (int m = 0; m < 4; ++m) {
;                 const int row = u.pm * BM + ai * HALF + wr * 64 + m * 16 + fr;
;                 const float rstd = rs[ai][m];
;                 f32x4 v[2][2];
; #pragma unroll
;                 for (int bj = 0; bj < 2; ++bj)
; #pragma unroll
;                     for (int n = 0; n < 2; ++n) v[bj][n] = acc[ai][bj][m][n] * rstd;
;                 if (mode == 2) {
;                     float q = (sq4(v[0][0]) + sq4(v[0][1])) + (sq4(v[1][0]) + sq4(v[1][1]));
;                     q += shx(q, 16); q += shx(q, 32);
;                     const float r2 = __builtin_amdgcn_rsqf(q * (1.0f / 64.0f) + RMS_EPS);
.LBB0_123:
	s_lshl_b32 s9, s36, 2
	s_or_b32 s11, s9, s47
	s_cmp_gt_i32 s11, 35
	s_cselect_b64 s[34:35], -1, 0
	s_cmp_lt_i32 s11, 36
	s_cselect_b64 s[42:43], -1, 0
	s_add_i32 s11, s11, -12
	s_cmp_lt_u32 s11, -6
	s_cselect_b64 s[40:41], -1, 0
	s_sub_i32 s9, s9, 24
	s_cmp_gt_u32 s9, 11
	s_cselect_b64 s[26:27], -1, 0
	s_lshl_b32 s9, s38, 8
	v_add_u32_e32 v176, s9, v192
	v_ashrrev_i32_e32 v177, 31, v176
	v_or_b32_e32 v158, 16, v176
	v_lshlrev_b64 v[148:149], 6, v[176:177]
	v_ashrrev_i32_e32 v159, 31, v158
	v_lshl_add_u64 v[148:149], v[136:137], 0, v[148:149]
	v_lshlrev_b64 v[158:159], 6, v[158:159]
	global_load_dwordx4 v[150:153], v[138:139], off offset:16
	global_load_dwordx4 v[154:157], v[138:139], off
	global_load_dwordx4 v[168:171], v[138:139], off offset:144
	global_load_dwordx4 v[178:181], v[138:139], off offset:128
	v_lshl_add_u64 v[158:159], v[136:137], 0, v[158:159]
	ds_read_b128 v[182:185], v239
	ds_read_b128 v[186:189], v239 offset:1024
	v_or_b32_e32 v148, 32, v176
	v_ashrrev_i32_e32 v149, 31, v148
	v_or_b32_e32 v158, 48, v176
	v_lshlrev_b64 v[148:149], 6, v[148:149]
	v_ashrrev_i32_e32 v159, 31, v158
	v_lshl_add_u64 v[148:149], v[136:137], 0, v[148:149]
	v_lshlrev_b64 v[158:159], 6, v[158:159]
	v_lshl_add_u64 v[158:159], v[136:137], 0, v[158:159]
	ds_read_b128 v[206:209], v239 offset:2048
	ds_read_b128 v[210:213], v239 offset:3072
	v_add_u32_e32 v174, 0x80, v176
	v_ashrrev_i32_e32 v175, 31, v174
	v_add_u32_e32 v172, 0x90, v176
	v_lshlrev_b64 v[148:149], 6, v[174:175]
	v_ashrrev_i32_e32 v173, 31, v172
	v_lshl_add_u64 v[148:149], v[136:137], 0, v[148:149]
	v_lshlrev_b64 v[158:159], 6, v[172:173]
	v_lshl_add_u64 v[158:159], v[136:137], 0, v[158:159]
	ds_read_b128 v[214:217], v239 offset:8192
	ds_read_b128 v[218:221], v239 offset:9216
	v_add_u32_e32 v166, 0xa0, v176
	v_ashrrev_i32_e32 v167, 31, v166
	v_lshlrev_b64 v[148:149], 6, v[166:167]
	v_lshl_add_u64 v[148:149], v[136:137], 0, v[148:149]
	ds_read_b128 v[222:225], v239 offset:10240
	v_add_u32_e32 v148, 0xb0, v176
	v_ashrrev_i32_e32 v149, 31, v148
	v_lshlrev_b64 v[158:159], 6, v[148:149]
	v_lshl_add_u64 v[158:159], v[136:137], 0, v[158:159]
	ds_read_b128 v[226:229], v239 offset:11264
	s_nop 0
	v_mov_b32_e32 v158, v201
	v_cndmask_b32_e64 v190, v203, 1.0, s[42:43]
	v_lshlrev_b32_e32 v158, 2, v158
	v_xor_b32_e32 v173, 0x80, v158
	s_nop 2
	s_mov_b64 s[38:39], -1
	s_nop 1
	s_and_b64 vcc, exec, s[42:43]
	s_waitcnt vmcnt(0) lgkmcnt(0)
	v_pk_mul_f32 v[158:159], v[190:191], v[152:153] op_sel_hi:[0,1]
	v_pk_mul_f32 v[160:161], v[190:191], v[150:151] op_sel_hi:[0,1]
	v_pk_mul_f32 v[152:153], v[190:191], v[168:169] op_sel_hi:[0,1]
	v_pk_mul_f32 v[150:151], v[190:191], v[170:171] op_sel_hi:[0,1]
	v_mov_b32_e32 v168, v183
	v_mov_b32_e32 v169, v184
	v_mov_b32_e32 v183, v185
	v_pk_add_f32 v[168:169], v[168:169], v[182:183]
	v_add_f32_e32 v170, v186, v187
	v_add_f32_e32 v168, v168, v169
	v_mov_b32_e32 v149, v168
	s_nop 1
	v_permlane16_swap_b32_e32 v149, v168
	v_add_f32_e32 v171, v188, v189
	v_add_f32_e32 v169, v170, v171
	v_mov_b32_e32 v167, v169
	s_nop 1
	v_permlane16_swap_b32_e32 v167, v169
	v_pk_mul_f32 v[162:163], v[190:191], v[156:157] op_sel_hi:[0,1]
	s_waitcnt lgkmcnt(0)
	v_add_f32_e32 v149, v168, v149
	v_mov_b32_e32 v168, v149
	s_nop 1
	v_permlane32_swap_b32_e32 v168, v149
	v_pk_mul_f32 v[156:157], v[190:191], v[178:179] op_sel_hi:[0,1]
	v_add_f32_e32 v179, v212, v213
	s_waitcnt lgkmcnt(0)
	v_add_f32_e32 v212, v169, v167
	v_add_f32_e32 v175, v206, v207
	s_waitcnt lgkmcnt(0)
	v_add_f32_e32 v149, v149, v168
	v_fmamk_f32 v149, v149, 0x3a800000, v202
	v_rsq_f32_e32 v168, v149
	s_nop 0
	v_add_f32_e32 v177, v208, v209
	s_nop 1
	v_mov_b32_e32 v213, v212
	s_nop 1
	v_permlane32_swap_b32_e32 v213, v212
	s_nop 0
	v_add_f32_e32 v170, v175, v177
	s_nop 1
	v_mov_b32_e32 v149, v170
	s_nop 1
	v_permlane16_swap_b32_e32 v149, v170
	v_mov_b32_e32 v167, v201
	s_nop 0
	v_add_f32_e32 v178, v210, v211
	s_nop 0
	v_add_f32_e32 v171, v178, v179
	s_nop 0
	v_mov_b32_e32 v169, v171
	s_nop 1
	v_permlane16_swap_b32_e32 v169, v171
	s_waitcnt lgkmcnt(0)
	v_add_f32_e32 v210, v170, v149
	v_lshlrev_b32_e32 v149, 2, v167
	v_xor_b32_e32 v149, 0x80, v149
	v_mov_b32_e32 v211, v210
	s_nop 1
	v_permlane32_swap_b32_e32 v211, v210
	s_nop 0
	s_waitcnt lgkmcnt(0)
	v_add_f32_e32 v208, v171, v169
	s_nop 1
	v_mov_b32_e32 v209, v208
	s_nop 1
	v_permlane32_swap_b32_e32 v209, v208
	s_nop 0
	v_pk_mul_f32 v[164:165], v[190:191], v[154:155] op_sel_hi:[0,1]
	v_pk_mul_f32 v[154:155], v[190:191], v[180:181] op_sel_hi:[0,1]
	v_add_f32_e32 v180, v214, v215
	v_add_f32_e32 v181, v216, v217
	s_nop 0
	v_add_f32_e32 v175, v180, v181
	s_nop 0
	v_mov_b32_e32 v149, v175
	s_nop 1
	v_permlane16_swap_b32_e32 v149, v175
	v_mov_b32_e32 v167, v201
	s_nop 0
	v_add_f32_e32 v182, v218, v219
	v_add_f32_e32 v183, v220, v221
	s_nop 0
	v_add_f32_e32 v177, v182, v183
	s_nop 0
	v_mov_b32_e32 v169, v177
	s_nop 1
	v_permlane16_swap_b32_e32 v169, v177
	s_waitcnt lgkmcnt(0)
	v_add_f32_e32 v206, v175, v149
	v_lshlrev_b32_e32 v149, 2, v167
	v_xor_b32_e32 v149, 0x80, v149
	v_mov_b32_e32 v207, v206
	s_nop 1
	v_permlane32_swap_b32_e32 v207, v206
	s_nop 0
	s_waitcnt lgkmcnt(0)
	v_add_f32_e32 v177, v177, v169
	s_nop 1
	v_mov_b32_e32 v205, v177
	s_nop 1
	v_permlane32_swap_b32_e32 v205, v177
	s_nop 0
	v_add_f32_e32 v184, v222, v223
	v_add_f32_e32 v185, v224, v225
	s_nop 0
	v_add_f32_e32 v178, v184, v185
	s_nop 0
	v_mov_b32_e32 v167, v201
	s_nop 0
	v_mov_b32_e32 v149, v178
	s_nop 1
	v_permlane16_swap_b32_e32 v149, v178
	v_add_f32_e32 v186, v226, v227
	v_add_f32_e32 v187, v228, v229
	s_nop 0
	v_add_f32_e32 v179, v186, v187
	s_nop 0
	v_mov_b32_e32 v169, v179
	s_nop 1
	v_permlane16_swap_b32_e32 v169, v179
	s_waitcnt lgkmcnt(0)
	v_add_f32_e32 v173, v178, v149
	v_lshlrev_b32_e32 v149, 2, v167
	s_nop 0
	v_xor_b32_e32 v149, 0x80, v149
	s_nop 0
	v_mov_b32_e32 v175, v173
	s_nop 1
	v_permlane32_swap_b32_e32 v175, v173
	s_waitcnt lgkmcnt(0)
	v_add_f32_e32 v149, v179, v169
	s_nop 0
	v_mov_b32_e32 v167, v149
	s_nop 1
	v_permlane32_swap_b32_e32 v167, v149
	v_pk_mul_f32 v[190:191], v[126:127], v[168:169] op_sel_hi:[1,0]
	v_pk_mul_f32 v[184:185], v[124:125], v[168:169] op_sel_hi:[1,0]
	v_pk_mul_f32 v[186:187], v[122:123], v[168:169] op_sel_hi:[1,0]
	v_pk_mul_f32 v[188:189], v[120:121], v[168:169] op_sel_hi:[1,0]
	v_pk_mul_f32 v[180:181], v[118:119], v[168:169] op_sel_hi:[1,0]
	v_pk_mul_f32 v[182:183], v[116:117], v[168:169] op_sel_hi:[1,0]
	v_pk_mul_f32 v[178:179], v[114:115], v[168:169] op_sel_hi:[1,0]
	v_pk_mul_f32 v[170:171], v[112:113], v[168:169] op_sel_hi:[1,0]
	s_cbranch_vccnz .LBB0_125
; __device__ __forceinline__ float sq4(f32x4 v) { return (v[0] * v[0] + v[1] * v[1]) + (v[2] * v[2] + v[3] * v[3]); }
;     __device__ __forceinline__ void operator()(const f32x4 (&acc)[2][2][4][2], const Unit& u, int wr, int wc, int fr, int fq) const {
;     ...
;                 if (mode == 2) {
;                     float q = (sq4(v[0][0]) + sq4(v[0][1])) + (sq4(v[1][0]) + sq4(v[1][1]));
;                     q += shx(q, 16); q += shx(q, 32);
;                     const float r2 = __builtin_amdgcn_rsqf(q * (1.0f / 64.0f) + RMS_EPS);
; #pragma unroll
;                     for (int bj = 0; bj < 2; ++bj)
; #pragma unroll
;                         for (int n = 0; n < 2; ++n) v[bj][n] = v[bj][n] * r2 * wv[bj][n];
	v_mov_b32_e32 v114, v185
	v_mov_b32_e32 v115, v183
	v_mov_b32_e32 v112, v184
	v_mov_b32_e32 v113, v182
	v_pk_mul_f32 v[114:115], v[114:115], v[114:115]
	v_mov_b32_e32 v116, v191
	v_mov_b32_e32 v117, v181
	v_pk_fma_f32 v[112:113], v[112:113], v[112:113], v[114:115]
	v_mov_b32_e32 v114, v190
	v_mov_b32_e32 v115, v180
	v_pk_mul_f32 v[116:117], v[116:117], v[116:117]
	v_mov_b32_e32 v118, v187
	v_pk_fma_f32 v[114:115], v[114:115], v[114:115], v[116:117]
	v_mov_b32_e32 v116, v189
	v_mov_b32_e32 v117, v171
	v_pk_add_f32 v[112:113], v[112:113], v[114:115]
	v_mov_b32_e32 v114, v188
	v_mov_b32_e32 v115, v170
	v_pk_mul_f32 v[116:117], v[116:117], v[116:117]
	v_mov_b32_e32 v119, v179
	v_pk_fma_f32 v[114:115], v[114:115], v[114:115], v[116:117]
	v_mov_b32_e32 v116, v186
	v_mov_b32_e32 v117, v178
	v_pk_mul_f32 v[118:119], v[118:119], v[118:119]
	s_mov_b64 s[38:39], 0
	v_pk_fma_f32 v[116:117], v[116:117], v[116:117], v[118:119]
	s_nop 0
	v_pk_add_f32 v[114:115], v[114:115], v[116:117]
	s_nop 0
	v_pk_add_f32 v[112:113], v[112:113], v[114:115]
	s_nop 0
	v_add_f32_e32 v112, v112, v113
	s_nop 0
	s_nop 0
	s_nop 1
	v_mov_b32_e32 v113, v112
	s_nop 1
	v_permlane16_swap_b32_e32 v113, v112
	s_waitcnt lgkmcnt(0)
	v_add_f32_e32 v112, v112, v113
	s_nop 0
	s_nop 0
	s_nop 1
	v_mov_b32_e32 v113, v112
	s_nop 1
	v_permlane32_swap_b32_e32 v113, v112
	s_waitcnt lgkmcnt(0)
	v_add_f32_e32 v112, v112, v113
	v_fmamk_f32 v112, v112, 0x3c800000, v202
	v_rsq_f32_e32 v124, v112
	s_nop 0
	v_pk_mul_f32 v[112:113], v[184:185], v[124:125] op_sel_hi:[1,0]
	v_pk_mul_f32 v[114:115], v[190:191], v[124:125] op_sel_hi:[1,0]
	v_pk_mul_f32 v[116:117], v[188:189], v[124:125] op_sel_hi:[1,0]
	v_pk_mul_f32 v[118:119], v[186:187], v[124:125] op_sel_hi:[1,0]
	v_pk_mul_f32 v[120:121], v[182:183], v[124:125] op_sel_hi:[1,0]
	v_pk_mul_f32 v[122:123], v[180:181], v[124:125] op_sel_hi:[1,0]
	v_pk_mul_f32 v[168:169], v[170:171], v[124:125] op_sel_hi:[1,0]
	v_pk_mul_f32 v[124:125], v[178:179], v[124:125] op_sel_hi:[1,0]
	v_pk_mul_f32 v[114:115], v[162:163], v[114:115]
	v_pk_mul_f32 v[112:113], v[164:165], v[112:113]
	v_pk_mul_f32 v[118:119], v[158:159], v[118:119]
	v_pk_mul_f32 v[116:117], v[160:161], v[116:117]
	v_pk_mul_f32 v[122:123], v[154:155], v[122:123]
	v_pk_mul_f32 v[120:121], v[156:157], v[120:121]
	v_pk_mul_f32 v[126:127], v[150:151], v[124:125]
	v_pk_mul_f32 v[124:125], v[152:153], v[168:169]

; __device__ __forceinline__ float sq4(f32x4 v) { return (v[0] * v[0] + v[1] * v[1]) + (v[2] * v[2] + v[3] * v[3]); }
; __device__ __forceinline__ u32x4 pack8(f32x4 a, f32x4 b) { u32x4 w; w.x = cvt_pk_bf16(a[0], a[1]); w.y = cvt_pk_bf16(a[2], a[3]); w.z = cvt_pk_bf16(b[0], b[1]); w.w = cvt_pk_bf16(b[2], b[3]); return w; }
;     __device__ __forceinline__ void operator()(const f32x4 (&acc)[2][2][4][2], const Unit& u, int wr, int wc, int fr, int fq) const {
;     ...
;                 const int row = u.pm * BM + ai * HALF + wr * 64 + m * 16 + fr;
;                 const float rstd = rs[ai][m];
;                 f32x4 v[2][2];
; #pragma unroll
;                 for (int bj = 0; bj < 2; ++bj)
; #pragma unroll
;                     for (int n = 0; n < 2; ++n) v[bj][n] = acc[ai][bj][m][n] * rstd;
;                 if (mode == 2) {
;                     float q = (sq4(v[0][0]) + sq4(v[0][1])) + (sq4(v[1][0]) + sq4(v[1][1]));
;                     q += shx(q, 16); q += shx(q, 32);
;                     const float r2 = __builtin_amdgcn_rsqf(q * (1.0f / 64.0f) + RMS_EPS);
; #pragma unroll
;                     for (int bj = 0; bj < 2; ++bj)
; #pragma unroll
;                         for (int n = 0; n < 2; ++n) v[bj][n] = v[bj][n] * r2 * wv[bj][n];
;     ...
;                 bf16_t* rowp = U + (size_t)row * 2560 + lcol;
; #pragma unroll
;                 for (int bj = 0; bj < 2; ++bj) *(u32x4*)(rowp + 32 * bj) = pack8(v[bj][0], v[bj][1]);
.LBB0_130:
	v_add_f32_e32 v170, v212, v213
	v_fmamk_f32 v170, v170, 0x3a800000, v202
	v_rsq_f32_e32 v178, v170
	v_lshl_or_b32 v170, s36, 8, v197
	v_mov_b64_e32 v[180:181], s[14:15]
	v_ashrrev_i32_e32 v171, 31, v170
	v_mad_i64_i32 v[180:181], s[36:37], v176, s56, v[180:181]
	v_lshl_add_u64 v[180:181], v[170:171], 1, v[180:181]
	v_cvt_pk_bf16_f32 v112, v112, v113
	v_cvt_pk_bf16_f32 v113, v114, v115
	v_cvt_pk_bf16_f32 v114, v116, v117
	v_cvt_pk_bf16_f32 v115, v118, v119
	global_store_dwordx4 v[180:181], v[112:115], off
	v_pk_mul_f32 v[116:117], v[102:103], v[178:179] op_sel_hi:[1,0]
	v_pk_mul_f32 v[118:119], v[100:101], v[178:179] op_sel_hi:[1,0]
	v_cvt_pk_bf16_f32 v112, v120, v121
	v_cvt_pk_bf16_f32 v113, v122, v123
	v_cvt_pk_bf16_f32 v114, v124, v125
	v_cvt_pk_bf16_f32 v115, v126, v127
	global_store_dwordx4 v[180:181], v[112:115], off offset:64
	v_pk_mul_f32 v[126:127], v[110:111], v[178:179] op_sel_hi:[1,0]
	v_pk_mul_f32 v[120:121], v[108:109], v[178:179] op_sel_hi:[1,0]
	v_pk_mul_f32 v[122:123], v[106:107], v[178:179] op_sel_hi:[1,0]
	v_pk_mul_f32 v[124:125], v[104:105], v[178:179] op_sel_hi:[1,0]
	v_pk_mul_f32 v[114:115], v[98:99], v[178:179] op_sel_hi:[1,0]
	v_pk_mul_f32 v[112:113], v[96:97], v[178:179] op_sel_hi:[1,0]
	s_mov_b64 s[36:37], -1
	s_and_b64 vcc, exec, s[34:35]
	s_cbranch_vccz .LBB0_132
	v_mov_b32_e32 v98, v121
	v_mov_b32_e32 v99, v119
	v_mov_b32_e32 v96, v120
	v_mov_b32_e32 v97, v118
	v_pk_mul_f32 v[98:99], v[98:99], v[98:99]
	v_mov_b32_e32 v100, v127
	v_mov_b32_e32 v101, v117
	v_pk_fma_f32 v[96:97], v[96:97], v[96:97], v[98:99]
	v_mov_b32_e32 v98, v126
	v_mov_b32_e32 v99, v116
	v_pk_mul_f32 v[100:101], v[100:101], v[100:101]
	v_mov_b32_e32 v102, v123
	v_pk_fma_f32 v[98:99], v[98:99], v[98:99], v[100:101]
	v_mov_b32_e32 v100, v125
	v_mov_b32_e32 v101, v113
	v_pk_add_f32 v[96:97], v[96:97], v[98:99]
	v_mov_b32_e32 v98, v124
	v_mov_b32_e32 v99, v112
	v_pk_mul_f32 v[100:101], v[100:101], v[100:101]
	v_mov_b32_e32 v103, v115
	v_pk_fma_f32 v[98:99], v[98:99], v[98:99], v[100:101]
	v_mov_b32_e32 v100, v122
	v_mov_b32_e32 v101, v114
	v_pk_mul_f32 v[102:103], v[102:103], v[102:103]
	s_mov_b64 s[36:37], 0
	v_pk_fma_f32 v[100:101], v[100:101], v[100:101], v[102:103]
	s_nop 0
	v_pk_add_f32 v[98:99], v[98:99], v[100:101]
	s_nop 0
	v_pk_add_f32 v[96:97], v[96:97], v[98:99]
	s_nop 0
	v_add_f32_e32 v96, v96, v97
	s_nop 0
	s_nop 0
	s_nop 1
	v_mov_b32_e32 v97, v96
	s_nop 1
	v_permlane16_swap_b32_e32 v97, v96
	s_waitcnt lgkmcnt(0)
	v_add_f32_e32 v96, v96, v97
	s_nop 0
	s_nop 0
	s_nop 1
	v_mov_b32_e32 v97, v96
	s_nop 1
	v_permlane32_swap_b32_e32 v97, v96
	s_waitcnt lgkmcnt(0)
	v_add_f32_e32 v96, v96, v97
	v_fmamk_f32 v96, v96, 0x3c800000, v202
	v_rsq_f32_e32 v108, v96
	s_nop 0
	v_pk_mul_f32 v[96:97], v[120:121], v[108:109] op_sel_hi:[1,0]
	v_pk_mul_f32 v[98:99], v[126:127], v[108:109] op_sel_hi:[1,0]
	v_pk_mul_f32 v[100:101], v[124:125], v[108:109] op_sel_hi:[1,0]
	v_pk_mul_f32 v[102:103], v[122:123], v[108:109] op_sel_hi:[1,0]
	v_pk_mul_f32 v[104:105], v[118:119], v[108:109] op_sel_hi:[1,0]
	v_pk_mul_f32 v[106:107], v[116:117], v[108:109] op_sel_hi:[1,0]
	v_pk_mul_f32 v[178:179], v[112:113], v[108:109] op_sel_hi:[1,0]
	v_pk_mul_f32 v[108:109], v[114:115], v[108:109] op_sel_hi:[1,0]
	v_pk_mul_f32 v[98:99], v[162:163], v[98:99]
	v_pk_mul_f32 v[96:97], v[164:165], v[96:97]
	v_pk_mul_f32 v[102:103], v[158:159], v[102:103]
	v_pk_mul_f32 v[100:101], v[160:161], v[100:101]
	v_pk_mul_f32 v[106:107], v[154:155], v[106:107]
	v_pk_mul_f32 v[104:105], v[156:157], v[104:105]
	v_pk_mul_f32 v[110:111], v[150:151], v[108:109]
	v_pk_mul_f32 v[108:109], v[152:153], v[178:179]

; __device__ __forceinline__ float sq4(f32x4 v) { return (v[0] * v[0] + v[1] * v[1]) + (v[2] * v[2] + v[3] * v[3]); }
; __device__ __forceinline__ u32x4 pack8(f32x4 a, f32x4 b) { u32x4 w; w.x = cvt_pk_bf16(a[0], a[1]); w.y = cvt_pk_bf16(a[2], a[3]); w.z = cvt_pk_bf16(b[0], b[1]); w.w = cvt_pk_bf16(b[2], b[3]); return w; }
;     __device__ __forceinline__ void operator()(const f32x4 (&acc)[2][2][4][2], const Unit& u, int wr, int wc, int fr, int fq) const {
;     ...
;                 const int row = u.pm * BM + ai * HALF + wr * 64 + m * 16 + fr;
;                 const float rstd = rs[ai][m];
;                 f32x4 v[2][2];
; #pragma unroll
;                 for (int bj = 0; bj < 2; ++bj)
; #pragma unroll
;                     for (int n = 0; n < 2; ++n) v[bj][n] = acc[ai][bj][m][n] * rstd;
;                 if (mode == 2) {
;                     float q = (sq4(v[0][0]) + sq4(v[0][1])) + (sq4(v[1][0]) + sq4(v[1][1]));
;                     q += shx(q, 16); q += shx(q, 32);
;                     const float r2 = __builtin_amdgcn_rsqf(q * (1.0f / 64.0f) + RMS_EPS);
; #pragma unroll
;                     for (int bj = 0; bj < 2; ++bj)
; #pragma unroll
;                         for (int n = 0; n < 2; ++n) v[bj][n] = v[bj][n] * r2 * wv[bj][n];
;     ...
;                 bf16_t* rowp = U + (size_t)row * 2560 + lcol;
; #pragma unroll
;                 for (int bj = 0; bj < 2; ++bj) *(u32x4*)(rowp + 32 * bj) = pack8(v[bj][0], v[bj][1]);
.LBB0_137:
	v_add_f32_e32 v112, v210, v211
	v_fmamk_f32 v112, v112, 0x3a800000, v202
	v_add_u32_e32 v113, s9, v194
	v_rsq_f32_e32 v112, v112
	v_mov_b64_e32 v[114:115], s[14:15]
	v_mad_i64_i32 v[114:115], s[36:37], v113, s56, v[114:115]
	v_lshl_add_u64 v[114:115], v[170:171], 1, v[114:115]
	v_cvt_pk_bf16_f32 v96, v96, v97
	v_cvt_pk_bf16_f32 v97, v98, v99
	v_cvt_pk_bf16_f32 v98, v100, v101
	v_cvt_pk_bf16_f32 v99, v102, v103
	global_store_dwordx4 v[114:115], v[96:99], off
	v_pk_mul_f32 v[100:101], v[86:87], v[112:113] op_sel_hi:[1,0]
	v_pk_mul_f32 v[102:103], v[84:85], v[112:113] op_sel_hi:[1,0]
	v_cvt_pk_bf16_f32 v96, v104, v105
	v_cvt_pk_bf16_f32 v97, v106, v107
	v_cvt_pk_bf16_f32 v98, v108, v109
	v_cvt_pk_bf16_f32 v99, v110, v111
	global_store_dwordx4 v[114:115], v[96:99], off offset:64
	v_pk_mul_f32 v[110:111], v[94:95], v[112:113] op_sel_hi:[1,0]
	v_pk_mul_f32 v[104:105], v[92:93], v[112:113] op_sel_hi:[1,0]
	v_pk_mul_f32 v[106:107], v[90:91], v[112:113] op_sel_hi:[1,0]
	v_pk_mul_f32 v[108:109], v[88:89], v[112:113] op_sel_hi:[1,0]
	v_pk_mul_f32 v[98:99], v[82:83], v[112:113] op_sel_hi:[1,0]
	v_pk_mul_f32 v[96:97], v[80:81], v[112:113] op_sel_hi:[1,0]
	s_mov_b64 s[36:37], -1
	s_and_b64 vcc, exec, s[34:35]
	s_cbranch_vccz .LBB0_139
	v_mov_b32_e32 v82, v105
	v_mov_b32_e32 v83, v103
	v_mov_b32_e32 v80, v104
	v_mov_b32_e32 v81, v102
	v_pk_mul_f32 v[82:83], v[82:83], v[82:83]
	v_mov_b32_e32 v84, v111
	v_mov_b32_e32 v85, v101
	v_pk_fma_f32 v[80:81], v[80:81], v[80:81], v[82:83]
	v_mov_b32_e32 v82, v110
	v_mov_b32_e32 v83, v100
	v_pk_mul_f32 v[84:85], v[84:85], v[84:85]
	v_mov_b32_e32 v86, v107
	v_pk_fma_f32 v[82:83], v[82:83], v[82:83], v[84:85]
	v_mov_b32_e32 v84, v109
	v_mov_b32_e32 v85, v97
	v_pk_add_f32 v[80:81], v[80:81], v[82:83]
	v_mov_b32_e32 v82, v108
	v_mov_b32_e32 v83, v96
	v_pk_mul_f32 v[84:85], v[84:85], v[84:85]
	v_mov_b32_e32 v87, v99
	v_pk_fma_f32 v[82:83], v[82:83], v[82:83], v[84:85]
	v_mov_b32_e32 v84, v106
	v_mov_b32_e32 v85, v98
	v_pk_mul_f32 v[86:87], v[86:87], v[86:87]
	s_mov_b64 s[36:37], 0
	v_pk_fma_f32 v[84:85], v[84:85], v[84:85], v[86:87]
	s_nop 0
	v_pk_add_f32 v[82:83], v[82:83], v[84:85]
	s_nop 0
	v_pk_add_f32 v[80:81], v[80:81], v[82:83]
	s_nop 0
	v_add_f32_e32 v80, v80, v81
	s_nop 0
	s_nop 0
	s_nop 1
	v_mov_b32_e32 v81, v80
	s_nop 1
	v_permlane16_swap_b32_e32 v81, v80
	s_waitcnt lgkmcnt(0)
	v_add_f32_e32 v80, v80, v81
	s_nop 0
	s_nop 0
	s_nop 1
	v_mov_b32_e32 v81, v80
	s_nop 1
	v_permlane32_swap_b32_e32 v81, v80
	s_waitcnt lgkmcnt(0)
	v_add_f32_e32 v80, v80, v81
	v_fmamk_f32 v80, v80, 0x3c800000, v202
	v_rsq_f32_e32 v92, v80
	s_nop 0
	v_pk_mul_f32 v[80:81], v[104:105], v[92:93] op_sel_hi:[1,0]
	v_pk_mul_f32 v[82:83], v[110:111], v[92:93] op_sel_hi:[1,0]
	v_pk_mul_f32 v[84:85], v[108:109], v[92:93] op_sel_hi:[1,0]
	v_pk_mul_f32 v[86:87], v[106:107], v[92:93] op_sel_hi:[1,0]
	v_pk_mul_f32 v[88:89], v[102:103], v[92:93] op_sel_hi:[1,0]
	v_pk_mul_f32 v[90:91], v[100:101], v[92:93] op_sel_hi:[1,0]
	v_pk_mul_f32 v[112:113], v[96:97], v[92:93] op_sel_hi:[1,0]
	v_pk_mul_f32 v[92:93], v[98:99], v[92:93] op_sel_hi:[1,0]
	v_pk_mul_f32 v[82:83], v[162:163], v[82:83]
	v_pk_mul_f32 v[80:81], v[164:165], v[80:81]
	v_pk_mul_f32 v[86:87], v[158:159], v[86:87]
	v_pk_mul_f32 v[84:85], v[160:161], v[84:85]
	v_pk_mul_f32 v[90:91], v[154:155], v[90:91]
	v_pk_mul_f32 v[88:89], v[156:157], v[88:89]
	v_pk_mul_f32 v[94:95], v[150:151], v[92:93]
	v_pk_mul_f32 v[92:93], v[152:153], v[112:113]

; __device__ __forceinline__ float sq4(f32x4 v) { return (v[0] * v[0] + v[1] * v[1]) + (v[2] * v[2] + v[3] * v[3]); }
; __device__ __forceinline__ u32x4 pack8(f32x4 a, f32x4 b) { u32x4 w; w.x = cvt_pk_bf16(a[0], a[1]); w.y = cvt_pk_bf16(a[2], a[3]); w.z = cvt_pk_bf16(b[0], b[1]); w.w = cvt_pk_bf16(b[2], b[3]); return w; }
;     __device__ __forceinline__ void operator()(const f32x4 (&acc)[2][2][4][2], const Unit& u, int wr, int wc, int fr, int fq) const {
;     ...
;                 const int row = u.pm * BM + ai * HALF + wr * 64 + m * 16 + fr;
;                 const float rstd = rs[ai][m];
;                 f32x4 v[2][2];
; #pragma unroll
;                 for (int bj = 0; bj < 2; ++bj)
; #pragma unroll
;                     for (int n = 0; n < 2; ++n) v[bj][n] = acc[ai][bj][m][n] * rstd;
;                 if (mode == 2) {
;                     float q = (sq4(v[0][0]) + sq4(v[0][1])) + (sq4(v[1][0]) + sq4(v[1][1]));
;                     q += shx(q, 16); q += shx(q, 32);
;                     const float r2 = __builtin_amdgcn_rsqf(q * (1.0f / 64.0f) + RMS_EPS);
; #pragma unroll
;                     for (int bj = 0; bj < 2; ++bj)
; #pragma unroll
;                         for (int n = 0; n < 2; ++n) v[bj][n] = v[bj][n] * r2 * wv[bj][n];
;     ...
;                 bf16_t* rowp = U + (size_t)row * 2560 + lcol;
; #pragma unroll
;                 for (int bj = 0; bj < 2; ++bj) *(u32x4*)(rowp + 32 * bj) = pack8(v[bj][0], v[bj][1]);
.LBB0_144:
	v_add_f32_e32 v96, v208, v209
	v_fmamk_f32 v96, v96, 0x3a800000, v202
	v_add_u32_e32 v97, s9, v195
	v_rsq_f32_e32 v96, v96
	v_mov_b64_e32 v[98:99], s[14:15]
	v_mad_i64_i32 v[98:99], s[36:37], v97, s56, v[98:99]
	v_lshl_add_u64 v[98:99], v[170:171], 1, v[98:99]
	v_cvt_pk_bf16_f32 v80, v80, v81
	v_cvt_pk_bf16_f32 v81, v82, v83
	v_cvt_pk_bf16_f32 v82, v84, v85
	v_cvt_pk_bf16_f32 v83, v86, v87
	global_store_dwordx4 v[98:99], v[80:83], off
	v_pk_mul_f32 v[84:85], v[70:71], v[96:97] op_sel_hi:[1,0]
	v_pk_mul_f32 v[86:87], v[68:69], v[96:97] op_sel_hi:[1,0]
	v_cvt_pk_bf16_f32 v80, v88, v89
	v_cvt_pk_bf16_f32 v81, v90, v91
	v_cvt_pk_bf16_f32 v82, v92, v93
	v_cvt_pk_bf16_f32 v83, v94, v95
	global_store_dwordx4 v[98:99], v[80:83], off offset:64
	v_pk_mul_f32 v[94:95], v[78:79], v[96:97] op_sel_hi:[1,0]
	v_pk_mul_f32 v[88:89], v[76:77], v[96:97] op_sel_hi:[1,0]
	v_pk_mul_f32 v[90:91], v[74:75], v[96:97] op_sel_hi:[1,0]
	v_pk_mul_f32 v[92:93], v[72:73], v[96:97] op_sel_hi:[1,0]
	v_pk_mul_f32 v[82:83], v[66:67], v[96:97] op_sel_hi:[1,0]
	v_pk_mul_f32 v[80:81], v[64:65], v[96:97] op_sel_hi:[1,0]
	s_mov_b64 s[36:37], -1
	s_and_b64 vcc, exec, s[34:35]
	s_cbranch_vccz .LBB0_146
	v_mov_b32_e32 v66, v89
	v_mov_b32_e32 v67, v87
	v_mov_b32_e32 v64, v88
	v_mov_b32_e32 v65, v86
	v_pk_mul_f32 v[66:67], v[66:67], v[66:67]
	v_mov_b32_e32 v68, v95
	v_mov_b32_e32 v69, v85
	v_pk_fma_f32 v[64:65], v[64:65], v[64:65], v[66:67]
	v_mov_b32_e32 v66, v94
	v_mov_b32_e32 v67, v84
	v_pk_mul_f32 v[68:69], v[68:69], v[68:69]
	v_mov_b32_e32 v70, v91
	v_pk_fma_f32 v[66:67], v[66:67], v[66:67], v[68:69]
	v_mov_b32_e32 v68, v93
	v_mov_b32_e32 v69, v81
	v_pk_add_f32 v[64:65], v[64:65], v[66:67]
	v_mov_b32_e32 v66, v92
	v_mov_b32_e32 v67, v80
	v_pk_mul_f32 v[68:69], v[68:69], v[68:69]
	v_mov_b32_e32 v71, v83
	v_pk_fma_f32 v[66:67], v[66:67], v[66:67], v[68:69]
	v_mov_b32_e32 v68, v90
	v_mov_b32_e32 v69, v82
	v_pk_mul_f32 v[70:71], v[70:71], v[70:71]
	s_mov_b64 s[36:37], 0
	v_pk_fma_f32 v[68:69], v[68:69], v[68:69], v[70:71]
	s_nop 0
	v_pk_add_f32 v[66:67], v[66:67], v[68:69]
	s_nop 0
	v_pk_add_f32 v[64:65], v[64:65], v[66:67]
	s_nop 0
	v_add_f32_e32 v64, v64, v65
	s_nop 0
	s_nop 0
	s_nop 1
	v_mov_b32_e32 v65, v64
	s_nop 1
	v_permlane16_swap_b32_e32 v65, v64
	s_waitcnt lgkmcnt(0)
	v_add_f32_e32 v64, v64, v65
	s_nop 0
	s_nop 0
	s_nop 1
	v_mov_b32_e32 v65, v64
	s_nop 1
	v_permlane32_swap_b32_e32 v65, v64
	s_waitcnt lgkmcnt(0)
	v_add_f32_e32 v64, v64, v65
	v_fmamk_f32 v64, v64, 0x3c800000, v202
	v_rsq_f32_e32 v76, v64
	s_nop 0
	v_pk_mul_f32 v[64:65], v[88:89], v[76:77] op_sel_hi:[1,0]
	v_pk_mul_f32 v[66:67], v[94:95], v[76:77] op_sel_hi:[1,0]
	v_pk_mul_f32 v[68:69], v[92:93], v[76:77] op_sel_hi:[1,0]
	v_pk_mul_f32 v[70:71], v[90:91], v[76:77] op_sel_hi:[1,0]
	v_pk_mul_f32 v[72:73], v[86:87], v[76:77] op_sel_hi:[1,0]
	v_pk_mul_f32 v[74:75], v[84:85], v[76:77] op_sel_hi:[1,0]
	v_pk_mul_f32 v[96:97], v[80:81], v[76:77] op_sel_hi:[1,0]
	v_pk_mul_f32 v[76:77], v[82:83], v[76:77] op_sel_hi:[1,0]
	v_pk_mul_f32 v[66:67], v[162:163], v[66:67]
	v_pk_mul_f32 v[64:65], v[164:165], v[64:65]
	v_pk_mul_f32 v[70:71], v[158:159], v[70:71]
	v_pk_mul_f32 v[68:69], v[160:161], v[68:69]
	v_pk_mul_f32 v[74:75], v[154:155], v[74:75]
	v_pk_mul_f32 v[72:73], v[156:157], v[72:73]
	v_pk_mul_f32 v[78:79], v[150:151], v[76:77]
	v_pk_mul_f32 v[76:77], v[152:153], v[96:97]

; __device__ __forceinline__ float sq4(f32x4 v) { return (v[0] * v[0] + v[1] * v[1]) + (v[2] * v[2] + v[3] * v[3]); }
; __device__ __forceinline__ u32x4 pack8(f32x4 a, f32x4 b) { u32x4 w; w.x = cvt_pk_bf16(a[0], a[1]); w.y = cvt_pk_bf16(a[2], a[3]); w.z = cvt_pk_bf16(b[0], b[1]); w.w = cvt_pk_bf16(b[2], b[3]); return w; }
;     __device__ __forceinline__ void operator()(const f32x4 (&acc)[2][2][4][2], const Unit& u, int wr, int wc, int fr, int fq) const {
;     ...
;                 const int row = u.pm * BM + ai * HALF + wr * 64 + m * 16 + fr;
;                 const float rstd = rs[ai][m];
;                 f32x4 v[2][2];
; #pragma unroll
;                 for (int bj = 0; bj < 2; ++bj)
; #pragma unroll
;                     for (int n = 0; n < 2; ++n) v[bj][n] = acc[ai][bj][m][n] * rstd;
;                 if (mode == 2) {
;                     float q = (sq4(v[0][0]) + sq4(v[0][1])) + (sq4(v[1][0]) + sq4(v[1][1]));
;                     q += shx(q, 16); q += shx(q, 32);
;                     const float r2 = __builtin_amdgcn_rsqf(q * (1.0f / 64.0f) + RMS_EPS);
; #pragma unroll
;                     for (int bj = 0; bj < 2; ++bj)
; #pragma unroll
;                         for (int n = 0; n < 2; ++n) v[bj][n] = v[bj][n] * r2 * wv[bj][n];
;     ...
;                 bf16_t* rowp = U + (size_t)row * 2560 + lcol;
; #pragma unroll
;                 for (int bj = 0; bj < 2; ++bj) *(u32x4*)(rowp + 32 * bj) = pack8(v[bj][0], v[bj][1]);
.LBB0_151:
	v_add_f32_e32 v80, v206, v207
	v_fmamk_f32 v80, v80, 0x3a800000, v202
	v_add_u32_e32 v81, s9, v196
	v_rsq_f32_e32 v80, v80
	v_mov_b64_e32 v[82:83], s[14:15]
	v_mad_i64_i32 v[82:83], s[36:37], v81, s56, v[82:83]
	v_lshl_add_u64 v[82:83], v[170:171], 1, v[82:83]
	v_cvt_pk_bf16_f32 v64, v64, v65
	v_cvt_pk_bf16_f32 v65, v66, v67
	v_cvt_pk_bf16_f32 v66, v68, v69
	v_cvt_pk_bf16_f32 v67, v70, v71
	global_store_dwordx4 v[82:83], v[64:67], off
	v_pk_mul_f32 v[68:69], v[54:55], v[80:81] op_sel_hi:[1,0]
	v_pk_mul_f32 v[70:71], v[52:53], v[80:81] op_sel_hi:[1,0]
	v_cvt_pk_bf16_f32 v64, v72, v73
	v_cvt_pk_bf16_f32 v65, v74, v75
	v_cvt_pk_bf16_f32 v66, v76, v77
	v_cvt_pk_bf16_f32 v67, v78, v79
	global_store_dwordx4 v[82:83], v[64:67], off offset:64
	v_pk_mul_f32 v[78:79], v[62:63], v[80:81] op_sel_hi:[1,0]
	v_pk_mul_f32 v[72:73], v[60:61], v[80:81] op_sel_hi:[1,0]
	v_pk_mul_f32 v[74:75], v[58:59], v[80:81] op_sel_hi:[1,0]
	v_pk_mul_f32 v[76:77], v[56:57], v[80:81] op_sel_hi:[1,0]
	v_pk_mul_f32 v[66:67], v[50:51], v[80:81] op_sel_hi:[1,0]
	v_pk_mul_f32 v[64:65], v[48:49], v[80:81] op_sel_hi:[1,0]
	s_mov_b64 s[36:37], -1
	s_and_b64 vcc, exec, s[34:35]
	s_cbranch_vccz .LBB0_153
	v_mov_b32_e32 v50, v73
	v_mov_b32_e32 v51, v71
	v_mov_b32_e32 v48, v72
	v_mov_b32_e32 v49, v70
	v_pk_mul_f32 v[50:51], v[50:51], v[50:51]
	v_mov_b32_e32 v52, v79
	v_mov_b32_e32 v53, v69
	v_pk_fma_f32 v[48:49], v[48:49], v[48:49], v[50:51]
	v_mov_b32_e32 v50, v78
	v_mov_b32_e32 v51, v68
	v_pk_mul_f32 v[52:53], v[52:53], v[52:53]
	v_mov_b32_e32 v54, v75
	v_pk_fma_f32 v[50:51], v[50:51], v[50:51], v[52:53]
	v_mov_b32_e32 v52, v77
	v_mov_b32_e32 v53, v65
	v_pk_add_f32 v[48:49], v[48:49], v[50:51]
	v_mov_b32_e32 v50, v76
	v_mov_b32_e32 v51, v64
	v_pk_mul_f32 v[52:53], v[52:53], v[52:53]
	v_mov_b32_e32 v55, v67
	v_pk_fma_f32 v[50:51], v[50:51], v[50:51], v[52:53]
	v_mov_b32_e32 v52, v74
	v_mov_b32_e32 v53, v66
	v_pk_mul_f32 v[54:55], v[54:55], v[54:55]
	s_mov_b64 s[36:37], 0
	v_pk_fma_f32 v[52:53], v[52:53], v[52:53], v[54:55]
	s_nop 0
	v_pk_add_f32 v[50:51], v[50:51], v[52:53]
	s_nop 0
	v_pk_add_f32 v[48:49], v[48:49], v[50:51]
	s_nop 0
	v_add_f32_e32 v48, v48, v49
	s_nop 0
	s_nop 0
	s_nop 1
	v_mov_b32_e32 v49, v48
	s_nop 1
	v_permlane16_swap_b32_e32 v49, v48
	s_waitcnt lgkmcnt(0)
	v_add_f32_e32 v48, v48, v49
	s_nop 0
	s_nop 0
	s_nop 1
	v_mov_b32_e32 v49, v48
	s_nop 1
	v_permlane32_swap_b32_e32 v49, v48
	s_waitcnt lgkmcnt(0)
	v_add_f32_e32 v48, v48, v49
	v_fmamk_f32 v48, v48, 0x3c800000, v202
	v_rsq_f32_e32 v60, v48
	s_nop 0
	v_pk_mul_f32 v[48:49], v[72:73], v[60:61] op_sel_hi:[1,0]
	v_pk_mul_f32 v[50:51], v[78:79], v[60:61] op_sel_hi:[1,0]
	v_pk_mul_f32 v[52:53], v[76:77], v[60:61] op_sel_hi:[1,0]
	v_pk_mul_f32 v[54:55], v[74:75], v[60:61] op_sel_hi:[1,0]
	v_pk_mul_f32 v[56:57], v[70:71], v[60:61] op_sel_hi:[1,0]
	v_pk_mul_f32 v[58:59], v[68:69], v[60:61] op_sel_hi:[1,0]
	v_pk_mul_f32 v[80:81], v[64:65], v[60:61] op_sel_hi:[1,0]
	v_pk_mul_f32 v[60:61], v[66:67], v[60:61] op_sel_hi:[1,0]
	v_pk_mul_f32 v[50:51], v[162:163], v[50:51]
	v_pk_mul_f32 v[48:49], v[164:165], v[48:49]
	v_pk_mul_f32 v[54:55], v[158:159], v[54:55]
	v_pk_mul_f32 v[52:53], v[160:161], v[52:53]
	v_pk_mul_f32 v[58:59], v[154:155], v[58:59]
	v_pk_mul_f32 v[56:57], v[156:157], v[56:57]
	v_pk_mul_f32 v[62:63], v[150:151], v[60:61]
	v_pk_mul_f32 v[60:61], v[152:153], v[80:81]

; __device__ __forceinline__ f32x4 silu4(f32x4 v) { return (f32x4){silu_f(v[0]), silu_f(v[1]), silu_f(v[2]), silu_f(v[3])}; }
; __device__ __forceinline__ float sq4(f32x4 v) { return (v[0] * v[0] + v[1] * v[1]) + (v[2] * v[2] + v[3] * v[3]); }
; __device__ __forceinline__ u32x4 pack8(f32x4 a, f32x4 b) { u32x4 w; w.x = cvt_pk_bf16(a[0], a[1]); w.y = cvt_pk_bf16(a[2], a[3]); w.z = cvt_pk_bf16(b[0], b[1]); w.w = cvt_pk_bf16(b[2], b[3]); return w; }
;     __device__ __forceinline__ void operator()(const f32x4 (&acc)[2][2][4][2], const Unit& u, int wr, int wc, int fr, int fq) const {
;     ...
;                 const int row = u.pm * BM + ai * HALF + wr * 64 + m * 16 + fr;
;                 const float rstd = rs[ai][m];
;                 f32x4 v[2][2];
; #pragma unroll
;                 for (int bj = 0; bj < 2; ++bj)
; #pragma unroll
;                     for (int n = 0; n < 2; ++n) v[bj][n] = acc[ai][bj][m][n] * rstd;
;                 if (mode == 2) {
;                     float q = (sq4(v[0][0]) + sq4(v[0][1])) + (sq4(v[1][0]) + sq4(v[1][1]));
;                     q += shx(q, 16); q += shx(q, 32);
;                     const float r2 = __builtin_amdgcn_rsqf(q * (1.0f / 64.0f) + RMS_EPS);
; #pragma unroll
;                     for (int bj = 0; bj < 2; ++bj)
; #pragma unroll
;                         for (int n = 0; n < 2; ++n) v[bj][n] = v[bj][n] * r2 * wv[bj][n];
;                 } else if (mode == 1) {
; #pragma unroll
;                     for (int bj = 0; bj < 2; ++bj)
; #pragma unroll
;                         for (int n = 0; n < 2; ++n) v[bj][n] = silu4(v[bj][n]);
;                 } else {
; #pragma unroll
;                     for (int bj = 0; bj < 2; ++bj)
; #pragma unroll
;                         for (int n = 0; n < 2; ++n) v[bj][n] = v[bj][n] * sc;
;                 }
;                 bf16_t* rowp = U + (size_t)row * 2560 + lcol;
; #pragma unroll
;                 for (int bj = 0; bj < 2; ++bj) *(u32x4*)(rowp + 32 * bj) = pack8(v[bj][0], v[bj][1]);
.LBB0_158:
	v_add_f32_e32 v64, v177, v205
	v_fmamk_f32 v64, v64, 0x3a800000, v202
	v_rsq_f32_e32 v64, v64
	v_mov_b64_e32 v[66:67], s[14:15]
	v_mad_i64_i32 v[66:67], s[36:37], v174, s56, v[66:67]
	v_lshl_add_u64 v[66:67], v[170:171], 1, v[66:67]
	v_cvt_pk_bf16_f32 v48, v48, v49
	v_cvt_pk_bf16_f32 v49, v50, v51
	v_cvt_pk_bf16_f32 v50, v52, v53
	v_cvt_pk_bf16_f32 v51, v54, v55
	global_store_dwordx4 v[66:67], v[48:51], off
	v_pk_mul_f32 v[52:53], v[38:39], v[64:65] op_sel_hi:[1,0]
	v_pk_mul_f32 v[54:55], v[36:37], v[64:65] op_sel_hi:[1,0]
	v_cvt_pk_bf16_f32 v48, v56, v57
	v_cvt_pk_bf16_f32 v49, v58, v59
	v_cvt_pk_bf16_f32 v50, v60, v61
	v_cvt_pk_bf16_f32 v51, v62, v63
	global_store_dwordx4 v[66:67], v[48:51], off offset:64
	v_pk_mul_f32 v[62:63], v[46:47], v[64:65] op_sel_hi:[1,0]
	v_pk_mul_f32 v[56:57], v[44:45], v[64:65] op_sel_hi:[1,0]
	v_pk_mul_f32 v[58:59], v[42:43], v[64:65] op_sel_hi:[1,0]
	v_pk_mul_f32 v[60:61], v[40:41], v[64:65] op_sel_hi:[1,0]
	v_pk_mul_f32 v[50:51], v[34:35], v[64:65] op_sel_hi:[1,0]
	v_pk_mul_f32 v[48:49], v[32:33], v[64:65] op_sel_hi:[1,0]
	s_mov_b64 s[36:37], -1
	s_and_b64 vcc, exec, s[34:35]
	s_cbranch_vccz .LBB0_160
	v_mov_b32_e32 v34, v57
	v_mov_b32_e32 v35, v55
	v_mov_b32_e32 v32, v56
	v_mov_b32_e32 v33, v54
	v_pk_mul_f32 v[34:35], v[34:35], v[34:35]
	v_mov_b32_e32 v36, v63
	v_mov_b32_e32 v37, v53
	v_pk_fma_f32 v[32:33], v[32:33], v[32:33], v[34:35]
	v_mov_b32_e32 v34, v62
	v_mov_b32_e32 v35, v52
	v_pk_mul_f32 v[36:37], v[36:37], v[36:37]
	v_mov_b32_e32 v38, v59
	v_pk_fma_f32 v[34:35], v[34:35], v[34:35], v[36:37]
	v_mov_b32_e32 v36, v61
	v_mov_b32_e32 v37, v49
	v_pk_add_f32 v[32:33], v[32:33], v[34:35]
	v_mov_b32_e32 v34, v60
	v_mov_b32_e32 v35, v48
	v_pk_mul_f32 v[36:37], v[36:37], v[36:37]
	v_mov_b32_e32 v39, v51
	v_pk_fma_f32 v[34:35], v[34:35], v[34:35], v[36:37]
	v_mov_b32_e32 v36, v58
	v_mov_b32_e32 v37, v50
	v_pk_mul_f32 v[38:39], v[38:39], v[38:39]
	s_mov_b64 s[36:37], 0
	v_pk_fma_f32 v[36:37], v[36:37], v[36:37], v[38:39]
	s_nop 0
	v_pk_add_f32 v[34:35], v[34:35], v[36:37]
	s_nop 0
	v_pk_add_f32 v[32:33], v[32:33], v[34:35]
	s_nop 0
	v_add_f32_e32 v32, v32, v33
	s_nop 0
	s_nop 0
	s_nop 1
	v_mov_b32_e32 v33, v32
	s_nop 1
	v_permlane16_swap_b32_e32 v33, v32
	s_waitcnt lgkmcnt(0)
	v_add_f32_e32 v32, v32, v33
	s_nop 0
	s_nop 0
	s_nop 1
	v_mov_b32_e32 v33, v32
	s_nop 1
	v_permlane32_swap_b32_e32 v33, v32
	s_waitcnt lgkmcnt(0)
	v_add_f32_e32 v32, v32, v33
	v_fmamk_f32 v32, v32, 0x3c800000, v202
	v_rsq_f32_e32 v44, v32
	s_nop 0
	v_pk_mul_f32 v[32:33], v[56:57], v[44:45] op_sel_hi:[1,0]
	v_pk_mul_f32 v[34:35], v[62:63], v[44:45] op_sel_hi:[1,0]
	v_pk_mul_f32 v[36:37], v[60:61], v[44:45] op_sel_hi:[1,0]
	v_pk_mul_f32 v[38:39], v[58:59], v[44:45] op_sel_hi:[1,0]
	v_pk_mul_f32 v[40:41], v[54:55], v[44:45] op_sel_hi:[1,0]
	v_pk_mul_f32 v[42:43], v[52:53], v[44:45] op_sel_hi:[1,0]
	v_pk_mul_f32 v[64:65], v[48:49], v[44:45] op_sel_hi:[1,0]
	v_pk_mul_f32 v[44:45], v[50:51], v[44:45] op_sel_hi:[1,0]
	v_pk_mul_f32 v[34:35], v[162:163], v[34:35]
	v_pk_mul_f32 v[32:33], v[164:165], v[32:33]
	v_pk_mul_f32 v[38:39], v[158:159], v[38:39]
	v_pk_mul_f32 v[36:37], v[160:161], v[36:37]
	v_pk_mul_f32 v[42:43], v[154:155], v[42:43]
	v_pk_mul_f32 v[40:41], v[156:157], v[40:41]
	v_pk_mul_f32 v[46:47], v[150:151], v[44:45]
	v_pk_mul_f32 v[44:45], v[152:153], v[64:65]

; __device__ __forceinline__ f32x4 silu4(f32x4 v) { return (f32x4){silu_f(v[0]), silu_f(v[1]), silu_f(v[2]), silu_f(v[3])}; }
; __device__ __forceinline__ float sq4(f32x4 v) { return (v[0] * v[0] + v[1] * v[1]) + (v[2] * v[2] + v[3] * v[3]); }
; __device__ __forceinline__ u32x4 pack8(f32x4 a, f32x4 b) { u32x4 w; w.x = cvt_pk_bf16(a[0], a[1]); w.y = cvt_pk_bf16(a[2], a[3]); w.z = cvt_pk_bf16(b[0], b[1]); w.w = cvt_pk_bf16(b[2], b[3]); return w; }
;     __device__ __forceinline__ void operator()(const f32x4 (&acc)[2][2][4][2], const Unit& u, int wr, int wc, int fr, int fq) const {
;     ...
;                 const int row = u.pm * BM + ai * HALF + wr * 64 + m * 16 + fr;
;                 const float rstd = rs[ai][m];
;                 f32x4 v[2][2];
; #pragma unroll
;                 for (int bj = 0; bj < 2; ++bj)
; #pragma unroll
;                     for (int n = 0; n < 2; ++n) v[bj][n] = acc[ai][bj][m][n] * rstd;
;                 if (mode == 2) {
;                     float q = (sq4(v[0][0]) + sq4(v[0][1])) + (sq4(v[1][0]) + sq4(v[1][1]));
;                     q += shx(q, 16); q += shx(q, 32);
;                     const float r2 = __builtin_amdgcn_rsqf(q * (1.0f / 64.0f) + RMS_EPS);
; #pragma unroll
;                     for (int bj = 0; bj < 2; ++bj)
; #pragma unroll
;                         for (int n = 0; n < 2; ++n) v[bj][n] = v[bj][n] * r2 * wv[bj][n];
;                 } else if (mode == 1) {
; #pragma unroll
;                     for (int bj = 0; bj < 2; ++bj)
; #pragma unroll
;                         for (int n = 0; n < 2; ++n) v[bj][n] = silu4(v[bj][n]);
;                 } else {
; #pragma unroll
;                     for (int bj = 0; bj < 2; ++bj)
; #pragma unroll
;                         for (int n = 0; n < 2; ++n) v[bj][n] = v[bj][n] * sc;
;                 }
;                 bf16_t* rowp = U + (size_t)row * 2560 + lcol;
; #pragma unroll
;                 for (int bj = 0; bj < 2; ++bj) *(u32x4*)(rowp + 32 * bj) = pack8(v[bj][0], v[bj][1]);
.LBB0_165:
	s_waitcnt lgkmcnt(0)
	v_add_f32_e32 v48, v173, v175
	v_fmamk_f32 v48, v48, 0x3a800000, v202
	v_rsq_f32_e32 v48, v48
	v_mov_b64_e32 v[50:51], s[14:15]
	v_mad_i64_i32 v[50:51], s[36:37], v172, s56, v[50:51]
	v_lshl_add_u64 v[50:51], v[170:171], 1, v[50:51]
	v_cvt_pk_bf16_f32 v32, v32, v33
	v_cvt_pk_bf16_f32 v33, v34, v35
	v_cvt_pk_bf16_f32 v34, v36, v37
	v_cvt_pk_bf16_f32 v35, v38, v39
	global_store_dwordx4 v[50:51], v[32:35], off
	v_pk_mul_f32 v[36:37], v[22:23], v[48:49] op_sel_hi:[1,0]
	v_pk_mul_f32 v[38:39], v[20:21], v[48:49] op_sel_hi:[1,0]
	v_cvt_pk_bf16_f32 v32, v40, v41
	v_cvt_pk_bf16_f32 v33, v42, v43
	v_cvt_pk_bf16_f32 v34, v44, v45
	v_cvt_pk_bf16_f32 v35, v46, v47
	global_store_dwordx4 v[50:51], v[32:35], off offset:64
	v_pk_mul_f32 v[46:47], v[30:31], v[48:49] op_sel_hi:[1,0]
	v_pk_mul_f32 v[40:41], v[28:29], v[48:49] op_sel_hi:[1,0]
	v_pk_mul_f32 v[42:43], v[26:27], v[48:49] op_sel_hi:[1,0]
	v_pk_mul_f32 v[44:45], v[24:25], v[48:49] op_sel_hi:[1,0]
	v_pk_mul_f32 v[34:35], v[18:19], v[48:49] op_sel_hi:[1,0]
	v_pk_mul_f32 v[32:33], v[16:17], v[48:49] op_sel_hi:[1,0]
	s_mov_b64 s[36:37], -1
	s_and_b64 vcc, exec, s[34:35]
	s_cbranch_vccz .LBB0_167
	v_mov_b32_e32 v18, v41
	v_mov_b32_e32 v19, v39
	v_mov_b32_e32 v16, v40
	v_mov_b32_e32 v17, v38
	v_pk_mul_f32 v[18:19], v[18:19], v[18:19]
	v_mov_b32_e32 v20, v47
	v_mov_b32_e32 v21, v37
	v_pk_fma_f32 v[16:17], v[16:17], v[16:17], v[18:19]
	v_mov_b32_e32 v18, v46
	v_mov_b32_e32 v19, v36
	v_pk_mul_f32 v[20:21], v[20:21], v[20:21]
	v_mov_b32_e32 v22, v43
	v_pk_fma_f32 v[18:19], v[18:19], v[18:19], v[20:21]
	v_mov_b32_e32 v20, v45
	v_mov_b32_e32 v21, v33
	v_pk_add_f32 v[16:17], v[16:17], v[18:19]
	v_mov_b32_e32 v18, v44
	v_mov_b32_e32 v19, v32
	v_pk_mul_f32 v[20:21], v[20:21], v[20:21]
	v_mov_b32_e32 v23, v35
	v_pk_fma_f32 v[18:19], v[18:19], v[18:19], v[20:21]
	v_mov_b32_e32 v20, v42
	v_mov_b32_e32 v21, v34
	v_pk_mul_f32 v[22:23], v[22:23], v[22:23]
	s_mov_b64 s[36:37], 0
	v_pk_fma_f32 v[20:21], v[20:21], v[20:21], v[22:23]
	s_nop 0
	v_pk_add_f32 v[18:19], v[18:19], v[20:21]
	s_nop 0
	v_pk_add_f32 v[16:17], v[16:17], v[18:19]
	s_nop 0
	v_add_f32_e32 v16, v16, v17
	s_nop 0
	s_nop 0
	s_nop 1
	v_mov_b32_e32 v17, v16
	s_nop 1
	v_permlane16_swap_b32_e32 v17, v16
	s_waitcnt lgkmcnt(0)
	v_add_f32_e32 v16, v16, v17
	s_nop 0
	s_nop 0
	s_nop 1
	v_mov_b32_e32 v17, v16
	s_nop 1
	v_permlane32_swap_b32_e32 v17, v16
	s_waitcnt lgkmcnt(0)
	v_add_f32_e32 v16, v16, v17
	v_fmamk_f32 v16, v16, 0x3c800000, v202
	v_rsq_f32_e32 v28, v16
	s_nop 0
	v_pk_mul_f32 v[16:17], v[40:41], v[28:29] op_sel_hi:[1,0]
	v_pk_mul_f32 v[18:19], v[46:47], v[28:29] op_sel_hi:[1,0]
	v_pk_mul_f32 v[20:21], v[44:45], v[28:29] op_sel_hi:[1,0]
	v_pk_mul_f32 v[22:23], v[42:43], v[28:29] op_sel_hi:[1,0]
	v_pk_mul_f32 v[24:25], v[38:39], v[28:29] op_sel_hi:[1,0]
	v_pk_mul_f32 v[26:27], v[36:37], v[28:29] op_sel_hi:[1,0]
	v_pk_mul_f32 v[48:49], v[32:33], v[28:29] op_sel_hi:[1,0]
	v_pk_mul_f32 v[28:29], v[34:35], v[28:29] op_sel_hi:[1,0]
	v_pk_mul_f32 v[18:19], v[162:163], v[18:19]
	v_pk_mul_f32 v[16:17], v[164:165], v[16:17]
	v_pk_mul_f32 v[22:23], v[158:159], v[22:23]
	v_pk_mul_f32 v[20:21], v[160:161], v[20:21]
	v_pk_mul_f32 v[26:27], v[154:155], v[26:27]
	v_pk_mul_f32 v[24:25], v[156:157], v[24:25]
	v_pk_mul_f32 v[30:31], v[150:151], v[28:29]
	v_pk_mul_f32 v[28:29], v[152:153], v[48:49]

; __device__ __forceinline__ f32x4 silu4(f32x4 v) { return (f32x4){silu_f(v[0]), silu_f(v[1]), silu_f(v[2]), silu_f(v[3])}; }
; __device__ __forceinline__ float sq4(f32x4 v) { return (v[0] * v[0] + v[1] * v[1]) + (v[2] * v[2] + v[3] * v[3]); }
; __device__ __forceinline__ u32x4 pack8(f32x4 a, f32x4 b) { u32x4 w; w.x = cvt_pk_bf16(a[0], a[1]); w.y = cvt_pk_bf16(a[2], a[3]); w.z = cvt_pk_bf16(b[0], b[1]); w.w = cvt_pk_bf16(b[2], b[3]); return w; }
;     __device__ __forceinline__ void operator()(const f32x4 (&acc)[2][2][4][2], const Unit& u, int wr, int wc, int fr, int fq) const {
;     ...
;                 const int row = u.pm * BM + ai * HALF + wr * 64 + m * 16 + fr;
;                 const float rstd = rs[ai][m];
;                 f32x4 v[2][2];
; #pragma unroll
;                 for (int bj = 0; bj < 2; ++bj)
; #pragma unroll
;                     for (int n = 0; n < 2; ++n) v[bj][n] = acc[ai][bj][m][n] * rstd;
;                 if (mode == 2) {
;                     float q = (sq4(v[0][0]) + sq4(v[0][1])) + (sq4(v[1][0]) + sq4(v[1][1]));
;                     q += shx(q, 16); q += shx(q, 32);
;                     const float r2 = __builtin_amdgcn_rsqf(q * (1.0f / 64.0f) + RMS_EPS);
; #pragma unroll
;                     for (int bj = 0; bj < 2; ++bj)
; #pragma unroll
;                         for (int n = 0; n < 2; ++n) v[bj][n] = v[bj][n] * r2 * wv[bj][n];
;                 } else if (mode == 1) {
; #pragma unroll
;                     for (int bj = 0; bj < 2; ++bj)
; #pragma unroll
;                         for (int n = 0; n < 2; ++n) v[bj][n] = silu4(v[bj][n]);
;                 } else {
; #pragma unroll
;                     for (int bj = 0; bj < 2; ++bj)
; #pragma unroll
;                         for (int n = 0; n < 2; ++n) v[bj][n] = v[bj][n] * sc;
;                 }
;                 bf16_t* rowp = U + (size_t)row * 2560 + lcol;
; #pragma unroll
;                 for (int bj = 0; bj < 2; ++bj) *(u32x4*)(rowp + 32 * bj) = pack8(v[bj][0], v[bj][1]);
.LBB0_172:
	s_waitcnt lgkmcnt(0)
	v_add_f32_e32 v32, v149, v167
	v_fmamk_f32 v32, v32, 0x3a800000, v202
	v_rsq_f32_e32 v32, v32
	v_mov_b64_e32 v[34:35], s[14:15]
	v_mad_i64_i32 v[34:35], s[36:37], v166, s56, v[34:35]
	v_lshl_add_u64 v[34:35], v[170:171], 1, v[34:35]
	v_cvt_pk_bf16_f32 v16, v16, v17
	v_cvt_pk_bf16_f32 v17, v18, v19
	v_cvt_pk_bf16_f32 v18, v20, v21
	v_cvt_pk_bf16_f32 v19, v22, v23
	global_store_dwordx4 v[34:35], v[16:19], off
	v_pk_mul_f32 v[20:21], v[6:7], v[32:33] op_sel_hi:[1,0]
	v_pk_mul_f32 v[22:23], v[4:5], v[32:33] op_sel_hi:[1,0]
	v_cvt_pk_bf16_f32 v16, v24, v25
	v_cvt_pk_bf16_f32 v17, v26, v27
	v_cvt_pk_bf16_f32 v18, v28, v29
	v_cvt_pk_bf16_f32 v19, v30, v31
	global_store_dwordx4 v[34:35], v[16:19], off offset:64
	v_pk_mul_f32 v[30:31], v[14:15], v[32:33] op_sel_hi:[1,0]
	v_pk_mul_f32 v[24:25], v[12:13], v[32:33] op_sel_hi:[1,0]
	v_pk_mul_f32 v[26:27], v[10:11], v[32:33] op_sel_hi:[1,0]
	v_pk_mul_f32 v[28:29], v[8:9], v[32:33] op_sel_hi:[1,0]
	v_pk_mul_f32 v[18:19], v[2:3], v[32:33] op_sel_hi:[1,0]
	v_pk_mul_f32 v[16:17], v[0:1], v[32:33] op_sel_hi:[1,0]
	s_mov_b64 s[36:37], -1
	s_and_b64 vcc, exec, s[34:35]
	s_cbranch_vccz .LBB0_174
	v_mov_b32_e32 v2, v25
	v_mov_b32_e32 v3, v23
	v_mov_b32_e32 v0, v24
	v_mov_b32_e32 v1, v22
	v_pk_mul_f32 v[2:3], v[2:3], v[2:3]
	v_mov_b32_e32 v4, v31
	v_mov_b32_e32 v5, v21
	v_pk_fma_f32 v[0:1], v[0:1], v[0:1], v[2:3]
	v_mov_b32_e32 v2, v30
	v_mov_b32_e32 v3, v20
	v_pk_mul_f32 v[4:5], v[4:5], v[4:5]
	v_mov_b32_e32 v6, v27
	v_pk_fma_f32 v[2:3], v[2:3], v[2:3], v[4:5]
	v_mov_b32_e32 v4, v29
	v_mov_b32_e32 v5, v17
	v_pk_add_f32 v[0:1], v[0:1], v[2:3]
	v_mov_b32_e32 v2, v28
	v_mov_b32_e32 v3, v16
	v_pk_mul_f32 v[4:5], v[4:5], v[4:5]
	v_mov_b32_e32 v7, v19
	v_pk_fma_f32 v[2:3], v[2:3], v[2:3], v[4:5]
	v_mov_b32_e32 v4, v26
	v_mov_b32_e32 v5, v18
	v_pk_mul_f32 v[6:7], v[6:7], v[6:7]
	s_mov_b64 s[36:37], 0
	v_pk_fma_f32 v[4:5], v[4:5], v[4:5], v[6:7]
	s_nop 0
	v_pk_add_f32 v[2:3], v[2:3], v[4:5]
	s_nop 0
	v_pk_add_f32 v[0:1], v[0:1], v[2:3]
	s_nop 0
	v_add_f32_e32 v0, v0, v1
	s_nop 0
	s_nop 0
	s_nop 1
	v_mov_b32_e32 v1, v0
	s_nop 1
	v_permlane16_swap_b32_e32 v1, v0
	s_waitcnt lgkmcnt(0)
	v_add_f32_e32 v0, v0, v1
	s_nop 0
	s_nop 0
	s_nop 1
	v_mov_b32_e32 v1, v0
	s_nop 1
	v_permlane32_swap_b32_e32 v1, v0
	s_waitcnt lgkmcnt(0)
	v_add_f32_e32 v0, v0, v1
	v_fmamk_f32 v0, v0, 0x3c800000, v202
	v_rsq_f32_e32 v12, v0
	s_nop 0
	v_pk_mul_f32 v[0:1], v[24:25], v[12:13] op_sel_hi:[1,0]
	v_pk_mul_f32 v[2:3], v[30:31], v[12:13] op_sel_hi:[1,0]
	v_pk_mul_f32 v[4:5], v[28:29], v[12:13] op_sel_hi:[1,0]
	v_pk_mul_f32 v[6:7], v[26:27], v[12:13] op_sel_hi:[1,0]
	v_pk_mul_f32 v[8:9], v[22:23], v[12:13] op_sel_hi:[1,0]
	v_pk_mul_f32 v[10:11], v[20:21], v[12:13] op_sel_hi:[1,0]
	v_pk_mul_f32 v[32:33], v[16:17], v[12:13] op_sel_hi:[1,0]
	v_pk_mul_f32 v[12:13], v[18:19], v[12:13] op_sel_hi:[1,0]
	v_pk_mul_f32 v[2:3], v[162:163], v[2:3]
	v_pk_mul_f32 v[0:1], v[164:165], v[0:1]
	v_pk_mul_f32 v[6:7], v[158:159], v[6:7]
	v_pk_mul_f32 v[4:5], v[160:161], v[4:5]
	v_pk_mul_f32 v[10:11], v[154:155], v[10:11]
	v_pk_mul_f32 v[8:9], v[156:157], v[8:9]
	v_pk_mul_f32 v[14:15], v[150:151], v[12:13]
	v_pk_mul_f32 v[12:13], v[152:153], v[32:33]

; __device__ __forceinline__ float sq4(f32x4 v) { return (v[0] * v[0] + v[1] * v[1]) + (v[2] * v[2] + v[3] * v[3]); }
; __device__ __forceinline__ u32x4 pack8(f32x4 a, f32x4 b) { u32x4 w; w.x = cvt_pk_bf16(a[0], a[1]); w.y = cvt_pk_bf16(a[2], a[3]); w.z = cvt_pk_bf16(b[0], b[1]); w.w = cvt_pk_bf16(b[2], b[3]); return w; }
;     __device__ __forceinline__ void operator()(const f32x4 (&acc)[2][2][4][2], const Unit& u, int wr, int wc, int fr, int fq) const {
;     ...
;             for (int m = 0; m < 4; ++m) {
;                 const int row = u.pm * BM + ai * HALF + wr * 64 + m * 16 + fr;
;                 float q = 0.f;
; #pragma unroll
;                 for (int bj = 0; bj < 2; ++bj) {
;                     const size_t off = (size_t)row * 1024 + col0 + 128 * bj; const u32x4 w = bs[m][bj];
;                     const f32x4 b0 = (f32x4){__builtin_bit_cast(float, w.x << 16), __builtin_bit_cast(float, w.x & 0xffff0000u), __builtin_bit_cast(float, w.y << 16), __builtin_bit_cast(float, w.y & 0xffff0000u)};
;                     const f32x4 b1 = (f32x4){__builtin_bit_cast(float, w.z << 16), __builtin_bit_cast(float, w.z & 0xffff0000u), __builtin_bit_cast(float, w.w << 16), __builtin_bit_cast(float, w.w & 0xffff0000u)};
;                     const f32x4 v0 = acc[ai][bj][m][0] + b0, v1 = acc[ai][bj][m][1] + b1;
;                     if (last) { __builtin_nontemporal_store(v0, (f32x4*)(out + off)); __builtin_nontemporal_store(v1, (f32x4*)(out + off + 4)); }
;                     else { q += sq4(v0) + sq4(v1); *(u32x4*)(xb + off) = pack8(v0, v1); }
;                 }
;                 if (!last) { q += shx(q, 16); q += shx(q, 32); if (fq == 0) ss[(size_t)row * 16 + u.pn * 4 + wc] = q; }
.LBB0_441:
	s_or_b64 exec, exec, s[44:45]
	v_lshlrev_b32_e32 v112, 16, v148
	s_waitcnt lgkmcnt(0)
	v_and_b32_e32 v113, 0xffff0000, v148
	v_lshlrev_b32_e32 v114, 16, v149
	v_and_b32_e32 v115, 0xffff0000, v149
	v_lshlrev_b32_e32 v116, 16, v150
	v_and_b32_e32 v117, 0xffff0000, v150
	v_lshlrev_b32_e32 v118, 16, v151
	v_and_b32_e32 v119, 0xffff0000, v151
	v_pk_add_f32 v[110:111], v[110:111], v[114:115]
	v_pk_add_f32 v[108:109], v[108:109], v[112:113]
	v_pk_add_f32 v[112:113], v[106:107], v[118:119]
	v_pk_add_f32 v[106:107], v[104:105], v[116:117]
	v_mul_f32_e32 v104, v109, v109
	v_mul_f32_e32 v105, v111, v111
	v_fmac_f32_e32 v104, v108, v108
	v_fmac_f32_e32 v105, v110, v110
	v_add_f32_e32 v104, v104, v105
	v_mul_f32_e32 v105, v107, v107
	v_mul_f32_e32 v114, v113, v113
	v_fmac_f32_e32 v105, v106, v106
	v_fmac_f32_e32 v114, v112, v112
	v_add_f32_e32 v105, v105, v114
	v_add_f32_e32 v114, v104, v105
	v_cvt_pk_bf16_f32 v104, v108, v109
	v_lshl_add_u64 v[108:109], s[18:19], 0, v[184:185]
	v_cvt_pk_bf16_f32 v105, v110, v111
	v_cvt_pk_bf16_f32 v106, v106, v107
	v_cvt_pk_bf16_f32 v107, v112, v113
	v_lshl_add_u64 v[108:109], v[168:169], 1, v[108:109]
	global_store_dwordx4 v[108:109], v[104:107], off
	v_lshlrev_b32_e32 v110, 16, v146
	v_and_b32_e32 v111, 0xffff0000, v146
	v_lshlrev_b32_e32 v104, 16, v144
	v_and_b32_e32 v105, 0xffff0000, v144
	v_lshlrev_b32_e32 v106, 16, v145
	v_and_b32_e32 v107, 0xffff0000, v145
	v_lshlrev_b32_e32 v112, 16, v147
	v_and_b32_e32 v113, 0xffff0000, v147
	v_pk_add_f32 v[102:103], v[102:103], v[106:107]
	v_pk_add_f32 v[100:101], v[100:101], v[104:105]
	v_pk_add_f32 v[104:105], v[98:99], v[112:113]
	v_pk_add_f32 v[98:99], v[96:97], v[110:111]
	v_mul_f32_e32 v96, v101, v101
	v_mul_f32_e32 v97, v103, v103
	v_fmac_f32_e32 v96, v100, v100
	v_fmac_f32_e32 v97, v102, v102
	v_add_f32_e32 v96, v96, v97
	v_mul_f32_e32 v97, v99, v99
	v_mul_f32_e32 v106, v105, v105
	v_fmac_f32_e32 v97, v98, v98
	v_fmac_f32_e32 v106, v104, v104
	v_add_f32_e32 v97, v97, v106
	v_add_f32_e32 v96, v96, v97
	v_add_f32_e32 v106, v114, v96
	v_cvt_pk_bf16_f32 v96, v100, v101
	v_cvt_pk_bf16_f32 v97, v102, v103
	v_cvt_pk_bf16_f32 v98, v98, v99
	v_cvt_pk_bf16_f32 v99, v104, v105
	global_store_dwordx4 v[108:109], v[96:99], off offset:256
	s_nop 1
	s_nop 0
	s_nop 2
	v_mov_b32_e32 v96, v106
	s_nop 1
	v_permlane16_swap_b32_e32 v96, v106
	s_waitcnt lgkmcnt(0)
	v_add_f32_e32 v96, v106, v96
	s_nop 1
	v_mov_b32_e32 v97, v96
	s_nop 1
	v_permlane32_swap_b32_e32 v97, v96
	s_and_saveexec_b64 s[44:45], s[10:11]
	s_cbranch_execz .LBB0_443
	s_waitcnt lgkmcnt(0)
	v_add_f32_e32 v98, v96, v97
	v_lshlrev_b64 v[96:97], 6, v[182:183]
	v_lshl_add_u64 v[96:97], s[22:23], 0, v[96:97]
	v_lshl_add_u64 v[96:97], s[42:43], 2, v[96:97]
	s_lshl_b32 s14, s52, 2
	v_lshl_add_u64 v[96:97], v[96:97], 0, s[14:15]
	global_store_dword v[96:97], v98, off
; __device__ __forceinline__ float sq4(f32x4 v) { return (v[0] * v[0] + v[1] * v[1]) + (v[2] * v[2] + v[3] * v[3]); }
; __device__ __forceinline__ u32x4 pack8(f32x4 a, f32x4 b) { u32x4 w; w.x = cvt_pk_bf16(a[0], a[1]); w.y = cvt_pk_bf16(a[2], a[3]); w.z = cvt_pk_bf16(b[0], b[1]); w.w = cvt_pk_bf16(b[2], b[3]); return w; }
;     __device__ __forceinline__ void operator()(const f32x4 (&acc)[2][2][4][2], const Unit& u, int wr, int wc, int fr, int fq) const {
;     ...
;             for (int m = 0; m < 4; ++m) {
;                 const int row = u.pm * BM + ai * HALF + wr * 64 + m * 16 + fr;
;                 float q = 0.f;
; #pragma unroll
;                 for (int bj = 0; bj < 2; ++bj) {
;                     const size_t off = (size_t)row * 1024 + col0 + 128 * bj; const u32x4 w = bs[m][bj];
;                     const f32x4 b0 = (f32x4){__builtin_bit_cast(float, w.x << 16), __builtin_bit_cast(float, w.x & 0xffff0000u), __builtin_bit_cast(float, w.y << 16), __builtin_bit_cast(float, w.y & 0xffff0000u)};
;                     const f32x4 b1 = (f32x4){__builtin_bit_cast(float, w.z << 16), __builtin_bit_cast(float, w.z & 0xffff0000u), __builtin_bit_cast(float, w.w << 16), __builtin_bit_cast(float, w.w & 0xffff0000u)};
;                     const f32x4 v0 = acc[ai][bj][m][0] + b0, v1 = acc[ai][bj][m][1] + b1;
;                     if (last) { __builtin_nontemporal_store(v0, (f32x4*)(out + off)); __builtin_nontemporal_store(v1, (f32x4*)(out + off + 4)); }
;                     else { q += sq4(v0) + sq4(v1); *(u32x4*)(xb + off) = pack8(v0, v1); }
;                 }
;                 if (!last) { q += shx(q, 16); q += shx(q, 32); if (fq == 0) ss[(size_t)row * 16 + u.pn * 4 + wc] = q; }
.LBB0_443:
	s_or_b64 exec, exec, s[44:45]
	v_lshlrev_b32_e32 v96, 16, v140
	s_waitcnt lgkmcnt(0)
	v_and_b32_e32 v97, 0xffff0000, v140
	v_lshlrev_b32_e32 v98, 16, v141
	v_and_b32_e32 v99, 0xffff0000, v141
	v_lshlrev_b32_e32 v100, 16, v142
	v_and_b32_e32 v101, 0xffff0000, v142
	v_lshlrev_b32_e32 v102, 16, v143
	v_and_b32_e32 v103, 0xffff0000, v143
	v_pk_add_f32 v[94:95], v[94:95], v[98:99]
	v_pk_add_f32 v[92:93], v[92:93], v[96:97]
	v_pk_add_f32 v[96:97], v[90:91], v[102:103]
	v_pk_add_f32 v[90:91], v[88:89], v[100:101]
	v_mul_f32_e32 v88, v93, v93
	v_mul_f32_e32 v89, v95, v95
	v_fmac_f32_e32 v88, v92, v92
	v_fmac_f32_e32 v89, v94, v94
	v_add_f32_e32 v88, v88, v89
	v_mul_f32_e32 v89, v91, v91
	v_mul_f32_e32 v98, v97, v97
	v_fmac_f32_e32 v89, v90, v90
	v_fmac_f32_e32 v98, v96, v96
	v_add_f32_e32 v89, v89, v98
	v_add_f32_e32 v98, v88, v89
	v_cvt_pk_bf16_f32 v88, v92, v93
	v_lshl_add_u64 v[92:93], s[18:19], 0, v[180:181]
	v_cvt_pk_bf16_f32 v89, v94, v95
	v_cvt_pk_bf16_f32 v90, v90, v91
	v_cvt_pk_bf16_f32 v91, v96, v97
	v_lshl_add_u64 v[92:93], v[168:169], 1, v[92:93]
	global_store_dwordx4 v[92:93], v[88:91], off
	v_lshlrev_b32_e32 v94, 16, v138
	v_and_b32_e32 v95, 0xffff0000, v138
	v_lshlrev_b32_e32 v88, 16, v136
	v_and_b32_e32 v89, 0xffff0000, v136
	v_lshlrev_b32_e32 v90, 16, v137
	v_and_b32_e32 v91, 0xffff0000, v137
	v_lshlrev_b32_e32 v96, 16, v139
	v_and_b32_e32 v97, 0xffff0000, v139
	v_pk_add_f32 v[86:87], v[86:87], v[90:91]
	v_pk_add_f32 v[84:85], v[84:85], v[88:89]
	v_pk_add_f32 v[88:89], v[82:83], v[96:97]
	v_pk_add_f32 v[82:83], v[80:81], v[94:95]
	v_mul_f32_e32 v80, v85, v85
	v_mul_f32_e32 v81, v87, v87
	v_fmac_f32_e32 v80, v84, v84
	v_fmac_f32_e32 v81, v86, v86
	v_add_f32_e32 v80, v80, v81
	v_mul_f32_e32 v81, v83, v83
	v_mul_f32_e32 v90, v89, v89
	v_fmac_f32_e32 v81, v82, v82
	v_fmac_f32_e32 v90, v88, v88
	v_add_f32_e32 v81, v81, v90
	v_add_f32_e32 v80, v80, v81
	v_add_f32_e32 v90, v98, v80
	v_cvt_pk_bf16_f32 v80, v84, v85
	v_cvt_pk_bf16_f32 v81, v86, v87
	v_cvt_pk_bf16_f32 v82, v82, v83
	v_cvt_pk_bf16_f32 v83, v88, v89
	global_store_dwordx4 v[92:93], v[80:83], off offset:256
	s_nop 1
	s_nop 0
	s_nop 2
	v_mov_b32_e32 v80, v90
	s_nop 1
	v_permlane16_swap_b32_e32 v80, v90
	s_waitcnt lgkmcnt(0)
	v_add_f32_e32 v80, v90, v80
	s_nop 1
	v_mov_b32_e32 v81, v80
	s_nop 1
	v_permlane32_swap_b32_e32 v81, v80
	s_and_saveexec_b64 s[44:45], s[10:11]
	s_cbranch_execz .LBB0_445
	s_waitcnt lgkmcnt(0)
	v_add_f32_e32 v82, v80, v81
	v_lshlrev_b64 v[80:81], 6, v[178:179]
	v_lshl_add_u64 v[80:81], s[22:23], 0, v[80:81]
	v_lshl_add_u64 v[80:81], s[42:43], 2, v[80:81]
	s_lshl_b32 s14, s52, 2
	v_lshl_add_u64 v[80:81], v[80:81], 0, s[14:15]
	global_store_dword v[80:81], v82, off
.LBB0_445:
	s_or_b64 exec, exec, s[44:45]
	v_lshlrev_b32_e32 v80, 16, v132
	s_waitcnt lgkmcnt(0)
	v_and_b32_e32 v81, 0xffff0000, v132
	v_lshlrev_b32_e32 v82, 16, v133
	v_and_b32_e32 v83, 0xffff0000, v133
	v_lshlrev_b32_e32 v84, 16, v134
	v_and_b32_e32 v85, 0xffff0000, v134
	v_lshlrev_b32_e32 v86, 16, v135
	v_and_b32_e32 v87, 0xffff0000, v135
	v_pk_add_f32 v[78:79], v[78:79], v[82:83]
	v_pk_add_f32 v[76:77], v[76:77], v[80:81]
	v_pk_add_f32 v[80:81], v[74:75], v[86:87]
	v_pk_add_f32 v[74:75], v[72:73], v[84:85]
	v_mul_f32_e32 v72, v77, v77
	v_mul_f32_e32 v73, v79, v79
	v_fmac_f32_e32 v72, v76, v76
	v_fmac_f32_e32 v73, v78, v78
	v_add_f32_e32 v72, v72, v73
	v_mul_f32_e32 v73, v75, v75
	v_mul_f32_e32 v82, v81, v81
	v_fmac_f32_e32 v73, v74, v74
	v_fmac_f32_e32 v82, v80, v80
	v_add_f32_e32 v73, v73, v82
	v_add_f32_e32 v82, v72, v73
	v_cvt_pk_bf16_f32 v72, v76, v77
	v_lshl_add_u64 v[76:77], s[18:19], 0, v[176:177]
	v_cvt_pk_bf16_f32 v73, v78, v79
	v_cvt_pk_bf16_f32 v74, v74, v75
	v_cvt_pk_bf16_f32 v75, v80, v81
	v_lshl_add_u64 v[76:77], v[168:169], 1, v[76:77]
	global_store_dwordx4 v[76:77], v[72:75], off
	v_lshlrev_b32_e32 v78, 16, v130
	v_and_b32_e32 v79, 0xffff0000, v130
	v_lshlrev_b32_e32 v72, 16, v128
	v_and_b32_e32 v73, 0xffff0000, v128
	v_lshlrev_b32_e32 v74, 16, v129
	v_and_b32_e32 v75, 0xffff0000, v129
	v_lshlrev_b32_e32 v80, 16, v131
	v_and_b32_e32 v81, 0xffff0000, v131
	v_pk_add_f32 v[70:71], v[70:71], v[74:75]
	v_pk_add_f32 v[68:69], v[68:69], v[72:73]
	v_pk_add_f32 v[72:73], v[66:67], v[80:81]
	v_pk_add_f32 v[66:67], v[64:65], v[78:79]
	v_mul_f32_e32 v64, v69, v69
	v_mul_f32_e32 v65, v71, v71
	v_fmac_f32_e32 v64, v68, v68
	v_fmac_f32_e32 v65, v70, v70
	v_add_f32_e32 v64, v64, v65
	v_mul_f32_e32 v65, v67, v67
	v_mul_f32_e32 v74, v73, v73
	v_fmac_f32_e32 v65, v66, v66
	v_fmac_f32_e32 v74, v72, v72
	v_add_f32_e32 v65, v65, v74
	v_add_f32_e32 v64, v64, v65
	v_add_f32_e32 v74, v82, v64
	v_cvt_pk_bf16_f32 v64, v68, v69
	v_cvt_pk_bf16_f32 v65, v70, v71
	v_cvt_pk_bf16_f32 v66, v66, v67
	v_cvt_pk_bf16_f32 v67, v72, v73
	global_store_dwordx4 v[76:77], v[64:67], off offset:256
	s_nop 1
	s_nop 0
	s_nop 2
	v_mov_b32_e32 v64, v74
	s_nop 1
	v_permlane16_swap_b32_e32 v64, v74
	s_waitcnt lgkmcnt(0)
	v_add_f32_e32 v64, v74, v64
	s_nop 1
	v_mov_b32_e32 v65, v64
	s_nop 1
	v_permlane32_swap_b32_e32 v65, v64
	s_and_saveexec_b64 s[44:45], s[10:11]
	s_cbranch_execz .LBB0_447
	s_waitcnt lgkmcnt(0)
	v_add_f32_e32 v66, v64, v65
	v_lshlrev_b64 v[64:65], 6, v[174:175]
	v_lshl_add_u64 v[64:65], s[22:23], 0, v[64:65]
	v_lshl_add_u64 v[64:65], s[42:43], 2, v[64:65]
	s_lshl_b32 s14, s52, 2
	v_lshl_add_u64 v[64:65], v[64:65], 0, s[14:15]
	global_store_dword v[64:65], v66, off

; __device__ __forceinline__ float sq4(f32x4 v) { return (v[0] * v[0] + v[1] * v[1]) + (v[2] * v[2] + v[3] * v[3]); }
; __device__ __forceinline__ u32x4 pack8(f32x4 a, f32x4 b) { u32x4 w; w.x = cvt_pk_bf16(a[0], a[1]); w.y = cvt_pk_bf16(a[2], a[3]); w.z = cvt_pk_bf16(b[0], b[1]); w.w = cvt_pk_bf16(b[2], b[3]); return w; }
;     __device__ __forceinline__ void operator()(const f32x4 (&acc)[2][2][4][2], const Unit& u, int wr, int wc, int fr, int fq) const {
;     ...
;             for (int m = 0; m < 4; ++m) {
;                 const int row = u.pm * BM + ai * HALF + wr * 64 + m * 16 + fr;
;                 float q = 0.f;
; #pragma unroll
;                 for (int bj = 0; bj < 2; ++bj) {
;                     const size_t off = (size_t)row * 1024 + col0 + 128 * bj; const u32x4 w = bs[m][bj];
;                     const f32x4 b0 = (f32x4){__builtin_bit_cast(float, w.x << 16), __builtin_bit_cast(float, w.x & 0xffff0000u), __builtin_bit_cast(float, w.y << 16), __builtin_bit_cast(float, w.y & 0xffff0000u)};
;                     const f32x4 b1 = (f32x4){__builtin_bit_cast(float, w.z << 16), __builtin_bit_cast(float, w.z & 0xffff0000u), __builtin_bit_cast(float, w.w << 16), __builtin_bit_cast(float, w.w & 0xffff0000u)};
;                     const f32x4 v0 = acc[ai][bj][m][0] + b0, v1 = acc[ai][bj][m][1] + b1;
;                     if (last) { __builtin_nontemporal_store(v0, (f32x4*)(out + off)); __builtin_nontemporal_store(v1, (f32x4*)(out + off + 4)); }
;                     else { q += sq4(v0) + sq4(v1); *(u32x4*)(xb + off) = pack8(v0, v1); }
;                 }
;                 if (!last) { q += shx(q, 16); q += shx(q, 32); if (fq == 0) ss[(size_t)row * 16 + u.pn * 4 + wc] = q; }
.LBB0_449:
	s_or_b64 exec, exec, s[44:45]
	s_waitcnt vmcnt(7)
	v_lshlrev_b32_e32 v48, 16, v84
	s_waitcnt lgkmcnt(0)
	v_and_b32_e32 v49, 0xffff0000, v84
	v_lshlrev_b32_e32 v50, 16, v85
	v_and_b32_e32 v51, 0xffff0000, v85
	v_lshlrev_b32_e32 v52, 16, v86
	v_and_b32_e32 v53, 0xffff0000, v86
	v_lshlrev_b32_e32 v54, 16, v87
	v_and_b32_e32 v55, 0xffff0000, v87
	v_pk_add_f32 v[46:47], v[46:47], v[50:51]
	v_pk_add_f32 v[44:45], v[44:45], v[48:49]
	v_pk_add_f32 v[48:49], v[42:43], v[54:55]
	v_pk_add_f32 v[42:43], v[40:41], v[52:53]
	v_mul_f32_e32 v40, v45, v45
	v_mul_f32_e32 v41, v47, v47
	v_fmac_f32_e32 v40, v44, v44
	v_fmac_f32_e32 v41, v46, v46
	v_add_f32_e32 v40, v40, v41
	v_mul_f32_e32 v41, v43, v43
	v_mul_f32_e32 v50, v49, v49
	v_fmac_f32_e32 v41, v42, v42
	v_fmac_f32_e32 v50, v48, v48
	v_add_f32_e32 v41, v41, v50
	v_add_f32_e32 v50, v40, v41
	v_cvt_pk_bf16_f32 v40, v44, v45
	v_lshl_add_u64 v[44:45], s[18:19], 0, v[98:99]
	v_cvt_pk_bf16_f32 v41, v46, v47
	v_cvt_pk_bf16_f32 v42, v42, v43
	v_cvt_pk_bf16_f32 v43, v48, v49
	v_lshl_add_u64 v[44:45], v[168:169], 1, v[44:45]
	global_store_dwordx4 v[44:45], v[40:43], off
	s_waitcnt vmcnt(7)
	v_lshlrev_b32_e32 v46, 16, v82
	v_and_b32_e32 v47, 0xffff0000, v82
	v_lshlrev_b32_e32 v40, 16, v80
	v_and_b32_e32 v41, 0xffff0000, v80
	v_lshlrev_b32_e32 v42, 16, v81
	v_and_b32_e32 v43, 0xffff0000, v81
	v_lshlrev_b32_e32 v48, 16, v83
	v_and_b32_e32 v49, 0xffff0000, v83
	v_pk_add_f32 v[38:39], v[38:39], v[42:43]
	v_pk_add_f32 v[36:37], v[36:37], v[40:41]
	v_pk_add_f32 v[40:41], v[34:35], v[48:49]
	v_pk_add_f32 v[34:35], v[32:33], v[46:47]
	v_mul_f32_e32 v32, v37, v37
	v_mul_f32_e32 v33, v39, v39
	v_fmac_f32_e32 v32, v36, v36
	v_fmac_f32_e32 v33, v38, v38
	v_add_f32_e32 v32, v32, v33
	v_mul_f32_e32 v33, v35, v35
	v_mul_f32_e32 v42, v41, v41
	v_fmac_f32_e32 v33, v34, v34
	v_fmac_f32_e32 v42, v40, v40
	v_add_f32_e32 v33, v33, v42
	v_add_f32_e32 v32, v32, v33
	v_add_f32_e32 v42, v50, v32
	v_cvt_pk_bf16_f32 v32, v36, v37
	v_cvt_pk_bf16_f32 v33, v38, v39
	v_cvt_pk_bf16_f32 v34, v34, v35
	v_cvt_pk_bf16_f32 v35, v40, v41
	global_store_dwordx4 v[44:45], v[32:35], off offset:256
	s_nop 1
	s_nop 0
	s_nop 2
	v_mov_b32_e32 v32, v42
	s_nop 1
	v_permlane16_swap_b32_e32 v32, v42
	s_waitcnt lgkmcnt(0)
	v_add_f32_e32 v32, v42, v32
	s_nop 1
	v_mov_b32_e32 v33, v32
	s_nop 1
	v_permlane32_swap_b32_e32 v33, v32
	s_and_saveexec_b64 s[44:45], s[10:11]
	s_cbranch_execz .LBB0_451
	s_waitcnt lgkmcnt(0)
	v_add_f32_e32 v34, v32, v33
	v_lshlrev_b64 v[32:33], 6, v[96:97]
	v_lshl_add_u64 v[32:33], s[22:23], 0, v[32:33]
	v_lshl_add_u64 v[32:33], s[42:43], 2, v[32:33]
	s_lshl_b32 s14, s52, 2
	v_lshl_add_u64 v[32:33], v[32:33], 0, s[14:15]
	global_store_dword v[32:33], v34, off
; __device__ __forceinline__ float sq4(f32x4 v) { return (v[0] * v[0] + v[1] * v[1]) + (v[2] * v[2] + v[3] * v[3]); }
; __device__ __forceinline__ u32x4 pack8(f32x4 a, f32x4 b) { u32x4 w; w.x = cvt_pk_bf16(a[0], a[1]); w.y = cvt_pk_bf16(a[2], a[3]); w.z = cvt_pk_bf16(b[0], b[1]); w.w = cvt_pk_bf16(b[2], b[3]); return w; }
;     __device__ __forceinline__ void operator()(const f32x4 (&acc)[2][2][4][2], const Unit& u, int wr, int wc, int fr, int fq) const {
;     ...
;             for (int m = 0; m < 4; ++m) {
;                 const int row = u.pm * BM + ai * HALF + wr * 64 + m * 16 + fr;
;                 float q = 0.f;
; #pragma unroll
;                 for (int bj = 0; bj < 2; ++bj) {
;                     const size_t off = (size_t)row * 1024 + col0 + 128 * bj; const u32x4 w = bs[m][bj];
;                     const f32x4 b0 = (f32x4){__builtin_bit_cast(float, w.x << 16), __builtin_bit_cast(float, w.x & 0xffff0000u), __builtin_bit_cast(float, w.y << 16), __builtin_bit_cast(float, w.y & 0xffff0000u)};
;                     const f32x4 b1 = (f32x4){__builtin_bit_cast(float, w.z << 16), __builtin_bit_cast(float, w.z & 0xffff0000u), __builtin_bit_cast(float, w.w << 16), __builtin_bit_cast(float, w.w & 0xffff0000u)};
;                     const f32x4 v0 = acc[ai][bj][m][0] + b0, v1 = acc[ai][bj][m][1] + b1;
;                     if (last) { __builtin_nontemporal_store(v0, (f32x4*)(out + off)); __builtin_nontemporal_store(v1, (f32x4*)(out + off + 4)); }
;                     else { q += sq4(v0) + sq4(v1); *(u32x4*)(xb + off) = pack8(v0, v1); }
;                 }
;                 if (!last) { q += shx(q, 16); q += shx(q, 32); if (fq == 0) ss[(size_t)row * 16 + u.pn * 4 + wc] = q; }
.LBB0_451:
	s_or_b64 exec, exec, s[44:45]
	s_waitcnt vmcnt(7)
	v_lshlrev_b32_e32 v32, 16, v76
	s_waitcnt lgkmcnt(0)
	v_and_b32_e32 v33, 0xffff0000, v76
	v_lshlrev_b32_e32 v34, 16, v77
	v_and_b32_e32 v35, 0xffff0000, v77
	v_lshlrev_b32_e32 v36, 16, v78
	v_and_b32_e32 v37, 0xffff0000, v78
	v_lshlrev_b32_e32 v38, 16, v79
	v_and_b32_e32 v39, 0xffff0000, v79
	v_pk_add_f32 v[30:31], v[30:31], v[34:35]
	v_pk_add_f32 v[28:29], v[28:29], v[32:33]
	v_pk_add_f32 v[32:33], v[26:27], v[38:39]
	v_pk_add_f32 v[26:27], v[24:25], v[36:37]
	v_mul_f32_e32 v24, v29, v29
	v_mul_f32_e32 v25, v31, v31
	v_fmac_f32_e32 v24, v28, v28
	v_fmac_f32_e32 v25, v30, v30
	v_add_f32_e32 v24, v24, v25
	v_mul_f32_e32 v25, v27, v27
	v_mul_f32_e32 v34, v33, v33
	v_fmac_f32_e32 v25, v26, v26
	v_fmac_f32_e32 v34, v32, v32
	v_add_f32_e32 v25, v25, v34
	v_add_f32_e32 v34, v24, v25
	v_cvt_pk_bf16_f32 v24, v28, v29
	v_lshl_add_u64 v[28:29], s[18:19], 0, v[94:95]
	v_cvt_pk_bf16_f32 v25, v30, v31
	v_cvt_pk_bf16_f32 v26, v26, v27
	v_cvt_pk_bf16_f32 v27, v32, v33
	v_lshl_add_u64 v[28:29], v[168:169], 1, v[28:29]
	global_store_dwordx4 v[28:29], v[24:27], off
	s_waitcnt vmcnt(7)
	v_lshlrev_b32_e32 v30, 16, v74
	v_and_b32_e32 v31, 0xffff0000, v74
	v_lshlrev_b32_e32 v24, 16, v72
	v_and_b32_e32 v25, 0xffff0000, v72
	v_lshlrev_b32_e32 v26, 16, v73
	v_and_b32_e32 v27, 0xffff0000, v73
	v_lshlrev_b32_e32 v32, 16, v75
	v_and_b32_e32 v33, 0xffff0000, v75
	v_pk_add_f32 v[22:23], v[22:23], v[26:27]
	v_pk_add_f32 v[20:21], v[20:21], v[24:25]
	v_pk_add_f32 v[24:25], v[18:19], v[32:33]
	v_pk_add_f32 v[18:19], v[16:17], v[30:31]
	v_mul_f32_e32 v16, v21, v21
	v_mul_f32_e32 v17, v23, v23
	v_fmac_f32_e32 v16, v20, v20
	v_fmac_f32_e32 v17, v22, v22
	v_add_f32_e32 v16, v16, v17
	v_mul_f32_e32 v17, v19, v19
	v_mul_f32_e32 v26, v25, v25
	v_fmac_f32_e32 v17, v18, v18
	v_fmac_f32_e32 v26, v24, v24
	v_add_f32_e32 v17, v17, v26
	v_add_f32_e32 v16, v16, v17
	v_add_f32_e32 v26, v34, v16
	v_cvt_pk_bf16_f32 v16, v20, v21
	v_cvt_pk_bf16_f32 v17, v22, v23
	v_cvt_pk_bf16_f32 v18, v18, v19
	v_cvt_pk_bf16_f32 v19, v24, v25
	global_store_dwordx4 v[28:29], v[16:19], off offset:256
	s_nop 1
	s_nop 0
	s_nop 2
	v_mov_b32_e32 v16, v26
	s_nop 1
	v_permlane16_swap_b32_e32 v16, v26
	s_waitcnt lgkmcnt(0)
	v_add_f32_e32 v16, v26, v16
	s_nop 1
	v_mov_b32_e32 v17, v16
	s_nop 1
	v_permlane32_swap_b32_e32 v17, v16
	s_and_saveexec_b64 s[44:45], s[10:11]
	s_cbranch_execz .LBB0_453
	s_waitcnt lgkmcnt(0)
	v_add_f32_e32 v18, v16, v17
	v_lshlrev_b64 v[16:17], 6, v[92:93]
	v_lshl_add_u64 v[16:17], s[22:23], 0, v[16:17]
	v_lshl_add_u64 v[16:17], s[42:43], 2, v[16:17]
	s_lshl_b32 s14, s52, 2
	v_lshl_add_u64 v[16:17], v[16:17], 0, s[14:15]
	global_store_dword v[16:17], v18, off
.LBB0_453:
	s_or_b64 exec, exec, s[44:45]
	s_waitcnt vmcnt(7)
	v_lshlrev_b32_e32 v16, 16, v68
	s_waitcnt lgkmcnt(0)
	v_and_b32_e32 v17, 0xffff0000, v68
	v_lshlrev_b32_e32 v18, 16, v69
	v_and_b32_e32 v19, 0xffff0000, v69
	v_lshlrev_b32_e32 v20, 16, v70
	v_and_b32_e32 v21, 0xffff0000, v70
	v_lshlrev_b32_e32 v22, 16, v71
	v_and_b32_e32 v23, 0xffff0000, v71
	v_pk_add_f32 v[14:15], v[14:15], v[18:19]
	v_pk_add_f32 v[12:13], v[12:13], v[16:17]
	v_pk_add_f32 v[16:17], v[10:11], v[22:23]
	v_pk_add_f32 v[10:11], v[8:9], v[20:21]
	v_mul_f32_e32 v8, v13, v13
	v_mul_f32_e32 v9, v15, v15
	v_fmac_f32_e32 v8, v12, v12
	v_fmac_f32_e32 v9, v14, v14
	v_add_f32_e32 v8, v8, v9
	v_mul_f32_e32 v9, v11, v11
	v_mul_f32_e32 v18, v17, v17
	v_fmac_f32_e32 v9, v10, v10
	v_fmac_f32_e32 v18, v16, v16
	v_add_f32_e32 v9, v9, v18
	v_add_f32_e32 v18, v8, v9
	v_cvt_pk_bf16_f32 v8, v12, v13
	v_lshl_add_u64 v[12:13], s[18:19], 0, v[90:91]
	v_cvt_pk_bf16_f32 v9, v14, v15
	v_cvt_pk_bf16_f32 v10, v10, v11
	v_cvt_pk_bf16_f32 v11, v16, v17
	v_lshl_add_u64 v[12:13], v[168:169], 1, v[12:13]
	global_store_dwordx4 v[12:13], v[8:11], off
	s_waitcnt vmcnt(7)
	v_lshlrev_b32_e32 v14, 16, v66
	v_and_b32_e32 v15, 0xffff0000, v66
	v_lshlrev_b32_e32 v8, 16, v64
	v_and_b32_e32 v9, 0xffff0000, v64
	v_lshlrev_b32_e32 v10, 16, v65
	v_and_b32_e32 v11, 0xffff0000, v65
	v_lshlrev_b32_e32 v16, 16, v67
	v_and_b32_e32 v17, 0xffff0000, v67
	v_pk_add_f32 v[6:7], v[6:7], v[10:11]
	v_pk_add_f32 v[4:5], v[4:5], v[8:9]
	v_pk_add_f32 v[8:9], v[2:3], v[16:17]
	v_pk_add_f32 v[2:3], v[0:1], v[14:15]
	v_mul_f32_e32 v0, v5, v5
	v_mul_f32_e32 v1, v7, v7
	v_fmac_f32_e32 v0, v4, v4
	v_fmac_f32_e32 v1, v6, v6
	v_add_f32_e32 v0, v0, v1
	v_mul_f32_e32 v1, v3, v3
	v_mul_f32_e32 v10, v9, v9
	v_fmac_f32_e32 v1, v2, v2
	v_fmac_f32_e32 v10, v8, v8
	v_add_f32_e32 v1, v1, v10
	v_add_f32_e32 v0, v0, v1
	v_add_f32_e32 v10, v18, v0
	v_cvt_pk_bf16_f32 v0, v4, v5
	v_cvt_pk_bf16_f32 v1, v6, v7
	v_cvt_pk_bf16_f32 v2, v2, v3
	v_cvt_pk_bf16_f32 v3, v8, v9
	global_store_dwordx4 v[12:13], v[0:3], off offset:256
	s_nop 1
	s_nop 0
	s_nop 2
	v_mov_b32_e32 v0, v10
	s_nop 1
	v_permlane16_swap_b32_e32 v0, v10
	s_waitcnt lgkmcnt(0)
	v_add_f32_e32 v0, v10, v0
	s_nop 1
	v_mov_b32_e32 v1, v0
	s_nop 1
	v_permlane32_swap_b32_e32 v1, v0
	s_and_saveexec_b64 s[44:45], s[10:11]
	s_cbranch_execz .LBB0_455
	s_waitcnt lgkmcnt(0)
	v_add_f32_e32 v2, v0, v1
	v_lshlrev_b64 v[0:1], 6, v[88:89]
	v_lshl_add_u64 v[0:1], s[22:23], 0, v[0:1]
	v_lshl_add_u64 v[0:1], s[42:43], 2, v[0:1]
	s_lshl_b32 s14, s52, 2
	v_lshl_add_u64 v[0:1], v[0:1], 0, s[14:15]
	global_store_dword v[0:1], v2, off

; __device__ __forceinline__ float row_part(const float* ss, int row, int fq) { const f32x4 a = ((const f32x4*)(ss + (size_t)row * 16))[fq]; return (a[0] + a[1]) + (a[2] + a[3]); }
; __device__ __forceinline__ float row_finish(float t) { t += shx(t, 16); t += shx(t, 32); return __builtin_amdgcn_rsqf(t * (1.0f / 1024.0f) + RMS_EPS); }
;     __device__ __forceinline__ void operator()(const f32x4 (&acc)[2][2][4][2], const Unit& u, int wr, int wc, int fr, int fq) const {
;         const int col0 = u.pn * 128 + 32 * wc + 8 * fq;
;         float rs[2][4];
; #pragma unroll
;         for (int ai = 0; ai < 2; ++ai)
; #pragma unroll
;             for (int m = 0; m < 4; ++m) rs[ai][m] = row_part(ss, u.pm * BM + ai * HALF + wr * 64 + m * 16 + fr, fq);
; #pragma unroll
;         for (int ai = 0; ai < 2; ++ai)
; #pragma unroll
;             for (int m = 0; m < 4; ++m) rs[ai][m] = row_finish(rs[ai][m]);
.LBB0_523:
	v_lshl_add_u32 v170, s36, 8, v153
	v_ashrrev_i32_e32 v171, 31, v170
	v_or_b32_e32 v166, 16, v170
	v_lshlrev_b64 v[146:147], 6, v[170:171]
	v_ashrrev_i32_e32 v167, 31, v166
	v_lshl_add_u64 v[146:147], v[136:137], 0, v[146:147]
	v_lshlrev_b64 v[148:149], 6, v[166:167]
	v_lshl_add_u64 v[148:149], v[136:137], 0, v[148:149]
	ds_read_b128 v[176:179], v239
	ds_read_b128 v[180:183], v239 offset:1024
	v_or_b32_e32 v162, 32, v170
	v_ashrrev_i32_e32 v163, 31, v162
	v_or_b32_e32 v158, 48, v170
	v_lshlrev_b64 v[146:147], 6, v[162:163]
	v_ashrrev_i32_e32 v159, 31, v158
	v_lshl_add_u64 v[146:147], v[136:137], 0, v[146:147]
	v_lshlrev_b64 v[148:149], 6, v[158:159]
	v_lshl_add_u64 v[148:149], v[136:137], 0, v[148:149]
	ds_read_b128 v[184:187], v239 offset:2048
	ds_read_b128 v[188:191], v239 offset:3072
	v_add_u32_e32 v154, 0x80, v170
	v_ashrrev_i32_e32 v155, 31, v154
	v_add_u32_e32 v150, 0x90, v170
	v_lshlrev_b64 v[146:147], 6, v[154:155]
	v_ashrrev_i32_e32 v151, 31, v150
	v_lshl_add_u64 v[146:147], v[136:137], 0, v[146:147]
	v_lshlrev_b64 v[148:149], 6, v[150:151]
	v_lshl_add_u64 v[148:149], v[136:137], 0, v[148:149]
	ds_read_b128 v[192:195], v239 offset:8192
	ds_read_b128 v[196:199], v239 offset:9216
	v_add_u32_e32 v148, 0xa0, v170
	v_ashrrev_i32_e32 v149, 31, v148
	v_lshlrev_b64 v[146:147], 6, v[148:149]
	v_lshl_add_u64 v[146:147], v[136:137], 0, v[146:147]
	ds_read_b128 v[202:205], v239 offset:10240
	v_add_u32_e32 v146, 0xb0, v170
	v_ashrrev_i32_e32 v147, 31, v146
	v_lshlrev_b64 v[206:207], 6, v[146:147]
	v_lshl_add_u64 v[206:207], v[136:137], 0, v[206:207]
	ds_read_b128 v[206:209], v239 offset:11264
	s_nop 0
	s_nop 3
	s_andn2_b64 vcc, exec, s[10:11]
	s_nop 3
	s_mov_b64 s[10:11], -1
	s_waitcnt lgkmcnt(0)
	v_mov_b32_e32 v210, v177
	v_mov_b32_e32 v211, v178
	v_mov_b32_e32 v177, v179
	v_pk_add_f32 v[176:177], v[210:211], v[176:177]
	v_mov_b32_e32 v178, v181
	v_add_f32_e32 v152, v176, v177
	v_mov_b32_e32 v179, v182
	v_mov_b32_e32 v181, v183
	v_mov_b32_e32 v147, v152
	s_nop 1
	v_permlane16_swap_b32_e32 v147, v152
	v_pk_add_f32 v[176:177], v[178:179], v[180:181]
	v_mov_b32_e32 v182, v185
	v_add_f32_e32 v155, v176, v177
	v_mov_b32_e32 v151, v155
	s_nop 1
	v_permlane16_swap_b32_e32 v151, v155
	s_waitcnt lgkmcnt(0)
	v_add_f32_e32 v147, v152, v147
	s_nop 0
	v_mov_b32_e32 v149, v147
	s_nop 1
	v_permlane32_swap_b32_e32 v149, v147
	s_waitcnt lgkmcnt(0)
	v_add_f32_e32 v151, v155, v151
	s_nop 1
	v_mov_b32_e32 v152, v151
	s_nop 1
	v_permlane32_swap_b32_e32 v152, v151
	s_waitcnt lgkmcnt(0)
	v_add_f32_e32 v147, v147, v149
	s_nop 0
	v_mov_b32_e32 v183, v186
	v_mov_b32_e32 v185, v187
	v_pk_add_f32 v[178:179], v[182:183], v[184:185]
	v_fmamk_f32 v147, v147, 0x3a800000, v175
	s_nop 0
	v_add_f32_e32 v156, v178, v179
	v_rsq_f32_e32 v176, v147
	s_waitcnt lgkmcnt(0)
	v_add_f32_e32 v147, v151, v152
	s_nop 2
	v_mov_b32_e32 v186, v189
	v_mov_b32_e32 v187, v190
	v_mov_b32_e32 v189, v191
	v_mov_b32_e32 v149, v156
	s_nop 1
	v_permlane16_swap_b32_e32 v149, v156
	v_pk_add_f32 v[180:181], v[186:187], v[188:189]
	s_nop 0
	v_add_f32_e32 v159, v180, v181
	s_nop 0
	v_mov_b32_e32 v152, v159
	s_nop 1
	v_permlane16_swap_b32_e32 v152, v159
	s_waitcnt lgkmcnt(0)
	v_add_f32_e32 v149, v156, v149
	s_nop 2
	v_mov_b32_e32 v151, v149
	s_nop 1
	v_permlane32_swap_b32_e32 v151, v149
	s_nop 0
	s_waitcnt lgkmcnt(0)
	v_add_f32_e32 v152, v159, v152
	s_nop 0
	v_mov_b32_e32 v156, v152
	s_nop 1
	v_permlane32_swap_b32_e32 v156, v152
	v_fmamk_f32 v147, v147, 0x3a800000, v175
	v_rsq_f32_e32 v174, v147
	s_waitcnt lgkmcnt(0)
	v_add_f32_e32 v147, v149, v151
	s_nop 0
	v_mov_b32_e32 v190, v193
	v_mov_b32_e32 v191, v194
	v_mov_b32_e32 v193, v195
	v_fmamk_f32 v147, v147, 0x3a800000, v175
	v_pk_add_f32 v[182:183], v[190:191], v[192:193]
	v_rsq_f32_e32 v172, v147
	s_waitcnt lgkmcnt(0)
	v_add_f32_e32 v147, v152, v156
	s_nop 2
	v_mov_b32_e32 v194, v197
	v_mov_b32_e32 v195, v198
	v_mov_b32_e32 v197, v199
	v_add_f32_e32 v160, v182, v183
	s_nop 0
	v_pk_add_f32 v[184:185], v[194:195], v[196:197]
	v_mov_b32_e32 v149, v160
	s_nop 1
	v_permlane16_swap_b32_e32 v149, v160
	s_nop 0
	v_add_f32_e32 v163, v184, v185
	s_nop 0
	v_mov_b32_e32 v152, v163
	s_nop 1
	v_permlane16_swap_b32_e32 v152, v163
	s_nop 1
	s_waitcnt lgkmcnt(0)
	v_add_f32_e32 v149, v160, v149
	s_nop 0
	v_mov_b32_e32 v151, v149
	s_nop 1
	v_permlane32_swap_b32_e32 v151, v149
	s_nop 0
	s_waitcnt lgkmcnt(0)
	v_add_f32_e32 v152, v163, v152
	s_nop 0
	v_mov_b32_e32 v156, v152
	s_nop 1
	v_permlane32_swap_b32_e32 v156, v152
	v_fmamk_f32 v147, v147, 0x3a800000, v175
	v_rsq_f32_e32 v168, v147
	s_waitcnt lgkmcnt(0)
	v_add_f32_e32 v147, v149, v151
	v_fmamk_f32 v147, v147, 0x3a800000, v175
	v_rsq_f32_e32 v164, v147
	s_waitcnt lgkmcnt(0)
	v_add_f32_e32 v147, v152, v156
	s_nop 2
	v_mov_b32_e32 v198, v203
	v_mov_b32_e32 v199, v204
	v_mov_b32_e32 v203, v205
	v_mov_b32_e32 v204, v207
	v_mov_b32_e32 v205, v208
	v_mov_b32_e32 v207, v209
	v_pk_add_f32 v[188:189], v[204:205], v[206:207]
	s_nop 0
	v_pk_add_f32 v[186:187], v[198:199], v[202:203]
	v_add_f32_e32 v155, v188, v189
	s_nop 1
	v_add_f32_e32 v167, v186, v187
	s_nop 0
	v_mov_b32_e32 v152, v155
	s_nop 1
	v_permlane16_swap_b32_e32 v152, v155
	v_mov_b32_e32 v149, v167
	s_nop 1
	v_permlane16_swap_b32_e32 v149, v167
	s_nop 1
	v_fmamk_f32 v147, v147, 0x3a800000, v175
	s_waitcnt lgkmcnt(0)
	v_add_f32_e32 v152, v155, v152
	s_nop 0
	s_waitcnt lgkmcnt(0)
	v_add_f32_e32 v149, v167, v149
	v_mov_b32_e32 v151, v149
	s_nop 1
	v_permlane32_swap_b32_e32 v151, v149
	s_nop 1
	v_mov_b32_e32 v155, v152
	s_nop 1
	v_permlane32_swap_b32_e32 v155, v152
	v_rsq_f32_e32 v160, v147
	s_waitcnt lgkmcnt(0)
; __device__ __forceinline__ f32x4 silu4(f32x4 v) { return (f32x4){silu_f(v[0]), silu_f(v[1]), silu_f(v[2]), silu_f(v[3])}; }
; __device__ __forceinline__ u32x4 pack8(f32x4 a, f32x4 b) { u32x4 w; w.x = cvt_pk_bf16(a[0], a[1]); w.y = cvt_pk_bf16(a[2], a[3]); w.z = cvt_pk_bf16(b[0], b[1]); w.w = cvt_pk_bf16(b[2], b[3]); return w; }
;     __device__ __forceinline__ void operator()(const f32x4 (&acc)[2][2][4][2], const Unit& u, int wr, int wc, int fr, int fq) const {
;     ...
;         for (int ai = 0; ai < 2; ++ai)
; #pragma unroll
;             for (int m = 0; m < 4; ++m) {
;                 const int row = u.pm * BM + ai * HALF + wr * 64 + m * 16 + fr;
;                 const float rstd = rs[ai][m];
;                 const f32x4 a0 = silu4(acc[ai][0][m][0] * rstd) * (acc[ai][1][m][0] * rstd);
;                 const f32x4 a1 = silu4(acc[ai][0][m][1] * rstd) * (acc[ai][1][m][1] * rstd);
;                 *(u32x4*)(ACT + (size_t)row * 2816 + col0) = pack8(a0, a1);
;             }
	v_add_f32_e32 v147, v149, v151
	v_fmamk_f32 v147, v147, 0x3a800000, v175
	v_rsq_f32_e32 v156, v147
	s_waitcnt lgkmcnt(0)
	v_add_f32_e32 v147, v152, v155
	v_fmamk_f32 v147, v147, 0x3a800000, v175
	v_pk_mul_f32 v[124:125], v[124:125], v[176:177] op_sel_hi:[1,0]
	v_rsq_f32_e32 v152, v147
	v_mul_f32_e32 v147, 0xbfb8aa3b, v124
	v_exp_f32_e32 v147, v147
	v_mul_f32_e32 v149, 0xbfb8aa3b, v125
	v_exp_f32_e32 v149, v149
	v_pk_mul_f32 v[126:127], v[126:127], v[176:177] op_sel_hi:[1,0]
	v_add_f32_e32 v147, 1.0, v147
	v_rcp_f32_e32 v178, v147
	v_add_f32_e32 v147, 1.0, v149
	v_mul_f32_e32 v149, 0xbfb8aa3b, v126
	v_exp_f32_e32 v149, v149
	v_mul_f32_e32 v151, 0xbfb8aa3b, v127
	v_exp_f32_e32 v151, v151
	v_rcp_f32_e32 v179, v147
	v_add_f32_e32 v147, 1.0, v149
	v_rcp_f32_e32 v180, v147
	v_add_f32_e32 v147, 1.0, v151
	v_pk_mul_f32 v[120:121], v[120:121], v[176:177] op_sel_hi:[1,0]
	v_rcp_f32_e32 v181, v147
	v_mul_f32_e32 v147, 0xbfb8aa3b, v120
	v_exp_f32_e32 v147, v147
	v_mul_f32_e32 v149, 0xbfb8aa3b, v121
	v_exp_f32_e32 v149, v149
	v_pk_mul_f32 v[122:123], v[122:123], v[176:177] op_sel_hi:[1,0]
	v_add_f32_e32 v147, 1.0, v147
	v_pk_mul_f32 v[124:125], v[124:125], v[178:179]
	v_rcp_f32_e32 v178, v147
	v_add_f32_e32 v147, 1.0, v149
	v_mul_f32_e32 v149, 0xbfb8aa3b, v122
	v_exp_f32_e32 v149, v149
	v_mul_f32_e32 v151, 0xbfb8aa3b, v123
	v_exp_f32_e32 v151, v151
	v_rcp_f32_e32 v179, v147
	v_add_f32_e32 v147, 1.0, v149
	v_pk_mul_f32 v[126:127], v[126:127], v[180:181]
	v_rcp_f32_e32 v180, v147
	v_add_f32_e32 v147, 1.0, v151
	v_rcp_f32_e32 v181, v147
	v_pk_mul_f32 v[116:117], v[116:117], v[176:177] op_sel_hi:[1,0]
	v_pk_mul_f32 v[118:119], v[118:119], v[176:177] op_sel_hi:[1,0]
	v_pk_mul_f32 v[120:121], v[120:121], v[178:179]
	v_pk_mul_f32 v[112:113], v[112:113], v[176:177] op_sel_hi:[1,0]
	v_lshl_or_b32 v182, s57, 7, v161
	v_pk_mul_f32 v[118:119], v[118:119], v[126:127]
	v_pk_mul_f32 v[116:117], v[116:117], v[124:125]
	v_pk_mul_f32 v[122:123], v[122:123], v[180:181]
	v_pk_mul_f32 v[114:115], v[114:115], v[176:177] op_sel_hi:[1,0]
	v_pk_mul_f32 v[112:113], v[112:113], v[120:121]
	v_ashrrev_i32_e32 v183, 31, v182
	v_pk_mul_f32 v[114:115], v[114:115], v[122:123]
	v_cvt_pk_bf16_f32 v116, v116, v117
	v_cvt_pk_bf16_f32 v117, v118, v119
	v_cvt_pk_bf16_f32 v118, v112, v113
	v_mov_b64_e32 v[112:113], s[14:15]
	v_cvt_pk_bf16_f32 v119, v114, v115
	v_mad_i64_i32 v[120:121], s[38:39], v170, s56, v[112:113]
	v_lshlrev_b64 v[114:115], 1, v[182:183]
	v_pk_mul_f32 v[108:109], v[108:109], v[174:175] op_sel_hi:[1,0]
	v_pk_mul_f32 v[110:111], v[110:111], v[174:175] op_sel_hi:[1,0]
	v_mul_f32_e32 v122, 0xbfb8aa3b, v108
	v_mul_f32_e32 v123, 0xbfb8aa3b, v109
	v_lshl_add_u64 v[120:121], v[120:121], 0, v[114:115]
	v_pk_mul_f32 v[104:105], v[104:105], v[174:175] op_sel_hi:[1,0]
	v_pk_mul_f32 v[106:107], v[106:107], v[174:175] op_sel_hi:[1,0]
	v_exp_f32_e32 v122, v122
	v_exp_f32_e32 v123, v123
	v_mul_f32_e32 v124, 0xbfb8aa3b, v110
	v_mul_f32_e32 v125, 0xbfb8aa3b, v111
	global_store_dwordx4 v[120:121], v[116:119], off
	v_exp_f32_e32 v124, v124
	v_exp_f32_e32 v125, v125
	v_mul_f32_e32 v116, 0xbfb8aa3b, v104
	v_mul_f32_e32 v117, 0xbfb8aa3b, v105
	v_mul_f32_e32 v118, 0xbfb8aa3b, v106
	v_mul_f32_e32 v119, 0xbfb8aa3b, v107
	v_exp_f32_e32 v116, v116
	v_exp_f32_e32 v117, v117
	v_exp_f32_e32 v118, v118
	v_exp_f32_e32 v119, v119
	v_add_f32_e32 v122, 1.0, v122
	v_add_f32_e32 v123, 1.0, v123
	v_rcp_f32_e32 v122, v122
	v_rcp_f32_e32 v123, v123
	v_add_f32_e32 v124, 1.0, v124
	v_add_f32_e32 v125, 1.0, v125
	v_add_f32_e32 v116, 1.0, v116
	v_add_f32_e32 v117, 1.0, v117
	v_add_f32_e32 v118, 1.0, v118
	v_add_f32_e32 v119, 1.0, v119
	v_rcp_f32_e32 v124, v124
	v_rcp_f32_e32 v125, v125
	v_rcp_f32_e32 v116, v116
	v_rcp_f32_e32 v117, v117
	v_rcp_f32_e32 v118, v118
	v_rcp_f32_e32 v119, v119
	v_pk_mul_f32 v[108:109], v[108:109], v[122:123]
	v_pk_mul_f32 v[100:101], v[100:101], v[174:175] op_sel_hi:[1,0]
	v_pk_mul_f32 v[110:111], v[110:111], v[124:125]
	v_pk_mul_f32 v[102:103], v[102:103], v[174:175] op_sel_hi:[1,0]
	v_pk_mul_f32 v[100:101], v[100:101], v[108:109]
	v_pk_mul_f32 v[104:105], v[104:105], v[116:117]
	v_pk_mul_f32 v[106:107], v[106:107], v[118:119]
	v_pk_mul_f32 v[96:97], v[96:97], v[174:175] op_sel_hi:[1,0]
	v_pk_mul_f32 v[98:99], v[98:99], v[174:175] op_sel_hi:[1,0]
	v_pk_mul_f32 v[102:103], v[102:103], v[110:111]
	v_pk_mul_f32 v[106:107], v[98:99], v[106:107]
	v_pk_mul_f32 v[98:99], v[96:97], v[104:105]
	v_cvt_pk_bf16_f32 v96, v100, v101
	v_mad_i64_i32 v[100:101], s[38:39], v166, s56, v[112:113]
	v_pk_mul_f32 v[92:93], v[92:93], v[172:173] op_sel_hi:[1,0]
	v_cvt_pk_bf16_f32 v97, v102, v103
	v_cvt_pk_bf16_f32 v98, v98, v99
	v_cvt_pk_bf16_f32 v99, v106, v107
	v_pk_mul_f32 v[94:95], v[94:95], v[172:173] op_sel_hi:[1,0]
	v_mul_f32_e32 v102, 0xbfb8aa3b, v92
	v_mul_f32_e32 v103, 0xbfb8aa3b, v93
	v_lshl_add_u64 v[100:101], v[100:101], 0, v[114:115]
	v_pk_mul_f32 v[88:89], v[88:89], v[172:173] op_sel_hi:[1,0]
	v_pk_mul_f32 v[90:91], v[90:91], v[172:173] op_sel_hi:[1,0]
	v_exp_f32_e32 v102, v102
	v_exp_f32_e32 v103, v103
	v_mul_f32_e32 v104, 0xbfb8aa3b, v94
	v_mul_f32_e32 v105, 0xbfb8aa3b, v95
	global_store_dwordx4 v[100:101], v[96:99], off
	v_exp_f32_e32 v104, v104
	v_exp_f32_e32 v105, v105
	v_mul_f32_e32 v96, 0xbfb8aa3b, v88
	v_mul_f32_e32 v97, 0xbfb8aa3b, v89
	v_mul_f32_e32 v98, 0xbfb8aa3b, v90
	v_mul_f32_e32 v99, 0xbfb8aa3b, v91
	v_exp_f32_e32 v96, v96
	v_exp_f32_e32 v97, v97
	v_exp_f32_e32 v98, v98
	v_exp_f32_e32 v99, v99
	v_add_f32_e32 v102, 1.0, v102
	v_add_f32_e32 v103, 1.0, v103
	v_rcp_f32_e32 v102, v102
	v_rcp_f32_e32 v103, v103
	v_add_f32_e32 v104, 1.0, v104
	v_add_f32_e32 v105, 1.0, v105
; __device__ __forceinline__ f32x4 silu4(f32x4 v) { return (f32x4){silu_f(v[0]), silu_f(v[1]), silu_f(v[2]), silu_f(v[3])}; }
; __device__ __forceinline__ u32x4 pack8(f32x4 a, f32x4 b) { u32x4 w; w.x = cvt_pk_bf16(a[0], a[1]); w.y = cvt_pk_bf16(a[2], a[3]); w.z = cvt_pk_bf16(b[0], b[1]); w.w = cvt_pk_bf16(b[2], b[3]); return w; }
;     __device__ __forceinline__ void operator()(const f32x4 (&acc)[2][2][4][2], const Unit& u, int wr, int wc, int fr, int fq) const {
;     ...
;         for (int ai = 0; ai < 2; ++ai)
; #pragma unroll
;             for (int m = 0; m < 4; ++m) {
;                 const int row = u.pm * BM + ai * HALF + wr * 64 + m * 16 + fr;
;                 const float rstd = rs[ai][m];
;                 const f32x4 a0 = silu4(acc[ai][0][m][0] * rstd) * (acc[ai][1][m][0] * rstd);
;                 const f32x4 a1 = silu4(acc[ai][0][m][1] * rstd) * (acc[ai][1][m][1] * rstd);
;                 *(u32x4*)(ACT + (size_t)row * 2816 + col0) = pack8(a0, a1);
;             }
	v_add_f32_e32 v96, 1.0, v96
	v_add_f32_e32 v97, 1.0, v97
	v_add_f32_e32 v98, 1.0, v98
	v_add_f32_e32 v99, 1.0, v99
	v_rcp_f32_e32 v104, v104
	v_rcp_f32_e32 v105, v105
	v_rcp_f32_e32 v96, v96
	v_rcp_f32_e32 v97, v97
	v_rcp_f32_e32 v98, v98
	v_rcp_f32_e32 v99, v99
	v_pk_mul_f32 v[92:93], v[92:93], v[102:103]
	v_pk_mul_f32 v[84:85], v[84:85], v[172:173] op_sel_hi:[1,0]
	v_pk_mul_f32 v[94:95], v[94:95], v[104:105]
	v_pk_mul_f32 v[86:87], v[86:87], v[172:173] op_sel_hi:[1,0]
	v_pk_mul_f32 v[84:85], v[84:85], v[92:93]
	v_pk_mul_f32 v[88:89], v[88:89], v[96:97]
	v_pk_mul_f32 v[90:91], v[90:91], v[98:99]
	v_pk_mul_f32 v[80:81], v[80:81], v[172:173] op_sel_hi:[1,0]
	v_pk_mul_f32 v[82:83], v[82:83], v[172:173] op_sel_hi:[1,0]
	v_pk_mul_f32 v[86:87], v[86:87], v[94:95]
	v_pk_mul_f32 v[90:91], v[82:83], v[90:91]
	v_pk_mul_f32 v[82:83], v[80:81], v[88:89]
	v_cvt_pk_bf16_f32 v80, v84, v85
	v_mad_i64_i32 v[84:85], s[38:39], v162, s56, v[112:113]
	v_pk_mul_f32 v[76:77], v[76:77], v[168:169] op_sel_hi:[1,0]
	v_cvt_pk_bf16_f32 v81, v86, v87
	v_cvt_pk_bf16_f32 v82, v82, v83
	v_cvt_pk_bf16_f32 v83, v90, v91
	v_pk_mul_f32 v[78:79], v[78:79], v[168:169] op_sel_hi:[1,0]
	v_mul_f32_e32 v86, 0xbfb8aa3b, v76
	v_mul_f32_e32 v87, 0xbfb8aa3b, v77
	v_lshl_add_u64 v[84:85], v[84:85], 0, v[114:115]
	v_pk_mul_f32 v[72:73], v[72:73], v[168:169] op_sel_hi:[1,0]
	v_pk_mul_f32 v[74:75], v[74:75], v[168:169] op_sel_hi:[1,0]
	v_exp_f32_e32 v86, v86
	v_exp_f32_e32 v87, v87
	v_mul_f32_e32 v88, 0xbfb8aa3b, v78
	v_mul_f32_e32 v89, 0xbfb8aa3b, v79
	global_store_dwordx4 v[84:85], v[80:83], off
	v_exp_f32_e32 v88, v88
	v_exp_f32_e32 v89, v89
	v_mul_f32_e32 v80, 0xbfb8aa3b, v72
	v_mul_f32_e32 v81, 0xbfb8aa3b, v73
	v_mul_f32_e32 v82, 0xbfb8aa3b, v74
	v_mul_f32_e32 v83, 0xbfb8aa3b, v75
	v_exp_f32_e32 v80, v80
	v_exp_f32_e32 v81, v81
	v_exp_f32_e32 v82, v82
	v_exp_f32_e32 v83, v83
	v_add_f32_e32 v86, 1.0, v86
	v_add_f32_e32 v87, 1.0, v87
	v_rcp_f32_e32 v86, v86
	v_rcp_f32_e32 v87, v87
	v_add_f32_e32 v88, 1.0, v88
	v_add_f32_e32 v89, 1.0, v89
	v_add_f32_e32 v80, 1.0, v80
	v_add_f32_e32 v81, 1.0, v81
	v_add_f32_e32 v82, 1.0, v82
	v_add_f32_e32 v83, 1.0, v83
	v_rcp_f32_e32 v88, v88
	v_rcp_f32_e32 v89, v89
	v_rcp_f32_e32 v80, v80
	v_rcp_f32_e32 v81, v81
	v_rcp_f32_e32 v82, v82
	v_rcp_f32_e32 v83, v83
	v_pk_mul_f32 v[76:77], v[76:77], v[86:87]
	v_pk_mul_f32 v[68:69], v[68:69], v[168:169] op_sel_hi:[1,0]
	v_pk_mul_f32 v[78:79], v[78:79], v[88:89]
	v_pk_mul_f32 v[70:71], v[70:71], v[168:169] op_sel_hi:[1,0]
	v_pk_mul_f32 v[68:69], v[68:69], v[76:77]
	v_pk_mul_f32 v[72:73], v[72:73], v[80:81]
	v_pk_mul_f32 v[74:75], v[74:75], v[82:83]
	v_pk_mul_f32 v[64:65], v[64:65], v[168:169] op_sel_hi:[1,0]
	v_pk_mul_f32 v[66:67], v[66:67], v[168:169] op_sel_hi:[1,0]
	v_pk_mul_f32 v[70:71], v[70:71], v[78:79]
	v_pk_mul_f32 v[74:75], v[66:67], v[74:75]
	v_pk_mul_f32 v[66:67], v[64:65], v[72:73]
	v_cvt_pk_bf16_f32 v64, v68, v69
	v_mad_i64_i32 v[68:69], s[38:39], v158, s56, v[112:113]
	v_pk_mul_f32 v[60:61], v[60:61], v[164:165] op_sel_hi:[1,0]
	v_cvt_pk_bf16_f32 v65, v70, v71
	v_cvt_pk_bf16_f32 v66, v66, v67
	v_cvt_pk_bf16_f32 v67, v74, v75
	v_pk_mul_f32 v[62:63], v[62:63], v[164:165] op_sel_hi:[1,0]
	v_mul_f32_e32 v70, 0xbfb8aa3b, v60
	v_mul_f32_e32 v71, 0xbfb8aa3b, v61
	v_lshl_add_u64 v[68:69], v[68:69], 0, v[114:115]
	v_pk_mul_f32 v[56:57], v[56:57], v[164:165] op_sel_hi:[1,0]
	v_pk_mul_f32 v[58:59], v[58:59], v[164:165] op_sel_hi:[1,0]
	v_exp_f32_e32 v70, v70
	v_exp_f32_e32 v71, v71
	v_mul_f32_e32 v72, 0xbfb8aa3b, v62
	v_mul_f32_e32 v73, 0xbfb8aa3b, v63
	global_store_dwordx4 v[68:69], v[64:67], off
	v_exp_f32_e32 v72, v72
	v_exp_f32_e32 v73, v73
	v_mul_f32_e32 v64, 0xbfb8aa3b, v56
	v_mul_f32_e32 v65, 0xbfb8aa3b, v57
	v_mul_f32_e32 v66, 0xbfb8aa3b, v58
	v_mul_f32_e32 v67, 0xbfb8aa3b, v59
	v_exp_f32_e32 v64, v64
	v_exp_f32_e32 v65, v65
	v_exp_f32_e32 v66, v66
	v_exp_f32_e32 v67, v67
	v_add_f32_e32 v70, 1.0, v70
	v_add_f32_e32 v71, 1.0, v71
	v_rcp_f32_e32 v70, v70
	v_rcp_f32_e32 v71, v71
	v_add_f32_e32 v72, 1.0, v72
	v_add_f32_e32 v73, 1.0, v73
	v_add_f32_e32 v64, 1.0, v64
	v_add_f32_e32 v65, 1.0, v65
	v_add_f32_e32 v66, 1.0, v66
	v_add_f32_e32 v67, 1.0, v67
	v_rcp_f32_e32 v72, v72
	v_rcp_f32_e32 v73, v73
	v_rcp_f32_e32 v64, v64
	v_rcp_f32_e32 v65, v65
	v_rcp_f32_e32 v66, v66
	v_rcp_f32_e32 v67, v67
	v_pk_mul_f32 v[60:61], v[60:61], v[70:71]
	v_pk_mul_f32 v[52:53], v[52:53], v[164:165] op_sel_hi:[1,0]
	v_pk_mul_f32 v[62:63], v[62:63], v[72:73]
	v_pk_mul_f32 v[54:55], v[54:55], v[164:165] op_sel_hi:[1,0]
	v_pk_mul_f32 v[52:53], v[52:53], v[60:61]
	v_pk_mul_f32 v[56:57], v[56:57], v[64:65]
	v_pk_mul_f32 v[58:59], v[58:59], v[66:67]
	v_pk_mul_f32 v[48:49], v[48:49], v[164:165] op_sel_hi:[1,0]
	v_pk_mul_f32 v[50:51], v[50:51], v[164:165] op_sel_hi:[1,0]
	v_pk_mul_f32 v[54:55], v[54:55], v[62:63]
	v_pk_mul_f32 v[58:59], v[50:51], v[58:59]
	v_pk_mul_f32 v[50:51], v[48:49], v[56:57]
	v_cvt_pk_bf16_f32 v48, v52, v53
	v_mad_i64_i32 v[52:53], s[38:39], v154, s56, v[112:113]
	v_pk_mul_f32 v[44:45], v[44:45], v[160:161] op_sel_hi:[1,0]
	v_cvt_pk_bf16_f32 v49, v54, v55
	v_cvt_pk_bf16_f32 v50, v50, v51
	v_cvt_pk_bf16_f32 v51, v58, v59
	v_pk_mul_f32 v[46:47], v[46:47], v[160:161] op_sel_hi:[1,0]
	v_mul_f32_e32 v54, 0xbfb8aa3b, v44
	v_mul_f32_e32 v55, 0xbfb8aa3b, v45
	v_lshl_add_u64 v[52:53], v[52:53], 0, v[114:115]
	v_pk_mul_f32 v[40:41], v[40:41], v[160:161] op_sel_hi:[1,0]
	v_pk_mul_f32 v[42:43], v[42:43], v[160:161] op_sel_hi:[1,0]
	v_exp_f32_e32 v54, v54
	v_exp_f32_e32 v55, v55
	v_mul_f32_e32 v56, 0xbfb8aa3b, v46
	v_mul_f32_e32 v57, 0xbfb8aa3b, v47
	global_store_dwordx4 v[52:53], v[48:51], off
	v_exp_f32_e32 v56, v56
; __device__ __forceinline__ f32x4 silu4(f32x4 v) { return (f32x4){silu_f(v[0]), silu_f(v[1]), silu_f(v[2]), silu_f(v[3])}; }
; __device__ __forceinline__ u32x4 pack8(f32x4 a, f32x4 b) { u32x4 w; w.x = cvt_pk_bf16(a[0], a[1]); w.y = cvt_pk_bf16(a[2], a[3]); w.z = cvt_pk_bf16(b[0], b[1]); w.w = cvt_pk_bf16(b[2], b[3]); return w; }
;     __device__ __forceinline__ void operator()(const f32x4 (&acc)[2][2][4][2], const Unit& u, int wr, int wc, int fr, int fq) const {
;     ...
;         for (int ai = 0; ai < 2; ++ai)
; #pragma unroll
;             for (int m = 0; m < 4; ++m) {
;                 const int row = u.pm * BM + ai * HALF + wr * 64 + m * 16 + fr;
;                 const float rstd = rs[ai][m];
;                 const f32x4 a0 = silu4(acc[ai][0][m][0] * rstd) * (acc[ai][1][m][0] * rstd);
;                 const f32x4 a1 = silu4(acc[ai][0][m][1] * rstd) * (acc[ai][1][m][1] * rstd);
;                 *(u32x4*)(ACT + (size_t)row * 2816 + col0) = pack8(a0, a1);
;             }
	v_exp_f32_e32 v57, v57
	v_mul_f32_e32 v48, 0xbfb8aa3b, v40
	v_mul_f32_e32 v49, 0xbfb8aa3b, v41
	v_mul_f32_e32 v50, 0xbfb8aa3b, v42
	v_mul_f32_e32 v51, 0xbfb8aa3b, v43
	v_exp_f32_e32 v48, v48
	v_exp_f32_e32 v49, v49
	v_exp_f32_e32 v50, v50
	v_exp_f32_e32 v51, v51
	v_add_f32_e32 v54, 1.0, v54
	v_add_f32_e32 v55, 1.0, v55
	v_rcp_f32_e32 v54, v54
	v_rcp_f32_e32 v55, v55
	v_add_f32_e32 v56, 1.0, v56
	v_add_f32_e32 v57, 1.0, v57
	v_add_f32_e32 v48, 1.0, v48
	v_add_f32_e32 v49, 1.0, v49
	v_add_f32_e32 v50, 1.0, v50
	v_add_f32_e32 v51, 1.0, v51
	v_rcp_f32_e32 v56, v56
	v_rcp_f32_e32 v57, v57
	v_rcp_f32_e32 v48, v48
	v_rcp_f32_e32 v49, v49
	v_rcp_f32_e32 v50, v50
	v_rcp_f32_e32 v51, v51
	v_pk_mul_f32 v[44:45], v[44:45], v[54:55]
	v_pk_mul_f32 v[36:37], v[36:37], v[160:161] op_sel_hi:[1,0]
	v_pk_mul_f32 v[46:47], v[46:47], v[56:57]
	v_pk_mul_f32 v[38:39], v[38:39], v[160:161] op_sel_hi:[1,0]
	v_pk_mul_f32 v[36:37], v[36:37], v[44:45]
	v_pk_mul_f32 v[40:41], v[40:41], v[48:49]
	v_pk_mul_f32 v[42:43], v[42:43], v[50:51]
	v_pk_mul_f32 v[32:33], v[32:33], v[160:161] op_sel_hi:[1,0]
	v_pk_mul_f32 v[34:35], v[34:35], v[160:161] op_sel_hi:[1,0]
	v_pk_mul_f32 v[38:39], v[38:39], v[46:47]
	v_pk_mul_f32 v[42:43], v[34:35], v[42:43]
	v_pk_mul_f32 v[34:35], v[32:33], v[40:41]
	v_cvt_pk_bf16_f32 v32, v36, v37
	v_mad_i64_i32 v[36:37], s[38:39], v150, s56, v[112:113]
	v_pk_mul_f32 v[28:29], v[28:29], v[156:157] op_sel_hi:[1,0]
	v_cvt_pk_bf16_f32 v33, v38, v39
	v_cvt_pk_bf16_f32 v34, v34, v35
	v_cvt_pk_bf16_f32 v35, v42, v43
	v_pk_mul_f32 v[30:31], v[30:31], v[156:157] op_sel_hi:[1,0]
	v_mul_f32_e32 v38, 0xbfb8aa3b, v28
	v_mul_f32_e32 v39, 0xbfb8aa3b, v29
	v_lshl_add_u64 v[36:37], v[36:37], 0, v[114:115]
	v_pk_mul_f32 v[24:25], v[24:25], v[156:157] op_sel_hi:[1,0]
	v_pk_mul_f32 v[26:27], v[26:27], v[156:157] op_sel_hi:[1,0]
	v_exp_f32_e32 v38, v38
	v_exp_f32_e32 v39, v39
	v_mul_f32_e32 v40, 0xbfb8aa3b, v30
	v_mul_f32_e32 v41, 0xbfb8aa3b, v31
	global_store_dwordx4 v[36:37], v[32:35], off
	v_exp_f32_e32 v40, v40
	v_exp_f32_e32 v41, v41
	v_mul_f32_e32 v32, 0xbfb8aa3b, v24
	v_mul_f32_e32 v33, 0xbfb8aa3b, v25
	v_mul_f32_e32 v34, 0xbfb8aa3b, v26
	v_mul_f32_e32 v35, 0xbfb8aa3b, v27
	v_exp_f32_e32 v32, v32
	v_exp_f32_e32 v33, v33
	v_exp_f32_e32 v34, v34
	v_exp_f32_e32 v35, v35
	v_add_f32_e32 v38, 1.0, v38
	v_add_f32_e32 v39, 1.0, v39
	v_rcp_f32_e32 v38, v38
	v_rcp_f32_e32 v39, v39
	v_add_f32_e32 v40, 1.0, v40
	v_add_f32_e32 v41, 1.0, v41
	v_add_f32_e32 v32, 1.0, v32
	v_add_f32_e32 v33, 1.0, v33
	v_add_f32_e32 v34, 1.0, v34
	v_add_f32_e32 v35, 1.0, v35
	v_rcp_f32_e32 v40, v40
	v_rcp_f32_e32 v41, v41
	v_rcp_f32_e32 v32, v32
	v_rcp_f32_e32 v33, v33
	v_rcp_f32_e32 v34, v34
	v_rcp_f32_e32 v35, v35
	v_pk_mul_f32 v[28:29], v[28:29], v[38:39]
	v_pk_mul_f32 v[20:21], v[20:21], v[156:157] op_sel_hi:[1,0]
	v_pk_mul_f32 v[30:31], v[30:31], v[40:41]
	v_pk_mul_f32 v[22:23], v[22:23], v[156:157] op_sel_hi:[1,0]
	v_pk_mul_f32 v[20:21], v[20:21], v[28:29]
	v_pk_mul_f32 v[24:25], v[24:25], v[32:33]
	v_pk_mul_f32 v[26:27], v[26:27], v[34:35]
	v_pk_mul_f32 v[16:17], v[16:17], v[156:157] op_sel_hi:[1,0]
	v_pk_mul_f32 v[18:19], v[18:19], v[156:157] op_sel_hi:[1,0]
	v_pk_mul_f32 v[22:23], v[22:23], v[30:31]
	v_pk_mul_f32 v[26:27], v[18:19], v[26:27]
	v_pk_mul_f32 v[18:19], v[16:17], v[24:25]
	v_cvt_pk_bf16_f32 v16, v20, v21
	v_mad_i64_i32 v[20:21], s[38:39], v148, s56, v[112:113]
	v_pk_mul_f32 v[12:13], v[12:13], v[152:153] op_sel_hi:[1,0]
	v_cvt_pk_bf16_f32 v17, v22, v23
	v_cvt_pk_bf16_f32 v18, v18, v19
	v_cvt_pk_bf16_f32 v19, v26, v27
	v_lshl_add_u64 v[20:21], v[20:21], 0, v[114:115]
	v_mul_f32_e32 v22, 0xbfb8aa3b, v12
	v_mul_f32_e32 v23, 0xbfb8aa3b, v13
	v_pk_mul_f32 v[8:9], v[8:9], v[152:153] op_sel_hi:[1,0]
	v_pk_mul_f32 v[10:11], v[10:11], v[152:153] op_sel_hi:[1,0]
	v_exp_f32_e32 v22, v22
	v_exp_f32_e32 v23, v23
	global_store_dwordx4 v[20:21], v[16:19], off
	v_pk_mul_f32 v[14:15], v[14:15], v[152:153] op_sel_hi:[1,0]
	v_add_f32_e32 v22, 1.0, v22
	v_mul_f32_e32 v16, 0xbfb8aa3b, v8
	v_mul_f32_e32 v17, 0xbfb8aa3b, v9
	v_mul_f32_e32 v18, 0xbfb8aa3b, v10
	v_mul_f32_e32 v19, 0xbfb8aa3b, v11
	v_exp_f32_e32 v16, v16
	v_exp_f32_e32 v17, v17
	v_exp_f32_e32 v18, v18
	v_exp_f32_e32 v19, v19
	v_mul_f32_e32 v24, 0xbfb8aa3b, v14
	v_mul_f32_e32 v25, 0xbfb8aa3b, v15
	v_exp_f32_e32 v24, v24
	v_exp_f32_e32 v25, v25
	v_add_f32_e32 v23, 1.0, v23
	v_rcp_f32_e32 v22, v22
	v_rcp_f32_e32 v23, v23
	v_add_f32_e32 v16, 1.0, v16
	v_add_f32_e32 v17, 1.0, v17
	v_add_f32_e32 v18, 1.0, v18
	v_add_f32_e32 v19, 1.0, v19
	v_rcp_f32_e32 v16, v16
	v_rcp_f32_e32 v17, v17
	v_rcp_f32_e32 v18, v18
	v_rcp_f32_e32 v19, v19
	v_add_f32_e32 v24, 1.0, v24
	v_add_f32_e32 v25, 1.0, v25
	v_rcp_f32_e32 v24, v24
	v_rcp_f32_e32 v25, v25
	v_pk_mul_f32 v[12:13], v[12:13], v[22:23]
	v_pk_mul_f32 v[4:5], v[4:5], v[152:153] op_sel_hi:[1,0]
	v_pk_mul_f32 v[8:9], v[8:9], v[16:17]
	v_pk_mul_f32 v[4:5], v[4:5], v[12:13]
	v_pk_mul_f32 v[10:11], v[10:11], v[18:19]
	v_pk_mul_f32 v[0:1], v[0:1], v[152:153] op_sel_hi:[1,0]
	v_pk_mul_f32 v[2:3], v[2:3], v[152:153] op_sel_hi:[1,0]
	v_pk_mul_f32 v[14:15], v[14:15], v[24:25]
	v_pk_mul_f32 v[10:11], v[2:3], v[10:11]
	v_pk_mul_f32 v[2:3], v[0:1], v[8:9]
	v_cvt_pk_bf16_f32 v0, v4, v5
	v_mad_i64_i32 v[4:5], s[38:39], v146, s56, v[112:113]
	v_pk_mul_f32 v[6:7], v[6:7], v[152:153] op_sel_hi:[1,0]
	v_lshl_add_u64 v[4:5], v[4:5], 0, v[114:115]
	v_pk_mul_f32 v[6:7], v[6:7], v[14:15]
	s_nop 0
	v_cvt_pk_bf16_f32 v1, v6, v7
	v_cvt_pk_bf16_f32 v2, v2, v3
	v_cvt_pk_bf16_f32 v3, v10, v11
	global_store_dwordx4 v[4:5], v[0:3], off
	s_cbranch_vccnz .LBB0_516
	s_andn2_b64 vcc, exec, s[12:13]
	s_cbranch_vccnz .LBB0_515
	s_barrier
	s_branch .LBB0_515

; __device__ __forceinline__ float sq4(f32x4 v) { return (v[0] * v[0] + v[1] * v[1]) + (v[2] * v[2] + v[3] * v[3]); }
; __device__ __forceinline__ u32x4 pack8(f32x4 a, f32x4 b) { u32x4 w; w.x = cvt_pk_bf16(a[0], a[1]); w.y = cvt_pk_bf16(a[2], a[3]); w.z = cvt_pk_bf16(b[0], b[1]); w.w = cvt_pk_bf16(b[2], b[3]); return w; }
;     __device__ __forceinline__ void operator()(const f32x4 (&acc)[2][2][4][2], const Unit& u, int wr, int wc, int fr, int fq) const {
;     ...
;             for (int m = 0; m < 4; ++m) {
;                 const int row = u.pm * BM + ai * HALF + wr * 64 + m * 16 + fr;
;                 float q = 0.f;
; #pragma unroll
;                 for (int bj = 0; bj < 2; ++bj) {
;                     const size_t off = (size_t)row * 1024 + col0 + 128 * bj; const u32x4 w = bs[m][bj];
;                     const f32x4 b0 = (f32x4){__builtin_bit_cast(float, w.x << 16), __builtin_bit_cast(float, w.x & 0xffff0000u), __builtin_bit_cast(float, w.y << 16), __builtin_bit_cast(float, w.y & 0xffff0000u)};
;                     const f32x4 b1 = (f32x4){__builtin_bit_cast(float, w.z << 16), __builtin_bit_cast(float, w.z & 0xffff0000u), __builtin_bit_cast(float, w.w << 16), __builtin_bit_cast(float, w.w & 0xffff0000u)};
;                     const f32x4 v0 = acc[ai][bj][m][0] + b0, v1 = acc[ai][bj][m][1] + b1;
;                     if (last) { __builtin_nontemporal_store(v0, (f32x4*)(out + off)); __builtin_nontemporal_store(v1, (f32x4*)(out + off + 4)); }
;                     else { q += sq4(v0) + sq4(v1); *(u32x4*)(xb + off) = pack8(v0, v1); }
;                 }
;                 if (!last) { q += shx(q, 16); q += shx(q, 32); if (fq == 0) ss[(size_t)row * 16 + u.pn * 4 + wc] = q; }
.LBB0_607:
	s_or_b64 exec, exec, s[40:41]
	v_lshlrev_b32_e32 v112, 16, v148
	s_waitcnt lgkmcnt(0)
	v_and_b32_e32 v113, 0xffff0000, v148
	v_lshlrev_b32_e32 v114, 16, v149
	v_and_b32_e32 v115, 0xffff0000, v149
	v_lshlrev_b32_e32 v116, 16, v150
	v_and_b32_e32 v117, 0xffff0000, v150
	v_lshlrev_b32_e32 v118, 16, v151
	v_and_b32_e32 v119, 0xffff0000, v151
	v_pk_add_f32 v[110:111], v[110:111], v[114:115]
	v_pk_add_f32 v[108:109], v[108:109], v[112:113]
	v_pk_add_f32 v[112:113], v[106:107], v[118:119]
	v_pk_add_f32 v[106:107], v[104:105], v[116:117]
	v_mul_f32_e32 v104, v109, v109
	v_mul_f32_e32 v105, v111, v111
	v_fmac_f32_e32 v104, v108, v108
	v_fmac_f32_e32 v105, v110, v110
	v_add_f32_e32 v104, v104, v105
	v_mul_f32_e32 v105, v107, v107
	v_mul_f32_e32 v114, v113, v113
	v_fmac_f32_e32 v105, v106, v106
	v_fmac_f32_e32 v114, v112, v112
	v_add_f32_e32 v105, v105, v114
	v_add_f32_e32 v114, v104, v105
	v_cvt_pk_bf16_f32 v104, v108, v109
	v_lshl_add_u64 v[108:109], s[22:23], 0, v[184:185]
	v_cvt_pk_bf16_f32 v105, v110, v111
	v_cvt_pk_bf16_f32 v106, v106, v107
	v_cvt_pk_bf16_f32 v107, v112, v113
	v_lshl_add_u64 v[108:109], v[168:169], 1, v[108:109]
	global_store_dwordx4 v[108:109], v[104:107], off
	v_lshlrev_b32_e32 v110, 16, v146
	v_and_b32_e32 v111, 0xffff0000, v146
	v_lshlrev_b32_e32 v104, 16, v144
	v_and_b32_e32 v105, 0xffff0000, v144
	v_lshlrev_b32_e32 v106, 16, v145
	v_and_b32_e32 v107, 0xffff0000, v145
	v_lshlrev_b32_e32 v112, 16, v147
	v_and_b32_e32 v113, 0xffff0000, v147
	v_pk_add_f32 v[102:103], v[102:103], v[106:107]
	v_pk_add_f32 v[100:101], v[100:101], v[104:105]
	v_pk_add_f32 v[104:105], v[98:99], v[112:113]
	v_pk_add_f32 v[98:99], v[96:97], v[110:111]
	v_mul_f32_e32 v96, v101, v101
	v_mul_f32_e32 v97, v103, v103
	v_fmac_f32_e32 v96, v100, v100
	v_fmac_f32_e32 v97, v102, v102
	v_add_f32_e32 v96, v96, v97
	v_mul_f32_e32 v97, v99, v99
	v_mul_f32_e32 v106, v105, v105
	v_fmac_f32_e32 v97, v98, v98
	v_fmac_f32_e32 v106, v104, v104
	v_add_f32_e32 v97, v97, v106
	v_add_f32_e32 v96, v96, v97
	v_add_f32_e32 v106, v114, v96
	v_cvt_pk_bf16_f32 v96, v100, v101
	v_cvt_pk_bf16_f32 v97, v102, v103
	v_cvt_pk_bf16_f32 v98, v98, v99
	v_cvt_pk_bf16_f32 v99, v104, v105
	global_store_dwordx4 v[108:109], v[96:99], off offset:256
	s_nop 1
	s_nop 0
	s_nop 2
	v_mov_b32_e32 v96, v106
	s_nop 1
	v_permlane16_swap_b32_e32 v96, v106
	s_waitcnt lgkmcnt(0)
	v_add_f32_e32 v96, v106, v96
	s_nop 1
	v_mov_b32_e32 v97, v96
	s_nop 1
	v_permlane32_swap_b32_e32 v97, v96
	s_and_saveexec_b64 s[40:41], s[10:11]
	s_cbranch_execz .LBB0_609
	s_waitcnt lgkmcnt(0)
	v_add_f32_e32 v98, v96, v97
	v_lshlrev_b64 v[96:97], 6, v[182:183]
	v_lshl_add_u64 v[96:97], s[24:25], 0, v[96:97]
	v_lshl_add_u64 v[96:97], s[38:39], 2, v[96:97]
	s_lshl_b32 s16, s50, 2
	v_lshl_add_u64 v[96:97], v[96:97], 0, s[16:17]
	global_store_dword v[96:97], v98, off
; __device__ __forceinline__ float sq4(f32x4 v) { return (v[0] * v[0] + v[1] * v[1]) + (v[2] * v[2] + v[3] * v[3]); }
; __device__ __forceinline__ u32x4 pack8(f32x4 a, f32x4 b) { u32x4 w; w.x = cvt_pk_bf16(a[0], a[1]); w.y = cvt_pk_bf16(a[2], a[3]); w.z = cvt_pk_bf16(b[0], b[1]); w.w = cvt_pk_bf16(b[2], b[3]); return w; }
;     __device__ __forceinline__ void operator()(const f32x4 (&acc)[2][2][4][2], const Unit& u, int wr, int wc, int fr, int fq) const {
;     ...
;             for (int m = 0; m < 4; ++m) {
;                 const int row = u.pm * BM + ai * HALF + wr * 64 + m * 16 + fr;
;                 float q = 0.f;
; #pragma unroll
;                 for (int bj = 0; bj < 2; ++bj) {
;                     const size_t off = (size_t)row * 1024 + col0 + 128 * bj; const u32x4 w = bs[m][bj];
;                     const f32x4 b0 = (f32x4){__builtin_bit_cast(float, w.x << 16), __builtin_bit_cast(float, w.x & 0xffff0000u), __builtin_bit_cast(float, w.y << 16), __builtin_bit_cast(float, w.y & 0xffff0000u)};
;                     const f32x4 b1 = (f32x4){__builtin_bit_cast(float, w.z << 16), __builtin_bit_cast(float, w.z & 0xffff0000u), __builtin_bit_cast(float, w.w << 16), __builtin_bit_cast(float, w.w & 0xffff0000u)};
;                     const f32x4 v0 = acc[ai][bj][m][0] + b0, v1 = acc[ai][bj][m][1] + b1;
;                     if (last) { __builtin_nontemporal_store(v0, (f32x4*)(out + off)); __builtin_nontemporal_store(v1, (f32x4*)(out + off + 4)); }
;                     else { q += sq4(v0) + sq4(v1); *(u32x4*)(xb + off) = pack8(v0, v1); }
;                 }
;                 if (!last) { q += shx(q, 16); q += shx(q, 32); if (fq == 0) ss[(size_t)row * 16 + u.pn * 4 + wc] = q; }
.LBB0_609:
	s_or_b64 exec, exec, s[40:41]
	v_lshlrev_b32_e32 v96, 16, v140
	s_waitcnt lgkmcnt(0)
	v_and_b32_e32 v97, 0xffff0000, v140
	v_lshlrev_b32_e32 v98, 16, v141
	v_and_b32_e32 v99, 0xffff0000, v141
	v_lshlrev_b32_e32 v100, 16, v142
	v_and_b32_e32 v101, 0xffff0000, v142
	v_lshlrev_b32_e32 v102, 16, v143
	v_and_b32_e32 v103, 0xffff0000, v143
	v_pk_add_f32 v[94:95], v[94:95], v[98:99]
	v_pk_add_f32 v[92:93], v[92:93], v[96:97]
	v_pk_add_f32 v[96:97], v[90:91], v[102:103]
	v_pk_add_f32 v[90:91], v[88:89], v[100:101]
	v_mul_f32_e32 v88, v93, v93
	v_mul_f32_e32 v89, v95, v95
	v_fmac_f32_e32 v88, v92, v92
	v_fmac_f32_e32 v89, v94, v94
	v_add_f32_e32 v88, v88, v89
	v_mul_f32_e32 v89, v91, v91
	v_mul_f32_e32 v98, v97, v97
	v_fmac_f32_e32 v89, v90, v90
	v_fmac_f32_e32 v98, v96, v96
	v_add_f32_e32 v89, v89, v98
	v_add_f32_e32 v98, v88, v89
	v_cvt_pk_bf16_f32 v88, v92, v93
	v_lshl_add_u64 v[92:93], s[22:23], 0, v[180:181]
	v_cvt_pk_bf16_f32 v89, v94, v95
	v_cvt_pk_bf16_f32 v90, v90, v91
	v_cvt_pk_bf16_f32 v91, v96, v97
	v_lshl_add_u64 v[92:93], v[168:169], 1, v[92:93]
	global_store_dwordx4 v[92:93], v[88:91], off
	v_lshlrev_b32_e32 v94, 16, v138
	v_and_b32_e32 v95, 0xffff0000, v138
	v_lshlrev_b32_e32 v88, 16, v136
	v_and_b32_e32 v89, 0xffff0000, v136
	v_lshlrev_b32_e32 v90, 16, v137
	v_and_b32_e32 v91, 0xffff0000, v137
	v_lshlrev_b32_e32 v96, 16, v139
	v_and_b32_e32 v97, 0xffff0000, v139
	v_pk_add_f32 v[86:87], v[86:87], v[90:91]
	v_pk_add_f32 v[84:85], v[84:85], v[88:89]
	v_pk_add_f32 v[88:89], v[82:83], v[96:97]
	v_pk_add_f32 v[82:83], v[80:81], v[94:95]
	v_mul_f32_e32 v80, v85, v85
	v_mul_f32_e32 v81, v87, v87
	v_fmac_f32_e32 v80, v84, v84
	v_fmac_f32_e32 v81, v86, v86
	v_add_f32_e32 v80, v80, v81
	v_mul_f32_e32 v81, v83, v83
	v_mul_f32_e32 v90, v89, v89
	v_fmac_f32_e32 v81, v82, v82
	v_fmac_f32_e32 v90, v88, v88
	v_add_f32_e32 v81, v81, v90
	v_add_f32_e32 v80, v80, v81
	v_add_f32_e32 v90, v98, v80
	v_cvt_pk_bf16_f32 v80, v84, v85
	v_cvt_pk_bf16_f32 v81, v86, v87
	v_cvt_pk_bf16_f32 v82, v82, v83
	v_cvt_pk_bf16_f32 v83, v88, v89
	global_store_dwordx4 v[92:93], v[80:83], off offset:256
	s_nop 1
	s_nop 0
	s_nop 2
	v_mov_b32_e32 v80, v90
	s_nop 1
	v_permlane16_swap_b32_e32 v80, v90
	s_waitcnt lgkmcnt(0)
	v_add_f32_e32 v80, v90, v80
	s_nop 1
	v_mov_b32_e32 v81, v80
	s_nop 1
	v_permlane32_swap_b32_e32 v81, v80
	s_and_saveexec_b64 s[40:41], s[10:11]
	s_cbranch_execz .LBB0_611
	s_waitcnt lgkmcnt(0)
	v_add_f32_e32 v82, v80, v81
	v_lshlrev_b64 v[80:81], 6, v[178:179]
	v_lshl_add_u64 v[80:81], s[24:25], 0, v[80:81]
	v_lshl_add_u64 v[80:81], s[38:39], 2, v[80:81]
	s_lshl_b32 s16, s50, 2
	v_lshl_add_u64 v[80:81], v[80:81], 0, s[16:17]
	global_store_dword v[80:81], v82, off
.LBB0_611:
	s_or_b64 exec, exec, s[40:41]
	v_lshlrev_b32_e32 v80, 16, v132
	s_waitcnt lgkmcnt(0)
	v_and_b32_e32 v81, 0xffff0000, v132
	v_lshlrev_b32_e32 v82, 16, v133
	v_and_b32_e32 v83, 0xffff0000, v133
	v_lshlrev_b32_e32 v84, 16, v134
	v_and_b32_e32 v85, 0xffff0000, v134
	v_lshlrev_b32_e32 v86, 16, v135
	v_and_b32_e32 v87, 0xffff0000, v135
	v_pk_add_f32 v[78:79], v[78:79], v[82:83]
	v_pk_add_f32 v[76:77], v[76:77], v[80:81]
	v_pk_add_f32 v[80:81], v[74:75], v[86:87]
	v_pk_add_f32 v[74:75], v[72:73], v[84:85]
	v_mul_f32_e32 v72, v77, v77
	v_mul_f32_e32 v73, v79, v79
	v_fmac_f32_e32 v72, v76, v76
	v_fmac_f32_e32 v73, v78, v78
	v_add_f32_e32 v72, v72, v73
	v_mul_f32_e32 v73, v75, v75
	v_mul_f32_e32 v82, v81, v81
	v_fmac_f32_e32 v73, v74, v74
	v_fmac_f32_e32 v82, v80, v80
	v_add_f32_e32 v73, v73, v82
	v_add_f32_e32 v82, v72, v73
	v_cvt_pk_bf16_f32 v72, v76, v77
	v_lshl_add_u64 v[76:77], s[22:23], 0, v[176:177]
	v_cvt_pk_bf16_f32 v73, v78, v79
	v_cvt_pk_bf16_f32 v74, v74, v75
	v_cvt_pk_bf16_f32 v75, v80, v81
	v_lshl_add_u64 v[76:77], v[168:169], 1, v[76:77]
	global_store_dwordx4 v[76:77], v[72:75], off
	v_lshlrev_b32_e32 v78, 16, v130
	v_and_b32_e32 v79, 0xffff0000, v130
	v_lshlrev_b32_e32 v72, 16, v128
	v_and_b32_e32 v73, 0xffff0000, v128
	v_lshlrev_b32_e32 v74, 16, v129
	v_and_b32_e32 v75, 0xffff0000, v129
	v_lshlrev_b32_e32 v80, 16, v131
	v_and_b32_e32 v81, 0xffff0000, v131
	v_pk_add_f32 v[70:71], v[70:71], v[74:75]
	v_pk_add_f32 v[68:69], v[68:69], v[72:73]
	v_pk_add_f32 v[72:73], v[66:67], v[80:81]
	v_pk_add_f32 v[66:67], v[64:65], v[78:79]
	v_mul_f32_e32 v64, v69, v69
	v_mul_f32_e32 v65, v71, v71
	v_fmac_f32_e32 v64, v68, v68
	v_fmac_f32_e32 v65, v70, v70
	v_add_f32_e32 v64, v64, v65
	v_mul_f32_e32 v65, v67, v67
	v_mul_f32_e32 v74, v73, v73
	v_fmac_f32_e32 v65, v66, v66
	v_fmac_f32_e32 v74, v72, v72
	v_add_f32_e32 v65, v65, v74
	v_add_f32_e32 v64, v64, v65
	v_add_f32_e32 v74, v82, v64
	v_cvt_pk_bf16_f32 v64, v68, v69
	v_cvt_pk_bf16_f32 v65, v70, v71
	v_cvt_pk_bf16_f32 v66, v66, v67
	v_cvt_pk_bf16_f32 v67, v72, v73
	global_store_dwordx4 v[76:77], v[64:67], off offset:256
	s_nop 1
	s_nop 0
	s_nop 2
	v_mov_b32_e32 v64, v74
	s_nop 1
	v_permlane16_swap_b32_e32 v64, v74
	s_waitcnt lgkmcnt(0)
	v_add_f32_e32 v64, v74, v64
	s_nop 1
	v_mov_b32_e32 v65, v64
	s_nop 1
	v_permlane32_swap_b32_e32 v65, v64
	s_and_saveexec_b64 s[40:41], s[10:11]
	s_cbranch_execz .LBB0_613
	s_waitcnt lgkmcnt(0)
	v_add_f32_e32 v66, v64, v65
	v_lshlrev_b64 v[64:65], 6, v[174:175]
	v_lshl_add_u64 v[64:65], s[24:25], 0, v[64:65]
	v_lshl_add_u64 v[64:65], s[38:39], 2, v[64:65]
	s_lshl_b32 s16, s50, 2
	v_lshl_add_u64 v[64:65], v[64:65], 0, s[16:17]
	global_store_dword v[64:65], v66, off

; __device__ __forceinline__ float sq4(f32x4 v) { return (v[0] * v[0] + v[1] * v[1]) + (v[2] * v[2] + v[3] * v[3]); }
; __device__ __forceinline__ u32x4 pack8(f32x4 a, f32x4 b) { u32x4 w; w.x = cvt_pk_bf16(a[0], a[1]); w.y = cvt_pk_bf16(a[2], a[3]); w.z = cvt_pk_bf16(b[0], b[1]); w.w = cvt_pk_bf16(b[2], b[3]); return w; }
;     __device__ __forceinline__ void operator()(const f32x4 (&acc)[2][2][4][2], const Unit& u, int wr, int wc, int fr, int fq) const {
;     ...
;             for (int m = 0; m < 4; ++m) {
;                 const int row = u.pm * BM + ai * HALF + wr * 64 + m * 16 + fr;
;                 float q = 0.f;
; #pragma unroll
;                 for (int bj = 0; bj < 2; ++bj) {
;                     const size_t off = (size_t)row * 1024 + col0 + 128 * bj; const u32x4 w = bs[m][bj];
;                     const f32x4 b0 = (f32x4){__builtin_bit_cast(float, w.x << 16), __builtin_bit_cast(float, w.x & 0xffff0000u), __builtin_bit_cast(float, w.y << 16), __builtin_bit_cast(float, w.y & 0xffff0000u)};
;                     const f32x4 b1 = (f32x4){__builtin_bit_cast(float, w.z << 16), __builtin_bit_cast(float, w.z & 0xffff0000u), __builtin_bit_cast(float, w.w << 16), __builtin_bit_cast(float, w.w & 0xffff0000u)};
;                     const f32x4 v0 = acc[ai][bj][m][0] + b0, v1 = acc[ai][bj][m][1] + b1;
;                     if (last) { __builtin_nontemporal_store(v0, (f32x4*)(out + off)); __builtin_nontemporal_store(v1, (f32x4*)(out + off + 4)); }
;                     else { q += sq4(v0) + sq4(v1); *(u32x4*)(xb + off) = pack8(v0, v1); }
;                 }
;                 if (!last) { q += shx(q, 16); q += shx(q, 32); if (fq == 0) ss[(size_t)row * 16 + u.pn * 4 + wc] = q; }
.LBB0_615:
	s_or_b64 exec, exec, s[40:41]
	s_waitcnt vmcnt(7)
	v_lshlrev_b32_e32 v48, 16, v84
	s_waitcnt lgkmcnt(0)
	v_and_b32_e32 v49, 0xffff0000, v84
	v_lshlrev_b32_e32 v50, 16, v85
	v_and_b32_e32 v51, 0xffff0000, v85
	v_lshlrev_b32_e32 v52, 16, v86
	v_and_b32_e32 v53, 0xffff0000, v86
	v_lshlrev_b32_e32 v54, 16, v87
	v_and_b32_e32 v55, 0xffff0000, v87
	v_pk_add_f32 v[46:47], v[46:47], v[50:51]
	v_pk_add_f32 v[44:45], v[44:45], v[48:49]
	v_pk_add_f32 v[48:49], v[42:43], v[54:55]
	v_pk_add_f32 v[42:43], v[40:41], v[52:53]
	v_mul_f32_e32 v40, v45, v45
	v_mul_f32_e32 v41, v47, v47
	v_fmac_f32_e32 v40, v44, v44
	v_fmac_f32_e32 v41, v46, v46
	v_add_f32_e32 v40, v40, v41
	v_mul_f32_e32 v41, v43, v43
	v_mul_f32_e32 v50, v49, v49
	v_fmac_f32_e32 v41, v42, v42
	v_fmac_f32_e32 v50, v48, v48
	v_add_f32_e32 v41, v41, v50
	v_add_f32_e32 v50, v40, v41
	v_cvt_pk_bf16_f32 v40, v44, v45
	v_lshl_add_u64 v[44:45], s[22:23], 0, v[98:99]
	v_cvt_pk_bf16_f32 v41, v46, v47
	v_cvt_pk_bf16_f32 v42, v42, v43
	v_cvt_pk_bf16_f32 v43, v48, v49
	v_lshl_add_u64 v[44:45], v[168:169], 1, v[44:45]
	global_store_dwordx4 v[44:45], v[40:43], off
	s_waitcnt vmcnt(7)
	v_lshlrev_b32_e32 v46, 16, v82
	v_and_b32_e32 v47, 0xffff0000, v82
	v_lshlrev_b32_e32 v40, 16, v80
	v_and_b32_e32 v41, 0xffff0000, v80
	v_lshlrev_b32_e32 v42, 16, v81
	v_and_b32_e32 v43, 0xffff0000, v81
	v_lshlrev_b32_e32 v48, 16, v83
	v_and_b32_e32 v49, 0xffff0000, v83
	v_pk_add_f32 v[38:39], v[38:39], v[42:43]
	v_pk_add_f32 v[36:37], v[36:37], v[40:41]
	v_pk_add_f32 v[40:41], v[34:35], v[48:49]
	v_pk_add_f32 v[34:35], v[32:33], v[46:47]
	v_mul_f32_e32 v32, v37, v37
	v_mul_f32_e32 v33, v39, v39
	v_fmac_f32_e32 v32, v36, v36
	v_fmac_f32_e32 v33, v38, v38
	v_add_f32_e32 v32, v32, v33
	v_mul_f32_e32 v33, v35, v35
	v_mul_f32_e32 v42, v41, v41
	v_fmac_f32_e32 v33, v34, v34
	v_fmac_f32_e32 v42, v40, v40
	v_add_f32_e32 v33, v33, v42
	v_add_f32_e32 v32, v32, v33
	v_add_f32_e32 v42, v50, v32
	v_cvt_pk_bf16_f32 v32, v36, v37
	v_cvt_pk_bf16_f32 v33, v38, v39
	v_cvt_pk_bf16_f32 v34, v34, v35
	v_cvt_pk_bf16_f32 v35, v40, v41
	global_store_dwordx4 v[44:45], v[32:35], off offset:256
	s_nop 1
	s_nop 0
	s_nop 2
	v_mov_b32_e32 v32, v42
	s_nop 1
	v_permlane16_swap_b32_e32 v32, v42
	s_waitcnt lgkmcnt(0)
	v_add_f32_e32 v32, v42, v32
	s_nop 1
	v_mov_b32_e32 v33, v32
	s_nop 1
	v_permlane32_swap_b32_e32 v33, v32
	s_and_saveexec_b64 s[40:41], s[10:11]
	s_cbranch_execz .LBB0_617
	s_waitcnt lgkmcnt(0)
	v_add_f32_e32 v34, v32, v33
	v_lshlrev_b64 v[32:33], 6, v[96:97]
	v_lshl_add_u64 v[32:33], s[24:25], 0, v[32:33]
	v_lshl_add_u64 v[32:33], s[38:39], 2, v[32:33]
	s_lshl_b32 s16, s50, 2
	v_lshl_add_u64 v[32:33], v[32:33], 0, s[16:17]
	global_store_dword v[32:33], v34, off
; __device__ __forceinline__ float sq4(f32x4 v) { return (v[0] * v[0] + v[1] * v[1]) + (v[2] * v[2] + v[3] * v[3]); }
; __device__ __forceinline__ u32x4 pack8(f32x4 a, f32x4 b) { u32x4 w; w.x = cvt_pk_bf16(a[0], a[1]); w.y = cvt_pk_bf16(a[2], a[3]); w.z = cvt_pk_bf16(b[0], b[1]); w.w = cvt_pk_bf16(b[2], b[3]); return w; }
;     __device__ __forceinline__ void operator()(const f32x4 (&acc)[2][2][4][2], const Unit& u, int wr, int wc, int fr, int fq) const {
;     ...
;             for (int m = 0; m < 4; ++m) {
;                 const int row = u.pm * BM + ai * HALF + wr * 64 + m * 16 + fr;
;                 float q = 0.f;
; #pragma unroll
;                 for (int bj = 0; bj < 2; ++bj) {
;                     const size_t off = (size_t)row * 1024 + col0 + 128 * bj; const u32x4 w = bs[m][bj];
;                     const f32x4 b0 = (f32x4){__builtin_bit_cast(float, w.x << 16), __builtin_bit_cast(float, w.x & 0xffff0000u), __builtin_bit_cast(float, w.y << 16), __builtin_bit_cast(float, w.y & 0xffff0000u)};
;                     const f32x4 b1 = (f32x4){__builtin_bit_cast(float, w.z << 16), __builtin_bit_cast(float, w.z & 0xffff0000u), __builtin_bit_cast(float, w.w << 16), __builtin_bit_cast(float, w.w & 0xffff0000u)};
;                     const f32x4 v0 = acc[ai][bj][m][0] + b0, v1 = acc[ai][bj][m][1] + b1;
;                     if (last) { __builtin_nontemporal_store(v0, (f32x4*)(out + off)); __builtin_nontemporal_store(v1, (f32x4*)(out + off + 4)); }
;                     else { q += sq4(v0) + sq4(v1); *(u32x4*)(xb + off) = pack8(v0, v1); }
;                 }
;                 if (!last) { q += shx(q, 16); q += shx(q, 32); if (fq == 0) ss[(size_t)row * 16 + u.pn * 4 + wc] = q; }
.LBB0_617:
	s_or_b64 exec, exec, s[40:41]
	s_waitcnt vmcnt(7)
	v_lshlrev_b32_e32 v32, 16, v76
	s_waitcnt lgkmcnt(0)
	v_and_b32_e32 v33, 0xffff0000, v76
	v_lshlrev_b32_e32 v34, 16, v77
	v_and_b32_e32 v35, 0xffff0000, v77
	v_lshlrev_b32_e32 v36, 16, v78
	v_and_b32_e32 v37, 0xffff0000, v78
	v_lshlrev_b32_e32 v38, 16, v79
	v_and_b32_e32 v39, 0xffff0000, v79
	v_pk_add_f32 v[30:31], v[30:31], v[34:35]
	v_pk_add_f32 v[28:29], v[28:29], v[32:33]
	v_pk_add_f32 v[32:33], v[26:27], v[38:39]
	v_pk_add_f32 v[26:27], v[24:25], v[36:37]
	v_mul_f32_e32 v24, v29, v29
	v_mul_f32_e32 v25, v31, v31
	v_fmac_f32_e32 v24, v28, v28
	v_fmac_f32_e32 v25, v30, v30
	v_add_f32_e32 v24, v24, v25
	v_mul_f32_e32 v25, v27, v27
	v_mul_f32_e32 v34, v33, v33
	v_fmac_f32_e32 v25, v26, v26
	v_fmac_f32_e32 v34, v32, v32
	v_add_f32_e32 v25, v25, v34
	v_add_f32_e32 v34, v24, v25
	v_cvt_pk_bf16_f32 v24, v28, v29
	v_lshl_add_u64 v[28:29], s[22:23], 0, v[94:95]
	v_cvt_pk_bf16_f32 v25, v30, v31
	v_cvt_pk_bf16_f32 v26, v26, v27
	v_cvt_pk_bf16_f32 v27, v32, v33
	v_lshl_add_u64 v[28:29], v[168:169], 1, v[28:29]
	global_store_dwordx4 v[28:29], v[24:27], off
	s_waitcnt vmcnt(7)
	v_lshlrev_b32_e32 v30, 16, v74
	v_and_b32_e32 v31, 0xffff0000, v74
	v_lshlrev_b32_e32 v24, 16, v72
	v_and_b32_e32 v25, 0xffff0000, v72
	v_lshlrev_b32_e32 v26, 16, v73
	v_and_b32_e32 v27, 0xffff0000, v73
	v_lshlrev_b32_e32 v32, 16, v75
	v_and_b32_e32 v33, 0xffff0000, v75
	v_pk_add_f32 v[22:23], v[22:23], v[26:27]
	v_pk_add_f32 v[20:21], v[20:21], v[24:25]
	v_pk_add_f32 v[24:25], v[18:19], v[32:33]
	v_pk_add_f32 v[18:19], v[16:17], v[30:31]
	v_mul_f32_e32 v16, v21, v21
	v_mul_f32_e32 v17, v23, v23
	v_fmac_f32_e32 v16, v20, v20
	v_fmac_f32_e32 v17, v22, v22
	v_add_f32_e32 v16, v16, v17
	v_mul_f32_e32 v17, v19, v19
	v_mul_f32_e32 v26, v25, v25
	v_fmac_f32_e32 v17, v18, v18
	v_fmac_f32_e32 v26, v24, v24
	v_add_f32_e32 v17, v17, v26
	v_add_f32_e32 v16, v16, v17
	v_add_f32_e32 v26, v34, v16
	v_cvt_pk_bf16_f32 v16, v20, v21
	v_cvt_pk_bf16_f32 v17, v22, v23
	v_cvt_pk_bf16_f32 v18, v18, v19
	v_cvt_pk_bf16_f32 v19, v24, v25
	global_store_dwordx4 v[28:29], v[16:19], off offset:256
	s_nop 1
	s_nop 0
	s_nop 2
	v_mov_b32_e32 v16, v26
	s_nop 1
	v_permlane16_swap_b32_e32 v16, v26
	s_waitcnt lgkmcnt(0)
	v_add_f32_e32 v16, v26, v16
	s_nop 1
	v_mov_b32_e32 v17, v16
	s_nop 1
	v_permlane32_swap_b32_e32 v17, v16
	s_and_saveexec_b64 s[40:41], s[10:11]
	s_cbranch_execz .LBB0_619
	s_waitcnt lgkmcnt(0)
	v_add_f32_e32 v18, v16, v17
	v_lshlrev_b64 v[16:17], 6, v[92:93]
	v_lshl_add_u64 v[16:17], s[24:25], 0, v[16:17]
	v_lshl_add_u64 v[16:17], s[38:39], 2, v[16:17]
	s_lshl_b32 s16, s50, 2
	v_lshl_add_u64 v[16:17], v[16:17], 0, s[16:17]
	global_store_dword v[16:17], v18, off
.LBB0_619:
	s_or_b64 exec, exec, s[40:41]
	s_waitcnt vmcnt(7)
	v_lshlrev_b32_e32 v16, 16, v68
	s_waitcnt lgkmcnt(0)
	v_and_b32_e32 v17, 0xffff0000, v68
	v_lshlrev_b32_e32 v18, 16, v69
	v_and_b32_e32 v19, 0xffff0000, v69
	v_lshlrev_b32_e32 v20, 16, v70
	v_and_b32_e32 v21, 0xffff0000, v70
	v_lshlrev_b32_e32 v22, 16, v71
	v_and_b32_e32 v23, 0xffff0000, v71
	v_pk_add_f32 v[14:15], v[14:15], v[18:19]
	v_pk_add_f32 v[12:13], v[12:13], v[16:17]
	v_pk_add_f32 v[16:17], v[10:11], v[22:23]
	v_pk_add_f32 v[10:11], v[8:9], v[20:21]
	v_mul_f32_e32 v8, v13, v13
	v_mul_f32_e32 v9, v15, v15
	v_fmac_f32_e32 v8, v12, v12
	v_fmac_f32_e32 v9, v14, v14
	v_add_f32_e32 v8, v8, v9
	v_mul_f32_e32 v9, v11, v11
	v_mul_f32_e32 v18, v17, v17
	v_fmac_f32_e32 v9, v10, v10
	v_fmac_f32_e32 v18, v16, v16
	v_add_f32_e32 v9, v9, v18
	v_add_f32_e32 v18, v8, v9
	v_cvt_pk_bf16_f32 v8, v12, v13
	v_lshl_add_u64 v[12:13], s[22:23], 0, v[90:91]
	v_cvt_pk_bf16_f32 v9, v14, v15
	v_cvt_pk_bf16_f32 v10, v10, v11
	v_cvt_pk_bf16_f32 v11, v16, v17
	v_lshl_add_u64 v[12:13], v[168:169], 1, v[12:13]
	global_store_dwordx4 v[12:13], v[8:11], off
	s_waitcnt vmcnt(7)
	v_lshlrev_b32_e32 v14, 16, v66
	v_and_b32_e32 v15, 0xffff0000, v66
	v_lshlrev_b32_e32 v8, 16, v64
	v_and_b32_e32 v9, 0xffff0000, v64
	v_lshlrev_b32_e32 v10, 16, v65
	v_and_b32_e32 v11, 0xffff0000, v65
	v_lshlrev_b32_e32 v16, 16, v67
	v_and_b32_e32 v17, 0xffff0000, v67
	v_pk_add_f32 v[6:7], v[6:7], v[10:11]
	v_pk_add_f32 v[4:5], v[4:5], v[8:9]
	v_pk_add_f32 v[8:9], v[2:3], v[16:17]
	v_pk_add_f32 v[2:3], v[0:1], v[14:15]
	v_mul_f32_e32 v0, v5, v5
	v_mul_f32_e32 v1, v7, v7
	v_fmac_f32_e32 v0, v4, v4
	v_fmac_f32_e32 v1, v6, v6
	v_add_f32_e32 v0, v0, v1
	v_mul_f32_e32 v1, v3, v3
	v_mul_f32_e32 v10, v9, v9
	v_fmac_f32_e32 v1, v2, v2
	v_fmac_f32_e32 v10, v8, v8
	v_add_f32_e32 v1, v1, v10
	v_add_f32_e32 v0, v0, v1
	v_add_f32_e32 v10, v18, v0
	v_cvt_pk_bf16_f32 v0, v4, v5
	v_cvt_pk_bf16_f32 v1, v6, v7
	v_cvt_pk_bf16_f32 v2, v2, v3
	v_cvt_pk_bf16_f32 v3, v8, v9
	global_store_dwordx4 v[12:13], v[0:3], off offset:256
	s_nop 1
	s_nop 0
	s_nop 2
	v_mov_b32_e32 v0, v10
	s_nop 1
	v_permlane16_swap_b32_e32 v0, v10
	s_waitcnt lgkmcnt(0)
	v_add_f32_e32 v0, v10, v0
	s_nop 1
	v_mov_b32_e32 v1, v0
	s_nop 1
	v_permlane32_swap_b32_e32 v1, v0
	s_and_saveexec_b64 s[40:41], s[10:11]
	s_cbranch_execz .LBB0_621
	s_waitcnt lgkmcnt(0)
	v_add_f32_e32 v2, v0, v1
	v_lshlrev_b64 v[0:1], 6, v[88:89]
	v_lshl_add_u64 v[0:1], s[24:25], 0, v[0:1]
	v_lshl_add_u64 v[0:1], s[38:39], 2, v[0:1]
	s_lshl_b32 s16, s50, 2
	v_lshl_add_u64 v[0:1], v[0:1], 0, s[16:17]
	global_store_dword v[0:1], v2, off

; __device__ __forceinline__ float row_part(const float* ss, int row, int fq) { const f32x4 a = ((const f32x4*)(ss + (size_t)row * 16))[fq]; return (a[0] + a[1]) + (a[2] + a[3]); }
; __device__ __forceinline__ float row_finish(float t) { t += shx(t, 16); t += shx(t, 32); return __builtin_amdgcn_rsqf(t * (1.0f / 1024.0f) + RMS_EPS); }
;     __device__ __forceinline__ void operator()(const f32x4 (&acc)[2][2][4][2], const Unit& u, int wr, int wc, int fr, int fq) const {
;         const int g = u.pn * 4 + wc;
;         int mode = 0; const float* w = mqw; float sc = 1.f, nsc = 1.f;
;         if (g >= 36) { mode = 2; w = mqw; nsc = qscale; }
;         else if (diff) { if (g < 12) { mode = 2; w = qw; nsc = qscale; } else if (g < 24) { mode = 2; w = kw; } }
;         else { if (g >= 6 && g < 12) sc = 0.125f; else if (g >= 24) mode = 1; }
;         f32x4 wv[2][2];
; #pragma unroll
;         for (int bj = 0; bj < 2; ++bj)
; #pragma unroll
;             for (int n = 0; n < 2; ++n) wv[bj][n] = *(const f32x4*)(w + 32 * bj + 8 * fq + 4 * n) * nsc;
;         const int lcol = u.pn * 256 + 64 * wc + 8 * fq;
;         float rs[2][4];
; #pragma unroll
;         for (int ai = 0; ai < 2; ++ai)
; #pragma unroll
;             for (int m = 0; m < 4; ++m) rs[ai][m] = row_part(ss, u.pm * BM + ai * HALF + wr * 64 + m * 16 + fr, fq);
; #pragma unroll
;         for (int ai = 0; ai < 2; ++ai)
; #pragma unroll
;             for (int m = 0; m < 4; ++m) rs[ai][m] = row_finish(rs[ai][m]);
.LBB0_715:
	s_lshl_b32 s12, s44, 2
	s_or_b32 s13, s12, s53
	s_cmp_lt_u32 s12, 24
	s_cselect_b32 s14, s19, s55
	s_cselect_b32 s15, s18, s54
	s_cmp_lt_i32 s13, 12
	s_cselect_b32 s15, s16, s15
	s_cselect_b32 s14, s17, s14
	s_sub_i32 s37, s12, 36
	s_cmp_lt_u32 s37, 0xffffffe8
	s_cselect_b64 vcc, -1, 0
	s_cmp_gt_i32 s13, 35
	s_cselect_b32 s13, s55, s14
	s_cselect_b32 s12, s54, s15
	s_cmp_lt_u32 s37, -12
	s_cselect_b64 s[48:49], -1, 0
	s_lshl_b32 s35, s46, 8
	v_add_u32_e32 v170, s35, v174
	v_ashrrev_i32_e32 v171, 31, v170
	v_or_b32_e32 v156, 16, v170
	v_lshlrev_b64 v[146:147], 6, v[170:171]
	v_ashrrev_i32_e32 v157, 31, v156
	global_load_dwordx4 v[148:151], v183, s[12:13] offset:16
	global_load_dwordx4 v[152:155], v183, s[12:13]
	global_load_dwordx4 v[186:189], v183, s[12:13] offset:144
	global_load_dwordx4 v[190:193], v183, s[12:13] offset:128
	v_lshl_add_u64 v[146:147], v[136:137], 0, v[146:147]
	v_lshlrev_b64 v[156:157], 6, v[156:157]
	v_lshl_add_u64 v[156:157], v[136:137], 0, v[156:157]
	ds_read_b128 v[194:197], v239
	ds_read_b128 v[202:205], v239 offset:1024
	v_or_b32_e32 v146, 32, v170
	v_ashrrev_i32_e32 v147, 31, v146
	v_or_b32_e32 v156, 48, v170
	v_lshlrev_b64 v[146:147], 6, v[146:147]
	v_ashrrev_i32_e32 v157, 31, v156
	v_lshl_add_u64 v[146:147], v[136:137], 0, v[146:147]
	v_lshlrev_b64 v[156:157], 6, v[156:157]
	v_lshl_add_u64 v[156:157], v[136:137], 0, v[156:157]
	ds_read_b128 v[206:209], v239 offset:2048
	ds_read_b128 v[210:213], v239 offset:3072
	v_add_u32_e32 v168, 0x80, v170
	v_ashrrev_i32_e32 v169, 31, v168
	v_add_u32_e32 v166, 0x90, v170
	v_lshlrev_b64 v[146:147], 6, v[168:169]
	v_ashrrev_i32_e32 v167, 31, v166
	v_add_u32_e32 v164, 0xa0, v170
	v_lshl_add_u64 v[146:147], v[136:137], 0, v[146:147]
	v_lshlrev_b64 v[156:157], 6, v[166:167]
	v_ashrrev_i32_e32 v165, 31, v164
	v_lshl_add_u64 v[156:157], v[136:137], 0, v[156:157]
	ds_read_b128 v[214:217], v239 offset:8192
	ds_read_b128 v[218:221], v239 offset:9216
	v_lshlrev_b64 v[146:147], 6, v[164:165]
	v_lshl_add_u64 v[146:147], v[136:137], 0, v[146:147]
	ds_read_b128 v[222:225], v239 offset:10240
	v_add_u32_e32 v146, 0xb0, v170
	v_ashrrev_i32_e32 v147, 31, v146
	v_lshlrev_b64 v[156:157], 6, v[146:147]
	v_lshl_add_u64 v[156:157], v[136:137], 0, v[156:157]
	ds_read_b128 v[226:229], v239 offset:11264
	s_nop 0
	v_cndmask_b32_e32 v172, 1.0, v185, vcc
	s_cmp_gt_u32 s37, -13
	s_nop 1
	s_waitcnt vmcnt(0) lgkmcnt(0)
	v_pk_mul_f32 v[156:157], v[172:173], v[150:151] op_sel_hi:[0,1]
	v_pk_mul_f32 v[160:161], v[172:173], v[154:155] op_sel_hi:[0,1]
	v_pk_mul_f32 v[162:163], v[172:173], v[152:153] op_sel_hi:[0,1]
	v_pk_mul_f32 v[158:159], v[172:173], v[148:149] op_sel_hi:[0,1]
	v_pk_mul_f32 v[152:153], v[172:173], v[192:193] op_sel_hi:[0,1]
	v_pk_mul_f32 v[154:155], v[172:173], v[190:191] op_sel_hi:[0,1]
	v_pk_mul_f32 v[148:149], v[172:173], v[188:189] op_sel_hi:[0,1]
	v_pk_mul_f32 v[150:151], v[172:173], v[186:187] op_sel_hi:[0,1]
	v_mov_b32_e32 v172, v195
	v_mov_b32_e32 v173, v196
	v_mov_b32_e32 v195, v197
	v_pk_add_f32 v[172:173], v[172:173], v[194:195]
	v_add_f32_e32 v165, v202, v203
	v_add_f32_e32 v172, v172, v173
	v_mov_b32_e32 v147, v172
	s_nop 1
	v_permlane16_swap_b32_e32 v147, v172
	v_add_f32_e32 v167, v204, v205
	v_add_f32_e32 v169, v206, v207
	v_add_f32_e32 v171, v208, v209
	v_add_f32_e32 v186, v210, v211
	s_waitcnt lgkmcnt(0)
	v_add_f32_e32 v147, v172, v147
	s_nop 0
	v_add_f32_e32 v187, v212, v213
	s_nop 1
	v_mov_b32_e32 v172, v147
	s_nop 1
	v_permlane32_swap_b32_e32 v172, v147
	v_add_f32_e32 v165, v165, v167
	v_add_f32_e32 v167, v169, v171
	v_add_f32_e32 v169, v186, v187
	s_nop 0
	s_waitcnt lgkmcnt(0)
	v_add_f32_e32 v147, v147, v172
	s_nop 1
	v_mov_b32_e32 v186, v165
	s_nop 1
	v_permlane16_swap_b32_e32 v186, v165
	v_fmamk_f32 v147, v147, 0x3a800000, v184
	v_rsq_f32_e32 v196, v147
	s_nop 0
	v_add_f32_e32 v192, v222, v223
	v_add_f32_e32 v193, v224, v225
	s_nop 0
	v_add_f32_e32 v194, v226, v227
	v_add_f32_e32 v195, v228, v229
	v_add_f32_e32 v197, v192, v193
	s_waitcnt lgkmcnt(0)
	v_add_f32_e32 v193, v165, v186
	s_nop 0
	v_add_f32_e32 v195, v194, v195
	v_mov_b32_e32 v194, v193
	s_nop 1
	v_permlane32_swap_b32_e32 v194, v193
	s_nop 0
	v_mov_b32_e32 v165, v201
	s_nop 1
	v_mov_b32_e32 v147, v167
	s_nop 1
	v_permlane16_swap_b32_e32 v147, v167
	s_nop 0
	v_add_f32_e32 v190, v218, v219
	s_nop 0
	v_add_f32_e32 v191, v220, v221
	s_nop 0
	v_add_f32_e32 v173, v190, v191
	v_mov_b32_e32 v172, v169
	s_nop 1
	v_permlane16_swap_b32_e32 v172, v169
	s_waitcnt lgkmcnt(0)
	v_add_f32_e32 v191, v167, v147
	v_lshlrev_b32_e32 v147, 2, v165
	v_xor_b32_e32 v147, 0x80, v147
	v_mov_b32_e32 v192, v191
	s_nop 1
	v_permlane32_swap_b32_e32 v192, v191
	s_nop 0
	v_add_f32_e32 v188, v214, v215
	v_add_f32_e32 v189, v216, v217
	s_nop 0
	v_add_f32_e32 v171, v188, v189
	s_waitcnt lgkmcnt(0)
	v_add_f32_e32 v189, v169, v172
	s_nop 0
	v_mov_b32_e32 v190, v189
	s_nop 1
	v_permlane32_swap_b32_e32 v190, v189
	s_nop 0
	v_mov_b32_e32 v165, v201
	s_nop 1
	v_mov_b32_e32 v147, v171
	s_nop 1
	v_permlane16_swap_b32_e32 v147, v171
	s_nop 0
	v_pk_mul_f32 v[126:127], v[126:127], v[196:197] op_sel_hi:[1,0]
	s_nop 1
	v_mov_b32_e32 v167, v173
	s_nop 1
	v_permlane16_swap_b32_e32 v167, v173
	s_waitcnt lgkmcnt(0)
	v_add_f32_e32 v187, v171, v147
	v_lshlrev_b32_e32 v147, 2, v165
	v_xor_b32_e32 v147, 0x80, v147
	v_mov_b32_e32 v188, v187
	s_nop 1
	v_permlane32_swap_b32_e32 v188, v187
	s_nop 0
	s_waitcnt lgkmcnt(0)
	v_add_f32_e32 v171, v173, v167
	s_nop 1
	v_mov_b32_e32 v186, v171
	s_nop 1
	v_permlane32_swap_b32_e32 v186, v171
	s_nop 0
	v_mov_b32_e32 v165, v201
	s_nop 2
	v_mov_b32_e32 v147, v197
	s_nop 1
	v_permlane16_swap_b32_e32 v147, v197
	v_pk_mul_f32 v[124:125], v[124:125], v[196:197] op_sel_hi:[1,0]
	s_nop 1
	v_mov_b32_e32 v172, v195
	s_nop 1
	v_permlane16_swap_b32_e32 v172, v195
	s_waitcnt lgkmcnt(0)
	v_add_f32_e32 v167, v197, v147
	v_lshlrev_b32_e32 v147, 2, v165
	s_nop 0
	v_xor_b32_e32 v147, 0x80, v147
	s_nop 0
	v_mov_b32_e32 v169, v167
	s_nop 1
	v_permlane32_swap_b32_e32 v169, v167
	s_waitcnt lgkmcnt(0)
	v_add_f32_e32 v147, v195, v172
	s_nop 0
	v_mov_b32_e32 v165, v147
	s_nop 1
	v_permlane32_swap_b32_e32 v165, v147
	v_pk_mul_f32 v[122:123], v[122:123], v[196:197] op_sel_hi:[1,0]
	v_pk_mul_f32 v[172:173], v[120:121], v[196:197] op_sel_hi:[1,0]
	v_pk_mul_f32 v[118:119], v[118:119], v[196:197] op_sel_hi:[1,0]
	v_pk_mul_f32 v[116:117], v[116:117], v[196:197] op_sel_hi:[1,0]
	v_pk_mul_f32 v[114:115], v[114:115], v[196:197] op_sel_hi:[1,0]
	v_pk_mul_f32 v[120:121], v[112:113], v[196:197] op_sel_hi:[1,0]
	s_cbranch_scc1 .LBB0_717
; __device__ __forceinline__ f32x4 silu4(f32x4 v) { return (f32x4){silu_f(v[0]), silu_f(v[1]), silu_f(v[2]), silu_f(v[3])}; }
; __device__ __forceinline__ float sq4(f32x4 v) { return (v[0] * v[0] + v[1] * v[1]) + (v[2] * v[2] + v[3] * v[3]); }
; __device__ __forceinline__ u32x4 pack8(f32x4 a, f32x4 b) { u32x4 w; w.x = cvt_pk_bf16(a[0], a[1]); w.y = cvt_pk_bf16(a[2], a[3]); w.z = cvt_pk_bf16(b[0], b[1]); w.w = cvt_pk_bf16(b[2], b[3]); return w; }
;     __device__ __forceinline__ void operator()(const f32x4 (&acc)[2][2][4][2], const Unit& u, int wr, int wc, int fr, int fq) const {
;     ...
;                 const int row = u.pm * BM + ai * HALF + wr * 64 + m * 16 + fr;
;                 const float rstd = rs[ai][m];
;                 f32x4 v[2][2];
; #pragma unroll
;                 for (int bj = 0; bj < 2; ++bj)
; #pragma unroll
;                     for (int n = 0; n < 2; ++n) v[bj][n] = acc[ai][bj][m][n] * rstd;
;                 if (mode == 2) {
;                     float q = (sq4(v[0][0]) + sq4(v[0][1])) + (sq4(v[1][0]) + sq4(v[1][1]));
;                     q += shx(q, 16); q += shx(q, 32);
;                     const float r2 = __builtin_amdgcn_rsqf(q * (1.0f / 64.0f) + RMS_EPS);
; #pragma unroll
;                     for (int bj = 0; bj < 2; ++bj)
; #pragma unroll
;                         for (int n = 0; n < 2; ++n) v[bj][n] = v[bj][n] * r2 * wv[bj][n];
;                 } else if (mode == 1) {
; #pragma unroll
;                     for (int bj = 0; bj < 2; ++bj)
; #pragma unroll
;                         for (int n = 0; n < 2; ++n) v[bj][n] = silu4(v[bj][n]);
;                 } else {
; #pragma unroll
;                     for (int bj = 0; bj < 2; ++bj)
; #pragma unroll
;                         for (int n = 0; n < 2; ++n) v[bj][n] = v[bj][n] * sc;
;                 }
;                 bf16_t* rowp = U + (size_t)row * 2560 + lcol;
; #pragma unroll
;                 for (int bj = 0; bj < 2; ++bj) *(u32x4*)(rowp + 32 * bj) = pack8(v[bj][0], v[bj][1]);
	v_mov_b32_e32 v196, v125
	v_mov_b32_e32 v197, v117
	v_mov_b32_e32 v112, v124
	v_mov_b32_e32 v113, v116
	v_pk_mul_f32 v[196:197], v[196:197], v[196:197]
	v_mov_b32_e32 v198, v127
	v_mov_b32_e32 v199, v119
	v_pk_fma_f32 v[112:113], v[112:113], v[112:113], v[196:197]
	v_mov_b32_e32 v196, v126
	v_mov_b32_e32 v197, v118
	v_pk_mul_f32 v[198:199], v[198:199], v[198:199]
	v_mov_b32_e32 v202, v123
	v_pk_fma_f32 v[196:197], v[196:197], v[196:197], v[198:199]
	v_mov_b32_e32 v198, v173
	v_mov_b32_e32 v199, v121
	v_pk_add_f32 v[112:113], v[112:113], v[196:197]
	v_mov_b32_e32 v196, v172
	v_mov_b32_e32 v197, v120
	v_pk_mul_f32 v[198:199], v[198:199], v[198:199]
	v_mov_b32_e32 v203, v115
	v_pk_fma_f32 v[196:197], v[196:197], v[196:197], v[198:199]
	v_mov_b32_e32 v198, v122
	v_mov_b32_e32 v199, v114
	v_pk_mul_f32 v[202:203], v[202:203], v[202:203]
	s_nop 0
	v_pk_fma_f32 v[198:199], v[198:199], v[198:199], v[202:203]
	s_nop 0
	v_pk_add_f32 v[196:197], v[196:197], v[198:199]
	s_nop 0
	v_pk_add_f32 v[112:113], v[112:113], v[196:197]
	s_nop 0
	v_add_f32_e32 v112, v112, v113
	s_nop 0
	s_nop 0
	s_nop 1
	v_mov_b32_e32 v113, v112
	s_nop 1
	v_permlane16_swap_b32_e32 v113, v112
	s_waitcnt lgkmcnt(0)
	v_add_f32_e32 v112, v112, v113
	s_nop 0
	s_nop 0
	s_nop 1
	v_mov_b32_e32 v113, v112
	s_nop 1
	v_permlane32_swap_b32_e32 v113, v112
	s_waitcnt lgkmcnt(0)
	v_add_f32_e32 v112, v112, v113
	v_fmamk_f32 v112, v112, 0x3c800000, v184
	v_rsq_f32_e32 v112, v112
	s_nop 0
	v_pk_mul_f32 v[124:125], v[124:125], v[112:113] op_sel_hi:[1,0]
	v_pk_mul_f32 v[126:127], v[126:127], v[112:113] op_sel_hi:[1,0]
	v_pk_mul_f32 v[172:173], v[172:173], v[112:113] op_sel_hi:[1,0]
	v_pk_mul_f32 v[122:123], v[122:123], v[112:113] op_sel_hi:[1,0]
	v_pk_mul_f32 v[116:117], v[116:117], v[112:113] op_sel_hi:[1,0]
	v_pk_mul_f32 v[118:119], v[118:119], v[112:113] op_sel_hi:[1,0]
	v_pk_mul_f32 v[120:121], v[120:121], v[112:113] op_sel_hi:[1,0]
	v_pk_mul_f32 v[112:113], v[114:115], v[112:113] op_sel_hi:[1,0]
	v_pk_mul_f32 v[126:127], v[160:161], v[126:127]
	v_pk_mul_f32 v[124:125], v[162:163], v[124:125]
	v_pk_mul_f32 v[122:123], v[156:157], v[122:123]
	v_pk_mul_f32 v[172:173], v[158:159], v[172:173]
	v_pk_mul_f32 v[118:119], v[152:153], v[118:119]
	v_pk_mul_f32 v[116:117], v[154:155], v[116:117]
	v_pk_mul_f32 v[114:115], v[148:149], v[112:113]
	v_pk_mul_f32 v[120:121], v[150:151], v[120:121]
.LBB0_717:
	v_add_f32_e32 v112, v193, v194
	v_fmamk_f32 v112, v112, 0x3a800000, v184
	v_rsq_f32_e32 v194, v112
	v_lshl_or_b32 v112, s44, 8, v179
	v_mov_b64_e32 v[196:197], s[22:23]
	v_ashrrev_i32_e32 v113, 31, v112
	v_mad_i64_i32 v[196:197], s[12:13], v170, s64, v[196:197]
	v_lshl_add_u64 v[196:197], v[112:113], 1, v[196:197]
	v_cvt_pk_bf16_f32 v124, v124, v125
	v_cvt_pk_bf16_f32 v125, v126, v127
	v_cvt_pk_bf16_f32 v126, v172, v173
	v_cvt_pk_bf16_f32 v127, v122, v123
	global_store_dwordx4 v[196:197], v[124:127], off
	v_cvt_pk_bf16_f32 v116, v116, v117
	v_cvt_pk_bf16_f32 v117, v118, v119
	v_cvt_pk_bf16_f32 v118, v120, v121
	v_cvt_pk_bf16_f32 v119, v114, v115
	v_cndmask_b32_e64 v114, 0, 1, s[48:49]
	v_pk_mul_f32 v[110:111], v[110:111], v[194:195] op_sel_hi:[1,0]
	v_pk_mul_f32 v[108:109], v[108:109], v[194:195] op_sel_hi:[1,0]
	v_pk_mul_f32 v[106:107], v[106:107], v[194:195] op_sel_hi:[1,0]
	v_pk_mul_f32 v[104:105], v[104:105], v[194:195] op_sel_hi:[1,0]
	v_pk_mul_f32 v[102:103], v[102:103], v[194:195] op_sel_hi:[1,0]
	v_pk_mul_f32 v[100:101], v[100:101], v[194:195] op_sel_hi:[1,0]
	v_pk_mul_f32 v[98:99], v[98:99], v[194:195] op_sel_hi:[1,0]
	v_cmp_ne_u32_e64 s[12:13], 1, v114
	s_andn2_b64 vcc, exec, s[48:49]
	v_pk_mul_f32 v[96:97], v[96:97], v[194:195] op_sel_hi:[1,0]
	global_store_dwordx4 v[196:197], v[116:119], off offset:64
	s_cbranch_vccnz .LBB0_719
	s_nop 0
	v_mov_b32_e32 v116, v109
	v_mov_b32_e32 v117, v101
	v_mov_b32_e32 v114, v108
	v_mov_b32_e32 v115, v100
	v_pk_mul_f32 v[116:117], v[116:117], v[116:117]
	v_mov_b32_e32 v118, v111
	v_mov_b32_e32 v119, v103
	v_pk_fma_f32 v[114:115], v[114:115], v[114:115], v[116:117]
	v_mov_b32_e32 v116, v110
	v_mov_b32_e32 v117, v102
	v_pk_mul_f32 v[118:119], v[118:119], v[118:119]
	v_mov_b32_e32 v120, v107
	v_pk_fma_f32 v[116:117], v[116:117], v[116:117], v[118:119]
	v_mov_b32_e32 v118, v105
	v_mov_b32_e32 v119, v97
	v_pk_add_f32 v[114:115], v[114:115], v[116:117]
	v_mov_b32_e32 v116, v104
	v_mov_b32_e32 v117, v96
	v_pk_mul_f32 v[118:119], v[118:119], v[118:119]
	v_mov_b32_e32 v121, v99
	v_pk_fma_f32 v[116:117], v[116:117], v[116:117], v[118:119]
	v_mov_b32_e32 v118, v106
	v_mov_b32_e32 v119, v98
	v_pk_mul_f32 v[120:121], v[120:121], v[120:121]
	s_nop 0
	v_pk_fma_f32 v[118:119], v[118:119], v[118:119], v[120:121]
	s_nop 0
	v_pk_add_f32 v[116:117], v[116:117], v[118:119]
	s_nop 0
	v_pk_add_f32 v[114:115], v[114:115], v[116:117]
	s_nop 0
	v_add_f32_e32 v114, v114, v115
	s_nop 0
	s_nop 0
	s_nop 1
	v_mov_b32_e32 v115, v114
	s_nop 1
	v_permlane16_swap_b32_e32 v115, v114
	s_waitcnt lgkmcnt(0)
	v_add_f32_e32 v114, v114, v115
	s_nop 0
	s_nop 0
	s_nop 1
	v_mov_b32_e32 v115, v114
	s_nop 1
	v_permlane32_swap_b32_e32 v115, v114
	s_waitcnt lgkmcnt(0)
	v_add_f32_e32 v114, v114, v115
	v_fmamk_f32 v114, v114, 0x3c800000, v184
	v_rsq_f32_e32 v114, v114
	s_nop 0
	v_pk_mul_f32 v[108:109], v[108:109], v[114:115] op_sel_hi:[1,0]
	v_pk_mul_f32 v[110:111], v[110:111], v[114:115] op_sel_hi:[1,0]
	v_pk_mul_f32 v[104:105], v[104:105], v[114:115] op_sel_hi:[1,0]
	v_pk_mul_f32 v[106:107], v[106:107], v[114:115] op_sel_hi:[1,0]
	v_pk_mul_f32 v[100:101], v[100:101], v[114:115] op_sel_hi:[1,0]
	v_pk_mul_f32 v[102:103], v[102:103], v[114:115] op_sel_hi:[1,0]
	v_pk_mul_f32 v[96:97], v[96:97], v[114:115] op_sel_hi:[1,0]
	v_pk_mul_f32 v[98:99], v[98:99], v[114:115] op_sel_hi:[1,0]
	v_pk_mul_f32 v[110:111], v[160:161], v[110:111]
	v_pk_mul_f32 v[108:109], v[162:163], v[108:109]
	v_pk_mul_f32 v[106:107], v[156:157], v[106:107]
	v_pk_mul_f32 v[104:105], v[158:159], v[104:105]
	v_pk_mul_f32 v[102:103], v[152:153], v[102:103]
	v_pk_mul_f32 v[100:101], v[154:155], v[100:101]
	v_pk_mul_f32 v[98:99], v[148:149], v[98:99]
	v_pk_mul_f32 v[96:97], v[150:151], v[96:97]
; __device__ __forceinline__ f32x4 silu4(f32x4 v) { return (f32x4){silu_f(v[0]), silu_f(v[1]), silu_f(v[2]), silu_f(v[3])}; }
; __device__ __forceinline__ float sq4(f32x4 v) { return (v[0] * v[0] + v[1] * v[1]) + (v[2] * v[2] + v[3] * v[3]); }
; __device__ __forceinline__ u32x4 pack8(f32x4 a, f32x4 b) { u32x4 w; w.x = cvt_pk_bf16(a[0], a[1]); w.y = cvt_pk_bf16(a[2], a[3]); w.z = cvt_pk_bf16(b[0], b[1]); w.w = cvt_pk_bf16(b[2], b[3]); return w; }
;     __device__ __forceinline__ void operator()(const f32x4 (&acc)[2][2][4][2], const Unit& u, int wr, int wc, int fr, int fq) const {
;     ...
;                 const int row = u.pm * BM + ai * HALF + wr * 64 + m * 16 + fr;
;                 const float rstd = rs[ai][m];
;                 f32x4 v[2][2];
; #pragma unroll
;                 for (int bj = 0; bj < 2; ++bj)
; #pragma unroll
;                     for (int n = 0; n < 2; ++n) v[bj][n] = acc[ai][bj][m][n] * rstd;
;                 if (mode == 2) {
;                     float q = (sq4(v[0][0]) + sq4(v[0][1])) + (sq4(v[1][0]) + sq4(v[1][1]));
;                     q += shx(q, 16); q += shx(q, 32);
;                     const float r2 = __builtin_amdgcn_rsqf(q * (1.0f / 64.0f) + RMS_EPS);
; #pragma unroll
;                     for (int bj = 0; bj < 2; ++bj)
; #pragma unroll
;                         for (int n = 0; n < 2; ++n) v[bj][n] = v[bj][n] * r2 * wv[bj][n];
;                 } else if (mode == 1) {
; #pragma unroll
;                     for (int bj = 0; bj < 2; ++bj)
; #pragma unroll
;                         for (int n = 0; n < 2; ++n) v[bj][n] = silu4(v[bj][n]);
;                 } else {
; #pragma unroll
;                     for (int bj = 0; bj < 2; ++bj)
; #pragma unroll
;                         for (int n = 0; n < 2; ++n) v[bj][n] = v[bj][n] * sc;
;                 }
;                 bf16_t* rowp = U + (size_t)row * 2560 + lcol;
; #pragma unroll
;                 for (int bj = 0; bj < 2; ++bj) *(u32x4*)(rowp + 32 * bj) = pack8(v[bj][0], v[bj][1]);
.LBB0_719:
	v_add_f32_e32 v114, v191, v192
	v_fmamk_f32 v114, v114, 0x3a800000, v184
	v_rsq_f32_e32 v114, v114
	v_add_u32_e32 v115, s35, v176
	v_mov_b64_e32 v[116:117], s[22:23]
	v_mad_i64_i32 v[116:117], s[48:49], v115, s64, v[116:117]
	v_lshl_add_u64 v[116:117], v[112:113], 1, v[116:117]
	v_pk_mul_f32 v[94:95], v[94:95], v[114:115] op_sel_hi:[1,0]
	v_pk_mul_f32 v[92:93], v[92:93], v[114:115] op_sel_hi:[1,0]
	v_pk_mul_f32 v[90:91], v[90:91], v[114:115] op_sel_hi:[1,0]
	v_pk_mul_f32 v[88:89], v[88:89], v[114:115] op_sel_hi:[1,0]
	v_pk_mul_f32 v[86:87], v[86:87], v[114:115] op_sel_hi:[1,0]
	v_pk_mul_f32 v[84:85], v[84:85], v[114:115] op_sel_hi:[1,0]
	v_pk_mul_f32 v[82:83], v[82:83], v[114:115] op_sel_hi:[1,0]
	s_and_b64 vcc, exec, s[12:13]
	v_pk_mul_f32 v[80:81], v[80:81], v[114:115] op_sel_hi:[1,0]
	v_cvt_pk_bf16_f32 v108, v108, v109
	v_cvt_pk_bf16_f32 v109, v110, v111
	v_cvt_pk_bf16_f32 v110, v104, v105
	v_cvt_pk_bf16_f32 v111, v106, v107
	global_store_dwordx4 v[116:117], v[108:111], off
	v_cvt_pk_bf16_f32 v100, v100, v101
	v_cvt_pk_bf16_f32 v101, v102, v103
	v_cvt_pk_bf16_f32 v102, v96, v97
	v_cvt_pk_bf16_f32 v103, v98, v99
	global_store_dwordx4 v[116:117], v[100:103], off offset:64
	s_cbranch_vccnz .LBB0_721
	v_mov_b32_e32 v98, v93
	v_mov_b32_e32 v99, v85
	v_mov_b32_e32 v96, v92
	v_mov_b32_e32 v97, v84
	v_pk_mul_f32 v[98:99], v[98:99], v[98:99]
	v_mov_b32_e32 v100, v95
	v_mov_b32_e32 v101, v87
	v_pk_fma_f32 v[96:97], v[96:97], v[96:97], v[98:99]
	v_mov_b32_e32 v98, v94
	v_mov_b32_e32 v99, v86
	v_pk_mul_f32 v[100:101], v[100:101], v[100:101]
	v_mov_b32_e32 v102, v91
	v_pk_fma_f32 v[98:99], v[98:99], v[98:99], v[100:101]
	v_mov_b32_e32 v100, v89
	v_mov_b32_e32 v101, v81
	v_pk_add_f32 v[96:97], v[96:97], v[98:99]
	v_mov_b32_e32 v98, v88
	v_mov_b32_e32 v99, v80
	v_pk_mul_f32 v[100:101], v[100:101], v[100:101]
	v_mov_b32_e32 v103, v83
	v_pk_fma_f32 v[98:99], v[98:99], v[98:99], v[100:101]
	v_mov_b32_e32 v100, v90
	v_mov_b32_e32 v101, v82
	v_pk_mul_f32 v[102:103], v[102:103], v[102:103]
	s_nop 0
	v_pk_fma_f32 v[100:101], v[100:101], v[100:101], v[102:103]
	s_nop 0
	v_pk_add_f32 v[98:99], v[98:99], v[100:101]
	s_nop 0
	v_pk_add_f32 v[96:97], v[96:97], v[98:99]
	s_nop 0
	v_add_f32_e32 v96, v96, v97
	s_nop 0
	s_nop 0
	s_nop 1
	v_mov_b32_e32 v97, v96
	s_nop 1
	v_permlane16_swap_b32_e32 v97, v96
	s_waitcnt lgkmcnt(0)
	v_add_f32_e32 v96, v96, v97
	s_nop 0
	s_nop 0
	s_nop 1
	v_mov_b32_e32 v97, v96
	s_nop 1
	v_permlane32_swap_b32_e32 v97, v96
	s_waitcnt lgkmcnt(0)
	v_add_f32_e32 v96, v96, v97
	v_fmamk_f32 v96, v96, 0x3c800000, v184
	v_rsq_f32_e32 v96, v96
	s_nop 0
	v_pk_mul_f32 v[92:93], v[92:93], v[96:97] op_sel_hi:[1,0]
	v_pk_mul_f32 v[94:95], v[94:95], v[96:97] op_sel_hi:[1,0]
	v_pk_mul_f32 v[88:89], v[88:89], v[96:97] op_sel_hi:[1,0]
	v_pk_mul_f32 v[90:91], v[90:91], v[96:97] op_sel_hi:[1,0]
	v_pk_mul_f32 v[84:85], v[84:85], v[96:97] op_sel_hi:[1,0]
	v_pk_mul_f32 v[86:87], v[86:87], v[96:97] op_sel_hi:[1,0]
	v_pk_mul_f32 v[80:81], v[80:81], v[96:97] op_sel_hi:[1,0]
	v_pk_mul_f32 v[82:83], v[82:83], v[96:97] op_sel_hi:[1,0]
	v_pk_mul_f32 v[94:95], v[160:161], v[94:95]
	v_pk_mul_f32 v[92:93], v[162:163], v[92:93]
	v_pk_mul_f32 v[90:91], v[156:157], v[90:91]
	v_pk_mul_f32 v[88:89], v[158:159], v[88:89]
	v_pk_mul_f32 v[86:87], v[152:153], v[86:87]
	v_pk_mul_f32 v[84:85], v[154:155], v[84:85]
	v_pk_mul_f32 v[82:83], v[148:149], v[82:83]
	v_pk_mul_f32 v[80:81], v[150:151], v[80:81]
.LBB0_721:
	v_add_f32_e32 v96, v189, v190
	v_fmamk_f32 v96, v96, 0x3a800000, v184
	v_rsq_f32_e32 v96, v96
	v_add_u32_e32 v97, s35, v177
	v_mov_b64_e32 v[98:99], s[22:23]
	v_mad_i64_i32 v[98:99], s[48:49], v97, s64, v[98:99]
	v_lshl_add_u64 v[98:99], v[112:113], 1, v[98:99]
	v_pk_mul_f32 v[78:79], v[78:79], v[96:97] op_sel_hi:[1,0]
	v_pk_mul_f32 v[76:77], v[76:77], v[96:97] op_sel_hi:[1,0]
	v_pk_mul_f32 v[74:75], v[74:75], v[96:97] op_sel_hi:[1,0]
	v_pk_mul_f32 v[72:73], v[72:73], v[96:97] op_sel_hi:[1,0]
	v_pk_mul_f32 v[70:71], v[70:71], v[96:97] op_sel_hi:[1,0]
	v_pk_mul_f32 v[68:69], v[68:69], v[96:97] op_sel_hi:[1,0]
	v_pk_mul_f32 v[66:67], v[66:67], v[96:97] op_sel_hi:[1,0]
	s_and_b64 vcc, exec, s[12:13]
	v_pk_mul_f32 v[64:65], v[64:65], v[96:97] op_sel_hi:[1,0]
	v_cvt_pk_bf16_f32 v92, v92, v93
	v_cvt_pk_bf16_f32 v93, v94, v95
	v_cvt_pk_bf16_f32 v94, v88, v89
	v_cvt_pk_bf16_f32 v95, v90, v91
	global_store_dwordx4 v[98:99], v[92:95], off
	v_cvt_pk_bf16_f32 v84, v84, v85
	v_cvt_pk_bf16_f32 v85, v86, v87
	v_cvt_pk_bf16_f32 v86, v80, v81
	v_cvt_pk_bf16_f32 v87, v82, v83
	global_store_dwordx4 v[98:99], v[84:87], off offset:64
	s_cbranch_vccnz .LBB0_723
	v_mov_b32_e32 v82, v77
	v_mov_b32_e32 v83, v69
	v_mov_b32_e32 v80, v76
	v_mov_b32_e32 v81, v68
	v_pk_mul_f32 v[82:83], v[82:83], v[82:83]
	v_mov_b32_e32 v84, v79
	v_mov_b32_e32 v85, v71
	v_pk_fma_f32 v[80:81], v[80:81], v[80:81], v[82:83]
	v_mov_b32_e32 v82, v78
	v_mov_b32_e32 v83, v70
	v_pk_mul_f32 v[84:85], v[84:85], v[84:85]
	v_mov_b32_e32 v86, v75
	v_pk_fma_f32 v[82:83], v[82:83], v[82:83], v[84:85]
	v_mov_b32_e32 v84, v73
	v_mov_b32_e32 v85, v65
	v_pk_add_f32 v[80:81], v[80:81], v[82:83]
	v_mov_b32_e32 v82, v72
	v_mov_b32_e32 v83, v64
	v_pk_mul_f32 v[84:85], v[84:85], v[84:85]
	v_mov_b32_e32 v87, v67
	v_pk_fma_f32 v[82:83], v[82:83], v[82:83], v[84:85]
	v_mov_b32_e32 v84, v74
	v_mov_b32_e32 v85, v66
	v_pk_mul_f32 v[86:87], v[86:87], v[86:87]
	s_nop 0
	v_pk_fma_f32 v[84:85], v[84:85], v[84:85], v[86:87]
	s_nop 0
	v_pk_add_f32 v[82:83], v[82:83], v[84:85]
	s_nop 0
	v_pk_add_f32 v[80:81], v[80:81], v[82:83]
	s_nop 0
	v_add_f32_e32 v80, v80, v81
	s_nop 0
	s_nop 0
	s_nop 1
	v_mov_b32_e32 v81, v80
	s_nop 1
	v_permlane16_swap_b32_e32 v81, v80
	s_waitcnt lgkmcnt(0)
	v_add_f32_e32 v80, v80, v81
	s_nop 0
	s_nop 0
	s_nop 1
	v_mov_b32_e32 v81, v80
	s_nop 1
	v_permlane32_swap_b32_e32 v81, v80
	s_waitcnt lgkmcnt(0)
	v_add_f32_e32 v80, v80, v81
	v_fmamk_f32 v80, v80, 0x3c800000, v184
	v_rsq_f32_e32 v80, v80
	s_nop 0
	v_pk_mul_f32 v[76:77], v[76:77], v[80:81] op_sel_hi:[1,0]
	v_pk_mul_f32 v[78:79], v[78:79], v[80:81] op_sel_hi:[1,0]
	v_pk_mul_f32 v[72:73], v[72:73], v[80:81] op_sel_hi:[1,0]
	v_pk_mul_f32 v[74:75], v[74:75], v[80:81] op_sel_hi:[1,0]
	v_pk_mul_f32 v[68:69], v[68:69], v[80:81] op_sel_hi:[1,0]
	v_pk_mul_f32 v[70:71], v[70:71], v[80:81] op_sel_hi:[1,0]
	v_pk_mul_f32 v[64:65], v[64:65], v[80:81] op_sel_hi:[1,0]
	v_pk_mul_f32 v[66:67], v[66:67], v[80:81] op_sel_hi:[1,0]
	v_pk_mul_f32 v[78:79], v[160:161], v[78:79]
	v_pk_mul_f32 v[76:77], v[162:163], v[76:77]
	v_pk_mul_f32 v[74:75], v[156:157], v[74:75]
	v_pk_mul_f32 v[72:73], v[158:159], v[72:73]
	v_pk_mul_f32 v[70:71], v[152:153], v[70:71]
	v_pk_mul_f32 v[68:69], v[154:155], v[68:69]
	v_pk_mul_f32 v[66:67], v[148:149], v[66:67]
	v_pk_mul_f32 v[64:65], v[150:151], v[64:65]
; __device__ __forceinline__ f32x4 silu4(f32x4 v) { return (f32x4){silu_f(v[0]), silu_f(v[1]), silu_f(v[2]), silu_f(v[3])}; }
; __device__ __forceinline__ float sq4(f32x4 v) { return (v[0] * v[0] + v[1] * v[1]) + (v[2] * v[2] + v[3] * v[3]); }
; __device__ __forceinline__ u32x4 pack8(f32x4 a, f32x4 b) { u32x4 w; w.x = cvt_pk_bf16(a[0], a[1]); w.y = cvt_pk_bf16(a[2], a[3]); w.z = cvt_pk_bf16(b[0], b[1]); w.w = cvt_pk_bf16(b[2], b[3]); return w; }
;     __device__ __forceinline__ void operator()(const f32x4 (&acc)[2][2][4][2], const Unit& u, int wr, int wc, int fr, int fq) const {
;     ...
;                 const int row = u.pm * BM + ai * HALF + wr * 64 + m * 16 + fr;
;                 const float rstd = rs[ai][m];
;                 f32x4 v[2][2];
; #pragma unroll
;                 for (int bj = 0; bj < 2; ++bj)
; #pragma unroll
;                     for (int n = 0; n < 2; ++n) v[bj][n] = acc[ai][bj][m][n] * rstd;
;                 if (mode == 2) {
;                     float q = (sq4(v[0][0]) + sq4(v[0][1])) + (sq4(v[1][0]) + sq4(v[1][1]));
;                     q += shx(q, 16); q += shx(q, 32);
;                     const float r2 = __builtin_amdgcn_rsqf(q * (1.0f / 64.0f) + RMS_EPS);
; #pragma unroll
;                     for (int bj = 0; bj < 2; ++bj)
; #pragma unroll
;                         for (int n = 0; n < 2; ++n) v[bj][n] = v[bj][n] * r2 * wv[bj][n];
;                 } else if (mode == 1) {
; #pragma unroll
;                     for (int bj = 0; bj < 2; ++bj)
; #pragma unroll
;                         for (int n = 0; n < 2; ++n) v[bj][n] = silu4(v[bj][n]);
;                 } else {
; #pragma unroll
;                     for (int bj = 0; bj < 2; ++bj)
; #pragma unroll
;                         for (int n = 0; n < 2; ++n) v[bj][n] = v[bj][n] * sc;
;                 }
;                 bf16_t* rowp = U + (size_t)row * 2560 + lcol;
; #pragma unroll
;                 for (int bj = 0; bj < 2; ++bj) *(u32x4*)(rowp + 32 * bj) = pack8(v[bj][0], v[bj][1]);
.LBB0_723:
	v_add_f32_e32 v80, v187, v188
	v_fmamk_f32 v80, v80, 0x3a800000, v184
	v_rsq_f32_e32 v80, v80
	v_add_u32_e32 v81, s35, v178
	v_mov_b64_e32 v[82:83], s[22:23]
	v_mad_i64_i32 v[82:83], s[48:49], v81, s64, v[82:83]
	v_lshl_add_u64 v[82:83], v[112:113], 1, v[82:83]
	v_pk_mul_f32 v[62:63], v[62:63], v[80:81] op_sel_hi:[1,0]
	v_pk_mul_f32 v[60:61], v[60:61], v[80:81] op_sel_hi:[1,0]
	v_pk_mul_f32 v[58:59], v[58:59], v[80:81] op_sel_hi:[1,0]
	v_pk_mul_f32 v[56:57], v[56:57], v[80:81] op_sel_hi:[1,0]
	v_pk_mul_f32 v[54:55], v[54:55], v[80:81] op_sel_hi:[1,0]
	v_pk_mul_f32 v[52:53], v[52:53], v[80:81] op_sel_hi:[1,0]
	v_pk_mul_f32 v[50:51], v[50:51], v[80:81] op_sel_hi:[1,0]
	s_and_b64 vcc, exec, s[12:13]
	v_pk_mul_f32 v[48:49], v[48:49], v[80:81] op_sel_hi:[1,0]
	v_cvt_pk_bf16_f32 v76, v76, v77
	v_cvt_pk_bf16_f32 v77, v78, v79
	v_cvt_pk_bf16_f32 v78, v72, v73
	v_cvt_pk_bf16_f32 v79, v74, v75
	global_store_dwordx4 v[82:83], v[76:79], off
	v_cvt_pk_bf16_f32 v68, v68, v69
	v_cvt_pk_bf16_f32 v69, v70, v71
	v_cvt_pk_bf16_f32 v70, v64, v65
	v_cvt_pk_bf16_f32 v71, v66, v67
	global_store_dwordx4 v[82:83], v[68:71], off offset:64
	s_cbranch_vccnz .LBB0_725
	v_mov_b32_e32 v66, v61
	v_mov_b32_e32 v67, v53
	v_mov_b32_e32 v64, v60
	v_mov_b32_e32 v65, v52
	v_pk_mul_f32 v[66:67], v[66:67], v[66:67]
	v_mov_b32_e32 v68, v63
	v_mov_b32_e32 v69, v55
	v_pk_fma_f32 v[64:65], v[64:65], v[64:65], v[66:67]
	v_mov_b32_e32 v66, v62
	v_mov_b32_e32 v67, v54
	v_pk_mul_f32 v[68:69], v[68:69], v[68:69]
	v_mov_b32_e32 v70, v59
	v_pk_fma_f32 v[66:67], v[66:67], v[66:67], v[68:69]
	v_mov_b32_e32 v68, v57
	v_mov_b32_e32 v69, v49
	v_pk_add_f32 v[64:65], v[64:65], v[66:67]
	v_mov_b32_e32 v66, v56
	v_mov_b32_e32 v67, v48
	v_pk_mul_f32 v[68:69], v[68:69], v[68:69]
	v_mov_b32_e32 v71, v51
	v_pk_fma_f32 v[66:67], v[66:67], v[66:67], v[68:69]
	v_mov_b32_e32 v68, v58
	v_mov_b32_e32 v69, v50
	v_pk_mul_f32 v[70:71], v[70:71], v[70:71]
	s_nop 0
	v_pk_fma_f32 v[68:69], v[68:69], v[68:69], v[70:71]
	s_nop 0
	v_pk_add_f32 v[66:67], v[66:67], v[68:69]
	s_nop 0
	v_pk_add_f32 v[64:65], v[64:65], v[66:67]
	s_nop 0
	v_add_f32_e32 v64, v64, v65
	s_nop 0
	s_nop 0
	s_nop 1
	v_mov_b32_e32 v65, v64
	s_nop 1
	v_permlane16_swap_b32_e32 v65, v64
	s_waitcnt lgkmcnt(0)
	v_add_f32_e32 v64, v64, v65
	s_nop 0
	s_nop 0
	s_nop 1
	v_mov_b32_e32 v65, v64
	s_nop 1
	v_permlane32_swap_b32_e32 v65, v64
	s_waitcnt lgkmcnt(0)
	v_add_f32_e32 v64, v64, v65
	v_fmamk_f32 v64, v64, 0x3c800000, v184
	v_rsq_f32_e32 v64, v64
	s_nop 0
	v_pk_mul_f32 v[60:61], v[60:61], v[64:65] op_sel_hi:[1,0]
	v_pk_mul_f32 v[62:63], v[62:63], v[64:65] op_sel_hi:[1,0]
	v_pk_mul_f32 v[56:57], v[56:57], v[64:65] op_sel_hi:[1,0]
	v_pk_mul_f32 v[58:59], v[58:59], v[64:65] op_sel_hi:[1,0]
	v_pk_mul_f32 v[52:53], v[52:53], v[64:65] op_sel_hi:[1,0]
	v_pk_mul_f32 v[54:55], v[54:55], v[64:65] op_sel_hi:[1,0]
	v_pk_mul_f32 v[48:49], v[48:49], v[64:65] op_sel_hi:[1,0]
	v_pk_mul_f32 v[50:51], v[50:51], v[64:65] op_sel_hi:[1,0]
	v_pk_mul_f32 v[62:63], v[160:161], v[62:63]
	v_pk_mul_f32 v[60:61], v[162:163], v[60:61]
	v_pk_mul_f32 v[58:59], v[156:157], v[58:59]
	v_pk_mul_f32 v[56:57], v[158:159], v[56:57]
	v_pk_mul_f32 v[54:55], v[152:153], v[54:55]
	v_pk_mul_f32 v[52:53], v[154:155], v[52:53]
	v_pk_mul_f32 v[50:51], v[148:149], v[50:51]
	v_pk_mul_f32 v[48:49], v[150:151], v[48:49]
.LBB0_725:
	v_add_f32_e32 v64, v171, v186
	v_fmamk_f32 v64, v64, 0x3a800000, v184
	v_rsq_f32_e32 v64, v64
	v_mov_b64_e32 v[66:67], s[22:23]
	v_mad_i64_i32 v[66:67], s[48:49], v168, s64, v[66:67]
	v_lshl_add_u64 v[66:67], v[112:113], 1, v[66:67]
	v_pk_mul_f32 v[46:47], v[46:47], v[64:65] op_sel_hi:[1,0]
	v_pk_mul_f32 v[44:45], v[44:45], v[64:65] op_sel_hi:[1,0]
	v_pk_mul_f32 v[42:43], v[42:43], v[64:65] op_sel_hi:[1,0]
	v_pk_mul_f32 v[40:41], v[40:41], v[64:65] op_sel_hi:[1,0]
	v_pk_mul_f32 v[38:39], v[38:39], v[64:65] op_sel_hi:[1,0]
	v_pk_mul_f32 v[36:37], v[36:37], v[64:65] op_sel_hi:[1,0]
	v_pk_mul_f32 v[34:35], v[34:35], v[64:65] op_sel_hi:[1,0]
	s_and_b64 vcc, exec, s[12:13]
	v_pk_mul_f32 v[32:33], v[32:33], v[64:65] op_sel_hi:[1,0]
	v_cvt_pk_bf16_f32 v60, v60, v61
	v_cvt_pk_bf16_f32 v61, v62, v63
	v_cvt_pk_bf16_f32 v62, v56, v57
	v_cvt_pk_bf16_f32 v63, v58, v59
	global_store_dwordx4 v[66:67], v[60:63], off
	v_cvt_pk_bf16_f32 v52, v52, v53
	v_cvt_pk_bf16_f32 v53, v54, v55
	v_cvt_pk_bf16_f32 v54, v48, v49
	v_cvt_pk_bf16_f32 v55, v50, v51
	global_store_dwordx4 v[66:67], v[52:55], off offset:64
	s_cbranch_vccnz .LBB0_727
	v_mov_b32_e32 v50, v45
	v_mov_b32_e32 v51, v37
	v_mov_b32_e32 v48, v44
	v_mov_b32_e32 v49, v36
	v_pk_mul_f32 v[50:51], v[50:51], v[50:51]
	v_mov_b32_e32 v52, v47
	v_mov_b32_e32 v53, v39
	v_pk_fma_f32 v[48:49], v[48:49], v[48:49], v[50:51]
	v_mov_b32_e32 v50, v46
	v_mov_b32_e32 v51, v38
	v_pk_mul_f32 v[52:53], v[52:53], v[52:53]
	v_mov_b32_e32 v54, v43
	v_pk_fma_f32 v[50:51], v[50:51], v[50:51], v[52:53]
	v_mov_b32_e32 v52, v41
	v_mov_b32_e32 v53, v33
	v_pk_add_f32 v[48:49], v[48:49], v[50:51]
	v_mov_b32_e32 v50, v40
	v_mov_b32_e32 v51, v32
	v_pk_mul_f32 v[52:53], v[52:53], v[52:53]
	v_mov_b32_e32 v55, v35
	v_pk_fma_f32 v[50:51], v[50:51], v[50:51], v[52:53]
	v_mov_b32_e32 v52, v42
	v_mov_b32_e32 v53, v34
	v_pk_mul_f32 v[54:55], v[54:55], v[54:55]
	s_nop 0
	v_pk_fma_f32 v[52:53], v[52:53], v[52:53], v[54:55]
	s_nop 0
	v_pk_add_f32 v[50:51], v[50:51], v[52:53]
	s_nop 0
	v_pk_add_f32 v[48:49], v[48:49], v[50:51]
	s_nop 0
	v_add_f32_e32 v48, v48, v49
	s_nop 0
	s_nop 0
	s_nop 1
	v_mov_b32_e32 v49, v48
	s_nop 1
	v_permlane16_swap_b32_e32 v49, v48
	s_waitcnt lgkmcnt(0)
	v_add_f32_e32 v48, v48, v49
	s_nop 0
	s_nop 0
	s_nop 1
	v_mov_b32_e32 v49, v48
	s_nop 1
	v_permlane32_swap_b32_e32 v49, v48
	s_waitcnt lgkmcnt(0)
	v_add_f32_e32 v48, v48, v49
	v_fmamk_f32 v48, v48, 0x3c800000, v184
	v_rsq_f32_e32 v48, v48
	s_nop 0
	v_pk_mul_f32 v[44:45], v[44:45], v[48:49] op_sel_hi:[1,0]
	v_pk_mul_f32 v[46:47], v[46:47], v[48:49] op_sel_hi:[1,0]
	v_pk_mul_f32 v[40:41], v[40:41], v[48:49] op_sel_hi:[1,0]
	v_pk_mul_f32 v[42:43], v[42:43], v[48:49] op_sel_hi:[1,0]
	v_pk_mul_f32 v[36:37], v[36:37], v[48:49] op_sel_hi:[1,0]
	v_pk_mul_f32 v[38:39], v[38:39], v[48:49] op_sel_hi:[1,0]
	v_pk_mul_f32 v[32:33], v[32:33], v[48:49] op_sel_hi:[1,0]
	v_pk_mul_f32 v[34:35], v[34:35], v[48:49] op_sel_hi:[1,0]
	v_pk_mul_f32 v[46:47], v[160:161], v[46:47]
	v_pk_mul_f32 v[44:45], v[162:163], v[44:45]
	v_pk_mul_f32 v[42:43], v[156:157], v[42:43]
	v_pk_mul_f32 v[40:41], v[158:159], v[40:41]
	v_pk_mul_f32 v[38:39], v[152:153], v[38:39]
	v_pk_mul_f32 v[36:37], v[154:155], v[36:37]
	v_pk_mul_f32 v[34:35], v[148:149], v[34:35]
	v_pk_mul_f32 v[32:33], v[150:151], v[32:33]
; __device__ __forceinline__ f32x4 silu4(f32x4 v) { return (f32x4){silu_f(v[0]), silu_f(v[1]), silu_f(v[2]), silu_f(v[3])}; }
; __device__ __forceinline__ float sq4(f32x4 v) { return (v[0] * v[0] + v[1] * v[1]) + (v[2] * v[2] + v[3] * v[3]); }
; __device__ __forceinline__ u32x4 pack8(f32x4 a, f32x4 b) { u32x4 w; w.x = cvt_pk_bf16(a[0], a[1]); w.y = cvt_pk_bf16(a[2], a[3]); w.z = cvt_pk_bf16(b[0], b[1]); w.w = cvt_pk_bf16(b[2], b[3]); return w; }
;     __device__ __forceinline__ void operator()(const f32x4 (&acc)[2][2][4][2], const Unit& u, int wr, int wc, int fr, int fq) const {
;     ...
;                 const int row = u.pm * BM + ai * HALF + wr * 64 + m * 16 + fr;
;                 const float rstd = rs[ai][m];
;                 f32x4 v[2][2];
; #pragma unroll
;                 for (int bj = 0; bj < 2; ++bj)
; #pragma unroll
;                     for (int n = 0; n < 2; ++n) v[bj][n] = acc[ai][bj][m][n] * rstd;
;                 if (mode == 2) {
;                     float q = (sq4(v[0][0]) + sq4(v[0][1])) + (sq4(v[1][0]) + sq4(v[1][1]));
;                     q += shx(q, 16); q += shx(q, 32);
;                     const float r2 = __builtin_amdgcn_rsqf(q * (1.0f / 64.0f) + RMS_EPS);
; #pragma unroll
;                     for (int bj = 0; bj < 2; ++bj)
; #pragma unroll
;                         for (int n = 0; n < 2; ++n) v[bj][n] = v[bj][n] * r2 * wv[bj][n];
;                 } else if (mode == 1) {
; #pragma unroll
;                     for (int bj = 0; bj < 2; ++bj)
; #pragma unroll
;                         for (int n = 0; n < 2; ++n) v[bj][n] = silu4(v[bj][n]);
;                 } else {
; #pragma unroll
;                     for (int bj = 0; bj < 2; ++bj)
; #pragma unroll
;                         for (int n = 0; n < 2; ++n) v[bj][n] = v[bj][n] * sc;
;                 }
;                 bf16_t* rowp = U + (size_t)row * 2560 + lcol;
; #pragma unroll
;                 for (int bj = 0; bj < 2; ++bj) *(u32x4*)(rowp + 32 * bj) = pack8(v[bj][0], v[bj][1]);
.LBB0_727:
	s_waitcnt lgkmcnt(0)
	v_add_f32_e32 v48, v167, v169
	v_fmamk_f32 v48, v48, 0x3a800000, v184
	v_rsq_f32_e32 v48, v48
	v_mov_b64_e32 v[50:51], s[22:23]
	v_mad_i64_i32 v[50:51], s[48:49], v166, s64, v[50:51]
	v_lshl_add_u64 v[50:51], v[112:113], 1, v[50:51]
	v_pk_mul_f32 v[30:31], v[30:31], v[48:49] op_sel_hi:[1,0]
	v_pk_mul_f32 v[28:29], v[28:29], v[48:49] op_sel_hi:[1,0]
	v_pk_mul_f32 v[26:27], v[26:27], v[48:49] op_sel_hi:[1,0]
	v_pk_mul_f32 v[24:25], v[24:25], v[48:49] op_sel_hi:[1,0]
	v_pk_mul_f32 v[22:23], v[22:23], v[48:49] op_sel_hi:[1,0]
	v_pk_mul_f32 v[20:21], v[20:21], v[48:49] op_sel_hi:[1,0]
	v_pk_mul_f32 v[18:19], v[18:19], v[48:49] op_sel_hi:[1,0]
	s_and_b64 vcc, exec, s[12:13]
	v_pk_mul_f32 v[16:17], v[16:17], v[48:49] op_sel_hi:[1,0]
	v_cvt_pk_bf16_f32 v44, v44, v45
	v_cvt_pk_bf16_f32 v45, v46, v47
	v_cvt_pk_bf16_f32 v46, v40, v41
	v_cvt_pk_bf16_f32 v47, v42, v43
	global_store_dwordx4 v[50:51], v[44:47], off
	v_cvt_pk_bf16_f32 v36, v36, v37
	v_cvt_pk_bf16_f32 v37, v38, v39
	v_cvt_pk_bf16_f32 v38, v32, v33
	v_cvt_pk_bf16_f32 v39, v34, v35
	global_store_dwordx4 v[50:51], v[36:39], off offset:64
	s_cbranch_vccnz .LBB0_729
	v_mov_b32_e32 v34, v29
	v_mov_b32_e32 v35, v21
	v_mov_b32_e32 v32, v28
	v_mov_b32_e32 v33, v20
	v_pk_mul_f32 v[34:35], v[34:35], v[34:35]
	v_mov_b32_e32 v36, v31
	v_mov_b32_e32 v37, v23
	v_pk_fma_f32 v[32:33], v[32:33], v[32:33], v[34:35]
	v_mov_b32_e32 v34, v30
	v_mov_b32_e32 v35, v22
	v_pk_mul_f32 v[36:37], v[36:37], v[36:37]
	v_mov_b32_e32 v38, v27
	v_pk_fma_f32 v[34:35], v[34:35], v[34:35], v[36:37]
	v_mov_b32_e32 v36, v25
	v_mov_b32_e32 v37, v17
	v_pk_add_f32 v[32:33], v[32:33], v[34:35]
	v_mov_b32_e32 v34, v24
	v_mov_b32_e32 v35, v16
	v_pk_mul_f32 v[36:37], v[36:37], v[36:37]
	v_mov_b32_e32 v39, v19
	v_pk_fma_f32 v[34:35], v[34:35], v[34:35], v[36:37]
	v_mov_b32_e32 v36, v26
	v_mov_b32_e32 v37, v18
	v_pk_mul_f32 v[38:39], v[38:39], v[38:39]
	s_nop 0
	v_pk_fma_f32 v[36:37], v[36:37], v[36:37], v[38:39]
	s_nop 0
	v_pk_add_f32 v[34:35], v[34:35], v[36:37]
	s_nop 0
	v_pk_add_f32 v[32:33], v[32:33], v[34:35]
	s_nop 0
	v_add_f32_e32 v32, v32, v33
	s_nop 0
	s_nop 0
	s_nop 1
	v_mov_b32_e32 v33, v32
	s_nop 1
	v_permlane16_swap_b32_e32 v33, v32
	s_waitcnt lgkmcnt(0)
	v_add_f32_e32 v32, v32, v33
	s_nop 0
	s_nop 0
	s_nop 1
	v_mov_b32_e32 v33, v32
	s_nop 1
	v_permlane32_swap_b32_e32 v33, v32
	s_waitcnt lgkmcnt(0)
	v_add_f32_e32 v32, v32, v33
	v_fmamk_f32 v32, v32, 0x3c800000, v184
	v_rsq_f32_e32 v32, v32
	s_nop 0
	v_pk_mul_f32 v[28:29], v[28:29], v[32:33] op_sel_hi:[1,0]
	v_pk_mul_f32 v[30:31], v[30:31], v[32:33] op_sel_hi:[1,0]
	v_pk_mul_f32 v[24:25], v[24:25], v[32:33] op_sel_hi:[1,0]
	v_pk_mul_f32 v[26:27], v[26:27], v[32:33] op_sel_hi:[1,0]
	v_pk_mul_f32 v[20:21], v[20:21], v[32:33] op_sel_hi:[1,0]
	v_pk_mul_f32 v[22:23], v[22:23], v[32:33] op_sel_hi:[1,0]
	v_pk_mul_f32 v[16:17], v[16:17], v[32:33] op_sel_hi:[1,0]
	v_pk_mul_f32 v[18:19], v[18:19], v[32:33] op_sel_hi:[1,0]
	v_pk_mul_f32 v[30:31], v[160:161], v[30:31]
	v_pk_mul_f32 v[28:29], v[162:163], v[28:29]
	v_pk_mul_f32 v[26:27], v[156:157], v[26:27]
	v_pk_mul_f32 v[24:25], v[158:159], v[24:25]
	v_pk_mul_f32 v[22:23], v[152:153], v[22:23]
	v_pk_mul_f32 v[20:21], v[154:155], v[20:21]
	v_pk_mul_f32 v[18:19], v[148:149], v[18:19]
	v_pk_mul_f32 v[16:17], v[150:151], v[16:17]
.LBB0_729:
	s_waitcnt lgkmcnt(0)
	v_add_f32_e32 v32, v147, v165
	v_fmamk_f32 v32, v32, 0x3a800000, v184
	v_rsq_f32_e32 v32, v32
	v_mov_b64_e32 v[34:35], s[22:23]
	v_mad_i64_i32 v[34:35], s[48:49], v164, s64, v[34:35]
	v_lshl_add_u64 v[34:35], v[112:113], 1, v[34:35]
	v_pk_mul_f32 v[14:15], v[14:15], v[32:33] op_sel_hi:[1,0]
	v_pk_mul_f32 v[12:13], v[12:13], v[32:33] op_sel_hi:[1,0]
	v_pk_mul_f32 v[10:11], v[10:11], v[32:33] op_sel_hi:[1,0]
	v_pk_mul_f32 v[8:9], v[8:9], v[32:33] op_sel_hi:[1,0]
	v_pk_mul_f32 v[6:7], v[6:7], v[32:33] op_sel_hi:[1,0]
	v_pk_mul_f32 v[4:5], v[4:5], v[32:33] op_sel_hi:[1,0]
	v_pk_mul_f32 v[2:3], v[2:3], v[32:33] op_sel_hi:[1,0]
	s_and_b64 vcc, exec, s[12:13]
	v_pk_mul_f32 v[0:1], v[0:1], v[32:33] op_sel_hi:[1,0]
	v_cvt_pk_bf16_f32 v28, v28, v29
	v_cvt_pk_bf16_f32 v29, v30, v31
	v_cvt_pk_bf16_f32 v30, v24, v25
	v_cvt_pk_bf16_f32 v31, v26, v27
	global_store_dwordx4 v[34:35], v[28:31], off
	v_cvt_pk_bf16_f32 v20, v20, v21
	v_cvt_pk_bf16_f32 v21, v22, v23
	v_cvt_pk_bf16_f32 v22, v16, v17
	v_cvt_pk_bf16_f32 v23, v18, v19
	global_store_dwordx4 v[34:35], v[20:23], off offset:64
	s_cbranch_vccnz .LBB0_731
	v_mov_b32_e32 v18, v13
	v_mov_b32_e32 v19, v5
	v_mov_b32_e32 v16, v12
	v_mov_b32_e32 v17, v4
	v_pk_mul_f32 v[18:19], v[18:19], v[18:19]
	v_mov_b32_e32 v20, v15
	v_mov_b32_e32 v21, v7
	v_pk_fma_f32 v[16:17], v[16:17], v[16:17], v[18:19]
	v_mov_b32_e32 v18, v14
	v_mov_b32_e32 v19, v6
	v_pk_mul_f32 v[20:21], v[20:21], v[20:21]
	v_mov_b32_e32 v22, v11
	v_pk_fma_f32 v[18:19], v[18:19], v[18:19], v[20:21]
	v_mov_b32_e32 v20, v9
	v_mov_b32_e32 v21, v1
	v_pk_add_f32 v[16:17], v[16:17], v[18:19]
	v_mov_b32_e32 v18, v8
	v_mov_b32_e32 v19, v0
	v_pk_mul_f32 v[20:21], v[20:21], v[20:21]
	v_mov_b32_e32 v23, v3
	v_pk_fma_f32 v[18:19], v[18:19], v[18:19], v[20:21]
	v_mov_b32_e32 v20, v10
	v_mov_b32_e32 v21, v2
	v_pk_mul_f32 v[22:23], v[22:23], v[22:23]
	s_nop 0
	v_pk_fma_f32 v[20:21], v[20:21], v[20:21], v[22:23]
	s_nop 0
	v_pk_add_f32 v[18:19], v[18:19], v[20:21]
	s_nop 0
	v_pk_add_f32 v[16:17], v[16:17], v[18:19]
	s_nop 0
	v_add_f32_e32 v16, v16, v17
	s_nop 0
	s_nop 0
	s_nop 1
	v_mov_b32_e32 v17, v16
	s_nop 1
	v_permlane16_swap_b32_e32 v17, v16
	s_waitcnt lgkmcnt(0)
	v_add_f32_e32 v16, v16, v17
	s_nop 0
	s_nop 0
	s_nop 1
	v_mov_b32_e32 v17, v16
	s_nop 1
	v_permlane32_swap_b32_e32 v17, v16
	s_waitcnt lgkmcnt(0)
	v_add_f32_e32 v16, v16, v17
	v_fmamk_f32 v16, v16, 0x3c800000, v184
	v_rsq_f32_e32 v16, v16
	s_nop 0
	v_pk_mul_f32 v[12:13], v[12:13], v[16:17] op_sel_hi:[1,0]
	v_pk_mul_f32 v[14:15], v[14:15], v[16:17] op_sel_hi:[1,0]
	v_pk_mul_f32 v[8:9], v[8:9], v[16:17] op_sel_hi:[1,0]
	v_pk_mul_f32 v[10:11], v[10:11], v[16:17] op_sel_hi:[1,0]
	v_pk_mul_f32 v[4:5], v[4:5], v[16:17] op_sel_hi:[1,0]
	v_pk_mul_f32 v[6:7], v[6:7], v[16:17] op_sel_hi:[1,0]
	v_pk_mul_f32 v[0:1], v[0:1], v[16:17] op_sel_hi:[1,0]
	v_pk_mul_f32 v[2:3], v[2:3], v[16:17] op_sel_hi:[1,0]
	v_pk_mul_f32 v[14:15], v[160:161], v[14:15]
	v_pk_mul_f32 v[12:13], v[162:163], v[12:13]
	v_pk_mul_f32 v[10:11], v[156:157], v[10:11]
	v_pk_mul_f32 v[8:9], v[158:159], v[8:9]
	v_pk_mul_f32 v[6:7], v[152:153], v[6:7]
	v_pk_mul_f32 v[4:5], v[154:155], v[4:5]
	v_pk_mul_f32 v[2:3], v[148:149], v[2:3]
	v_pk_mul_f32 v[0:1], v[150:151], v[0:1]

; __device__ __forceinline__ float sq4(f32x4 v) { return (v[0] * v[0] + v[1] * v[1]) + (v[2] * v[2] + v[3] * v[3]); }
; __device__ __forceinline__ u32x4 pack8(f32x4 a, f32x4 b) { u32x4 w; w.x = cvt_pk_bf16(a[0], a[1]); w.y = cvt_pk_bf16(a[2], a[3]); w.z = cvt_pk_bf16(b[0], b[1]); w.w = cvt_pk_bf16(b[2], b[3]); return w; }
;     __device__ __forceinline__ void operator()(const f32x4 (&acc)[2][2][4][2], const Unit& u, int wr, int wc, int fr, int fq) const {
;     ...
;         for (int ai = 0; ai < 2; ++ai) {
;             u32x4 bs[4][2];
; #pragma unroll
;             for (int m = 0; m < 4; ++m)
; #pragma unroll
;                 for (int bj = 0; bj < 2; ++bj) bs[m][bj] = *(const u32x4*)(xb + (size_t)(u.pm * BM + ai * HALF + wr * 64 + m * 16 + fr) * 1024 + col0 + 128 * bj);
; #pragma unroll
;             for (int m = 0; m < 4; ++m) {
;                 const int row = u.pm * BM + ai * HALF + wr * 64 + m * 16 + fr;
;                 float q = 0.f;
; #pragma unroll
;                 for (int bj = 0; bj < 2; ++bj) {
;                     const size_t off = (size_t)row * 1024 + col0 + 128 * bj; const u32x4 w = bs[m][bj];
;                     const f32x4 b0 = (f32x4){__builtin_bit_cast(float, w.x << 16), __builtin_bit_cast(float, w.x & 0xffff0000u), __builtin_bit_cast(float, w.y << 16), __builtin_bit_cast(float, w.y & 0xffff0000u)};
;                     const f32x4 b1 = (f32x4){__builtin_bit_cast(float, w.z << 16), __builtin_bit_cast(float, w.z & 0xffff0000u), __builtin_bit_cast(float, w.w << 16), __builtin_bit_cast(float, w.w & 0xffff0000u)};
;                     const f32x4 v0 = acc[ai][bj][m][0] + b0, v1 = acc[ai][bj][m][1] + b1;
;                     if (last) { __builtin_nontemporal_store(v0, (f32x4*)(out + off)); __builtin_nontemporal_store(v1, (f32x4*)(out + off + 4)); }
;                     else { q += sq4(v0) + sq4(v1); *(u32x4*)(xb + off) = pack8(v0, v1); }
;                 }
;                 if (!last) { q += shx(q, 16); q += shx(q, 32); if (fq == 0) ss[(size_t)row * 16 + u.pn * 4 + wc] = q; }
.LBB0_915:
	v_lshl_or_b32 v168, s18, 8, v188
	v_lshl_add_u32 v172, s54, 8, v186
	v_ashrrev_i32_e32 v169, 31, v168
	v_lshlrev_b64 v[202:203], 1, v[168:169]
	v_ashrrev_i32_e32 v173, 31, v172
	v_lshl_add_u64 v[170:171], s[22:23], 0, v[202:203]
	v_lshlrev_b64 v[204:205], 11, v[172:173]
	v_lshl_add_u64 v[120:121], v[170:171], 0, v[204:205]
	global_load_dwordx4 v[192:195], v[120:121], off
	global_load_dwordx4 v[196:199], v[120:121], off offset:256
	v_or_b32_e32 v182, 16, v172
	v_ashrrev_i32_e32 v183, 31, v182
	v_or_b32_e32 v178, 32, v172
	v_lshlrev_b64 v[184:185], 11, v[182:183]
	v_ashrrev_i32_e32 v179, 31, v178
	v_or_b32_e32 v174, 48, v172
	v_lshl_add_u64 v[120:121], v[170:171], 0, v[184:185]
	v_lshlrev_b64 v[180:181], 11, v[178:179]
	v_ashrrev_i32_e32 v175, 31, v174
	global_load_dwordx4 v[148:151], v[120:121], off
	global_load_dwordx4 v[144:147], v[120:121], off offset:256
	v_lshl_add_u64 v[120:121], v[170:171], 0, v[180:181]
	v_lshlrev_b64 v[176:177], 11, v[174:175]
	global_load_dwordx4 v[140:143], v[120:121], off
	global_load_dwordx4 v[136:139], v[120:121], off offset:256
	v_lshl_add_u64 v[120:121], v[170:171], 0, v[176:177]
	global_load_dwordx4 v[132:135], v[120:121], off
	s_nop 0
	global_load_dwordx4 v[120:123], v[120:121], off offset:256
	s_lshl_b32 s54, s18, 2
	s_ashr_i32 s55, s54, 31
	s_waitcnt vmcnt(0)
	v_lshlrev_b32_e32 v206, 16, v192
	v_and_b32_e32 v207, 0xffff0000, v192
	v_lshlrev_b32_e32 v192, 16, v193
	v_and_b32_e32 v193, 0xffff0000, v193
	v_lshlrev_b32_e32 v208, 16, v194
	v_and_b32_e32 v209, 0xffff0000, v194
	v_lshlrev_b32_e32 v194, 16, v195
	v_and_b32_e32 v195, 0xffff0000, v195
	v_pk_add_f32 v[130:131], v[130:131], v[192:193]
	v_pk_add_f32 v[128:129], v[128:129], v[206:207]
	v_pk_add_f32 v[192:193], v[126:127], v[194:195]
	v_pk_add_f32 v[126:127], v[124:125], v[208:209]
	v_mul_f32_e32 v124, v129, v129
	v_mul_f32_e32 v125, v131, v131
	v_fmac_f32_e32 v124, v128, v128
	v_fmac_f32_e32 v125, v130, v130
	v_add_f32_e32 v124, v124, v125
	v_mul_f32_e32 v125, v127, v127
	v_mul_f32_e32 v194, v193, v193
	v_fmac_f32_e32 v125, v126, v126
	v_fmac_f32_e32 v194, v192, v192
	v_add_f32_e32 v125, v125, v194
	v_add_f32_e32 v194, v124, v125
	v_cvt_pk_bf16_f32 v124, v128, v129
	v_lshl_add_u64 v[128:129], s[22:23], 0, v[204:205]
	v_cvt_pk_bf16_f32 v125, v130, v131
	v_cvt_pk_bf16_f32 v126, v126, v127
	v_cvt_pk_bf16_f32 v127, v192, v193
	v_lshl_add_u64 v[128:129], v[128:129], 0, v[202:203]
	global_store_dwordx4 v[128:129], v[124:127], off
	v_lshlrev_b32_e32 v130, 16, v198
	v_and_b32_e32 v131, 0xffff0000, v198
	v_lshlrev_b32_e32 v124, 16, v196
	v_and_b32_e32 v125, 0xffff0000, v196
	v_lshlrev_b32_e32 v126, 16, v197
	v_and_b32_e32 v127, 0xffff0000, v197
	v_lshlrev_b32_e32 v192, 16, v199
	v_and_b32_e32 v193, 0xffff0000, v199
	v_pk_add_f32 v[118:119], v[118:119], v[126:127]
	v_pk_add_f32 v[116:117], v[116:117], v[124:125]
	v_pk_add_f32 v[124:125], v[114:115], v[192:193]
	v_pk_add_f32 v[114:115], v[112:113], v[130:131]
	v_mul_f32_e32 v112, v117, v117
	v_mul_f32_e32 v113, v119, v119
	v_fmac_f32_e32 v112, v116, v116
	v_fmac_f32_e32 v113, v118, v118
	v_add_f32_e32 v112, v112, v113
	v_mul_f32_e32 v113, v115, v115
	v_mul_f32_e32 v126, v125, v125
	v_fmac_f32_e32 v113, v114, v114
	v_fmac_f32_e32 v126, v124, v124
	v_add_f32_e32 v113, v113, v126
	v_add_f32_e32 v112, v112, v113
	v_add_f32_e32 v126, v194, v112
	v_cvt_pk_bf16_f32 v112, v116, v117
	v_cvt_pk_bf16_f32 v113, v118, v119
	v_cvt_pk_bf16_f32 v114, v114, v115
	v_cvt_pk_bf16_f32 v115, v124, v125
	global_store_dwordx4 v[128:129], v[112:115], off offset:256
	s_nop 1
	s_nop 0
	s_nop 2
	v_mov_b32_e32 v112, v126
	s_nop 1
	v_permlane16_swap_b32_e32 v112, v126
	s_waitcnt lgkmcnt(0)
	v_add_f32_e32 v112, v126, v112
	s_nop 1
	v_mov_b32_e32 v113, v112
	s_nop 1
	v_permlane32_swap_b32_e32 v113, v112
	s_and_saveexec_b64 s[56:57], s[12:13]
	s_cbranch_execz .LBB0_917
	s_waitcnt lgkmcnt(0)
	v_add_f32_e32 v114, v112, v113
	v_lshlrev_b64 v[112:113], 6, v[172:173]
	v_lshl_add_u64 v[112:113], s[24:25], 0, v[112:113]
	v_lshl_add_u64 v[112:113], s[54:55], 2, v[112:113]
	s_lshl_b32 s18, s67, 2
	v_lshl_add_u64 v[112:113], v[112:113], 0, s[18:19]
	global_store_dword v[112:113], v114, off
.LBB0_917:
	s_or_b64 exec, exec, s[56:57]
	v_lshlrev_b32_e32 v112, 16, v148
	s_waitcnt lgkmcnt(0)
	v_and_b32_e32 v113, 0xffff0000, v148
	v_lshlrev_b32_e32 v114, 16, v149
	v_and_b32_e32 v115, 0xffff0000, v149
	v_lshlrev_b32_e32 v116, 16, v150
	v_and_b32_e32 v117, 0xffff0000, v150
	v_lshlrev_b32_e32 v118, 16, v151
	v_and_b32_e32 v119, 0xffff0000, v151
	v_pk_add_f32 v[110:111], v[110:111], v[114:115]
	v_pk_add_f32 v[108:109], v[108:109], v[112:113]
	v_pk_add_f32 v[112:113], v[106:107], v[118:119]
	v_pk_add_f32 v[106:107], v[104:105], v[116:117]
	v_mul_f32_e32 v104, v109, v109
	v_mul_f32_e32 v105, v111, v111
	v_fmac_f32_e32 v104, v108, v108
	v_fmac_f32_e32 v105, v110, v110
	v_add_f32_e32 v104, v104, v105
	v_mul_f32_e32 v105, v107, v107
	v_mul_f32_e32 v114, v113, v113
	v_fmac_f32_e32 v105, v106, v106
	v_fmac_f32_e32 v114, v112, v112
	v_add_f32_e32 v105, v105, v114
	v_add_f32_e32 v114, v104, v105
	v_cvt_pk_bf16_f32 v104, v108, v109
	v_lshl_add_u64 v[108:109], s[22:23], 0, v[184:185]
	v_cvt_pk_bf16_f32 v105, v110, v111
	v_cvt_pk_bf16_f32 v106, v106, v107
	v_cvt_pk_bf16_f32 v107, v112, v113
	v_lshl_add_u64 v[108:109], v[168:169], 1, v[108:109]
	global_store_dwordx4 v[108:109], v[104:107], off
	v_lshlrev_b32_e32 v110, 16, v146
	v_and_b32_e32 v111, 0xffff0000, v146
	v_lshlrev_b32_e32 v104, 16, v144
	v_and_b32_e32 v105, 0xffff0000, v144
	v_lshlrev_b32_e32 v106, 16, v145
	v_and_b32_e32 v107, 0xffff0000, v145
	v_lshlrev_b32_e32 v112, 16, v147
	v_and_b32_e32 v113, 0xffff0000, v147
	v_pk_add_f32 v[102:103], v[102:103], v[106:107]
	v_pk_add_f32 v[100:101], v[100:101], v[104:105]
	v_pk_add_f32 v[104:105], v[98:99], v[112:113]
	v_pk_add_f32 v[98:99], v[96:97], v[110:111]
	v_mul_f32_e32 v96, v101, v101
	v_mul_f32_e32 v97, v103, v103
	v_fmac_f32_e32 v96, v100, v100
	v_fmac_f32_e32 v97, v102, v102
	v_add_f32_e32 v96, v96, v97
	v_mul_f32_e32 v97, v99, v99
	v_mul_f32_e32 v106, v105, v105
	v_fmac_f32_e32 v97, v98, v98
	v_fmac_f32_e32 v106, v104, v104
	v_add_f32_e32 v97, v97, v106
	v_add_f32_e32 v96, v96, v97
	v_add_f32_e32 v106, v114, v96
	v_cvt_pk_bf16_f32 v96, v100, v101
	v_cvt_pk_bf16_f32 v97, v102, v103
	v_cvt_pk_bf16_f32 v98, v98, v99
	v_cvt_pk_bf16_f32 v99, v104, v105
	global_store_dwordx4 v[108:109], v[96:99], off offset:256
	s_nop 1
	s_nop 0
	s_nop 2
	v_mov_b32_e32 v96, v106
	s_nop 1
	v_permlane16_swap_b32_e32 v96, v106
	s_waitcnt lgkmcnt(0)
	v_add_f32_e32 v96, v106, v96
	s_nop 1
	v_mov_b32_e32 v97, v96
	s_nop 1
	v_permlane32_swap_b32_e32 v97, v96
	s_and_saveexec_b64 s[56:57], s[12:13]
	s_cbranch_execz .LBB0_919
	s_waitcnt lgkmcnt(0)
	v_add_f32_e32 v98, v96, v97
	v_lshlrev_b64 v[96:97], 6, v[182:183]
	v_lshl_add_u64 v[96:97], s[24:25], 0, v[96:97]
	v_lshl_add_u64 v[96:97], s[54:55], 2, v[96:97]
	s_lshl_b32 s18, s67, 2
	v_lshl_add_u64 v[96:97], v[96:97], 0, s[18:19]
	global_store_dword v[96:97], v98, off
; __device__ __forceinline__ float sq4(f32x4 v) { return (v[0] * v[0] + v[1] * v[1]) + (v[2] * v[2] + v[3] * v[3]); }
; __device__ __forceinline__ u32x4 pack8(f32x4 a, f32x4 b) { u32x4 w; w.x = cvt_pk_bf16(a[0], a[1]); w.y = cvt_pk_bf16(a[2], a[3]); w.z = cvt_pk_bf16(b[0], b[1]); w.w = cvt_pk_bf16(b[2], b[3]); return w; }
;     __device__ __forceinline__ void operator()(const f32x4 (&acc)[2][2][4][2], const Unit& u, int wr, int wc, int fr, int fq) const {
;     ...
;             for (int m = 0; m < 4; ++m) {
;                 const int row = u.pm * BM + ai * HALF + wr * 64 + m * 16 + fr;
;                 float q = 0.f;
; #pragma unroll
;                 for (int bj = 0; bj < 2; ++bj) {
;                     const size_t off = (size_t)row * 1024 + col0 + 128 * bj; const u32x4 w = bs[m][bj];
;                     const f32x4 b0 = (f32x4){__builtin_bit_cast(float, w.x << 16), __builtin_bit_cast(float, w.x & 0xffff0000u), __builtin_bit_cast(float, w.y << 16), __builtin_bit_cast(float, w.y & 0xffff0000u)};
;                     const f32x4 b1 = (f32x4){__builtin_bit_cast(float, w.z << 16), __builtin_bit_cast(float, w.z & 0xffff0000u), __builtin_bit_cast(float, w.w << 16), __builtin_bit_cast(float, w.w & 0xffff0000u)};
;                     const f32x4 v0 = acc[ai][bj][m][0] + b0, v1 = acc[ai][bj][m][1] + b1;
;                     if (last) { __builtin_nontemporal_store(v0, (f32x4*)(out + off)); __builtin_nontemporal_store(v1, (f32x4*)(out + off + 4)); }
;                     else { q += sq4(v0) + sq4(v1); *(u32x4*)(xb + off) = pack8(v0, v1); }
;                 }
;                 if (!last) { q += shx(q, 16); q += shx(q, 32); if (fq == 0) ss[(size_t)row * 16 + u.pn * 4 + wc] = q; }
.LBB0_919:
	s_or_b64 exec, exec, s[56:57]
	v_lshlrev_b32_e32 v96, 16, v140
	s_waitcnt lgkmcnt(0)
	v_and_b32_e32 v97, 0xffff0000, v140
	v_lshlrev_b32_e32 v98, 16, v141
	v_and_b32_e32 v99, 0xffff0000, v141
	v_lshlrev_b32_e32 v100, 16, v142
	v_and_b32_e32 v101, 0xffff0000, v142
	v_lshlrev_b32_e32 v102, 16, v143
	v_and_b32_e32 v103, 0xffff0000, v143
	v_pk_add_f32 v[94:95], v[94:95], v[98:99]
	v_pk_add_f32 v[92:93], v[92:93], v[96:97]
	v_pk_add_f32 v[96:97], v[90:91], v[102:103]
	v_pk_add_f32 v[90:91], v[88:89], v[100:101]
	v_mul_f32_e32 v88, v93, v93
	v_mul_f32_e32 v89, v95, v95
	v_fmac_f32_e32 v88, v92, v92
	v_fmac_f32_e32 v89, v94, v94
	v_add_f32_e32 v88, v88, v89
	v_mul_f32_e32 v89, v91, v91
	v_mul_f32_e32 v98, v97, v97
	v_fmac_f32_e32 v89, v90, v90
	v_fmac_f32_e32 v98, v96, v96
	v_add_f32_e32 v89, v89, v98
	v_add_f32_e32 v98, v88, v89
	v_cvt_pk_bf16_f32 v88, v92, v93
	v_lshl_add_u64 v[92:93], s[22:23], 0, v[180:181]
	v_cvt_pk_bf16_f32 v89, v94, v95
	v_cvt_pk_bf16_f32 v90, v90, v91
	v_cvt_pk_bf16_f32 v91, v96, v97
	v_lshl_add_u64 v[92:93], v[168:169], 1, v[92:93]
	global_store_dwordx4 v[92:93], v[88:91], off
	v_lshlrev_b32_e32 v94, 16, v138
	v_and_b32_e32 v95, 0xffff0000, v138
	v_lshlrev_b32_e32 v88, 16, v136
	v_and_b32_e32 v89, 0xffff0000, v136
	v_lshlrev_b32_e32 v90, 16, v137
	v_and_b32_e32 v91, 0xffff0000, v137
	v_lshlrev_b32_e32 v96, 16, v139
	v_and_b32_e32 v97, 0xffff0000, v139
	v_pk_add_f32 v[86:87], v[86:87], v[90:91]
	v_pk_add_f32 v[84:85], v[84:85], v[88:89]
	v_pk_add_f32 v[88:89], v[82:83], v[96:97]
	v_pk_add_f32 v[82:83], v[80:81], v[94:95]
	v_mul_f32_e32 v80, v85, v85
	v_mul_f32_e32 v81, v87, v87
	v_fmac_f32_e32 v80, v84, v84
	v_fmac_f32_e32 v81, v86, v86
	v_add_f32_e32 v80, v80, v81
	v_mul_f32_e32 v81, v83, v83
	v_mul_f32_e32 v90, v89, v89
	v_fmac_f32_e32 v81, v82, v82
	v_fmac_f32_e32 v90, v88, v88
	v_add_f32_e32 v81, v81, v90
	v_add_f32_e32 v80, v80, v81
	v_add_f32_e32 v90, v98, v80
	v_cvt_pk_bf16_f32 v80, v84, v85
	v_cvt_pk_bf16_f32 v81, v86, v87
	v_cvt_pk_bf16_f32 v82, v82, v83
	v_cvt_pk_bf16_f32 v83, v88, v89
	global_store_dwordx4 v[92:93], v[80:83], off offset:256
	s_nop 1
	s_nop 0
	s_nop 2
	v_mov_b32_e32 v80, v90
	s_nop 1
	v_permlane16_swap_b32_e32 v80, v90
	s_waitcnt lgkmcnt(0)
	v_add_f32_e32 v80, v90, v80
	s_nop 1
	v_mov_b32_e32 v81, v80
	s_nop 1
	v_permlane32_swap_b32_e32 v81, v80
	s_and_saveexec_b64 s[56:57], s[12:13]
	s_cbranch_execz .LBB0_921
	s_waitcnt lgkmcnt(0)
	v_add_f32_e32 v82, v80, v81
	v_lshlrev_b64 v[80:81], 6, v[178:179]
	v_lshl_add_u64 v[80:81], s[24:25], 0, v[80:81]
	v_lshl_add_u64 v[80:81], s[54:55], 2, v[80:81]
	s_lshl_b32 s18, s67, 2
	v_lshl_add_u64 v[80:81], v[80:81], 0, s[18:19]
	global_store_dword v[80:81], v82, off
.LBB0_921:
	s_or_b64 exec, exec, s[56:57]
	v_lshlrev_b32_e32 v80, 16, v132
	s_waitcnt lgkmcnt(0)
	v_and_b32_e32 v81, 0xffff0000, v132
	v_lshlrev_b32_e32 v82, 16, v133
	v_and_b32_e32 v83, 0xffff0000, v133
	v_lshlrev_b32_e32 v84, 16, v134
	v_and_b32_e32 v85, 0xffff0000, v134
	v_lshlrev_b32_e32 v86, 16, v135
	v_and_b32_e32 v87, 0xffff0000, v135
	v_pk_add_f32 v[78:79], v[78:79], v[82:83]
	v_pk_add_f32 v[76:77], v[76:77], v[80:81]
	v_pk_add_f32 v[80:81], v[74:75], v[86:87]
	v_pk_add_f32 v[74:75], v[72:73], v[84:85]
	v_mul_f32_e32 v72, v77, v77
	v_mul_f32_e32 v73, v79, v79
	v_fmac_f32_e32 v72, v76, v76
	v_fmac_f32_e32 v73, v78, v78
	v_add_f32_e32 v72, v72, v73
	v_mul_f32_e32 v73, v75, v75
	v_mul_f32_e32 v82, v81, v81
	v_fmac_f32_e32 v73, v74, v74
	v_fmac_f32_e32 v82, v80, v80
	v_add_f32_e32 v73, v73, v82
	v_add_f32_e32 v82, v72, v73
	v_cvt_pk_bf16_f32 v72, v76, v77
	v_lshl_add_u64 v[76:77], s[22:23], 0, v[176:177]
	v_cvt_pk_bf16_f32 v73, v78, v79
	v_cvt_pk_bf16_f32 v74, v74, v75
	v_cvt_pk_bf16_f32 v75, v80, v81
	v_lshl_add_u64 v[76:77], v[168:169], 1, v[76:77]
	global_store_dwordx4 v[76:77], v[72:75], off
	v_lshlrev_b32_e32 v78, 16, v122
	v_and_b32_e32 v79, 0xffff0000, v122
	v_lshlrev_b32_e32 v72, 16, v120
	v_and_b32_e32 v73, 0xffff0000, v120
	v_lshlrev_b32_e32 v74, 16, v121
	v_and_b32_e32 v75, 0xffff0000, v121
	v_lshlrev_b32_e32 v80, 16, v123
	v_and_b32_e32 v81, 0xffff0000, v123
	v_pk_add_f32 v[70:71], v[70:71], v[74:75]
	v_pk_add_f32 v[68:69], v[68:69], v[72:73]
	v_pk_add_f32 v[72:73], v[66:67], v[80:81]
	v_pk_add_f32 v[66:67], v[64:65], v[78:79]
	v_mul_f32_e32 v64, v69, v69
	v_mul_f32_e32 v65, v71, v71
	v_fmac_f32_e32 v64, v68, v68
	v_fmac_f32_e32 v65, v70, v70
	v_add_f32_e32 v64, v64, v65
	v_mul_f32_e32 v65, v67, v67
	v_mul_f32_e32 v74, v73, v73
	v_fmac_f32_e32 v65, v66, v66
	v_fmac_f32_e32 v74, v72, v72
	v_add_f32_e32 v65, v65, v74
	v_add_f32_e32 v64, v64, v65
	v_add_f32_e32 v74, v82, v64
	v_cvt_pk_bf16_f32 v64, v68, v69
	v_cvt_pk_bf16_f32 v65, v70, v71
	v_cvt_pk_bf16_f32 v66, v66, v67
	v_cvt_pk_bf16_f32 v67, v72, v73
	global_store_dwordx4 v[76:77], v[64:67], off offset:256
	s_nop 1
	s_nop 0
	s_nop 2
	v_mov_b32_e32 v64, v74
	s_nop 1
	v_permlane16_swap_b32_e32 v64, v74
	s_waitcnt lgkmcnt(0)
	v_add_f32_e32 v64, v74, v64
	s_nop 1
	v_mov_b32_e32 v65, v64
	s_nop 1
	v_permlane32_swap_b32_e32 v65, v64
	s_and_saveexec_b64 s[56:57], s[12:13]
	s_cbranch_execz .LBB0_923
	s_waitcnt lgkmcnt(0)
	v_add_f32_e32 v66, v64, v65
	v_lshlrev_b64 v[64:65], 6, v[174:175]
	v_lshl_add_u64 v[64:65], s[24:25], 0, v[64:65]
	v_lshl_add_u64 v[64:65], s[54:55], 2, v[64:65]
	s_lshl_b32 s18, s67, 2
	v_lshl_add_u64 v[64:65], v[64:65], 0, s[18:19]
	global_store_dword v[64:65], v66, off
; __device__ __forceinline__ float sq4(f32x4 v) { return (v[0] * v[0] + v[1] * v[1]) + (v[2] * v[2] + v[3] * v[3]); }
; __device__ __forceinline__ u32x4 pack8(f32x4 a, f32x4 b) { u32x4 w; w.x = cvt_pk_bf16(a[0], a[1]); w.y = cvt_pk_bf16(a[2], a[3]); w.z = cvt_pk_bf16(b[0], b[1]); w.w = cvt_pk_bf16(b[2], b[3]); return w; }
;     __device__ __forceinline__ void operator()(const f32x4 (&acc)[2][2][4][2], const Unit& u, int wr, int wc, int fr, int fq) const {
;     ...
;         for (int ai = 0; ai < 2; ++ai) {
;             u32x4 bs[4][2];
; #pragma unroll
;             for (int m = 0; m < 4; ++m)
; #pragma unroll
;                 for (int bj = 0; bj < 2; ++bj) bs[m][bj] = *(const u32x4*)(xb + (size_t)(u.pm * BM + ai * HALF + wr * 64 + m * 16 + fr) * 1024 + col0 + 128 * bj);
; #pragma unroll
;             for (int m = 0; m < 4; ++m) {
;                 const int row = u.pm * BM + ai * HALF + wr * 64 + m * 16 + fr;
;                 float q = 0.f;
; #pragma unroll
;                 for (int bj = 0; bj < 2; ++bj) {
;                     const size_t off = (size_t)row * 1024 + col0 + 128 * bj; const u32x4 w = bs[m][bj];
;                     const f32x4 b0 = (f32x4){__builtin_bit_cast(float, w.x << 16), __builtin_bit_cast(float, w.x & 0xffff0000u), __builtin_bit_cast(float, w.y << 16), __builtin_bit_cast(float, w.y & 0xffff0000u)};
;                     const f32x4 b1 = (f32x4){__builtin_bit_cast(float, w.z << 16), __builtin_bit_cast(float, w.z & 0xffff0000u), __builtin_bit_cast(float, w.w << 16), __builtin_bit_cast(float, w.w & 0xffff0000u)};
;                     const f32x4 v0 = acc[ai][bj][m][0] + b0, v1 = acc[ai][bj][m][1] + b1;
;                     if (last) { __builtin_nontemporal_store(v0, (f32x4*)(out + off)); __builtin_nontemporal_store(v1, (f32x4*)(out + off + 4)); }
;                     else { q += sq4(v0) + sq4(v1); *(u32x4*)(xb + off) = pack8(v0, v1); }
;                 }
;                 if (!last) { q += shx(q, 16); q += shx(q, 32); if (fq == 0) ss[(size_t)row * 16 + u.pn * 4 + wc] = q; }
.LBB0_923:
	s_or_b64 exec, exec, s[56:57]
	v_add_u32_e32 v100, 0x80, v172
	v_ashrrev_i32_e32 v101, 31, v100
	v_lshlrev_b64 v[110:111], 11, v[100:101]
	s_waitcnt lgkmcnt(0)
	v_lshl_add_u64 v[64:65], v[170:171], 0, v[110:111]
	global_load_dwordx4 v[102:105], v[64:65], off
	global_load_dwordx4 v[106:109], v[64:65], off offset:256
	v_add_u32_e32 v96, 0x90, v172
	v_ashrrev_i32_e32 v97, 31, v96
	v_add_u32_e32 v92, 0xa0, v172
	v_lshlrev_b64 v[98:99], 11, v[96:97]
	v_ashrrev_i32_e32 v93, 31, v92
	v_add_u32_e32 v88, 0xb0, v172
	v_lshl_add_u64 v[64:65], v[170:171], 0, v[98:99]
	v_lshlrev_b64 v[94:95], 11, v[92:93]
	v_ashrrev_i32_e32 v89, 31, v88
	global_load_dwordx4 v[84:87], v[64:65], off
	global_load_dwordx4 v[80:83], v[64:65], off offset:256
	v_lshl_add_u64 v[64:65], v[170:171], 0, v[94:95]
	v_lshlrev_b64 v[90:91], 11, v[88:89]
	global_load_dwordx4 v[76:79], v[64:65], off
	global_load_dwordx4 v[72:75], v[64:65], off offset:256
	v_lshl_add_u64 v[64:65], v[170:171], 0, v[90:91]
	global_load_dwordx4 v[68:71], v[64:65], off
	s_nop 0
	global_load_dwordx4 v[64:67], v[64:65], off offset:256
	s_waitcnt vmcnt(7)
	v_lshlrev_b32_e32 v112, 16, v102
	v_and_b32_e32 v113, 0xffff0000, v102
	v_lshlrev_b32_e32 v102, 16, v103
	v_and_b32_e32 v103, 0xffff0000, v103
	v_lshlrev_b32_e32 v114, 16, v104
	v_and_b32_e32 v115, 0xffff0000, v104
	v_lshlrev_b32_e32 v104, 16, v105
	v_and_b32_e32 v105, 0xffff0000, v105
	v_pk_add_f32 v[62:63], v[62:63], v[102:103]
	v_pk_add_f32 v[60:61], v[60:61], v[112:113]
	v_pk_add_f32 v[102:103], v[58:59], v[104:105]
	v_pk_add_f32 v[58:59], v[56:57], v[114:115]
	v_mul_f32_e32 v56, v61, v61
	v_mul_f32_e32 v57, v63, v63
	v_fmac_f32_e32 v56, v60, v60
	v_fmac_f32_e32 v57, v62, v62
	v_add_f32_e32 v56, v56, v57
	v_mul_f32_e32 v57, v59, v59
	v_mul_f32_e32 v104, v103, v103
	v_fmac_f32_e32 v57, v58, v58
	v_fmac_f32_e32 v104, v102, v102
	v_add_f32_e32 v57, v57, v104
	v_add_f32_e32 v104, v56, v57
	v_cvt_pk_bf16_f32 v56, v60, v61
	v_lshl_add_u64 v[60:61], s[22:23], 0, v[110:111]
	v_cvt_pk_bf16_f32 v57, v62, v63
	v_cvt_pk_bf16_f32 v58, v58, v59
	v_cvt_pk_bf16_f32 v59, v102, v103
	v_lshl_add_u64 v[60:61], v[168:169], 1, v[60:61]
	global_store_dwordx4 v[60:61], v[56:59], off
	s_waitcnt vmcnt(7)
	v_lshlrev_b32_e32 v62, 16, v108
	v_and_b32_e32 v63, 0xffff0000, v108
	v_lshlrev_b32_e32 v56, 16, v106
	v_and_b32_e32 v57, 0xffff0000, v106
	v_lshlrev_b32_e32 v58, 16, v107
	v_and_b32_e32 v59, 0xffff0000, v107
	v_lshlrev_b32_e32 v102, 16, v109
	v_and_b32_e32 v103, 0xffff0000, v109
	v_pk_add_f32 v[54:55], v[54:55], v[58:59]
	v_pk_add_f32 v[52:53], v[52:53], v[56:57]
	v_pk_add_f32 v[56:57], v[50:51], v[102:103]
	v_pk_add_f32 v[50:51], v[48:49], v[62:63]
	v_mul_f32_e32 v48, v53, v53
	v_mul_f32_e32 v49, v55, v55
	v_fmac_f32_e32 v48, v52, v52
	v_fmac_f32_e32 v49, v54, v54
	v_add_f32_e32 v48, v48, v49
	v_mul_f32_e32 v49, v51, v51
	v_mul_f32_e32 v58, v57, v57
	v_fmac_f32_e32 v49, v50, v50
	v_fmac_f32_e32 v58, v56, v56
	v_add_f32_e32 v49, v49, v58
	v_add_f32_e32 v48, v48, v49
	v_add_f32_e32 v58, v104, v48
	v_cvt_pk_bf16_f32 v48, v52, v53
	v_cvt_pk_bf16_f32 v49, v54, v55
	v_cvt_pk_bf16_f32 v50, v50, v51
	v_cvt_pk_bf16_f32 v51, v56, v57
	global_store_dwordx4 v[60:61], v[48:51], off offset:256
	s_nop 1
	s_nop 0
	s_nop 2
	v_mov_b32_e32 v48, v58
	s_nop 1
	v_permlane16_swap_b32_e32 v48, v58
	s_waitcnt lgkmcnt(0)
	v_add_f32_e32 v48, v58, v48
	s_nop 1
	v_mov_b32_e32 v49, v48
	s_nop 1
	v_permlane32_swap_b32_e32 v49, v48
	s_and_saveexec_b64 s[56:57], s[12:13]
	s_cbranch_execz .LBB0_925
	s_waitcnt lgkmcnt(0)
	v_add_f32_e32 v50, v48, v49
	v_lshlrev_b64 v[48:49], 6, v[100:101]
	v_lshl_add_u64 v[48:49], s[24:25], 0, v[48:49]
	v_lshl_add_u64 v[48:49], s[54:55], 2, v[48:49]
	s_lshl_b32 s18, s67, 2
	v_lshl_add_u64 v[48:49], v[48:49], 0, s[18:19]
	global_store_dword v[48:49], v50, off
.LBB0_925:
	s_or_b64 exec, exec, s[56:57]
	s_waitcnt vmcnt(7)
	v_lshlrev_b32_e32 v48, 16, v84
	s_waitcnt lgkmcnt(0)
	v_and_b32_e32 v49, 0xffff0000, v84
	v_lshlrev_b32_e32 v50, 16, v85
	v_and_b32_e32 v51, 0xffff0000, v85
	v_lshlrev_b32_e32 v52, 16, v86
	v_and_b32_e32 v53, 0xffff0000, v86
	v_lshlrev_b32_e32 v54, 16, v87
	v_and_b32_e32 v55, 0xffff0000, v87
	v_pk_add_f32 v[46:47], v[46:47], v[50:51]
	v_pk_add_f32 v[44:45], v[44:45], v[48:49]
	v_pk_add_f32 v[48:49], v[42:43], v[54:55]
	v_pk_add_f32 v[42:43], v[40:41], v[52:53]
	v_mul_f32_e32 v40, v45, v45
	v_mul_f32_e32 v41, v47, v47
	v_fmac_f32_e32 v40, v44, v44
	v_fmac_f32_e32 v41, v46, v46
	v_add_f32_e32 v40, v40, v41
	v_mul_f32_e32 v41, v43, v43
	v_mul_f32_e32 v50, v49, v49
	v_fmac_f32_e32 v41, v42, v42
	v_fmac_f32_e32 v50, v48, v48
	v_add_f32_e32 v41, v41, v50
	v_add_f32_e32 v50, v40, v41
	v_cvt_pk_bf16_f32 v40, v44, v45
	v_lshl_add_u64 v[44:45], s[22:23], 0, v[98:99]
	v_cvt_pk_bf16_f32 v41, v46, v47
	v_cvt_pk_bf16_f32 v42, v42, v43
	v_cvt_pk_bf16_f32 v43, v48, v49
	v_lshl_add_u64 v[44:45], v[168:169], 1, v[44:45]
	global_store_dwordx4 v[44:45], v[40:43], off
	s_waitcnt vmcnt(7)
	v_lshlrev_b32_e32 v46, 16, v82
	v_and_b32_e32 v47, 0xffff0000, v82
	v_lshlrev_b32_e32 v40, 16, v80
	v_and_b32_e32 v41, 0xffff0000, v80
	v_lshlrev_b32_e32 v42, 16, v81
	v_and_b32_e32 v43, 0xffff0000, v81
	v_lshlrev_b32_e32 v48, 16, v83
	v_and_b32_e32 v49, 0xffff0000, v83
	v_pk_add_f32 v[38:39], v[38:39], v[42:43]
	v_pk_add_f32 v[36:37], v[36:37], v[40:41]
	v_pk_add_f32 v[40:41], v[34:35], v[48:49]
	v_pk_add_f32 v[34:35], v[32:33], v[46:47]
	v_mul_f32_e32 v32, v37, v37
	v_mul_f32_e32 v33, v39, v39
	v_fmac_f32_e32 v32, v36, v36
	v_fmac_f32_e32 v33, v38, v38
	v_add_f32_e32 v32, v32, v33
	v_mul_f32_e32 v33, v35, v35
	v_mul_f32_e32 v42, v41, v41
	v_fmac_f32_e32 v33, v34, v34
	v_fmac_f32_e32 v42, v40, v40
	v_add_f32_e32 v33, v33, v42
	v_add_f32_e32 v32, v32, v33
	v_add_f32_e32 v42, v50, v32
	v_cvt_pk_bf16_f32 v32, v36, v37
	v_cvt_pk_bf16_f32 v33, v38, v39
	v_cvt_pk_bf16_f32 v34, v34, v35
	v_cvt_pk_bf16_f32 v35, v40, v41
	global_store_dwordx4 v[44:45], v[32:35], off offset:256
	s_nop 1
	s_nop 0
	s_nop 2
	v_mov_b32_e32 v32, v42
	s_nop 1
	v_permlane16_swap_b32_e32 v32, v42
	s_waitcnt lgkmcnt(0)
	v_add_f32_e32 v32, v42, v32
	s_nop 1
	v_mov_b32_e32 v33, v32
	s_nop 1
	v_permlane32_swap_b32_e32 v33, v32
	s_and_saveexec_b64 s[56:57], s[12:13]
	s_cbranch_execz .LBB0_927
	s_waitcnt lgkmcnt(0)
	v_add_f32_e32 v34, v32, v33
	v_lshlrev_b64 v[32:33], 6, v[96:97]
	v_lshl_add_u64 v[32:33], s[24:25], 0, v[32:33]
	v_lshl_add_u64 v[32:33], s[54:55], 2, v[32:33]
	s_lshl_b32 s18, s67, 2
	v_lshl_add_u64 v[32:33], v[32:33], 0, s[18:19]
	global_store_dword v[32:33], v34, off
; __device__ __forceinline__ float sq4(f32x4 v) { return (v[0] * v[0] + v[1] * v[1]) + (v[2] * v[2] + v[3] * v[3]); }
; __device__ __forceinline__ u32x4 pack8(f32x4 a, f32x4 b) { u32x4 w; w.x = cvt_pk_bf16(a[0], a[1]); w.y = cvt_pk_bf16(a[2], a[3]); w.z = cvt_pk_bf16(b[0], b[1]); w.w = cvt_pk_bf16(b[2], b[3]); return w; }
;     __device__ __forceinline__ void operator()(const f32x4 (&acc)[2][2][4][2], const Unit& u, int wr, int wc, int fr, int fq) const {
;     ...
;             for (int m = 0; m < 4; ++m) {
;                 const int row = u.pm * BM + ai * HALF + wr * 64 + m * 16 + fr;
;                 float q = 0.f;
; #pragma unroll
;                 for (int bj = 0; bj < 2; ++bj) {
;                     const size_t off = (size_t)row * 1024 + col0 + 128 * bj; const u32x4 w = bs[m][bj];
;                     const f32x4 b0 = (f32x4){__builtin_bit_cast(float, w.x << 16), __builtin_bit_cast(float, w.x & 0xffff0000u), __builtin_bit_cast(float, w.y << 16), __builtin_bit_cast(float, w.y & 0xffff0000u)};
;                     const f32x4 b1 = (f32x4){__builtin_bit_cast(float, w.z << 16), __builtin_bit_cast(float, w.z & 0xffff0000u), __builtin_bit_cast(float, w.w << 16), __builtin_bit_cast(float, w.w & 0xffff0000u)};
;                     const f32x4 v0 = acc[ai][bj][m][0] + b0, v1 = acc[ai][bj][m][1] + b1;
;                     if (last) { __builtin_nontemporal_store(v0, (f32x4*)(out + off)); __builtin_nontemporal_store(v1, (f32x4*)(out + off + 4)); }
;                     else { q += sq4(v0) + sq4(v1); *(u32x4*)(xb + off) = pack8(v0, v1); }
;                 }
;                 if (!last) { q += shx(q, 16); q += shx(q, 32); if (fq == 0) ss[(size_t)row * 16 + u.pn * 4 + wc] = q; }
.LBB0_927:
	s_or_b64 exec, exec, s[56:57]
	s_waitcnt vmcnt(7)
	v_lshlrev_b32_e32 v32, 16, v76
	s_waitcnt lgkmcnt(0)
	v_and_b32_e32 v33, 0xffff0000, v76
	v_lshlrev_b32_e32 v34, 16, v77
	v_and_b32_e32 v35, 0xffff0000, v77
	v_lshlrev_b32_e32 v36, 16, v78
	v_and_b32_e32 v37, 0xffff0000, v78
	v_lshlrev_b32_e32 v38, 16, v79
	v_and_b32_e32 v39, 0xffff0000, v79
	v_pk_add_f32 v[30:31], v[30:31], v[34:35]
	v_pk_add_f32 v[28:29], v[28:29], v[32:33]
	v_pk_add_f32 v[32:33], v[26:27], v[38:39]
	v_pk_add_f32 v[26:27], v[24:25], v[36:37]
	v_mul_f32_e32 v24, v29, v29
	v_mul_f32_e32 v25, v31, v31
	v_fmac_f32_e32 v24, v28, v28
	v_fmac_f32_e32 v25, v30, v30
	v_add_f32_e32 v24, v24, v25
	v_mul_f32_e32 v25, v27, v27
	v_mul_f32_e32 v34, v33, v33
	v_fmac_f32_e32 v25, v26, v26
	v_fmac_f32_e32 v34, v32, v32
	v_add_f32_e32 v25, v25, v34
	v_add_f32_e32 v34, v24, v25
	v_cvt_pk_bf16_f32 v24, v28, v29
	v_lshl_add_u64 v[28:29], s[22:23], 0, v[94:95]
	v_cvt_pk_bf16_f32 v25, v30, v31
	v_cvt_pk_bf16_f32 v26, v26, v27
	v_cvt_pk_bf16_f32 v27, v32, v33
	v_lshl_add_u64 v[28:29], v[168:169], 1, v[28:29]
	global_store_dwordx4 v[28:29], v[24:27], off
	s_waitcnt vmcnt(7)
	v_lshlrev_b32_e32 v30, 16, v74
	v_and_b32_e32 v31, 0xffff0000, v74
	v_lshlrev_b32_e32 v24, 16, v72
	v_and_b32_e32 v25, 0xffff0000, v72
	v_lshlrev_b32_e32 v26, 16, v73
	v_and_b32_e32 v27, 0xffff0000, v73
	v_lshlrev_b32_e32 v32, 16, v75
	v_and_b32_e32 v33, 0xffff0000, v75
	v_pk_add_f32 v[22:23], v[22:23], v[26:27]
	v_pk_add_f32 v[20:21], v[20:21], v[24:25]
	v_pk_add_f32 v[24:25], v[18:19], v[32:33]
	v_pk_add_f32 v[18:19], v[16:17], v[30:31]
	v_mul_f32_e32 v16, v21, v21
	v_mul_f32_e32 v17, v23, v23
	v_fmac_f32_e32 v16, v20, v20
	v_fmac_f32_e32 v17, v22, v22
	v_add_f32_e32 v16, v16, v17
	v_mul_f32_e32 v17, v19, v19
	v_mul_f32_e32 v26, v25, v25
	v_fmac_f32_e32 v17, v18, v18
	v_fmac_f32_e32 v26, v24, v24
	v_add_f32_e32 v17, v17, v26
	v_add_f32_e32 v16, v16, v17
	v_add_f32_e32 v26, v34, v16
	v_cvt_pk_bf16_f32 v16, v20, v21
	v_cvt_pk_bf16_f32 v17, v22, v23
	v_cvt_pk_bf16_f32 v18, v18, v19
	v_cvt_pk_bf16_f32 v19, v24, v25
	global_store_dwordx4 v[28:29], v[16:19], off offset:256
	s_nop 1
	s_nop 0
	s_nop 2
	v_mov_b32_e32 v16, v26
	s_nop 1
	v_permlane16_swap_b32_e32 v16, v26
	s_waitcnt lgkmcnt(0)
	v_add_f32_e32 v16, v26, v16
	s_nop 1
	v_mov_b32_e32 v17, v16
	s_nop 1
	v_permlane32_swap_b32_e32 v17, v16
	s_and_saveexec_b64 s[56:57], s[12:13]
	s_cbranch_execz .LBB0_929
	s_waitcnt lgkmcnt(0)
	v_add_f32_e32 v18, v16, v17
	v_lshlrev_b64 v[16:17], 6, v[92:93]
	v_lshl_add_u64 v[16:17], s[24:25], 0, v[16:17]
	v_lshl_add_u64 v[16:17], s[54:55], 2, v[16:17]
	s_lshl_b32 s18, s67, 2
	v_lshl_add_u64 v[16:17], v[16:17], 0, s[18:19]
	global_store_dword v[16:17], v18, off
.LBB0_929:
	s_or_b64 exec, exec, s[56:57]
	s_waitcnt vmcnt(7)
	v_lshlrev_b32_e32 v16, 16, v68
	s_waitcnt lgkmcnt(0)
	v_and_b32_e32 v17, 0xffff0000, v68
	v_lshlrev_b32_e32 v18, 16, v69
	v_and_b32_e32 v19, 0xffff0000, v69
	v_lshlrev_b32_e32 v20, 16, v70
	v_and_b32_e32 v21, 0xffff0000, v70
	v_lshlrev_b32_e32 v22, 16, v71
	v_and_b32_e32 v23, 0xffff0000, v71
	v_pk_add_f32 v[14:15], v[14:15], v[18:19]
	v_pk_add_f32 v[12:13], v[12:13], v[16:17]
	v_pk_add_f32 v[16:17], v[10:11], v[22:23]
	v_pk_add_f32 v[10:11], v[8:9], v[20:21]
	v_mul_f32_e32 v8, v13, v13
	v_mul_f32_e32 v9, v15, v15
	v_fmac_f32_e32 v8, v12, v12
	v_fmac_f32_e32 v9, v14, v14
	v_add_f32_e32 v8, v8, v9
	v_mul_f32_e32 v9, v11, v11
	v_mul_f32_e32 v18, v17, v17
	v_fmac_f32_e32 v9, v10, v10
	v_fmac_f32_e32 v18, v16, v16
	v_add_f32_e32 v9, v9, v18
	v_add_f32_e32 v18, v8, v9
	v_cvt_pk_bf16_f32 v8, v12, v13
	v_lshl_add_u64 v[12:13], s[22:23], 0, v[90:91]
	v_cvt_pk_bf16_f32 v9, v14, v15
	v_cvt_pk_bf16_f32 v10, v10, v11
	v_cvt_pk_bf16_f32 v11, v16, v17
	v_lshl_add_u64 v[12:13], v[168:169], 1, v[12:13]
	global_store_dwordx4 v[12:13], v[8:11], off
	s_waitcnt vmcnt(7)
	v_lshlrev_b32_e32 v14, 16, v66
	v_and_b32_e32 v15, 0xffff0000, v66
	v_lshlrev_b32_e32 v8, 16, v64
	v_and_b32_e32 v9, 0xffff0000, v64
	v_lshlrev_b32_e32 v10, 16, v65
	v_and_b32_e32 v11, 0xffff0000, v65
	v_lshlrev_b32_e32 v16, 16, v67
	v_and_b32_e32 v17, 0xffff0000, v67
	v_pk_add_f32 v[6:7], v[6:7], v[10:11]
	v_pk_add_f32 v[4:5], v[4:5], v[8:9]
	v_pk_add_f32 v[8:9], v[2:3], v[16:17]
	v_pk_add_f32 v[2:3], v[0:1], v[14:15]
	v_mul_f32_e32 v0, v5, v5
	v_mul_f32_e32 v1, v7, v7
	v_fmac_f32_e32 v0, v4, v4
	v_fmac_f32_e32 v1, v6, v6
	v_add_f32_e32 v0, v0, v1
	v_mul_f32_e32 v1, v3, v3
	v_mul_f32_e32 v10, v9, v9
	v_fmac_f32_e32 v1, v2, v2
	v_fmac_f32_e32 v10, v8, v8
	v_add_f32_e32 v1, v1, v10
	v_add_f32_e32 v0, v0, v1
	v_add_f32_e32 v10, v18, v0
	v_cvt_pk_bf16_f32 v0, v4, v5
	v_cvt_pk_bf16_f32 v1, v6, v7
	v_cvt_pk_bf16_f32 v2, v2, v3
	v_cvt_pk_bf16_f32 v3, v8, v9
	global_store_dwordx4 v[12:13], v[0:3], off offset:256
	s_nop 1
	s_nop 0
	s_nop 2
	v_mov_b32_e32 v0, v10
	s_nop 1
	v_permlane16_swap_b32_e32 v0, v10
	s_waitcnt lgkmcnt(0)
	v_add_f32_e32 v0, v10, v0
	s_nop 1
	v_mov_b32_e32 v1, v0
	s_nop 1
	v_permlane32_swap_b32_e32 v1, v0
	s_and_saveexec_b64 s[56:57], s[12:13]
	s_cbranch_execz .LBB0_931
	s_waitcnt lgkmcnt(0)
	v_add_f32_e32 v2, v0, v1
	v_lshlrev_b64 v[0:1], 6, v[88:89]
	v_lshl_add_u64 v[0:1], s[24:25], 0, v[0:1]
	v_lshl_add_u64 v[0:1], s[54:55], 2, v[0:1]
	s_lshl_b32 s18, s67, 2
	v_lshl_add_u64 v[0:1], v[0:1], 0, s[18:19]
	global_store_dword v[0:1], v2, off

; __device__ __forceinline__ f32x4 silu4(f32x4 v) { return (f32x4){silu_f(v[0]), silu_f(v[1]), silu_f(v[2]), silu_f(v[3])}; }
; __device__ __forceinline__ float row_part(const float* ss, int row, int fq) { const f32x4 a = ((const f32x4*)(ss + (size_t)row * 16))[fq]; return (a[0] + a[1]) + (a[2] + a[3]); }
; __device__ __forceinline__ float row_finish(float t) { t += shx(t, 16); t += shx(t, 32); return __builtin_amdgcn_rsqf(t * (1.0f / 1024.0f) + RMS_EPS); }
;     __device__ __forceinline__ void operator()(const f32x4 (&acc)[2][2][4][2], const Unit& u, int wr, int wc, int fr, int fq) const {
;     ...
;         float rs[2][4];
; #pragma unroll
;         for (int ai = 0; ai < 2; ++ai)
; #pragma unroll
;             for (int m = 0; m < 4; ++m) rs[ai][m] = row_part(ss, u.pm * BM + ai * HALF + wr * 64 + m * 16 + fr, fq);
; #pragma unroll
;         for (int ai = 0; ai < 2; ++ai)
; #pragma unroll
;             for (int m = 0; m < 4; ++m) rs[ai][m] = row_finish(rs[ai][m]);
; #pragma unroll
;         for (int ai = 0; ai < 2; ++ai)
; #pragma unroll
;             for (int m = 0; m < 4; ++m) {
;                 const int row = u.pm * BM + ai * HALF + wr * 64 + m * 16 + fr;
;                 const float rstd = rs[ai][m];
;                 const f32x4 a0 = silu4(acc[ai][0][m][0] * rstd) * (acc[ai][1][m][0] * rstd);
.LBB0_999:
	v_lshl_add_u32 v168, s48, 8, v155
	v_ashrrev_i32_e32 v169, 31, v168
	v_lshlrev_b64 v[146:147], 6, v[168:169]
	v_lshl_add_u64 v[146:147], v[136:137], 0, v[146:147]
	ds_read_b128 v[146:149], v239
	v_or_b32_e32 v164, 16, v168
	v_ashrrev_i32_e32 v165, 31, v164
	v_or_b32_e32 v160, 32, v168
	v_ashrrev_i32_e32 v161, 31, v160
	v_or_b32_e32 v156, 48, v168
	v_ashrrev_i32_e32 v157, 31, v156
	v_add_u32_e32 v152, 0x80, v168
	v_ashrrev_i32_e32 v153, 31, v152
	s_nop 0
	s_andn2_b64 vcc, exec, s[16:17]
	s_waitcnt lgkmcnt(0)
	v_mov_b32_e32 v150, v147
	v_mov_b32_e32 v151, v148
	v_mov_b32_e32 v147, v149
	v_pk_add_f32 v[146:147], v[150:151], v[146:147]
	s_nop 0
	v_add_f32_e32 v154, v146, v147
	v_lshlrev_b64 v[146:147], 6, v[164:165]
	v_lshl_add_u64 v[146:147], v[136:137], 0, v[146:147]
	ds_read_b128 v[146:149], v239 offset:1024
	s_waitcnt lgkmcnt(0)
	v_mov_b32_e32 v150, v147
	v_mov_b32_e32 v151, v148
	v_mov_b32_e32 v147, v149
	v_pk_add_f32 v[146:147], v[150:151], v[146:147]
	s_nop 0
	v_add_f32_e32 v158, v146, v147
	v_lshlrev_b64 v[146:147], 6, v[160:161]
	v_lshl_add_u64 v[146:147], v[136:137], 0, v[146:147]
	ds_read_b128 v[146:149], v239 offset:2048
	s_waitcnt lgkmcnt(0)
	v_mov_b32_e32 v150, v147
	v_mov_b32_e32 v151, v148
	v_mov_b32_e32 v147, v149
	v_pk_add_f32 v[146:147], v[150:151], v[146:147]
	s_nop 0
	v_add_f32_e32 v161, v146, v147
	v_lshlrev_b64 v[146:147], 6, v[156:157]
	v_lshl_add_u64 v[146:147], v[136:137], 0, v[146:147]
	ds_read_b128 v[146:149], v239 offset:3072
	s_waitcnt lgkmcnt(0)
	v_mov_b32_e32 v150, v147
	v_mov_b32_e32 v151, v148
	v_mov_b32_e32 v147, v149
	v_pk_add_f32 v[146:147], v[150:151], v[146:147]
	s_nop 0
	v_add_f32_e32 v157, v146, v147
	v_lshlrev_b64 v[146:147], 6, v[152:153]
	v_lshl_add_u64 v[146:147], v[136:137], 0, v[146:147]
	ds_read_b128 v[146:149], v239 offset:8192
	s_waitcnt lgkmcnt(0)
	v_mov_b32_e32 v150, v147
	v_mov_b32_e32 v151, v148
	v_mov_b32_e32 v147, v149
	v_pk_add_f32 v[146:147], v[150:151], v[146:147]
	v_add_u32_e32 v150, 0x90, v168
	v_ashrrev_i32_e32 v151, 31, v150
	v_add_f32_e32 v153, v146, v147
	v_lshlrev_b64 v[146:147], 6, v[150:151]
	v_lshl_add_u64 v[146:147], v[136:137], 0, v[146:147]
	ds_read_b128 v[146:149], v239 offset:9216
	s_waitcnt lgkmcnt(0)
	v_mov_b32_e32 v176, v147
	v_mov_b32_e32 v177, v148
	v_mov_b32_e32 v147, v149
	v_add_u32_e32 v148, 0xa0, v168
	v_pk_add_f32 v[146:147], v[176:177], v[146:147]
	v_ashrrev_i32_e32 v149, 31, v148
	v_add_f32_e32 v151, v146, v147
	v_lshlrev_b64 v[146:147], 6, v[148:149]
	v_lshl_add_u64 v[146:147], v[136:137], 0, v[146:147]
	ds_read_b128 v[176:179], v239 offset:10240
	s_waitcnt lgkmcnt(0)
	v_mov_b32_e32 v146, v177
	v_mov_b32_e32 v147, v178
	v_mov_b32_e32 v177, v179
	v_pk_add_f32 v[146:147], v[146:147], v[176:177]
	s_nop 0
	v_add_f32_e32 v149, v146, v147
	v_add_u32_e32 v146, 0xb0, v168
	v_ashrrev_i32_e32 v147, 31, v146
	v_lshlrev_b64 v[176:177], 6, v[146:147]
	v_lshl_add_u64 v[176:177], v[136:137], 0, v[176:177]
	ds_read_b128 v[176:179], v239 offset:11264
	s_waitcnt lgkmcnt(0)
	v_mov_b32_e32 v180, v177
	s_nop 1
	v_mov_b32_e32 v162, v154
	s_nop 1
	v_permlane16_swap_b32_e32 v162, v154
	v_mov_b32_e32 v181, v178
	v_mov_b32_e32 v177, v179
	v_pk_add_f32 v[176:177], v[180:181], v[176:177]
	v_lshl_or_b32 v178, s49, 7, v163
	s_waitcnt lgkmcnt(0)
	v_add_f32_e32 v154, v154, v162
	s_nop 0
	v_add_f32_e32 v147, v176, v177
	s_nop 1
	v_mov_b32_e32 v162, v154
	s_nop 1
	v_permlane32_swap_b32_e32 v162, v154
	v_ashrrev_i32_e32 v179, 31, v178
	s_mov_b64 s[48:49], -1
	s_waitcnt lgkmcnt(0)
	v_add_f32_e32 v154, v154, v162
	v_fmamk_f32 v154, v154, 0x3a800000, v175
	v_rsq_f32_e32 v174, v154
	s_nop 0
	v_pk_mul_f32 v[124:125], v[124:125], v[174:175] op_sel_hi:[1,0]
	s_nop 1
	v_mov_b32_e32 v154, v158
	s_nop 1
	v_permlane16_swap_b32_e32 v154, v158
	v_pk_mul_f32 v[126:127], v[126:127], v[174:175] op_sel_hi:[1,0]
	v_pk_mul_f32 v[116:117], v[116:117], v[174:175] op_sel_hi:[1,0]
	v_pk_mul_f32 v[120:121], v[120:121], v[174:175] op_sel_hi:[1,0]
	v_pk_mul_f32 v[118:119], v[118:119], v[174:175] op_sel_hi:[1,0]
	s_waitcnt lgkmcnt(0)
	v_add_f32_e32 v154, v158, v154
	s_nop 0
	v_pk_mul_f32 v[122:123], v[122:123], v[174:175] op_sel_hi:[1,0]
	s_nop 1
	v_mov_b32_e32 v158, v154
	s_nop 1
	v_permlane32_swap_b32_e32 v158, v154
	v_pk_mul_f32 v[112:113], v[112:113], v[174:175] op_sel_hi:[1,0]
	v_pk_mul_f32 v[114:115], v[114:115], v[174:175] op_sel_hi:[1,0]
	s_waitcnt lgkmcnt(0)
	v_add_f32_e32 v154, v154, v158
	v_fmamk_f32 v154, v154, 0x3a800000, v175
	v_rsq_f32_e32 v176, v154
	s_nop 0
	s_nop 2
	v_mov_b32_e32 v154, v161
	s_nop 1
	v_permlane16_swap_b32_e32 v154, v161
	v_pk_mul_f32 v[110:111], v[110:111], v[176:177] op_sel_hi:[1,0]
	s_nop 1
	s_waitcnt lgkmcnt(0)
	v_add_f32_e32 v154, v161, v154
	v_mov_b32_e32 v158, v154
	s_nop 1
	v_permlane32_swap_b32_e32 v158, v154
	v_pk_mul_f32 v[108:109], v[108:109], v[176:177] op_sel_hi:[1,0]
	v_pk_mul_f32 v[100:101], v[100:101], v[176:177] op_sel_hi:[1,0]
	v_pk_mul_f32 v[102:103], v[102:103], v[176:177] op_sel_hi:[1,0]
	v_pk_mul_f32 v[106:107], v[106:107], v[176:177] op_sel_hi:[1,0]
	s_waitcnt lgkmcnt(0)
	v_add_f32_e32 v154, v154, v158
	v_fmamk_f32 v154, v154, 0x3a800000, v175
	v_rsq_f32_e32 v172, v154
	s_nop 0
	v_pk_mul_f32 v[104:105], v[104:105], v[176:177] op_sel_hi:[1,0]
	s_nop 1
	v_mov_b32_e32 v154, v157
	s_nop 1
	v_permlane16_swap_b32_e32 v154, v157
	v_pk_mul_f32 v[96:97], v[96:97], v[176:177] op_sel_hi:[1,0]
	v_pk_mul_f32 v[98:99], v[98:99], v[176:177] op_sel_hi:[1,0]
	v_pk_mul_f32 v[94:95], v[94:95], v[172:173] op_sel_hi:[1,0]
	v_pk_mul_f32 v[92:93], v[92:93], v[172:173] op_sel_hi:[1,0]
	s_waitcnt lgkmcnt(0)
; __device__ __forceinline__ float row_finish(float t) { t += shx(t, 16); t += shx(t, 32); return __builtin_amdgcn_rsqf(t * (1.0f / 1024.0f) + RMS_EPS); }
; __device__ __forceinline__ float silu_f(float v) { return v * __builtin_amdgcn_rcpf(1.0f + __builtin_amdgcn_exp2f(v * -1.4426950408889634f)); }
; __device__ __forceinline__ f32x4 silu4(f32x4 v) { return (f32x4){silu_f(v[0]), silu_f(v[1]), silu_f(v[2]), silu_f(v[3])}; }
;     __device__ __forceinline__ void operator()(const f32x4 (&acc)[2][2][4][2], const Unit& u, int wr, int wc, int fr, int fq) const {
;     ...
; #pragma unroll
;         for (int ai = 0; ai < 2; ++ai)
; #pragma unroll
;             for (int m = 0; m < 4; ++m) rs[ai][m] = row_finish(rs[ai][m]);
; #pragma unroll
;         for (int ai = 0; ai < 2; ++ai)
; #pragma unroll
;             for (int m = 0; m < 4; ++m) {
;                 const int row = u.pm * BM + ai * HALF + wr * 64 + m * 16 + fr;
;                 const float rstd = rs[ai][m];
;                 const f32x4 a0 = silu4(acc[ai][0][m][0] * rstd) * (acc[ai][1][m][0] * rstd);
;                 const f32x4 a1 = silu4(acc[ai][0][m][1] * rstd) * (acc[ai][1][m][1] * rstd);
	v_add_f32_e32 v154, v157, v154
	s_nop 0
	v_pk_mul_f32 v[84:85], v[84:85], v[172:173] op_sel_hi:[1,0]
	s_nop 1
	v_mov_b32_e32 v157, v154
	s_nop 1
	v_permlane32_swap_b32_e32 v157, v154
	v_pk_mul_f32 v[86:87], v[86:87], v[172:173] op_sel_hi:[1,0]
	v_pk_mul_f32 v[90:91], v[90:91], v[172:173] op_sel_hi:[1,0]
	v_pk_mul_f32 v[88:89], v[88:89], v[172:173] op_sel_hi:[1,0]
	v_pk_mul_f32 v[80:81], v[80:81], v[172:173] op_sel_hi:[1,0]
	s_waitcnt lgkmcnt(0)
	v_add_f32_e32 v154, v154, v157
	v_fmamk_f32 v154, v154, 0x3a800000, v175
	v_rsq_f32_e32 v170, v154
	s_nop 0
	v_pk_mul_f32 v[82:83], v[82:83], v[172:173] op_sel_hi:[1,0]
	s_nop 1
	v_mov_b32_e32 v154, v153
	s_nop 1
	v_permlane16_swap_b32_e32 v154, v153
	v_pk_mul_f32 v[78:79], v[78:79], v[170:171] op_sel_hi:[1,0]
	v_pk_mul_f32 v[76:77], v[76:77], v[170:171] op_sel_hi:[1,0]
	v_pk_mul_f32 v[68:69], v[68:69], v[170:171] op_sel_hi:[1,0]
	v_pk_mul_f32 v[70:71], v[70:71], v[170:171] op_sel_hi:[1,0]
	s_waitcnt lgkmcnt(0)
	v_add_f32_e32 v153, v153, v154
	s_nop 0
	v_pk_mul_f32 v[74:75], v[74:75], v[170:171] op_sel_hi:[1,0]
	s_nop 1
	v_mov_b32_e32 v154, v153
	s_nop 1
	v_permlane32_swap_b32_e32 v154, v153
	v_pk_mul_f32 v[72:73], v[72:73], v[170:171] op_sel_hi:[1,0]
	v_pk_mul_f32 v[64:65], v[64:65], v[170:171] op_sel_hi:[1,0]
	v_pk_mul_f32 v[66:67], v[66:67], v[170:171] op_sel_hi:[1,0]
	s_waitcnt lgkmcnt(0)
	v_add_f32_e32 v153, v153, v154
	v_fmamk_f32 v153, v153, 0x3a800000, v175
	v_rsq_f32_e32 v166, v153
	s_nop 0
	v_pk_mul_f32 v[62:63], v[62:63], v[166:167] op_sel_hi:[1,0]
	s_nop 1
	v_mov_b32_e32 v153, v151
	s_nop 1
	v_permlane16_swap_b32_e32 v153, v151
	v_pk_mul_f32 v[60:61], v[60:61], v[166:167] op_sel_hi:[1,0]
	v_pk_mul_f32 v[52:53], v[52:53], v[166:167] op_sel_hi:[1,0]
	v_pk_mul_f32 v[54:55], v[54:55], v[166:167] op_sel_hi:[1,0]
	v_pk_mul_f32 v[58:59], v[58:59], v[166:167] op_sel_hi:[1,0]
	s_waitcnt lgkmcnt(0)
	v_add_f32_e32 v151, v151, v153
	s_nop 0
	v_pk_mul_f32 v[56:57], v[56:57], v[166:167] op_sel_hi:[1,0]
	s_nop 1
	v_mov_b32_e32 v153, v151
	s_nop 1
	v_permlane32_swap_b32_e32 v153, v151
	v_pk_mul_f32 v[48:49], v[48:49], v[166:167] op_sel_hi:[1,0]
	v_pk_mul_f32 v[50:51], v[50:51], v[166:167] op_sel_hi:[1,0]
	s_waitcnt lgkmcnt(0)
	v_add_f32_e32 v151, v151, v153
	v_fmamk_f32 v151, v151, 0x3a800000, v175
	v_rsq_f32_e32 v162, v151
	s_nop 0
	v_pk_mul_f32 v[46:47], v[46:47], v[162:163] op_sel_hi:[1,0]
	s_nop 1
	v_mov_b32_e32 v151, v149
	s_nop 1
	v_permlane16_swap_b32_e32 v151, v149
	v_pk_mul_f32 v[44:45], v[44:45], v[162:163] op_sel_hi:[1,0]
	v_pk_mul_f32 v[36:37], v[36:37], v[162:163] op_sel_hi:[1,0]
	v_pk_mul_f32 v[38:39], v[38:39], v[162:163] op_sel_hi:[1,0]
	v_pk_mul_f32 v[42:43], v[42:43], v[162:163] op_sel_hi:[1,0]
	s_waitcnt lgkmcnt(0)
	v_add_f32_e32 v149, v149, v151
	s_nop 0
	v_pk_mul_f32 v[40:41], v[40:41], v[162:163] op_sel_hi:[1,0]
	s_nop 1
	v_mov_b32_e32 v151, v149
	s_nop 1
	v_permlane32_swap_b32_e32 v151, v149
	v_pk_mul_f32 v[32:33], v[32:33], v[162:163] op_sel_hi:[1,0]
	v_pk_mul_f32 v[34:35], v[34:35], v[162:163] op_sel_hi:[1,0]
	s_waitcnt lgkmcnt(0)
	v_add_f32_e32 v149, v149, v151
	v_fmamk_f32 v149, v149, 0x3a800000, v175
	v_rsq_f32_e32 v158, v149
	s_nop 0
	v_pk_mul_f32 v[30:31], v[30:31], v[158:159] op_sel_hi:[1,0]
	s_nop 1
	v_mov_b32_e32 v149, v147
	s_nop 1
	v_permlane16_swap_b32_e32 v149, v147
	v_pk_mul_f32 v[28:29], v[28:29], v[158:159] op_sel_hi:[1,0]
	v_pk_mul_f32 v[20:21], v[20:21], v[158:159] op_sel_hi:[1,0]
	v_pk_mul_f32 v[22:23], v[22:23], v[158:159] op_sel_hi:[1,0]
	v_pk_mul_f32 v[26:27], v[26:27], v[158:159] op_sel_hi:[1,0]
	s_waitcnt lgkmcnt(0)
	v_add_f32_e32 v147, v147, v149
	s_nop 0
	v_pk_mul_f32 v[24:25], v[24:25], v[158:159] op_sel_hi:[1,0]
	s_nop 1
	v_mov_b32_e32 v149, v147
	s_nop 1
	v_permlane32_swap_b32_e32 v149, v147
	v_pk_mul_f32 v[16:17], v[16:17], v[158:159] op_sel_hi:[1,0]
	v_pk_mul_f32 v[18:19], v[18:19], v[158:159] op_sel_hi:[1,0]
	s_waitcnt lgkmcnt(0)
	v_add_f32_e32 v147, v147, v149
	v_fmamk_f32 v147, v147, 0x3a800000, v175
	v_rsq_f32_e32 v154, v147
	v_mul_f32_e32 v147, 0xbfb8aa3b, v124
	v_exp_f32_e32 v147, v147
	v_pk_mul_f32 v[14:15], v[14:15], v[154:155] op_sel_hi:[1,0]
	v_pk_mul_f32 v[12:13], v[12:13], v[154:155] op_sel_hi:[1,0]
	v_add_f32_e32 v147, 1.0, v147
	v_rcp_f32_e32 v180, v147
	v_mul_f32_e32 v147, 0xbfb8aa3b, v125
	v_exp_f32_e32 v147, v147
	v_pk_mul_f32 v[4:5], v[4:5], v[154:155] op_sel_hi:[1,0]
	v_pk_mul_f32 v[6:7], v[6:7], v[154:155] op_sel_hi:[1,0]
	v_pk_mul_f32 v[10:11], v[10:11], v[154:155] op_sel_hi:[1,0]
	v_add_f32_e32 v147, 1.0, v147
	v_rcp_f32_e32 v181, v147
	v_mul_f32_e32 v147, 0xbfb8aa3b, v126
	v_exp_f32_e32 v147, v147
	v_pk_mul_f32 v[8:9], v[8:9], v[154:155] op_sel_hi:[1,0]
	v_pk_mul_f32 v[124:125], v[124:125], v[180:181]
	v_pk_mul_f32 v[0:1], v[0:1], v[154:155] op_sel_hi:[1,0]
	v_add_f32_e32 v147, 1.0, v147
	v_rcp_f32_e32 v182, v147
	v_mul_f32_e32 v147, 0xbfb8aa3b, v127
	v_exp_f32_e32 v147, v147
	v_pk_mul_f32 v[116:117], v[116:117], v[124:125]
	v_mul_f32_e32 v124, 0xbfb8aa3b, v120
	v_mul_f32_e32 v125, 0xbfb8aa3b, v121
	v_add_f32_e32 v147, 1.0, v147
	v_rcp_f32_e32 v183, v147
	v_exp_f32_e32 v124, v124
	v_exp_f32_e32 v125, v125
	v_cvt_pk_bf16_f32 v116, v116, v117
	v_pk_mul_f32 v[126:127], v[126:127], v[182:183]
	v_add_f32_e32 v124, 1.0, v124
	v_pk_mul_f32 v[118:119], v[118:119], v[126:127]
	v_mul_f32_e32 v126, 0xbfb8aa3b, v122
	v_mul_f32_e32 v127, 0xbfb8aa3b, v123
	v_exp_f32_e32 v126, v126
	v_exp_f32_e32 v127, v127
	v_add_f32_e32 v125, 1.0, v125
	v_rcp_f32_e32 v124, v124
	v_rcp_f32_e32 v125, v125
	v_add_f32_e32 v126, 1.0, v126
	v_add_f32_e32 v127, 1.0, v127
	v_rcp_f32_e32 v126, v126
	v_rcp_f32_e32 v127, v127
	v_pk_mul_f32 v[120:121], v[120:121], v[124:125]
; __device__ __forceinline__ f32x4 silu4(f32x4 v) { return (f32x4){silu_f(v[0]), silu_f(v[1]), silu_f(v[2]), silu_f(v[3])}; }
; __device__ __forceinline__ u32x4 pack8(f32x4 a, f32x4 b) { u32x4 w; w.x = cvt_pk_bf16(a[0], a[1]); w.y = cvt_pk_bf16(a[2], a[3]); w.z = cvt_pk_bf16(b[0], b[1]); w.w = cvt_pk_bf16(b[2], b[3]); return w; }
;     __device__ __forceinline__ void operator()(const f32x4 (&acc)[2][2][4][2], const Unit& u, int wr, int wc, int fr, int fq) const {
;     ...
;         for (int ai = 0; ai < 2; ++ai)
; #pragma unroll
;             for (int m = 0; m < 4; ++m) {
;                 const int row = u.pm * BM + ai * HALF + wr * 64 + m * 16 + fr;
;                 const float rstd = rs[ai][m];
;                 const f32x4 a0 = silu4(acc[ai][0][m][0] * rstd) * (acc[ai][1][m][0] * rstd);
;                 const f32x4 a1 = silu4(acc[ai][0][m][1] * rstd) * (acc[ai][1][m][1] * rstd);
;                 *(u32x4*)(ACT + (size_t)row * 2816 + col0) = pack8(a0, a1);
;             }
	v_cvt_pk_bf16_f32 v117, v118, v119
	v_pk_mul_f32 v[2:3], v[2:3], v[154:155] op_sel_hi:[1,0]
	v_pk_mul_f32 v[122:123], v[122:123], v[126:127]
	v_pk_mul_f32 v[112:113], v[112:113], v[120:121]
	v_pk_mul_f32 v[114:115], v[114:115], v[122:123]
	v_cvt_pk_bf16_f32 v118, v112, v113
	v_mov_b64_e32 v[112:113], s[20:21]
	v_cvt_pk_bf16_f32 v119, v114, v115
	v_mad_i64_i32 v[120:121], s[14:15], v168, s68, v[112:113]
	v_lshlrev_b64 v[114:115], 1, v[178:179]
	v_lshl_add_u64 v[120:121], v[120:121], 0, v[114:115]
	global_store_dwordx4 v[120:121], v[116:119], off
	s_nop 1
	v_mul_f32_e32 v116, 0xbfb8aa3b, v108
	v_mul_f32_e32 v117, 0xbfb8aa3b, v109
	v_mul_f32_e32 v118, 0xbfb8aa3b, v110
	v_mul_f32_e32 v119, 0xbfb8aa3b, v111
	v_exp_f32_e32 v116, v116
	v_exp_f32_e32 v117, v117
	v_exp_f32_e32 v118, v118
	v_exp_f32_e32 v119, v119
	v_add_f32_e32 v116, 1.0, v116
	v_add_f32_e32 v117, 1.0, v117
	v_add_f32_e32 v118, 1.0, v118
	v_add_f32_e32 v119, 1.0, v119
	v_rcp_f32_e32 v116, v116
	v_rcp_f32_e32 v117, v117
	v_rcp_f32_e32 v118, v118
	v_rcp_f32_e32 v119, v119
	v_pk_mul_f32 v[108:109], v[108:109], v[116:117]
	s_nop 0
	v_pk_mul_f32 v[100:101], v[100:101], v[108:109]
	v_pk_mul_f32 v[110:111], v[110:111], v[118:119]
	v_mul_f32_e32 v108, 0xbfb8aa3b, v104
	v_pk_mul_f32 v[102:103], v[102:103], v[110:111]
	v_mul_f32_e32 v109, 0xbfb8aa3b, v105
	v_mul_f32_e32 v110, 0xbfb8aa3b, v106
	v_mul_f32_e32 v111, 0xbfb8aa3b, v107
	v_exp_f32_e32 v108, v108
	v_exp_f32_e32 v109, v109
	v_exp_f32_e32 v110, v110
	v_exp_f32_e32 v111, v111
	v_add_f32_e32 v108, 1.0, v108
	v_add_f32_e32 v109, 1.0, v109
	v_add_f32_e32 v110, 1.0, v110
	v_add_f32_e32 v111, 1.0, v111
	v_rcp_f32_e32 v108, v108
	v_rcp_f32_e32 v109, v109
	v_rcp_f32_e32 v110, v110
	v_rcp_f32_e32 v111, v111
	v_pk_mul_f32 v[104:105], v[104:105], v[108:109]
	v_pk_mul_f32 v[106:107], v[106:107], v[110:111]
	s_nop 0
	v_pk_mul_f32 v[106:107], v[98:99], v[106:107]
	v_pk_mul_f32 v[98:99], v[96:97], v[104:105]
	v_cvt_pk_bf16_f32 v96, v100, v101
	v_mad_i64_i32 v[100:101], s[14:15], v164, s68, v[112:113]
	v_cvt_pk_bf16_f32 v97, v102, v103
	v_cvt_pk_bf16_f32 v98, v98, v99
	v_cvt_pk_bf16_f32 v99, v106, v107
	v_lshl_add_u64 v[100:101], v[100:101], 0, v[114:115]
	global_store_dwordx4 v[100:101], v[96:99], off
	s_nop 1
	v_mul_f32_e32 v96, 0xbfb8aa3b, v92
	v_mul_f32_e32 v97, 0xbfb8aa3b, v93
	v_mul_f32_e32 v98, 0xbfb8aa3b, v94
	v_mul_f32_e32 v99, 0xbfb8aa3b, v95
	v_exp_f32_e32 v96, v96
	v_exp_f32_e32 v97, v97
	v_exp_f32_e32 v98, v98
	v_exp_f32_e32 v99, v99
	v_add_f32_e32 v96, 1.0, v96
	v_add_f32_e32 v97, 1.0, v97
	v_add_f32_e32 v98, 1.0, v98
	v_add_f32_e32 v99, 1.0, v99
	v_rcp_f32_e32 v96, v96
	v_rcp_f32_e32 v97, v97
	v_rcp_f32_e32 v98, v98
	v_rcp_f32_e32 v99, v99
	v_pk_mul_f32 v[92:93], v[92:93], v[96:97]
	s_nop 0
	v_pk_mul_f32 v[84:85], v[84:85], v[92:93]
	v_pk_mul_f32 v[94:95], v[94:95], v[98:99]
	v_mul_f32_e32 v92, 0xbfb8aa3b, v88
	v_pk_mul_f32 v[86:87], v[86:87], v[94:95]
	v_mul_f32_e32 v93, 0xbfb8aa3b, v89
	v_mul_f32_e32 v94, 0xbfb8aa3b, v90
	v_mul_f32_e32 v95, 0xbfb8aa3b, v91
	v_exp_f32_e32 v92, v92
	v_exp_f32_e32 v93, v93
	v_exp_f32_e32 v94, v94
	v_exp_f32_e32 v95, v95
	v_add_f32_e32 v92, 1.0, v92
	v_add_f32_e32 v93, 1.0, v93
	v_add_f32_e32 v94, 1.0, v94
	v_add_f32_e32 v95, 1.0, v95
	v_rcp_f32_e32 v92, v92
	v_rcp_f32_e32 v93, v93
	v_rcp_f32_e32 v94, v94
	v_rcp_f32_e32 v95, v95
	v_pk_mul_f32 v[88:89], v[88:89], v[92:93]
	v_pk_mul_f32 v[90:91], v[90:91], v[94:95]
	s_nop 0
	v_pk_mul_f32 v[90:91], v[82:83], v[90:91]
	v_pk_mul_f32 v[82:83], v[80:81], v[88:89]
	v_cvt_pk_bf16_f32 v80, v84, v85
	v_mad_i64_i32 v[84:85], s[14:15], v160, s68, v[112:113]
	v_cvt_pk_bf16_f32 v81, v86, v87
	v_cvt_pk_bf16_f32 v82, v82, v83
	v_cvt_pk_bf16_f32 v83, v90, v91
	v_lshl_add_u64 v[84:85], v[84:85], 0, v[114:115]
	global_store_dwordx4 v[84:85], v[80:83], off
	s_nop 1
	v_mul_f32_e32 v80, 0xbfb8aa3b, v76
	v_mul_f32_e32 v81, 0xbfb8aa3b, v77
	v_mul_f32_e32 v82, 0xbfb8aa3b, v78
	v_mul_f32_e32 v83, 0xbfb8aa3b, v79
	v_exp_f32_e32 v80, v80
	v_exp_f32_e32 v81, v81
	v_exp_f32_e32 v82, v82
	v_exp_f32_e32 v83, v83
	v_add_f32_e32 v80, 1.0, v80
	v_add_f32_e32 v81, 1.0, v81
	v_add_f32_e32 v82, 1.0, v82
	v_add_f32_e32 v83, 1.0, v83
	v_rcp_f32_e32 v80, v80
	v_rcp_f32_e32 v81, v81
	v_rcp_f32_e32 v82, v82
	v_rcp_f32_e32 v83, v83
	v_pk_mul_f32 v[76:77], v[76:77], v[80:81]
	s_nop 0
	v_pk_mul_f32 v[68:69], v[68:69], v[76:77]
	v_pk_mul_f32 v[78:79], v[78:79], v[82:83]
	v_mul_f32_e32 v76, 0xbfb8aa3b, v72
	v_pk_mul_f32 v[70:71], v[70:71], v[78:79]
	v_mul_f32_e32 v77, 0xbfb8aa3b, v73
	v_mul_f32_e32 v78, 0xbfb8aa3b, v74
	v_mul_f32_e32 v79, 0xbfb8aa3b, v75
	v_exp_f32_e32 v76, v76
	v_exp_f32_e32 v77, v77
	v_exp_f32_e32 v78, v78
	v_exp_f32_e32 v79, v79
	v_add_f32_e32 v76, 1.0, v76
	v_add_f32_e32 v77, 1.0, v77
	v_add_f32_e32 v78, 1.0, v78
	v_add_f32_e32 v79, 1.0, v79
	v_rcp_f32_e32 v76, v76
	v_rcp_f32_e32 v77, v77
	v_rcp_f32_e32 v78, v78
	v_rcp_f32_e32 v79, v79
	v_pk_mul_f32 v[72:73], v[72:73], v[76:77]
	v_pk_mul_f32 v[74:75], v[74:75], v[78:79]
	s_nop 0
	v_pk_mul_f32 v[74:75], v[66:67], v[74:75]
	v_pk_mul_f32 v[66:67], v[64:65], v[72:73]
	v_cvt_pk_bf16_f32 v64, v68, v69
	v_mad_i64_i32 v[68:69], s[14:15], v156, s68, v[112:113]
	v_cvt_pk_bf16_f32 v65, v70, v71
	v_cvt_pk_bf16_f32 v66, v66, v67
	v_cvt_pk_bf16_f32 v67, v74, v75
	v_lshl_add_u64 v[68:69], v[68:69], 0, v[114:115]
	global_store_dwordx4 v[68:69], v[64:67], off
	s_nop 1
	v_mul_f32_e32 v64, 0xbfb8aa3b, v60
	v_mul_f32_e32 v65, 0xbfb8aa3b, v61
	v_mul_f32_e32 v66, 0xbfb8aa3b, v62
	v_mul_f32_e32 v67, 0xbfb8aa3b, v63
	v_exp_f32_e32 v64, v64
	v_exp_f32_e32 v65, v65
	v_exp_f32_e32 v66, v66
	v_exp_f32_e32 v67, v67
	v_add_f32_e32 v64, 1.0, v64
; __device__ __forceinline__ f32x4 silu4(f32x4 v) { return (f32x4){silu_f(v[0]), silu_f(v[1]), silu_f(v[2]), silu_f(v[3])}; }
; __device__ __forceinline__ u32x4 pack8(f32x4 a, f32x4 b) { u32x4 w; w.x = cvt_pk_bf16(a[0], a[1]); w.y = cvt_pk_bf16(a[2], a[3]); w.z = cvt_pk_bf16(b[0], b[1]); w.w = cvt_pk_bf16(b[2], b[3]); return w; }
;     __device__ __forceinline__ void operator()(const f32x4 (&acc)[2][2][4][2], const Unit& u, int wr, int wc, int fr, int fq) const {
;     ...
;         for (int ai = 0; ai < 2; ++ai)
; #pragma unroll
;             for (int m = 0; m < 4; ++m) {
;                 const int row = u.pm * BM + ai * HALF + wr * 64 + m * 16 + fr;
;                 const float rstd = rs[ai][m];
;                 const f32x4 a0 = silu4(acc[ai][0][m][0] * rstd) * (acc[ai][1][m][0] * rstd);
;                 const f32x4 a1 = silu4(acc[ai][0][m][1] * rstd) * (acc[ai][1][m][1] * rstd);
;                 *(u32x4*)(ACT + (size_t)row * 2816 + col0) = pack8(a0, a1);
;             }
	v_add_f32_e32 v65, 1.0, v65
	v_add_f32_e32 v66, 1.0, v66
	v_add_f32_e32 v67, 1.0, v67
	v_rcp_f32_e32 v64, v64
	v_rcp_f32_e32 v65, v65
	v_rcp_f32_e32 v66, v66
	v_rcp_f32_e32 v67, v67
	v_pk_mul_f32 v[60:61], v[60:61], v[64:65]
	s_nop 0
	v_pk_mul_f32 v[52:53], v[52:53], v[60:61]
	v_pk_mul_f32 v[62:63], v[62:63], v[66:67]
	v_mul_f32_e32 v60, 0xbfb8aa3b, v56
	v_pk_mul_f32 v[54:55], v[54:55], v[62:63]
	v_mul_f32_e32 v61, 0xbfb8aa3b, v57
	v_mul_f32_e32 v62, 0xbfb8aa3b, v58
	v_mul_f32_e32 v63, 0xbfb8aa3b, v59
	v_exp_f32_e32 v60, v60
	v_exp_f32_e32 v61, v61
	v_exp_f32_e32 v62, v62
	v_exp_f32_e32 v63, v63
	v_add_f32_e32 v60, 1.0, v60
	v_add_f32_e32 v61, 1.0, v61
	v_add_f32_e32 v62, 1.0, v62
	v_add_f32_e32 v63, 1.0, v63
	v_rcp_f32_e32 v60, v60
	v_rcp_f32_e32 v61, v61
	v_rcp_f32_e32 v62, v62
	v_rcp_f32_e32 v63, v63
	v_pk_mul_f32 v[56:57], v[56:57], v[60:61]
	v_pk_mul_f32 v[58:59], v[58:59], v[62:63]
	s_nop 0
	v_pk_mul_f32 v[58:59], v[50:51], v[58:59]
	v_pk_mul_f32 v[50:51], v[48:49], v[56:57]
	v_cvt_pk_bf16_f32 v48, v52, v53
	v_mad_i64_i32 v[52:53], s[14:15], v152, s68, v[112:113]
	v_cvt_pk_bf16_f32 v49, v54, v55
	v_cvt_pk_bf16_f32 v50, v50, v51
	v_cvt_pk_bf16_f32 v51, v58, v59
	v_lshl_add_u64 v[52:53], v[52:53], 0, v[114:115]
	global_store_dwordx4 v[52:53], v[48:51], off
	s_nop 1
	v_mul_f32_e32 v48, 0xbfb8aa3b, v44
	v_mul_f32_e32 v49, 0xbfb8aa3b, v45
	v_mul_f32_e32 v50, 0xbfb8aa3b, v46
	v_mul_f32_e32 v51, 0xbfb8aa3b, v47
	v_exp_f32_e32 v48, v48
	v_exp_f32_e32 v49, v49
	v_exp_f32_e32 v50, v50
	v_exp_f32_e32 v51, v51
	v_add_f32_e32 v48, 1.0, v48
	v_add_f32_e32 v49, 1.0, v49
	v_add_f32_e32 v50, 1.0, v50
	v_add_f32_e32 v51, 1.0, v51
	v_rcp_f32_e32 v48, v48
	v_rcp_f32_e32 v49, v49
	v_rcp_f32_e32 v50, v50
	v_rcp_f32_e32 v51, v51
	v_pk_mul_f32 v[44:45], v[44:45], v[48:49]
	s_nop 0
	v_pk_mul_f32 v[36:37], v[36:37], v[44:45]
	v_pk_mul_f32 v[46:47], v[46:47], v[50:51]
	v_mul_f32_e32 v44, 0xbfb8aa3b, v40
	v_pk_mul_f32 v[38:39], v[38:39], v[46:47]
	v_mul_f32_e32 v45, 0xbfb8aa3b, v41
	v_mul_f32_e32 v46, 0xbfb8aa3b, v42
	v_mul_f32_e32 v47, 0xbfb8aa3b, v43
	v_exp_f32_e32 v44, v44
	v_exp_f32_e32 v45, v45
	v_exp_f32_e32 v46, v46
	v_exp_f32_e32 v47, v47
	v_add_f32_e32 v44, 1.0, v44
	v_add_f32_e32 v45, 1.0, v45
	v_add_f32_e32 v46, 1.0, v46
	v_add_f32_e32 v47, 1.0, v47
	v_rcp_f32_e32 v44, v44
	v_rcp_f32_e32 v45, v45
	v_rcp_f32_e32 v46, v46
	v_rcp_f32_e32 v47, v47
	v_pk_mul_f32 v[40:41], v[40:41], v[44:45]
	v_pk_mul_f32 v[42:43], v[42:43], v[46:47]
	s_nop 0
	v_pk_mul_f32 v[42:43], v[34:35], v[42:43]
	v_pk_mul_f32 v[34:35], v[32:33], v[40:41]
	v_cvt_pk_bf16_f32 v32, v36, v37
	v_mad_i64_i32 v[36:37], s[14:15], v150, s68, v[112:113]
	v_cvt_pk_bf16_f32 v33, v38, v39
	v_cvt_pk_bf16_f32 v34, v34, v35
	v_cvt_pk_bf16_f32 v35, v42, v43
	v_lshl_add_u64 v[36:37], v[36:37], 0, v[114:115]
	global_store_dwordx4 v[36:37], v[32:35], off
	s_nop 1
	v_mul_f32_e32 v32, 0xbfb8aa3b, v28
	v_mul_f32_e32 v33, 0xbfb8aa3b, v29
	v_mul_f32_e32 v34, 0xbfb8aa3b, v30
	v_mul_f32_e32 v35, 0xbfb8aa3b, v31
	v_exp_f32_e32 v32, v32
	v_exp_f32_e32 v33, v33
	v_exp_f32_e32 v34, v34
	v_exp_f32_e32 v35, v35
	v_add_f32_e32 v32, 1.0, v32
	v_add_f32_e32 v33, 1.0, v33
	v_add_f32_e32 v34, 1.0, v34
	v_add_f32_e32 v35, 1.0, v35
	v_rcp_f32_e32 v32, v32
	v_rcp_f32_e32 v33, v33
	v_rcp_f32_e32 v34, v34
	v_rcp_f32_e32 v35, v35
	v_pk_mul_f32 v[28:29], v[28:29], v[32:33]
	s_nop 0
	v_pk_mul_f32 v[20:21], v[20:21], v[28:29]
	v_pk_mul_f32 v[30:31], v[30:31], v[34:35]
	v_mul_f32_e32 v28, 0xbfb8aa3b, v24
	v_pk_mul_f32 v[22:23], v[22:23], v[30:31]
	v_mul_f32_e32 v29, 0xbfb8aa3b, v25
	v_mul_f32_e32 v30, 0xbfb8aa3b, v26
	v_mul_f32_e32 v31, 0xbfb8aa3b, v27
	v_exp_f32_e32 v28, v28
	v_exp_f32_e32 v29, v29
	v_exp_f32_e32 v30, v30
	v_exp_f32_e32 v31, v31
	v_add_f32_e32 v28, 1.0, v28
	v_add_f32_e32 v29, 1.0, v29
	v_add_f32_e32 v30, 1.0, v30
	v_add_f32_e32 v31, 1.0, v31
	v_rcp_f32_e32 v28, v28
	v_rcp_f32_e32 v29, v29
	v_rcp_f32_e32 v30, v30
	v_rcp_f32_e32 v31, v31
	v_pk_mul_f32 v[24:25], v[24:25], v[28:29]
	v_pk_mul_f32 v[26:27], v[26:27], v[30:31]
	s_nop 0
	v_pk_mul_f32 v[26:27], v[18:19], v[26:27]
	v_pk_mul_f32 v[18:19], v[16:17], v[24:25]
	v_cvt_pk_bf16_f32 v16, v20, v21
	v_mad_i64_i32 v[20:21], s[14:15], v148, s68, v[112:113]
	v_cvt_pk_bf16_f32 v17, v22, v23
	v_cvt_pk_bf16_f32 v18, v18, v19
	v_cvt_pk_bf16_f32 v19, v26, v27
	v_lshl_add_u64 v[20:21], v[20:21], 0, v[114:115]
	global_store_dwordx4 v[20:21], v[16:19], off
	s_nop 1
	v_mul_f32_e32 v16, 0xbfb8aa3b, v12
	v_mul_f32_e32 v17, 0xbfb8aa3b, v13
	v_mul_f32_e32 v18, 0xbfb8aa3b, v14
	v_mul_f32_e32 v19, 0xbfb8aa3b, v15
	v_exp_f32_e32 v16, v16
	v_exp_f32_e32 v17, v17
	v_exp_f32_e32 v18, v18
	v_exp_f32_e32 v19, v19
	v_add_f32_e32 v16, 1.0, v16
	v_add_f32_e32 v17, 1.0, v17
	v_add_f32_e32 v18, 1.0, v18
	v_add_f32_e32 v19, 1.0, v19
	v_rcp_f32_e32 v16, v16
	v_rcp_f32_e32 v17, v17
	v_rcp_f32_e32 v18, v18
	v_rcp_f32_e32 v19, v19
	v_pk_mul_f32 v[12:13], v[12:13], v[16:17]
	s_nop 0
	v_pk_mul_f32 v[4:5], v[4:5], v[12:13]
	v_pk_mul_f32 v[14:15], v[14:15], v[18:19]
	v_mul_f32_e32 v12, 0xbfb8aa3b, v8
	v_pk_mul_f32 v[6:7], v[6:7], v[14:15]
	v_mul_f32_e32 v13, 0xbfb8aa3b, v9
	v_mul_f32_e32 v14, 0xbfb8aa3b, v10
	v_mul_f32_e32 v15, 0xbfb8aa3b, v11
	v_exp_f32_e32 v12, v12
	v_exp_f32_e32 v13, v13
	v_exp_f32_e32 v14, v14
	v_exp_f32_e32 v15, v15
	v_add_f32_e32 v12, 1.0, v12
	v_add_f32_e32 v13, 1.0, v13
	v_add_f32_e32 v14, 1.0, v14
	v_add_f32_e32 v15, 1.0, v15
	v_rcp_f32_e32 v12, v12
	v_rcp_f32_e32 v13, v13
	v_rcp_f32_e32 v14, v14
	v_rcp_f32_e32 v15, v15
	v_pk_mul_f32 v[8:9], v[8:9], v[12:13]
	v_pk_mul_f32 v[10:11], v[10:11], v[14:15]
	s_nop 0
	v_pk_mul_f32 v[10:11], v[2:3], v[10:11]
	v_pk_mul_f32 v[2:3], v[0:1], v[8:9]
	v_cvt_pk_bf16_f32 v0, v4, v5
	v_mad_i64_i32 v[4:5], s[14:15], v146, s68, v[112:113]
	v_lshl_add_u64 v[4:5], v[4:5], 0, v[114:115]
	v_cvt_pk_bf16_f32 v1, v6, v7
	v_cvt_pk_bf16_f32 v2, v2, v3
	v_cvt_pk_bf16_f32 v3, v10, v11
	global_store_dwordx4 v[4:5], v[0:3], off
	s_cbranch_vccnz .LBB0_992
	s_andn2_b64 vcc, exec, s[18:19]
	s_cbranch_vccnz .LBB0_991
	s_barrier
	s_branch .LBB0_991

; __device__ __forceinline__ float sq4(f32x4 v) { return (v[0] * v[0] + v[1] * v[1]) + (v[2] * v[2] + v[3] * v[3]); }
; __device__ __forceinline__ u32x4 pack8(f32x4 a, f32x4 b) { u32x4 w; w.x = cvt_pk_bf16(a[0], a[1]); w.y = cvt_pk_bf16(a[2], a[3]); w.z = cvt_pk_bf16(b[0], b[1]); w.w = cvt_pk_bf16(b[2], b[3]); return w; }
;     __device__ __forceinline__ void operator()(const f32x4 (&acc)[2][2][4][2], const Unit& u, int wr, int wc, int fr, int fq) const {
;         const int col0 = u.pn * 256 + 32 * wc + 8 * fq;
; #pragma unroll
;         for (int ai = 0; ai < 2; ++ai) {
;             u32x4 bs[4][2];
; #pragma unroll
;             for (int m = 0; m < 4; ++m)
; #pragma unroll
;                 for (int bj = 0; bj < 2; ++bj) bs[m][bj] = *(const u32x4*)(xb + (size_t)(u.pm * BM + ai * HALF + wr * 64 + m * 16 + fr) * 1024 + col0 + 128 * bj);
; #pragma unroll
;             for (int m = 0; m < 4; ++m) {
;                 const int row = u.pm * BM + ai * HALF + wr * 64 + m * 16 + fr;
;                 float q = 0.f;
; #pragma unroll
;                 for (int bj = 0; bj < 2; ++bj) {
;                     const size_t off = (size_t)row * 1024 + col0 + 128 * bj; const u32x4 w = bs[m][bj];
;                     const f32x4 b0 = (f32x4){__builtin_bit_cast(float, w.x << 16), __builtin_bit_cast(float, w.x & 0xffff0000u), __builtin_bit_cast(float, w.y << 16), __builtin_bit_cast(float, w.y & 0xffff0000u)};
;                     const f32x4 b1 = (f32x4){__builtin_bit_cast(float, w.z << 16), __builtin_bit_cast(float, w.z & 0xffff0000u), __builtin_bit_cast(float, w.w << 16), __builtin_bit_cast(float, w.w & 0xffff0000u)};
;                     const f32x4 v0 = acc[ai][bj][m][0] + b0, v1 = acc[ai][bj][m][1] + b1;
;                     if (last) { __builtin_nontemporal_store(v0, (f32x4*)(out + off)); __builtin_nontemporal_store(v1, (f32x4*)(out + off + 4)); }
;                     else { q += sq4(v0) + sq4(v1); *(u32x4*)(xb + off) = pack8(v0, v1); }
;                 }
;                 if (!last) { q += shx(q, 16); q += shx(q, 32); if (fq == 0) ss[(size_t)row * 16 + u.pn * 4 + wc] = q; }
.LBB0_1081:
	v_lshl_or_b32 v168, s22, 8, v188
	v_lshl_add_u32 v172, s72, 8, v186
	v_ashrrev_i32_e32 v169, 31, v168
	v_lshlrev_b64 v[202:203], 1, v[168:169]
	v_ashrrev_i32_e32 v173, 31, v172
	v_lshl_add_u64 v[170:171], s[26:27], 0, v[202:203]
	v_lshlrev_b64 v[204:205], 11, v[172:173]
	v_lshl_add_u64 v[120:121], v[170:171], 0, v[204:205]
	global_load_dwordx4 v[192:195], v[120:121], off
	global_load_dwordx4 v[196:199], v[120:121], off offset:256
	v_or_b32_e32 v182, 16, v172
	v_ashrrev_i32_e32 v183, 31, v182
	v_or_b32_e32 v178, 32, v172
	v_lshlrev_b64 v[184:185], 11, v[182:183]
	v_ashrrev_i32_e32 v179, 31, v178
	v_or_b32_e32 v174, 48, v172
	v_lshl_add_u64 v[120:121], v[170:171], 0, v[184:185]
	v_lshlrev_b64 v[180:181], 11, v[178:179]
	v_ashrrev_i32_e32 v175, 31, v174
	global_load_dwordx4 v[148:151], v[120:121], off
	global_load_dwordx4 v[144:147], v[120:121], off offset:256
	v_lshl_add_u64 v[120:121], v[170:171], 0, v[180:181]
	v_lshlrev_b64 v[176:177], 11, v[174:175]
	global_load_dwordx4 v[140:143], v[120:121], off
	global_load_dwordx4 v[136:139], v[120:121], off offset:256
	v_lshl_add_u64 v[120:121], v[170:171], 0, v[176:177]
	global_load_dwordx4 v[132:135], v[120:121], off
	s_nop 0
	global_load_dwordx4 v[120:123], v[120:121], off offset:256
	s_lshl_b32 s50, s22, 2
	s_ashr_i32 s51, s50, 31
	s_waitcnt vmcnt(0)
	v_lshlrev_b32_e32 v206, 16, v192
	v_and_b32_e32 v207, 0xffff0000, v192
	v_lshlrev_b32_e32 v192, 16, v193
	v_and_b32_e32 v193, 0xffff0000, v193
	v_lshlrev_b32_e32 v208, 16, v194
	v_and_b32_e32 v209, 0xffff0000, v194
	v_lshlrev_b32_e32 v194, 16, v195
	v_and_b32_e32 v195, 0xffff0000, v195
	v_pk_add_f32 v[130:131], v[130:131], v[192:193]
	v_pk_add_f32 v[128:129], v[128:129], v[206:207]
	v_pk_add_f32 v[192:193], v[126:127], v[194:195]
	v_pk_add_f32 v[126:127], v[124:125], v[208:209]
	v_mul_f32_e32 v124, v129, v129
	v_mul_f32_e32 v125, v131, v131
	v_fmac_f32_e32 v124, v128, v128
	v_fmac_f32_e32 v125, v130, v130
	v_add_f32_e32 v124, v124, v125
	v_mul_f32_e32 v125, v127, v127
	v_mul_f32_e32 v194, v193, v193
	v_fmac_f32_e32 v125, v126, v126
	v_fmac_f32_e32 v194, v192, v192
	v_add_f32_e32 v125, v125, v194
	v_add_f32_e32 v194, v124, v125
	v_cvt_pk_bf16_f32 v124, v128, v129
	v_lshl_add_u64 v[128:129], s[26:27], 0, v[204:205]
	v_cvt_pk_bf16_f32 v125, v130, v131
	v_cvt_pk_bf16_f32 v126, v126, v127
	v_cvt_pk_bf16_f32 v127, v192, v193
	v_lshl_add_u64 v[128:129], v[128:129], 0, v[202:203]
	global_store_dwordx4 v[128:129], v[124:127], off
	v_lshlrev_b32_e32 v130, 16, v198
	v_and_b32_e32 v131, 0xffff0000, v198
	v_lshlrev_b32_e32 v124, 16, v196
	v_and_b32_e32 v125, 0xffff0000, v196
	v_lshlrev_b32_e32 v126, 16, v197
	v_and_b32_e32 v127, 0xffff0000, v197
	v_lshlrev_b32_e32 v192, 16, v199
	v_and_b32_e32 v193, 0xffff0000, v199
	v_pk_add_f32 v[118:119], v[118:119], v[126:127]
	v_pk_add_f32 v[116:117], v[116:117], v[124:125]
	v_pk_add_f32 v[124:125], v[114:115], v[192:193]
	v_pk_add_f32 v[114:115], v[112:113], v[130:131]
	v_mul_f32_e32 v112, v117, v117
	v_mul_f32_e32 v113, v119, v119
	v_fmac_f32_e32 v112, v116, v116
	v_fmac_f32_e32 v113, v118, v118
	v_add_f32_e32 v112, v112, v113
	v_mul_f32_e32 v113, v115, v115
	v_mul_f32_e32 v126, v125, v125
	v_fmac_f32_e32 v113, v114, v114
	v_fmac_f32_e32 v126, v124, v124
	v_add_f32_e32 v113, v113, v126
	v_add_f32_e32 v112, v112, v113
	v_add_f32_e32 v126, v194, v112
	v_cvt_pk_bf16_f32 v112, v116, v117
	v_cvt_pk_bf16_f32 v113, v118, v119
	v_cvt_pk_bf16_f32 v114, v114, v115
	v_cvt_pk_bf16_f32 v115, v124, v125
	global_store_dwordx4 v[128:129], v[112:115], off offset:256
	s_nop 1
	s_nop 0
	s_nop 2
	v_mov_b32_e32 v112, v126
	s_nop 1
	v_permlane16_swap_b32_e32 v112, v126
	s_waitcnt lgkmcnt(0)
	v_add_f32_e32 v112, v126, v112
	s_nop 1
	v_mov_b32_e32 v113, v112
	s_nop 1
	v_permlane32_swap_b32_e32 v113, v112
	s_and_saveexec_b64 s[52:53], s[16:17]
	s_cbranch_execz .LBB0_1083
	s_waitcnt lgkmcnt(0)
	v_add_f32_e32 v114, v112, v113
	v_lshlrev_b64 v[112:113], 6, v[172:173]
	v_lshl_add_u64 v[112:113], s[42:43], 0, v[112:113]
	v_lshl_add_u64 v[112:113], s[50:51], 2, v[112:113]
	s_lshl_b32 s22, s61, 2
	v_lshl_add_u64 v[112:113], v[112:113], 0, s[22:23]
	global_store_dword v[112:113], v114, off
.LBB0_1083:
	s_or_b64 exec, exec, s[52:53]
	v_lshlrev_b32_e32 v112, 16, v148
	s_waitcnt lgkmcnt(0)
	v_and_b32_e32 v113, 0xffff0000, v148
	v_lshlrev_b32_e32 v114, 16, v149
	v_and_b32_e32 v115, 0xffff0000, v149
	v_lshlrev_b32_e32 v116, 16, v150
	v_and_b32_e32 v117, 0xffff0000, v150
	v_lshlrev_b32_e32 v118, 16, v151
	v_and_b32_e32 v119, 0xffff0000, v151
	v_pk_add_f32 v[110:111], v[110:111], v[114:115]
	v_pk_add_f32 v[108:109], v[108:109], v[112:113]
	v_pk_add_f32 v[112:113], v[106:107], v[118:119]
	v_pk_add_f32 v[106:107], v[104:105], v[116:117]
	v_mul_f32_e32 v104, v109, v109
	v_mul_f32_e32 v105, v111, v111
	v_fmac_f32_e32 v104, v108, v108
	v_fmac_f32_e32 v105, v110, v110
	v_add_f32_e32 v104, v104, v105
	v_mul_f32_e32 v105, v107, v107
	v_mul_f32_e32 v114, v113, v113
	v_fmac_f32_e32 v105, v106, v106
	v_fmac_f32_e32 v114, v112, v112
	v_add_f32_e32 v105, v105, v114
	v_add_f32_e32 v114, v104, v105
	v_cvt_pk_bf16_f32 v104, v108, v109
	v_lshl_add_u64 v[108:109], s[26:27], 0, v[184:185]
	v_cvt_pk_bf16_f32 v105, v110, v111
	v_cvt_pk_bf16_f32 v106, v106, v107
	v_cvt_pk_bf16_f32 v107, v112, v113
	v_lshl_add_u64 v[108:109], v[168:169], 1, v[108:109]
	global_store_dwordx4 v[108:109], v[104:107], off
	v_lshlrev_b32_e32 v110, 16, v146
	v_and_b32_e32 v111, 0xffff0000, v146
	v_lshlrev_b32_e32 v104, 16, v144
	v_and_b32_e32 v105, 0xffff0000, v144
	v_lshlrev_b32_e32 v106, 16, v145
	v_and_b32_e32 v107, 0xffff0000, v145
	v_lshlrev_b32_e32 v112, 16, v147
	v_and_b32_e32 v113, 0xffff0000, v147
	v_pk_add_f32 v[102:103], v[102:103], v[106:107]
	v_pk_add_f32 v[100:101], v[100:101], v[104:105]
	v_pk_add_f32 v[104:105], v[98:99], v[112:113]
	v_pk_add_f32 v[98:99], v[96:97], v[110:111]
	v_mul_f32_e32 v96, v101, v101
	v_mul_f32_e32 v97, v103, v103
	v_fmac_f32_e32 v96, v100, v100
	v_fmac_f32_e32 v97, v102, v102
	v_add_f32_e32 v96, v96, v97
	v_mul_f32_e32 v97, v99, v99
	v_mul_f32_e32 v106, v105, v105
	v_fmac_f32_e32 v97, v98, v98
	v_fmac_f32_e32 v106, v104, v104
	v_add_f32_e32 v97, v97, v106
	v_add_f32_e32 v96, v96, v97
	v_add_f32_e32 v106, v114, v96
	v_cvt_pk_bf16_f32 v96, v100, v101
	v_cvt_pk_bf16_f32 v97, v102, v103
	v_cvt_pk_bf16_f32 v98, v98, v99
	v_cvt_pk_bf16_f32 v99, v104, v105
	global_store_dwordx4 v[108:109], v[96:99], off offset:256
	s_nop 1
	s_nop 0
	s_nop 2
	v_mov_b32_e32 v96, v106
	s_nop 1
	v_permlane16_swap_b32_e32 v96, v106
	s_waitcnt lgkmcnt(0)
	v_add_f32_e32 v96, v106, v96
	s_nop 1
	v_mov_b32_e32 v97, v96
	s_nop 1
	v_permlane32_swap_b32_e32 v97, v96
	s_and_saveexec_b64 s[52:53], s[16:17]
	s_cbranch_execz .LBB0_1085
	s_waitcnt lgkmcnt(0)
	v_add_f32_e32 v98, v96, v97
	v_lshlrev_b64 v[96:97], 6, v[182:183]
	v_lshl_add_u64 v[96:97], s[42:43], 0, v[96:97]
	v_lshl_add_u64 v[96:97], s[50:51], 2, v[96:97]
	s_lshl_b32 s22, s61, 2
	v_lshl_add_u64 v[96:97], v[96:97], 0, s[22:23]
	global_store_dword v[96:97], v98, off
; __device__ __forceinline__ float sq4(f32x4 v) { return (v[0] * v[0] + v[1] * v[1]) + (v[2] * v[2] + v[3] * v[3]); }
; __device__ __forceinline__ u32x4 pack8(f32x4 a, f32x4 b) { u32x4 w; w.x = cvt_pk_bf16(a[0], a[1]); w.y = cvt_pk_bf16(a[2], a[3]); w.z = cvt_pk_bf16(b[0], b[1]); w.w = cvt_pk_bf16(b[2], b[3]); return w; }
;     __device__ __forceinline__ void operator()(const f32x4 (&acc)[2][2][4][2], const Unit& u, int wr, int wc, int fr, int fq) const {
;     ...
;             for (int m = 0; m < 4; ++m) {
;                 const int row = u.pm * BM + ai * HALF + wr * 64 + m * 16 + fr;
;                 float q = 0.f;
; #pragma unroll
;                 for (int bj = 0; bj < 2; ++bj) {
;                     const size_t off = (size_t)row * 1024 + col0 + 128 * bj; const u32x4 w = bs[m][bj];
;                     const f32x4 b0 = (f32x4){__builtin_bit_cast(float, w.x << 16), __builtin_bit_cast(float, w.x & 0xffff0000u), __builtin_bit_cast(float, w.y << 16), __builtin_bit_cast(float, w.y & 0xffff0000u)};
;                     const f32x4 b1 = (f32x4){__builtin_bit_cast(float, w.z << 16), __builtin_bit_cast(float, w.z & 0xffff0000u), __builtin_bit_cast(float, w.w << 16), __builtin_bit_cast(float, w.w & 0xffff0000u)};
;                     const f32x4 v0 = acc[ai][bj][m][0] + b0, v1 = acc[ai][bj][m][1] + b1;
;                     if (last) { __builtin_nontemporal_store(v0, (f32x4*)(out + off)); __builtin_nontemporal_store(v1, (f32x4*)(out + off + 4)); }
;                     else { q += sq4(v0) + sq4(v1); *(u32x4*)(xb + off) = pack8(v0, v1); }
;                 }
;                 if (!last) { q += shx(q, 16); q += shx(q, 32); if (fq == 0) ss[(size_t)row * 16 + u.pn * 4 + wc] = q; }
.LBB0_1085:
	s_or_b64 exec, exec, s[52:53]
	v_lshlrev_b32_e32 v96, 16, v140
	s_waitcnt lgkmcnt(0)
	v_and_b32_e32 v97, 0xffff0000, v140
	v_lshlrev_b32_e32 v98, 16, v141
	v_and_b32_e32 v99, 0xffff0000, v141
	v_lshlrev_b32_e32 v100, 16, v142
	v_and_b32_e32 v101, 0xffff0000, v142
	v_lshlrev_b32_e32 v102, 16, v143
	v_and_b32_e32 v103, 0xffff0000, v143
	v_pk_add_f32 v[94:95], v[94:95], v[98:99]
	v_pk_add_f32 v[92:93], v[92:93], v[96:97]
	v_pk_add_f32 v[96:97], v[90:91], v[102:103]
	v_pk_add_f32 v[90:91], v[88:89], v[100:101]
	v_mul_f32_e32 v88, v93, v93
	v_mul_f32_e32 v89, v95, v95
	v_fmac_f32_e32 v88, v92, v92
	v_fmac_f32_e32 v89, v94, v94
	v_add_f32_e32 v88, v88, v89
	v_mul_f32_e32 v89, v91, v91
	v_mul_f32_e32 v98, v97, v97
	v_fmac_f32_e32 v89, v90, v90
	v_fmac_f32_e32 v98, v96, v96
	v_add_f32_e32 v89, v89, v98
	v_add_f32_e32 v98, v88, v89
	v_cvt_pk_bf16_f32 v88, v92, v93
	v_lshl_add_u64 v[92:93], s[26:27], 0, v[180:181]
	v_cvt_pk_bf16_f32 v89, v94, v95
	v_cvt_pk_bf16_f32 v90, v90, v91
	v_cvt_pk_bf16_f32 v91, v96, v97
	v_lshl_add_u64 v[92:93], v[168:169], 1, v[92:93]
	global_store_dwordx4 v[92:93], v[88:91], off
	v_lshlrev_b32_e32 v94, 16, v138
	v_and_b32_e32 v95, 0xffff0000, v138
	v_lshlrev_b32_e32 v88, 16, v136
	v_and_b32_e32 v89, 0xffff0000, v136
	v_lshlrev_b32_e32 v90, 16, v137
	v_and_b32_e32 v91, 0xffff0000, v137
	v_lshlrev_b32_e32 v96, 16, v139
	v_and_b32_e32 v97, 0xffff0000, v139
	v_pk_add_f32 v[86:87], v[86:87], v[90:91]
	v_pk_add_f32 v[84:85], v[84:85], v[88:89]
	v_pk_add_f32 v[88:89], v[82:83], v[96:97]
	v_pk_add_f32 v[82:83], v[80:81], v[94:95]
	v_mul_f32_e32 v80, v85, v85
	v_mul_f32_e32 v81, v87, v87
	v_fmac_f32_e32 v80, v84, v84
	v_fmac_f32_e32 v81, v86, v86
	v_add_f32_e32 v80, v80, v81
	v_mul_f32_e32 v81, v83, v83
	v_mul_f32_e32 v90, v89, v89
	v_fmac_f32_e32 v81, v82, v82
	v_fmac_f32_e32 v90, v88, v88
	v_add_f32_e32 v81, v81, v90
	v_add_f32_e32 v80, v80, v81
	v_add_f32_e32 v90, v98, v80
	v_cvt_pk_bf16_f32 v80, v84, v85
	v_cvt_pk_bf16_f32 v81, v86, v87
	v_cvt_pk_bf16_f32 v82, v82, v83
	v_cvt_pk_bf16_f32 v83, v88, v89
	global_store_dwordx4 v[92:93], v[80:83], off offset:256
	s_nop 1
	s_nop 0
	s_nop 2
	v_mov_b32_e32 v80, v90
	s_nop 1
	v_permlane16_swap_b32_e32 v80, v90
	s_waitcnt lgkmcnt(0)
	v_add_f32_e32 v80, v90, v80
	s_nop 1
	v_mov_b32_e32 v81, v80
	s_nop 1
	v_permlane32_swap_b32_e32 v81, v80
	s_and_saveexec_b64 s[52:53], s[16:17]
	s_cbranch_execz .LBB0_1087
	s_waitcnt lgkmcnt(0)
	v_add_f32_e32 v82, v80, v81
	v_lshlrev_b64 v[80:81], 6, v[178:179]
	v_lshl_add_u64 v[80:81], s[42:43], 0, v[80:81]
	v_lshl_add_u64 v[80:81], s[50:51], 2, v[80:81]
	s_lshl_b32 s22, s61, 2
	v_lshl_add_u64 v[80:81], v[80:81], 0, s[22:23]
	global_store_dword v[80:81], v82, off
.LBB0_1087:
	s_or_b64 exec, exec, s[52:53]
	v_lshlrev_b32_e32 v80, 16, v132
	s_waitcnt lgkmcnt(0)
	v_and_b32_e32 v81, 0xffff0000, v132
	v_lshlrev_b32_e32 v82, 16, v133
	v_and_b32_e32 v83, 0xffff0000, v133
	v_lshlrev_b32_e32 v84, 16, v134
	v_and_b32_e32 v85, 0xffff0000, v134
	v_lshlrev_b32_e32 v86, 16, v135
	v_and_b32_e32 v87, 0xffff0000, v135
	v_pk_add_f32 v[78:79], v[78:79], v[82:83]
	v_pk_add_f32 v[76:77], v[76:77], v[80:81]
	v_pk_add_f32 v[80:81], v[74:75], v[86:87]
	v_pk_add_f32 v[74:75], v[72:73], v[84:85]
	v_mul_f32_e32 v72, v77, v77
	v_mul_f32_e32 v73, v79, v79
	v_fmac_f32_e32 v72, v76, v76
	v_fmac_f32_e32 v73, v78, v78
	v_add_f32_e32 v72, v72, v73
	v_mul_f32_e32 v73, v75, v75
	v_mul_f32_e32 v82, v81, v81
	v_fmac_f32_e32 v73, v74, v74
	v_fmac_f32_e32 v82, v80, v80
	v_add_f32_e32 v73, v73, v82
	v_add_f32_e32 v82, v72, v73
	v_cvt_pk_bf16_f32 v72, v76, v77
	v_lshl_add_u64 v[76:77], s[26:27], 0, v[176:177]
	v_cvt_pk_bf16_f32 v73, v78, v79
	v_cvt_pk_bf16_f32 v74, v74, v75
	v_cvt_pk_bf16_f32 v75, v80, v81
	v_lshl_add_u64 v[76:77], v[168:169], 1, v[76:77]
	global_store_dwordx4 v[76:77], v[72:75], off
	v_lshlrev_b32_e32 v78, 16, v122
	v_and_b32_e32 v79, 0xffff0000, v122
	v_lshlrev_b32_e32 v72, 16, v120
	v_and_b32_e32 v73, 0xffff0000, v120
	v_lshlrev_b32_e32 v74, 16, v121
	v_and_b32_e32 v75, 0xffff0000, v121
	v_lshlrev_b32_e32 v80, 16, v123
	v_and_b32_e32 v81, 0xffff0000, v123
	v_pk_add_f32 v[70:71], v[70:71], v[74:75]
	v_pk_add_f32 v[68:69], v[68:69], v[72:73]
	v_pk_add_f32 v[72:73], v[66:67], v[80:81]
	v_pk_add_f32 v[66:67], v[64:65], v[78:79]
	v_mul_f32_e32 v64, v69, v69
	v_mul_f32_e32 v65, v71, v71
	v_fmac_f32_e32 v64, v68, v68
	v_fmac_f32_e32 v65, v70, v70
	v_add_f32_e32 v64, v64, v65
	v_mul_f32_e32 v65, v67, v67
	v_mul_f32_e32 v74, v73, v73
	v_fmac_f32_e32 v65, v66, v66
	v_fmac_f32_e32 v74, v72, v72
	v_add_f32_e32 v65, v65, v74
	v_add_f32_e32 v64, v64, v65
	v_add_f32_e32 v74, v82, v64
	v_cvt_pk_bf16_f32 v64, v68, v69
	v_cvt_pk_bf16_f32 v65, v70, v71
	v_cvt_pk_bf16_f32 v66, v66, v67
	v_cvt_pk_bf16_f32 v67, v72, v73
	global_store_dwordx4 v[76:77], v[64:67], off offset:256
	s_nop 1
	s_nop 0
	s_nop 2
	v_mov_b32_e32 v64, v74
	s_nop 1
	v_permlane16_swap_b32_e32 v64, v74
	s_waitcnt lgkmcnt(0)
	v_add_f32_e32 v64, v74, v64
	s_nop 1
	v_mov_b32_e32 v65, v64
	s_nop 1
	v_permlane32_swap_b32_e32 v65, v64
	s_and_saveexec_b64 s[52:53], s[16:17]
	s_cbranch_execz .LBB0_1089
	s_waitcnt lgkmcnt(0)
	v_add_f32_e32 v66, v64, v65
	v_lshlrev_b64 v[64:65], 6, v[174:175]
	v_lshl_add_u64 v[64:65], s[42:43], 0, v[64:65]
	v_lshl_add_u64 v[64:65], s[50:51], 2, v[64:65]
	s_lshl_b32 s22, s61, 2
	v_lshl_add_u64 v[64:65], v[64:65], 0, s[22:23]
	global_store_dword v[64:65], v66, off
; __device__ __forceinline__ float sq4(f32x4 v) { return (v[0] * v[0] + v[1] * v[1]) + (v[2] * v[2] + v[3] * v[3]); }
; __device__ __forceinline__ u32x4 pack8(f32x4 a, f32x4 b) { u32x4 w; w.x = cvt_pk_bf16(a[0], a[1]); w.y = cvt_pk_bf16(a[2], a[3]); w.z = cvt_pk_bf16(b[0], b[1]); w.w = cvt_pk_bf16(b[2], b[3]); return w; }
;     __device__ __forceinline__ void operator()(const f32x4 (&acc)[2][2][4][2], const Unit& u, int wr, int wc, int fr, int fq) const {
;     ...
;         for (int ai = 0; ai < 2; ++ai) {
;             u32x4 bs[4][2];
; #pragma unroll
;             for (int m = 0; m < 4; ++m)
; #pragma unroll
;                 for (int bj = 0; bj < 2; ++bj) bs[m][bj] = *(const u32x4*)(xb + (size_t)(u.pm * BM + ai * HALF + wr * 64 + m * 16 + fr) * 1024 + col0 + 128 * bj);
; #pragma unroll
;             for (int m = 0; m < 4; ++m) {
;                 const int row = u.pm * BM + ai * HALF + wr * 64 + m * 16 + fr;
;                 float q = 0.f;
; #pragma unroll
;                 for (int bj = 0; bj < 2; ++bj) {
;                     const size_t off = (size_t)row * 1024 + col0 + 128 * bj; const u32x4 w = bs[m][bj];
;                     const f32x4 b0 = (f32x4){__builtin_bit_cast(float, w.x << 16), __builtin_bit_cast(float, w.x & 0xffff0000u), __builtin_bit_cast(float, w.y << 16), __builtin_bit_cast(float, w.y & 0xffff0000u)};
;                     const f32x4 b1 = (f32x4){__builtin_bit_cast(float, w.z << 16), __builtin_bit_cast(float, w.z & 0xffff0000u), __builtin_bit_cast(float, w.w << 16), __builtin_bit_cast(float, w.w & 0xffff0000u)};
;                     const f32x4 v0 = acc[ai][bj][m][0] + b0, v1 = acc[ai][bj][m][1] + b1;
;                     if (last) { __builtin_nontemporal_store(v0, (f32x4*)(out + off)); __builtin_nontemporal_store(v1, (f32x4*)(out + off + 4)); }
;                     else { q += sq4(v0) + sq4(v1); *(u32x4*)(xb + off) = pack8(v0, v1); }
;                 }
;                 if (!last) { q += shx(q, 16); q += shx(q, 32); if (fq == 0) ss[(size_t)row * 16 + u.pn * 4 + wc] = q; }
.LBB0_1089:
	s_or_b64 exec, exec, s[52:53]
	v_add_u32_e32 v100, 0x80, v172
	v_ashrrev_i32_e32 v101, 31, v100
	v_lshlrev_b64 v[110:111], 11, v[100:101]
	s_waitcnt lgkmcnt(0)
	v_lshl_add_u64 v[64:65], v[170:171], 0, v[110:111]
	global_load_dwordx4 v[102:105], v[64:65], off
	global_load_dwordx4 v[106:109], v[64:65], off offset:256
	v_add_u32_e32 v96, 0x90, v172
	v_ashrrev_i32_e32 v97, 31, v96
	v_add_u32_e32 v92, 0xa0, v172
	v_lshlrev_b64 v[98:99], 11, v[96:97]
	v_ashrrev_i32_e32 v93, 31, v92
	v_add_u32_e32 v88, 0xb0, v172
	v_lshl_add_u64 v[64:65], v[170:171], 0, v[98:99]
	v_lshlrev_b64 v[94:95], 11, v[92:93]
	v_ashrrev_i32_e32 v89, 31, v88
	global_load_dwordx4 v[84:87], v[64:65], off
	global_load_dwordx4 v[80:83], v[64:65], off offset:256
	v_lshl_add_u64 v[64:65], v[170:171], 0, v[94:95]
	v_lshlrev_b64 v[90:91], 11, v[88:89]
	global_load_dwordx4 v[76:79], v[64:65], off
	global_load_dwordx4 v[72:75], v[64:65], off offset:256
	v_lshl_add_u64 v[64:65], v[170:171], 0, v[90:91]
	global_load_dwordx4 v[68:71], v[64:65], off
	s_nop 0
	global_load_dwordx4 v[64:67], v[64:65], off offset:256
	s_waitcnt vmcnt(7)
	v_lshlrev_b32_e32 v112, 16, v102
	v_and_b32_e32 v113, 0xffff0000, v102
	v_lshlrev_b32_e32 v102, 16, v103
	v_and_b32_e32 v103, 0xffff0000, v103
	v_lshlrev_b32_e32 v114, 16, v104
	v_and_b32_e32 v115, 0xffff0000, v104
	v_lshlrev_b32_e32 v104, 16, v105
	v_and_b32_e32 v105, 0xffff0000, v105
	v_pk_add_f32 v[62:63], v[62:63], v[102:103]
	v_pk_add_f32 v[60:61], v[60:61], v[112:113]
	v_pk_add_f32 v[102:103], v[58:59], v[104:105]
	v_pk_add_f32 v[58:59], v[56:57], v[114:115]
	v_mul_f32_e32 v56, v61, v61
	v_mul_f32_e32 v57, v63, v63
	v_fmac_f32_e32 v56, v60, v60
	v_fmac_f32_e32 v57, v62, v62
	v_add_f32_e32 v56, v56, v57
	v_mul_f32_e32 v57, v59, v59
	v_mul_f32_e32 v104, v103, v103
	v_fmac_f32_e32 v57, v58, v58
	v_fmac_f32_e32 v104, v102, v102
	v_add_f32_e32 v57, v57, v104
	v_add_f32_e32 v104, v56, v57
	v_cvt_pk_bf16_f32 v56, v60, v61
	v_lshl_add_u64 v[60:61], s[26:27], 0, v[110:111]
	v_cvt_pk_bf16_f32 v57, v62, v63
	v_cvt_pk_bf16_f32 v58, v58, v59
	v_cvt_pk_bf16_f32 v59, v102, v103
	v_lshl_add_u64 v[60:61], v[168:169], 1, v[60:61]
	global_store_dwordx4 v[60:61], v[56:59], off
	s_waitcnt vmcnt(7)
	v_lshlrev_b32_e32 v62, 16, v108
	v_and_b32_e32 v63, 0xffff0000, v108
	v_lshlrev_b32_e32 v56, 16, v106
	v_and_b32_e32 v57, 0xffff0000, v106
	v_lshlrev_b32_e32 v58, 16, v107
	v_and_b32_e32 v59, 0xffff0000, v107
	v_lshlrev_b32_e32 v102, 16, v109
	v_and_b32_e32 v103, 0xffff0000, v109
	v_pk_add_f32 v[54:55], v[54:55], v[58:59]
	v_pk_add_f32 v[52:53], v[52:53], v[56:57]
	v_pk_add_f32 v[56:57], v[50:51], v[102:103]
	v_pk_add_f32 v[50:51], v[48:49], v[62:63]
	v_mul_f32_e32 v48, v53, v53
	v_mul_f32_e32 v49, v55, v55
	v_fmac_f32_e32 v48, v52, v52
	v_fmac_f32_e32 v49, v54, v54
	v_add_f32_e32 v48, v48, v49
	v_mul_f32_e32 v49, v51, v51
	v_mul_f32_e32 v58, v57, v57
	v_fmac_f32_e32 v49, v50, v50
	v_fmac_f32_e32 v58, v56, v56
	v_add_f32_e32 v49, v49, v58
	v_add_f32_e32 v48, v48, v49
	v_add_f32_e32 v58, v104, v48
	v_cvt_pk_bf16_f32 v48, v52, v53
	v_cvt_pk_bf16_f32 v49, v54, v55
	v_cvt_pk_bf16_f32 v50, v50, v51
	v_cvt_pk_bf16_f32 v51, v56, v57
	global_store_dwordx4 v[60:61], v[48:51], off offset:256
	s_nop 1
	s_nop 0
	s_nop 2
	v_mov_b32_e32 v48, v58
	s_nop 1
	v_permlane16_swap_b32_e32 v48, v58
	s_waitcnt lgkmcnt(0)
	v_add_f32_e32 v48, v58, v48
	s_nop 1
	v_mov_b32_e32 v49, v48
	s_nop 1
	v_permlane32_swap_b32_e32 v49, v48
	s_and_saveexec_b64 s[52:53], s[16:17]
	s_cbranch_execz .LBB0_1091
	s_waitcnt lgkmcnt(0)
	v_add_f32_e32 v50, v48, v49
	v_lshlrev_b64 v[48:49], 6, v[100:101]
	v_lshl_add_u64 v[48:49], s[42:43], 0, v[48:49]
	v_lshl_add_u64 v[48:49], s[50:51], 2, v[48:49]
	s_lshl_b32 s22, s61, 2
	v_lshl_add_u64 v[48:49], v[48:49], 0, s[22:23]
	global_store_dword v[48:49], v50, off
.LBB0_1091:
	s_or_b64 exec, exec, s[52:53]
	s_waitcnt vmcnt(7)
	v_lshlrev_b32_e32 v48, 16, v84
	s_waitcnt lgkmcnt(0)
	v_and_b32_e32 v49, 0xffff0000, v84
	v_lshlrev_b32_e32 v50, 16, v85
	v_and_b32_e32 v51, 0xffff0000, v85
	v_lshlrev_b32_e32 v52, 16, v86
	v_and_b32_e32 v53, 0xffff0000, v86
	v_lshlrev_b32_e32 v54, 16, v87
	v_and_b32_e32 v55, 0xffff0000, v87
	v_pk_add_f32 v[46:47], v[46:47], v[50:51]
	v_pk_add_f32 v[44:45], v[44:45], v[48:49]
	v_pk_add_f32 v[48:49], v[42:43], v[54:55]
	v_pk_add_f32 v[42:43], v[40:41], v[52:53]
	v_mul_f32_e32 v40, v45, v45
	v_mul_f32_e32 v41, v47, v47
	v_fmac_f32_e32 v40, v44, v44
	v_fmac_f32_e32 v41, v46, v46
	v_add_f32_e32 v40, v40, v41
	v_mul_f32_e32 v41, v43, v43
	v_mul_f32_e32 v50, v49, v49
	v_fmac_f32_e32 v41, v42, v42
	v_fmac_f32_e32 v50, v48, v48
	v_add_f32_e32 v41, v41, v50
	v_add_f32_e32 v50, v40, v41
	v_cvt_pk_bf16_f32 v40, v44, v45
	v_lshl_add_u64 v[44:45], s[26:27], 0, v[98:99]
	v_cvt_pk_bf16_f32 v41, v46, v47
	v_cvt_pk_bf16_f32 v42, v42, v43
	v_cvt_pk_bf16_f32 v43, v48, v49
	v_lshl_add_u64 v[44:45], v[168:169], 1, v[44:45]
	global_store_dwordx4 v[44:45], v[40:43], off
	s_waitcnt vmcnt(7)
	v_lshlrev_b32_e32 v46, 16, v82
	v_and_b32_e32 v47, 0xffff0000, v82
	v_lshlrev_b32_e32 v40, 16, v80
	v_and_b32_e32 v41, 0xffff0000, v80
	v_lshlrev_b32_e32 v42, 16, v81
	v_and_b32_e32 v43, 0xffff0000, v81
	v_lshlrev_b32_e32 v48, 16, v83
	v_and_b32_e32 v49, 0xffff0000, v83
	v_pk_add_f32 v[38:39], v[38:39], v[42:43]
	v_pk_add_f32 v[36:37], v[36:37], v[40:41]
	v_pk_add_f32 v[40:41], v[34:35], v[48:49]
	v_pk_add_f32 v[34:35], v[32:33], v[46:47]
	v_mul_f32_e32 v32, v37, v37
	v_mul_f32_e32 v33, v39, v39
	v_fmac_f32_e32 v32, v36, v36
	v_fmac_f32_e32 v33, v38, v38
	v_add_f32_e32 v32, v32, v33
	v_mul_f32_e32 v33, v35, v35
	v_mul_f32_e32 v42, v41, v41
	v_fmac_f32_e32 v33, v34, v34
	v_fmac_f32_e32 v42, v40, v40
	v_add_f32_e32 v33, v33, v42
	v_add_f32_e32 v32, v32, v33
	v_add_f32_e32 v42, v50, v32
	v_cvt_pk_bf16_f32 v32, v36, v37
	v_cvt_pk_bf16_f32 v33, v38, v39
	v_cvt_pk_bf16_f32 v34, v34, v35
	v_cvt_pk_bf16_f32 v35, v40, v41
	global_store_dwordx4 v[44:45], v[32:35], off offset:256
	s_nop 1
	s_nop 0
	s_nop 2
	v_mov_b32_e32 v32, v42
	s_nop 1
	v_permlane16_swap_b32_e32 v32, v42
	s_waitcnt lgkmcnt(0)
	v_add_f32_e32 v32, v42, v32
	s_nop 1
	v_mov_b32_e32 v33, v32
	s_nop 1
	v_permlane32_swap_b32_e32 v33, v32
	s_and_saveexec_b64 s[52:53], s[16:17]
	s_cbranch_execz .LBB0_1093
	s_waitcnt lgkmcnt(0)
	v_add_f32_e32 v34, v32, v33
	v_lshlrev_b64 v[32:33], 6, v[96:97]
	v_lshl_add_u64 v[32:33], s[42:43], 0, v[32:33]
	v_lshl_add_u64 v[32:33], s[50:51], 2, v[32:33]
	s_lshl_b32 s22, s61, 2
	v_lshl_add_u64 v[32:33], v[32:33], 0, s[22:23]
	global_store_dword v[32:33], v34, off
; __device__ __forceinline__ float sq4(f32x4 v) { return (v[0] * v[0] + v[1] * v[1]) + (v[2] * v[2] + v[3] * v[3]); }
; __device__ __forceinline__ u32x4 pack8(f32x4 a, f32x4 b) { u32x4 w; w.x = cvt_pk_bf16(a[0], a[1]); w.y = cvt_pk_bf16(a[2], a[3]); w.z = cvt_pk_bf16(b[0], b[1]); w.w = cvt_pk_bf16(b[2], b[3]); return w; }
;     __device__ __forceinline__ void operator()(const f32x4 (&acc)[2][2][4][2], const Unit& u, int wr, int wc, int fr, int fq) const {
;     ...
;             for (int m = 0; m < 4; ++m) {
;                 const int row = u.pm * BM + ai * HALF + wr * 64 + m * 16 + fr;
;                 float q = 0.f;
; #pragma unroll
;                 for (int bj = 0; bj < 2; ++bj) {
;                     const size_t off = (size_t)row * 1024 + col0 + 128 * bj; const u32x4 w = bs[m][bj];
;                     const f32x4 b0 = (f32x4){__builtin_bit_cast(float, w.x << 16), __builtin_bit_cast(float, w.x & 0xffff0000u), __builtin_bit_cast(float, w.y << 16), __builtin_bit_cast(float, w.y & 0xffff0000u)};
;                     const f32x4 b1 = (f32x4){__builtin_bit_cast(float, w.z << 16), __builtin_bit_cast(float, w.z & 0xffff0000u), __builtin_bit_cast(float, w.w << 16), __builtin_bit_cast(float, w.w & 0xffff0000u)};
;                     const f32x4 v0 = acc[ai][bj][m][0] + b0, v1 = acc[ai][bj][m][1] + b1;
;                     if (last) { __builtin_nontemporal_store(v0, (f32x4*)(out + off)); __builtin_nontemporal_store(v1, (f32x4*)(out + off + 4)); }
;                     else { q += sq4(v0) + sq4(v1); *(u32x4*)(xb + off) = pack8(v0, v1); }
;                 }
;                 if (!last) { q += shx(q, 16); q += shx(q, 32); if (fq == 0) ss[(size_t)row * 16 + u.pn * 4 + wc] = q; }
.LBB0_1093:
	s_or_b64 exec, exec, s[52:53]
	s_waitcnt vmcnt(7)
	v_lshlrev_b32_e32 v32, 16, v76
	s_waitcnt lgkmcnt(0)
	v_and_b32_e32 v33, 0xffff0000, v76
	v_lshlrev_b32_e32 v34, 16, v77
	v_and_b32_e32 v35, 0xffff0000, v77
	v_lshlrev_b32_e32 v36, 16, v78
	v_and_b32_e32 v37, 0xffff0000, v78
	v_lshlrev_b32_e32 v38, 16, v79
	v_and_b32_e32 v39, 0xffff0000, v79
	v_pk_add_f32 v[30:31], v[30:31], v[34:35]
	v_pk_add_f32 v[28:29], v[28:29], v[32:33]
	v_pk_add_f32 v[32:33], v[26:27], v[38:39]
	v_pk_add_f32 v[26:27], v[24:25], v[36:37]
	v_mul_f32_e32 v24, v29, v29
	v_mul_f32_e32 v25, v31, v31
	v_fmac_f32_e32 v24, v28, v28
	v_fmac_f32_e32 v25, v30, v30
	v_add_f32_e32 v24, v24, v25
	v_mul_f32_e32 v25, v27, v27
	v_mul_f32_e32 v34, v33, v33
	v_fmac_f32_e32 v25, v26, v26
	v_fmac_f32_e32 v34, v32, v32
	v_add_f32_e32 v25, v25, v34
	v_add_f32_e32 v34, v24, v25
	v_cvt_pk_bf16_f32 v24, v28, v29
	v_lshl_add_u64 v[28:29], s[26:27], 0, v[94:95]
	v_cvt_pk_bf16_f32 v25, v30, v31
	v_cvt_pk_bf16_f32 v26, v26, v27
	v_cvt_pk_bf16_f32 v27, v32, v33
	v_lshl_add_u64 v[28:29], v[168:169], 1, v[28:29]
	global_store_dwordx4 v[28:29], v[24:27], off
	s_waitcnt vmcnt(7)
	v_lshlrev_b32_e32 v30, 16, v74
	v_and_b32_e32 v31, 0xffff0000, v74
	v_lshlrev_b32_e32 v24, 16, v72
	v_and_b32_e32 v25, 0xffff0000, v72
	v_lshlrev_b32_e32 v26, 16, v73
	v_and_b32_e32 v27, 0xffff0000, v73
	v_lshlrev_b32_e32 v32, 16, v75
	v_and_b32_e32 v33, 0xffff0000, v75
	v_pk_add_f32 v[22:23], v[22:23], v[26:27]
	v_pk_add_f32 v[20:21], v[20:21], v[24:25]
	v_pk_add_f32 v[24:25], v[18:19], v[32:33]
	v_pk_add_f32 v[18:19], v[16:17], v[30:31]
	v_mul_f32_e32 v16, v21, v21
	v_mul_f32_e32 v17, v23, v23
	v_fmac_f32_e32 v16, v20, v20
	v_fmac_f32_e32 v17, v22, v22
	v_add_f32_e32 v16, v16, v17
	v_mul_f32_e32 v17, v19, v19
	v_mul_f32_e32 v26, v25, v25
	v_fmac_f32_e32 v17, v18, v18
	v_fmac_f32_e32 v26, v24, v24
	v_add_f32_e32 v17, v17, v26
	v_add_f32_e32 v16, v16, v17
	v_add_f32_e32 v26, v34, v16
	v_cvt_pk_bf16_f32 v16, v20, v21
	v_cvt_pk_bf16_f32 v17, v22, v23
	v_cvt_pk_bf16_f32 v18, v18, v19
	v_cvt_pk_bf16_f32 v19, v24, v25
	global_store_dwordx4 v[28:29], v[16:19], off offset:256
	s_nop 1
	s_nop 0
	s_nop 2
	v_mov_b32_e32 v16, v26
	s_nop 1
	v_permlane16_swap_b32_e32 v16, v26
	s_waitcnt lgkmcnt(0)
	v_add_f32_e32 v16, v26, v16
	s_nop 1
	v_mov_b32_e32 v17, v16
	s_nop 1
	v_permlane32_swap_b32_e32 v17, v16
	s_and_saveexec_b64 s[52:53], s[16:17]
	s_cbranch_execz .LBB0_1095
	s_waitcnt lgkmcnt(0)
	v_add_f32_e32 v18, v16, v17
	v_lshlrev_b64 v[16:17], 6, v[92:93]
	v_lshl_add_u64 v[16:17], s[42:43], 0, v[16:17]
	v_lshl_add_u64 v[16:17], s[50:51], 2, v[16:17]
	s_lshl_b32 s22, s61, 2
	v_lshl_add_u64 v[16:17], v[16:17], 0, s[22:23]
	global_store_dword v[16:17], v18, off
.LBB0_1095:
	s_or_b64 exec, exec, s[52:53]
	s_waitcnt vmcnt(7)
	v_lshlrev_b32_e32 v16, 16, v68
	s_waitcnt lgkmcnt(0)
	v_and_b32_e32 v17, 0xffff0000, v68
	v_lshlrev_b32_e32 v18, 16, v69
	v_and_b32_e32 v19, 0xffff0000, v69
	v_lshlrev_b32_e32 v20, 16, v70
	v_and_b32_e32 v21, 0xffff0000, v70
	v_lshlrev_b32_e32 v22, 16, v71
	v_and_b32_e32 v23, 0xffff0000, v71
	v_pk_add_f32 v[14:15], v[14:15], v[18:19]
	v_pk_add_f32 v[12:13], v[12:13], v[16:17]
	v_pk_add_f32 v[16:17], v[10:11], v[22:23]
	v_pk_add_f32 v[10:11], v[8:9], v[20:21]
	v_mul_f32_e32 v8, v13, v13
	v_mul_f32_e32 v9, v15, v15
	v_fmac_f32_e32 v8, v12, v12
	v_fmac_f32_e32 v9, v14, v14
	v_add_f32_e32 v8, v8, v9
	v_mul_f32_e32 v9, v11, v11
	v_mul_f32_e32 v18, v17, v17
	v_fmac_f32_e32 v9, v10, v10
	v_fmac_f32_e32 v18, v16, v16
	v_add_f32_e32 v9, v9, v18
	v_add_f32_e32 v18, v8, v9
	v_cvt_pk_bf16_f32 v8, v12, v13
	v_lshl_add_u64 v[12:13], s[26:27], 0, v[90:91]
	v_cvt_pk_bf16_f32 v9, v14, v15
	v_cvt_pk_bf16_f32 v10, v10, v11
	v_cvt_pk_bf16_f32 v11, v16, v17
	v_lshl_add_u64 v[12:13], v[168:169], 1, v[12:13]
	global_store_dwordx4 v[12:13], v[8:11], off
	s_waitcnt vmcnt(7)
	v_lshlrev_b32_e32 v14, 16, v66
	v_and_b32_e32 v15, 0xffff0000, v66
	v_lshlrev_b32_e32 v8, 16, v64
	v_and_b32_e32 v9, 0xffff0000, v64
	v_lshlrev_b32_e32 v10, 16, v65
	v_and_b32_e32 v11, 0xffff0000, v65
	v_lshlrev_b32_e32 v16, 16, v67
	v_and_b32_e32 v17, 0xffff0000, v67
	v_pk_add_f32 v[6:7], v[6:7], v[10:11]
	v_pk_add_f32 v[4:5], v[4:5], v[8:9]
	v_pk_add_f32 v[8:9], v[2:3], v[16:17]
	v_pk_add_f32 v[2:3], v[0:1], v[14:15]
	v_mul_f32_e32 v0, v5, v5
	v_mul_f32_e32 v1, v7, v7
	v_fmac_f32_e32 v0, v4, v4
	v_fmac_f32_e32 v1, v6, v6
	v_add_f32_e32 v0, v0, v1
	v_mul_f32_e32 v1, v3, v3
	v_mul_f32_e32 v10, v9, v9
	v_fmac_f32_e32 v1, v2, v2
	v_fmac_f32_e32 v10, v8, v8
	v_add_f32_e32 v1, v1, v10
	v_add_f32_e32 v0, v0, v1
	v_add_f32_e32 v10, v18, v0
	v_cvt_pk_bf16_f32 v0, v4, v5
	v_cvt_pk_bf16_f32 v1, v6, v7
	v_cvt_pk_bf16_f32 v2, v2, v3
	v_cvt_pk_bf16_f32 v3, v8, v9
	global_store_dwordx4 v[12:13], v[0:3], off offset:256
	s_nop 1
	s_nop 0
	s_nop 2
	v_mov_b32_e32 v0, v10
	s_nop 1
	v_permlane16_swap_b32_e32 v0, v10
	s_waitcnt lgkmcnt(0)
	v_add_f32_e32 v0, v10, v0
	s_nop 1
	v_mov_b32_e32 v1, v0
	s_nop 1
	v_permlane32_swap_b32_e32 v1, v0
	s_and_saveexec_b64 s[52:53], s[16:17]
	s_cbranch_execz .LBB0_1097
	s_waitcnt lgkmcnt(0)
	v_add_f32_e32 v2, v0, v1
	v_lshlrev_b64 v[0:1], 6, v[88:89]
	v_lshl_add_u64 v[0:1], s[42:43], 0, v[0:1]
	v_lshl_add_u64 v[0:1], s[50:51], 2, v[0:1]
	s_lshl_b32 s22, s61, 2
	v_lshl_add_u64 v[0:1], v[0:1], 0, s[22:23]
	global_store_dword v[0:1], v2, off

; __device__ __forceinline__ float row_part(const float* ss, int row, int fq) { const f32x4 a = ((const f32x4*)(ss + (size_t)row * 16))[fq]; return (a[0] + a[1]) + (a[2] + a[3]); }
; __device__ __forceinline__ float row_finish(float t) { t += shx(t, 16); t += shx(t, 32); return __builtin_amdgcn_rsqf(t * (1.0f / 1024.0f) + RMS_EPS); }
; __device__ __forceinline__ float sq4(f32x4 v) { return (v[0] * v[0] + v[1] * v[1]) + (v[2] * v[2] + v[3] * v[3]); }
;     __device__ __forceinline__ void operator()(const f32x4 (&acc)[2][2][4][2], const Unit& u, int wr, int wc, int fr, int fq) const {
;         const int g = u.pn * 4 + wc;
;         int mode = 0; const float* w = mqw; float sc = 1.f, nsc = 1.f;
;         if (g >= 36) { mode = 2; w = mqw; nsc = qscale; }
;         else if (diff) { if (g < 12) { mode = 2; w = qw; nsc = qscale; } else if (g < 24) { mode = 2; w = kw; } }
;         else { if (g >= 6 && g < 12) sc = 0.125f; else if (g >= 24) mode = 1; }
;         f32x4 wv[2][2];
; #pragma unroll
;         for (int bj = 0; bj < 2; ++bj)
; #pragma unroll
;             for (int n = 0; n < 2; ++n) wv[bj][n] = *(const f32x4*)(w + 32 * bj + 8 * fq + 4 * n) * nsc;
;         const int lcol = u.pn * 256 + 64 * wc + 8 * fq;
;         float rs[2][4];
; #pragma unroll
;         for (int ai = 0; ai < 2; ++ai)
; #pragma unroll
;             for (int m = 0; m < 4; ++m) rs[ai][m] = row_part(ss, u.pm * BM + ai * HALF + wr * 64 + m * 16 + fr, fq);
; #pragma unroll
;         for (int ai = 0; ai < 2; ++ai)
; #pragma unroll
;             for (int m = 0; m < 4; ++m) rs[ai][m] = row_finish(rs[ai][m]);
; #pragma unroll
;         for (int ai = 0; ai < 2; ++ai)
; #pragma unroll
;             for (int m = 0; m < 4; ++m) {
;                 const int row = u.pm * BM + ai * HALF + wr * 64 + m * 16 + fr;
;                 const float rstd = rs[ai][m];
;                 f32x4 v[2][2];
; #pragma unroll
;                 for (int bj = 0; bj < 2; ++bj)
; #pragma unroll
;                     for (int n = 0; n < 2; ++n) v[bj][n] = acc[ai][bj][m][n] * rstd;
;                 if (mode == 2) {
;                     float q = (sq4(v[0][0]) + sq4(v[0][1])) + (sq4(v[1][0]) + sq4(v[1][1]));
;                     q += shx(q, 16); q += shx(q, 32);
;                     const float r2 = __builtin_amdgcn_rsqf(q * (1.0f / 64.0f) + RMS_EPS);
.LBB0_1191:
	global_load_dwordx4 v[148:151], v[138:139], off offset:528
	global_load_dwordx4 v[152:155], v[138:139], off offset:512
	global_load_dwordx4 v[166:169], v[138:139], off offset:656
	global_load_dwordx4 v[170:173], v[138:139], off offset:640
	s_lshl_b32 s0, s50, 2
	s_or_b32 s4, s0, s67
	s_cmp_gt_i32 s4, 35
	s_cselect_b64 s[48:49], -1, 0
	s_cmp_lt_i32 s4, 36
	s_cselect_b64 s[56:57], -1, 0
	s_add_i32 s4, s4, -12
	s_cmp_lt_u32 s4, -6
	s_cselect_b64 s[54:55], -1, 0
	s_sub_i32 s0, s0, 24
	s_cmp_gt_u32 s0, 11
	s_cselect_b64 s[46:47], -1, 0
	s_lshl_b32 s0, s52, 8
	v_add_u32_e32 v176, s0, v192
	v_cndmask_b32_e64 v158, v203, 1.0, s[56:57]
	v_ashrrev_i32_e32 v177, 31, v176
	v_add_u32_e32 v174, 0x80, v176
	v_ashrrev_i32_e32 v175, 31, v174
	s_mov_b64 s[52:53], -1
	s_and_b64 vcc, exec, s[56:57]
	s_waitcnt vmcnt(0)
	v_pk_mul_f32 v[150:151], v[158:159], v[150:151] op_sel_hi:[0,1]
	v_pk_mul_f32 v[160:161], v[158:159], v[152:153] op_sel_hi:[0,1]
	v_pk_mul_f32 v[152:153], v[158:159], v[148:149] op_sel_hi:[0,1]
	v_lshlrev_b64 v[148:149], 6, v[176:177]
	v_lshl_add_u64 v[148:149], v[136:137], 0, v[148:149]
	v_pk_mul_f32 v[156:157], v[158:159], v[154:155] op_sel_hi:[0,1]
	v_pk_mul_f32 v[162:163], v[158:159], v[172:173] op_sel_hi:[0,1]
	v_pk_mul_f32 v[164:165], v[158:159], v[170:171] op_sel_hi:[0,1]
	v_pk_mul_f32 v[154:155], v[158:159], v[168:169] op_sel_hi:[0,1]
	v_pk_mul_f32 v[158:159], v[158:159], v[166:167] op_sel_hi:[0,1]
	ds_read_b128 v[166:169], v239
	v_add_u32_e32 v172, 0x90, v176
	v_ashrrev_i32_e32 v173, 31, v172
	s_waitcnt lgkmcnt(0)
	v_mov_b32_e32 v148, v167
	v_mov_b32_e32 v149, v168
	v_mov_b32_e32 v167, v169
	v_pk_add_f32 v[148:149], v[148:149], v[166:167]
	s_nop 0
	v_add_f32_e32 v177, v148, v149
	v_or_b32_e32 v148, 16, v176
	v_ashrrev_i32_e32 v149, 31, v148
	v_lshlrev_b64 v[148:149], 6, v[148:149]
	v_lshl_add_u64 v[148:149], v[136:137], 0, v[148:149]
	ds_read_b128 v[166:169], v239 offset:1024
	s_waitcnt lgkmcnt(0)
	v_add_f32_e32 v148, v166, v167
	v_add_f32_e32 v149, v168, v169
	v_add_f32_e32 v178, v148, v149
	v_or_b32_e32 v148, 32, v176
	v_ashrrev_i32_e32 v149, 31, v148
	v_lshlrev_b64 v[148:149], 6, v[148:149]
	v_lshl_add_u64 v[148:149], v[136:137], 0, v[148:149]
	ds_read_b128 v[166:169], v239 offset:2048
	s_waitcnt lgkmcnt(0)
	v_add_f32_e32 v148, v166, v167
	v_add_f32_e32 v149, v168, v169
	v_add_f32_e32 v179, v148, v149
	v_or_b32_e32 v148, 48, v176
	v_ashrrev_i32_e32 v149, 31, v148
	v_lshlrev_b64 v[148:149], 6, v[148:149]
	v_lshl_add_u64 v[148:149], v[136:137], 0, v[148:149]
	ds_read_b128 v[166:169], v239 offset:3072
	s_waitcnt lgkmcnt(0)
	v_add_f32_e32 v148, v166, v167
	v_add_f32_e32 v149, v168, v169
	v_add_f32_e32 v180, v148, v149
	v_lshlrev_b64 v[148:149], 6, v[174:175]
	v_lshl_add_u64 v[148:149], v[136:137], 0, v[148:149]
	ds_read_b128 v[166:169], v239 offset:8192
	s_waitcnt lgkmcnt(0)
	v_add_f32_e32 v148, v166, v167
	v_add_f32_e32 v149, v168, v169
	v_add_f32_e32 v175, v148, v149
	v_lshlrev_b64 v[148:149], 6, v[172:173]
	v_lshl_add_u64 v[148:149], v[136:137], 0, v[148:149]
	ds_read_b128 v[166:169], v239 offset:9216
	s_waitcnt lgkmcnt(0)
	v_add_f32_e32 v148, v166, v167
	v_add_u32_e32 v166, 0xa0, v176
	v_add_f32_e32 v149, v168, v169
	v_ashrrev_i32_e32 v167, 31, v166
	v_add_f32_e32 v173, v148, v149
	v_lshlrev_b64 v[148:149], 6, v[166:167]
	v_lshl_add_u64 v[148:149], v[136:137], 0, v[148:149]
	ds_read_b128 v[168:171], v239 offset:10240
	s_waitcnt lgkmcnt(0)
	v_add_f32_e32 v148, v168, v169
	v_add_f32_e32 v149, v170, v171
	v_add_f32_e32 v167, v148, v149
	v_add_u32_e32 v148, 0xb0, v176
	v_ashrrev_i32_e32 v149, 31, v148
	v_lshlrev_b64 v[168:169], 6, v[148:149]
	v_lshl_add_u64 v[168:169], v[136:137], 0, v[168:169]
	ds_read_b128 v[168:171], v239 offset:11264
	s_waitcnt lgkmcnt(0)
	v_add_f32_e32 v149, v168, v169
	v_add_f32_e32 v168, v170, v171
	v_add_f32_e32 v149, v149, v168
	s_nop 0
	s_nop 2
	v_mov_b32_e32 v168, v177
	s_nop 1
	v_permlane16_swap_b32_e32 v168, v177
	s_waitcnt lgkmcnt(0)
	v_add_f32_e32 v168, v177, v168
	s_nop 1
	v_mov_b32_e32 v169, v168
	s_nop 1
	v_permlane32_swap_b32_e32 v169, v168
	s_waitcnt lgkmcnt(0)
	v_add_f32_e32 v168, v168, v169
	s_nop 0
	v_fmamk_f32 v168, v168, 0x3a800000, v202
	s_nop 1
	v_mov_b32_e32 v169, v178
	s_nop 1
	v_permlane16_swap_b32_e32 v169, v178
	v_rsq_f32_e32 v168, v168
	s_waitcnt lgkmcnt(0)
	v_add_f32_e32 v212, v178, v169
	s_nop 0
	s_nop 0
	s_nop 1
	v_mov_b32_e32 v213, v212
	s_nop 1
	v_permlane32_swap_b32_e32 v213, v212
	s_nop 0
	s_nop 0
	s_nop 1
	v_mov_b32_e32 v169, v179
	s_nop 1
	v_permlane16_swap_b32_e32 v169, v179
	s_waitcnt lgkmcnt(0)
	v_add_f32_e32 v210, v179, v169
	s_nop 0
	s_nop 0
	s_nop 1
	v_mov_b32_e32 v211, v210
	s_nop 1
	v_permlane32_swap_b32_e32 v211, v210
	s_nop 0
	s_nop 0
	s_nop 1
	v_mov_b32_e32 v169, v180
	s_nop 1
	v_permlane16_swap_b32_e32 v169, v180
	s_waitcnt lgkmcnt(0)
	v_add_f32_e32 v208, v180, v169
	s_nop 0
	s_nop 0
	s_nop 1
	v_mov_b32_e32 v209, v208
	s_nop 1
	v_permlane32_swap_b32_e32 v209, v208
	s_nop 0
	s_nop 0
	s_nop 1
	v_mov_b32_e32 v169, v175
	s_nop 1
	v_permlane16_swap_b32_e32 v169, v175
	s_waitcnt lgkmcnt(0)
	v_add_f32_e32 v206, v175, v169
	s_nop 0
	s_nop 0
	s_nop 1
	v_mov_b32_e32 v207, v206
	s_nop 1
	v_permlane32_swap_b32_e32 v207, v206
	s_nop 0
	s_nop 0
	s_nop 1
	v_mov_b32_e32 v169, v173
	s_nop 1
	v_permlane16_swap_b32_e32 v169, v173
	s_waitcnt lgkmcnt(0)
	v_add_f32_e32 v177, v173, v169
	s_nop 0
	s_nop 0
	s_nop 1
	v_mov_b32_e32 v205, v177
	s_nop 1
	v_permlane32_swap_b32_e32 v205, v177
	s_nop 0
	s_nop 0
	s_nop 1
	v_mov_b32_e32 v169, v167
	s_nop 1
	v_permlane16_swap_b32_e32 v169, v167
	s_waitcnt lgkmcnt(0)
	v_add_f32_e32 v173, v167, v169
	s_nop 0
	v_pk_mul_f32 v[188:189], v[126:127], v[168:169] op_sel_hi:[1,0]
	s_nop 1
	v_mov_b32_e32 v175, v173
	s_nop 1
	v_permlane32_swap_b32_e32 v175, v173
	s_nop 0
	v_pk_mul_f32 v[190:191], v[124:125], v[168:169] op_sel_hi:[1,0]
	s_nop 1
	v_mov_b32_e32 v167, v149
	s_nop 1
	v_permlane16_swap_b32_e32 v167, v149
	v_pk_mul_f32 v[184:185], v[122:123], v[168:169] op_sel_hi:[1,0]
	v_pk_mul_f32 v[186:187], v[120:121], v[168:169] op_sel_hi:[1,0]
	v_pk_mul_f32 v[180:181], v[118:119], v[168:169] op_sel_hi:[1,0]
	v_pk_mul_f32 v[182:183], v[116:117], v[168:169] op_sel_hi:[1,0]
	s_waitcnt lgkmcnt(0)
	v_add_f32_e32 v149, v149, v167
	s_nop 0
	v_pk_mul_f32 v[178:179], v[114:115], v[168:169] op_sel_hi:[1,0]
	s_nop 1
	v_mov_b32_e32 v167, v149
	s_nop 1
	v_permlane32_swap_b32_e32 v167, v149
	v_pk_mul_f32 v[170:171], v[112:113], v[168:169] op_sel_hi:[1,0]
	s_cbranch_vccnz .LBB0_1193
; __device__ __forceinline__ float sq4(f32x4 v) { return (v[0] * v[0] + v[1] * v[1]) + (v[2] * v[2] + v[3] * v[3]); }
;     __device__ __forceinline__ void operator()(const f32x4 (&acc)[2][2][4][2], const Unit& u, int wr, int wc, int fr, int fq) const {
;     ...
;                 if (mode == 2) {
;                     float q = (sq4(v[0][0]) + sq4(v[0][1])) + (sq4(v[1][0]) + sq4(v[1][1]));
;                     q += shx(q, 16); q += shx(q, 32);
;                     const float r2 = __builtin_amdgcn_rsqf(q * (1.0f / 64.0f) + RMS_EPS);
; #pragma unroll
;                     for (int bj = 0; bj < 2; ++bj)
; #pragma unroll
;                         for (int n = 0; n < 2; ++n) v[bj][n] = v[bj][n] * r2 * wv[bj][n];
	v_mov_b32_e32 v114, v191
	v_mov_b32_e32 v115, v183
	v_mov_b32_e32 v112, v190
	v_mov_b32_e32 v113, v182
	v_pk_mul_f32 v[114:115], v[114:115], v[114:115]
	v_mov_b32_e32 v116, v189
	v_mov_b32_e32 v117, v181
	v_pk_fma_f32 v[112:113], v[112:113], v[112:113], v[114:115]
	v_mov_b32_e32 v114, v188
	v_mov_b32_e32 v115, v180
	v_pk_mul_f32 v[116:117], v[116:117], v[116:117]
	v_mov_b32_e32 v118, v185
	v_pk_fma_f32 v[114:115], v[114:115], v[114:115], v[116:117]
	v_mov_b32_e32 v116, v187
	v_mov_b32_e32 v117, v171
	v_pk_add_f32 v[112:113], v[112:113], v[114:115]
	v_mov_b32_e32 v114, v186
	v_mov_b32_e32 v115, v170
	v_pk_mul_f32 v[116:117], v[116:117], v[116:117]
	v_mov_b32_e32 v119, v179
	v_pk_fma_f32 v[114:115], v[114:115], v[114:115], v[116:117]
	v_mov_b32_e32 v116, v184
	v_mov_b32_e32 v117, v178
	v_pk_mul_f32 v[118:119], v[118:119], v[118:119]
	s_mov_b64 s[52:53], 0
	v_pk_fma_f32 v[116:117], v[116:117], v[116:117], v[118:119]
	s_nop 0
	v_pk_add_f32 v[114:115], v[114:115], v[116:117]
	s_nop 0
	v_pk_add_f32 v[112:113], v[112:113], v[114:115]
	s_nop 0
	v_add_f32_e32 v112, v112, v113
	s_nop 0
	s_nop 0
	s_nop 1
	v_mov_b32_e32 v113, v112
	s_nop 1
	v_permlane16_swap_b32_e32 v113, v112
	s_waitcnt lgkmcnt(0)
	v_add_f32_e32 v112, v112, v113
	s_nop 0
	s_nop 0
	s_nop 1
	v_mov_b32_e32 v113, v112
	s_nop 1
	v_permlane32_swap_b32_e32 v113, v112
	s_waitcnt lgkmcnt(0)
	v_add_f32_e32 v112, v112, v113
	v_fmamk_f32 v112, v112, 0x3c800000, v202
	v_rsq_f32_e32 v124, v112
	s_nop 0
	v_pk_mul_f32 v[112:113], v[190:191], v[124:125] op_sel_hi:[1,0]
	v_pk_mul_f32 v[114:115], v[188:189], v[124:125] op_sel_hi:[1,0]
	v_pk_mul_f32 v[116:117], v[186:187], v[124:125] op_sel_hi:[1,0]
	v_pk_mul_f32 v[118:119], v[184:185], v[124:125] op_sel_hi:[1,0]
	v_pk_mul_f32 v[120:121], v[182:183], v[124:125] op_sel_hi:[1,0]
	v_pk_mul_f32 v[122:123], v[180:181], v[124:125] op_sel_hi:[1,0]
	v_pk_mul_f32 v[168:169], v[170:171], v[124:125] op_sel_hi:[1,0]
	v_pk_mul_f32 v[124:125], v[178:179], v[124:125] op_sel_hi:[1,0]
	v_pk_mul_f32 v[114:115], v[156:157], v[114:115]
	v_pk_mul_f32 v[112:113], v[160:161], v[112:113]
	v_pk_mul_f32 v[118:119], v[150:151], v[118:119]
	v_pk_mul_f32 v[116:117], v[152:153], v[116:117]
	v_pk_mul_f32 v[122:123], v[162:163], v[122:123]
	v_pk_mul_f32 v[120:121], v[164:165], v[120:121]
	v_pk_mul_f32 v[126:127], v[154:155], v[124:125]
	v_pk_mul_f32 v[124:125], v[158:159], v[168:169]

; __device__ __forceinline__ f32x4 silu4(f32x4 v) { return (f32x4){silu_f(v[0]), silu_f(v[1]), silu_f(v[2]), silu_f(v[3])}; }
; __device__ __forceinline__ float sq4(f32x4 v) { return (v[0] * v[0] + v[1] * v[1]) + (v[2] * v[2] + v[3] * v[3]); }
; __device__ __forceinline__ u32x4 pack8(f32x4 a, f32x4 b) { u32x4 w; w.x = cvt_pk_bf16(a[0], a[1]); w.y = cvt_pk_bf16(a[2], a[3]); w.z = cvt_pk_bf16(b[0], b[1]); w.w = cvt_pk_bf16(b[2], b[3]); return w; }
;     __device__ __forceinline__ void operator()(const f32x4 (&acc)[2][2][4][2], const Unit& u, int wr, int wc, int fr, int fq) const {
;     ...
;                 const int row = u.pm * BM + ai * HALF + wr * 64 + m * 16 + fr;
;                 const float rstd = rs[ai][m];
;                 f32x4 v[2][2];
; #pragma unroll
;                 for (int bj = 0; bj < 2; ++bj)
; #pragma unroll
;                     for (int n = 0; n < 2; ++n) v[bj][n] = acc[ai][bj][m][n] * rstd;
;                 if (mode == 2) {
;                     float q = (sq4(v[0][0]) + sq4(v[0][1])) + (sq4(v[1][0]) + sq4(v[1][1]));
;                     q += shx(q, 16); q += shx(q, 32);
;                     const float r2 = __builtin_amdgcn_rsqf(q * (1.0f / 64.0f) + RMS_EPS);
; #pragma unroll
;                     for (int bj = 0; bj < 2; ++bj)
; #pragma unroll
;                         for (int n = 0; n < 2; ++n) v[bj][n] = v[bj][n] * r2 * wv[bj][n];
;                 } else if (mode == 1) {
; #pragma unroll
;                     for (int bj = 0; bj < 2; ++bj)
; #pragma unroll
;                         for (int n = 0; n < 2; ++n) v[bj][n] = silu4(v[bj][n]);
;                 } else {
; #pragma unroll
;                     for (int bj = 0; bj < 2; ++bj)
; #pragma unroll
;                         for (int n = 0; n < 2; ++n) v[bj][n] = v[bj][n] * sc;
;                 }
;                 bf16_t* rowp = U + (size_t)row * 2560 + lcol;
; #pragma unroll
;                 for (int bj = 0; bj < 2; ++bj) *(u32x4*)(rowp + 32 * bj) = pack8(v[bj][0], v[bj][1]);
.LBB0_1198:
	v_add_f32_e32 v170, v212, v213
	v_fmamk_f32 v170, v170, 0x3a800000, v202
	v_rsq_f32_e32 v178, v170
	v_lshl_or_b32 v170, s50, 8, v197
	v_mov_b64_e32 v[180:181], s[18:19]
	v_ashrrev_i32_e32 v171, 31, v170
	v_mad_i64_i32 v[180:181], s[50:51], v176, s12, v[180:181]
	v_lshl_add_u64 v[180:181], v[170:171], 1, v[180:181]
	v_cvt_pk_bf16_f32 v112, v112, v113
	v_cvt_pk_bf16_f32 v113, v114, v115
	v_cvt_pk_bf16_f32 v114, v116, v117
	v_cvt_pk_bf16_f32 v115, v118, v119
	global_store_dwordx4 v[180:181], v[112:115], off
	v_pk_mul_f32 v[116:117], v[102:103], v[178:179] op_sel_hi:[1,0]
	v_pk_mul_f32 v[118:119], v[100:101], v[178:179] op_sel_hi:[1,0]
	v_cvt_pk_bf16_f32 v112, v120, v121
	v_cvt_pk_bf16_f32 v113, v122, v123
	v_cvt_pk_bf16_f32 v114, v124, v125
	v_cvt_pk_bf16_f32 v115, v126, v127
	global_store_dwordx4 v[180:181], v[112:115], off offset:64
	v_pk_mul_f32 v[124:125], v[110:111], v[178:179] op_sel_hi:[1,0]
	v_pk_mul_f32 v[126:127], v[108:109], v[178:179] op_sel_hi:[1,0]
	v_pk_mul_f32 v[120:121], v[106:107], v[178:179] op_sel_hi:[1,0]
	v_pk_mul_f32 v[122:123], v[104:105], v[178:179] op_sel_hi:[1,0]
	v_pk_mul_f32 v[114:115], v[98:99], v[178:179] op_sel_hi:[1,0]
	v_pk_mul_f32 v[112:113], v[96:97], v[178:179] op_sel_hi:[1,0]
	s_mov_b64 s[50:51], -1
	s_and_b64 vcc, exec, s[48:49]
	s_cbranch_vccz .LBB0_1200
	v_mov_b32_e32 v98, v127
	v_mov_b32_e32 v99, v119
	v_mov_b32_e32 v96, v126
	v_mov_b32_e32 v97, v118
	v_pk_mul_f32 v[98:99], v[98:99], v[98:99]
	v_mov_b32_e32 v100, v125
	v_mov_b32_e32 v101, v117
	v_pk_fma_f32 v[96:97], v[96:97], v[96:97], v[98:99]
	v_mov_b32_e32 v98, v124
	v_mov_b32_e32 v99, v116
	v_pk_mul_f32 v[100:101], v[100:101], v[100:101]
	v_mov_b32_e32 v102, v121
	v_pk_fma_f32 v[98:99], v[98:99], v[98:99], v[100:101]
	v_mov_b32_e32 v100, v123
	v_mov_b32_e32 v101, v113
	v_pk_add_f32 v[96:97], v[96:97], v[98:99]
	v_mov_b32_e32 v98, v122
	v_mov_b32_e32 v99, v112
	v_pk_mul_f32 v[100:101], v[100:101], v[100:101]
	v_mov_b32_e32 v103, v115
	v_pk_fma_f32 v[98:99], v[98:99], v[98:99], v[100:101]
	v_mov_b32_e32 v100, v120
	v_mov_b32_e32 v101, v114
	v_pk_mul_f32 v[102:103], v[102:103], v[102:103]
	s_mov_b64 s[50:51], 0
	v_pk_fma_f32 v[100:101], v[100:101], v[100:101], v[102:103]
	s_nop 0
	v_pk_add_f32 v[98:99], v[98:99], v[100:101]
	s_nop 0
	v_pk_add_f32 v[96:97], v[96:97], v[98:99]
	s_nop 0
	v_add_f32_e32 v96, v96, v97
	s_nop 0
	s_nop 0
	s_nop 1
	v_mov_b32_e32 v97, v96
	s_nop 1
	v_permlane16_swap_b32_e32 v97, v96
	s_waitcnt lgkmcnt(0)
	v_add_f32_e32 v96, v96, v97
	s_nop 0
	s_nop 0
	s_nop 1
	v_mov_b32_e32 v97, v96
	s_nop 1
	v_permlane32_swap_b32_e32 v97, v96
	s_waitcnt lgkmcnt(0)
	v_add_f32_e32 v96, v96, v97
	v_fmamk_f32 v96, v96, 0x3c800000, v202
	v_rsq_f32_e32 v108, v96
	s_nop 0
	v_pk_mul_f32 v[96:97], v[126:127], v[108:109] op_sel_hi:[1,0]
	v_pk_mul_f32 v[98:99], v[124:125], v[108:109] op_sel_hi:[1,0]
	v_pk_mul_f32 v[100:101], v[122:123], v[108:109] op_sel_hi:[1,0]
	v_pk_mul_f32 v[102:103], v[120:121], v[108:109] op_sel_hi:[1,0]
	v_pk_mul_f32 v[104:105], v[118:119], v[108:109] op_sel_hi:[1,0]
	v_pk_mul_f32 v[106:107], v[116:117], v[108:109] op_sel_hi:[1,0]
	v_pk_mul_f32 v[178:179], v[112:113], v[108:109] op_sel_hi:[1,0]
	v_pk_mul_f32 v[108:109], v[114:115], v[108:109] op_sel_hi:[1,0]
	v_pk_mul_f32 v[98:99], v[156:157], v[98:99]
	v_pk_mul_f32 v[96:97], v[160:161], v[96:97]
	v_pk_mul_f32 v[102:103], v[150:151], v[102:103]
	v_pk_mul_f32 v[100:101], v[152:153], v[100:101]
	v_pk_mul_f32 v[106:107], v[162:163], v[106:107]
	v_pk_mul_f32 v[104:105], v[164:165], v[104:105]
	v_pk_mul_f32 v[110:111], v[154:155], v[108:109]
	v_pk_mul_f32 v[108:109], v[158:159], v[178:179]

; __device__ __forceinline__ f32x4 silu4(f32x4 v) { return (f32x4){silu_f(v[0]), silu_f(v[1]), silu_f(v[2]), silu_f(v[3])}; }
; __device__ __forceinline__ float sq4(f32x4 v) { return (v[0] * v[0] + v[1] * v[1]) + (v[2] * v[2] + v[3] * v[3]); }
; __device__ __forceinline__ u32x4 pack8(f32x4 a, f32x4 b) { u32x4 w; w.x = cvt_pk_bf16(a[0], a[1]); w.y = cvt_pk_bf16(a[2], a[3]); w.z = cvt_pk_bf16(b[0], b[1]); w.w = cvt_pk_bf16(b[2], b[3]); return w; }
;     __device__ __forceinline__ void operator()(const f32x4 (&acc)[2][2][4][2], const Unit& u, int wr, int wc, int fr, int fq) const {
;     ...
;                 const int row = u.pm * BM + ai * HALF + wr * 64 + m * 16 + fr;
;                 const float rstd = rs[ai][m];
;                 f32x4 v[2][2];
; #pragma unroll
;                 for (int bj = 0; bj < 2; ++bj)
; #pragma unroll
;                     for (int n = 0; n < 2; ++n) v[bj][n] = acc[ai][bj][m][n] * rstd;
;                 if (mode == 2) {
;                     float q = (sq4(v[0][0]) + sq4(v[0][1])) + (sq4(v[1][0]) + sq4(v[1][1]));
;                     q += shx(q, 16); q += shx(q, 32);
;                     const float r2 = __builtin_amdgcn_rsqf(q * (1.0f / 64.0f) + RMS_EPS);
; #pragma unroll
;                     for (int bj = 0; bj < 2; ++bj)
; #pragma unroll
;                         for (int n = 0; n < 2; ++n) v[bj][n] = v[bj][n] * r2 * wv[bj][n];
;                 } else if (mode == 1) {
; #pragma unroll
;                     for (int bj = 0; bj < 2; ++bj)
; #pragma unroll
;                         for (int n = 0; n < 2; ++n) v[bj][n] = silu4(v[bj][n]);
;                 } else {
; #pragma unroll
;                     for (int bj = 0; bj < 2; ++bj)
; #pragma unroll
;                         for (int n = 0; n < 2; ++n) v[bj][n] = v[bj][n] * sc;
;                 }
;                 bf16_t* rowp = U + (size_t)row * 2560 + lcol;
; #pragma unroll
;                 for (int bj = 0; bj < 2; ++bj) *(u32x4*)(rowp + 32 * bj) = pack8(v[bj][0], v[bj][1]);
.LBB0_1205:
	v_add_f32_e32 v112, v210, v211
	v_fmamk_f32 v112, v112, 0x3a800000, v202
	v_add_u32_e32 v113, s0, v194
	v_rsq_f32_e32 v112, v112
	v_mov_b64_e32 v[114:115], s[18:19]
	v_mad_i64_i32 v[114:115], s[50:51], v113, s12, v[114:115]
	v_lshl_add_u64 v[114:115], v[170:171], 1, v[114:115]
	v_cvt_pk_bf16_f32 v96, v96, v97
	v_cvt_pk_bf16_f32 v97, v98, v99
	v_cvt_pk_bf16_f32 v98, v100, v101
	v_cvt_pk_bf16_f32 v99, v102, v103
	global_store_dwordx4 v[114:115], v[96:99], off
	v_pk_mul_f32 v[100:101], v[86:87], v[112:113] op_sel_hi:[1,0]
	v_pk_mul_f32 v[102:103], v[84:85], v[112:113] op_sel_hi:[1,0]
	v_cvt_pk_bf16_f32 v96, v104, v105
	v_cvt_pk_bf16_f32 v97, v106, v107
	v_cvt_pk_bf16_f32 v98, v108, v109
	v_cvt_pk_bf16_f32 v99, v110, v111
	global_store_dwordx4 v[114:115], v[96:99], off offset:64
	v_pk_mul_f32 v[108:109], v[94:95], v[112:113] op_sel_hi:[1,0]
	v_pk_mul_f32 v[110:111], v[92:93], v[112:113] op_sel_hi:[1,0]
	v_pk_mul_f32 v[104:105], v[90:91], v[112:113] op_sel_hi:[1,0]
	v_pk_mul_f32 v[106:107], v[88:89], v[112:113] op_sel_hi:[1,0]
	v_pk_mul_f32 v[98:99], v[82:83], v[112:113] op_sel_hi:[1,0]
	v_pk_mul_f32 v[96:97], v[80:81], v[112:113] op_sel_hi:[1,0]
	s_mov_b64 s[50:51], -1
	s_and_b64 vcc, exec, s[48:49]
	s_cbranch_vccz .LBB0_1207
	v_mov_b32_e32 v82, v111
	v_mov_b32_e32 v83, v103
	v_mov_b32_e32 v80, v110
	v_mov_b32_e32 v81, v102
	v_pk_mul_f32 v[82:83], v[82:83], v[82:83]
	v_mov_b32_e32 v84, v109
	v_mov_b32_e32 v85, v101
	v_pk_fma_f32 v[80:81], v[80:81], v[80:81], v[82:83]
	v_mov_b32_e32 v82, v108
	v_mov_b32_e32 v83, v100
	v_pk_mul_f32 v[84:85], v[84:85], v[84:85]
	v_mov_b32_e32 v86, v105
	v_pk_fma_f32 v[82:83], v[82:83], v[82:83], v[84:85]
	v_mov_b32_e32 v84, v107
	v_mov_b32_e32 v85, v97
	v_pk_add_f32 v[80:81], v[80:81], v[82:83]
	v_mov_b32_e32 v82, v106
	v_mov_b32_e32 v83, v96
	v_pk_mul_f32 v[84:85], v[84:85], v[84:85]
	v_mov_b32_e32 v87, v99
	v_pk_fma_f32 v[82:83], v[82:83], v[82:83], v[84:85]
	v_mov_b32_e32 v84, v104
	v_mov_b32_e32 v85, v98
	v_pk_mul_f32 v[86:87], v[86:87], v[86:87]
	s_mov_b64 s[50:51], 0
	v_pk_fma_f32 v[84:85], v[84:85], v[84:85], v[86:87]
	s_nop 0
	v_pk_add_f32 v[82:83], v[82:83], v[84:85]
	s_nop 0
	v_pk_add_f32 v[80:81], v[80:81], v[82:83]
	s_nop 0
	v_add_f32_e32 v80, v80, v81
	s_nop 0
	s_nop 0
	s_nop 1
	v_mov_b32_e32 v81, v80
	s_nop 1
	v_permlane16_swap_b32_e32 v81, v80
	s_waitcnt lgkmcnt(0)
	v_add_f32_e32 v80, v80, v81
	s_nop 0
	s_nop 0
	s_nop 1
	v_mov_b32_e32 v81, v80
	s_nop 1
	v_permlane32_swap_b32_e32 v81, v80
	s_waitcnt lgkmcnt(0)
	v_add_f32_e32 v80, v80, v81
	v_fmamk_f32 v80, v80, 0x3c800000, v202
	v_rsq_f32_e32 v92, v80
	s_nop 0
	v_pk_mul_f32 v[80:81], v[110:111], v[92:93] op_sel_hi:[1,0]
	v_pk_mul_f32 v[82:83], v[108:109], v[92:93] op_sel_hi:[1,0]
	v_pk_mul_f32 v[84:85], v[106:107], v[92:93] op_sel_hi:[1,0]
	v_pk_mul_f32 v[86:87], v[104:105], v[92:93] op_sel_hi:[1,0]
	v_pk_mul_f32 v[88:89], v[102:103], v[92:93] op_sel_hi:[1,0]
	v_pk_mul_f32 v[90:91], v[100:101], v[92:93] op_sel_hi:[1,0]
	v_pk_mul_f32 v[112:113], v[96:97], v[92:93] op_sel_hi:[1,0]
	v_pk_mul_f32 v[92:93], v[98:99], v[92:93] op_sel_hi:[1,0]
	v_pk_mul_f32 v[82:83], v[156:157], v[82:83]
	v_pk_mul_f32 v[80:81], v[160:161], v[80:81]
	v_pk_mul_f32 v[86:87], v[150:151], v[86:87]
	v_pk_mul_f32 v[84:85], v[152:153], v[84:85]
	v_pk_mul_f32 v[90:91], v[162:163], v[90:91]
	v_pk_mul_f32 v[88:89], v[164:165], v[88:89]
	v_pk_mul_f32 v[94:95], v[154:155], v[92:93]
	v_pk_mul_f32 v[92:93], v[158:159], v[112:113]

; __device__ __forceinline__ f32x4 silu4(f32x4 v) { return (f32x4){silu_f(v[0]), silu_f(v[1]), silu_f(v[2]), silu_f(v[3])}; }
; __device__ __forceinline__ float sq4(f32x4 v) { return (v[0] * v[0] + v[1] * v[1]) + (v[2] * v[2] + v[3] * v[3]); }
; __device__ __forceinline__ u32x4 pack8(f32x4 a, f32x4 b) { u32x4 w; w.x = cvt_pk_bf16(a[0], a[1]); w.y = cvt_pk_bf16(a[2], a[3]); w.z = cvt_pk_bf16(b[0], b[1]); w.w = cvt_pk_bf16(b[2], b[3]); return w; }
;     __device__ __forceinline__ void operator()(const f32x4 (&acc)[2][2][4][2], const Unit& u, int wr, int wc, int fr, int fq) const {
;     ...
;                 const int row = u.pm * BM + ai * HALF + wr * 64 + m * 16 + fr;
;                 const float rstd = rs[ai][m];
;                 f32x4 v[2][2];
; #pragma unroll
;                 for (int bj = 0; bj < 2; ++bj)
; #pragma unroll
;                     for (int n = 0; n < 2; ++n) v[bj][n] = acc[ai][bj][m][n] * rstd;
;                 if (mode == 2) {
;                     float q = (sq4(v[0][0]) + sq4(v[0][1])) + (sq4(v[1][0]) + sq4(v[1][1]));
;                     q += shx(q, 16); q += shx(q, 32);
;                     const float r2 = __builtin_amdgcn_rsqf(q * (1.0f / 64.0f) + RMS_EPS);
; #pragma unroll
;                     for (int bj = 0; bj < 2; ++bj)
; #pragma unroll
;                         for (int n = 0; n < 2; ++n) v[bj][n] = v[bj][n] * r2 * wv[bj][n];
;                 } else if (mode == 1) {
; #pragma unroll
;                     for (int bj = 0; bj < 2; ++bj)
; #pragma unroll
;                         for (int n = 0; n < 2; ++n) v[bj][n] = silu4(v[bj][n]);
;                 } else {
; #pragma unroll
;                     for (int bj = 0; bj < 2; ++bj)
; #pragma unroll
;                         for (int n = 0; n < 2; ++n) v[bj][n] = v[bj][n] * sc;
;                 }
;                 bf16_t* rowp = U + (size_t)row * 2560 + lcol;
; #pragma unroll
;                 for (int bj = 0; bj < 2; ++bj) *(u32x4*)(rowp + 32 * bj) = pack8(v[bj][0], v[bj][1]);
.LBB0_1212:
	v_add_f32_e32 v96, v208, v209
	v_fmamk_f32 v96, v96, 0x3a800000, v202
	v_add_u32_e32 v97, s0, v195
	v_rsq_f32_e32 v96, v96
	v_mov_b64_e32 v[98:99], s[18:19]
	v_mad_i64_i32 v[98:99], s[50:51], v97, s12, v[98:99]
	v_lshl_add_u64 v[98:99], v[170:171], 1, v[98:99]
	v_cvt_pk_bf16_f32 v80, v80, v81
	v_cvt_pk_bf16_f32 v81, v82, v83
	v_cvt_pk_bf16_f32 v82, v84, v85
	v_cvt_pk_bf16_f32 v83, v86, v87
	global_store_dwordx4 v[98:99], v[80:83], off
	v_pk_mul_f32 v[84:85], v[70:71], v[96:97] op_sel_hi:[1,0]
	v_pk_mul_f32 v[86:87], v[68:69], v[96:97] op_sel_hi:[1,0]
	v_cvt_pk_bf16_f32 v80, v88, v89
	v_cvt_pk_bf16_f32 v81, v90, v91
	v_cvt_pk_bf16_f32 v82, v92, v93
	v_cvt_pk_bf16_f32 v83, v94, v95
	global_store_dwordx4 v[98:99], v[80:83], off offset:64
	v_pk_mul_f32 v[92:93], v[78:79], v[96:97] op_sel_hi:[1,0]
	v_pk_mul_f32 v[94:95], v[76:77], v[96:97] op_sel_hi:[1,0]
	v_pk_mul_f32 v[88:89], v[74:75], v[96:97] op_sel_hi:[1,0]
	v_pk_mul_f32 v[90:91], v[72:73], v[96:97] op_sel_hi:[1,0]
	v_pk_mul_f32 v[82:83], v[66:67], v[96:97] op_sel_hi:[1,0]
	v_pk_mul_f32 v[80:81], v[64:65], v[96:97] op_sel_hi:[1,0]
	s_mov_b64 s[50:51], -1
	s_and_b64 vcc, exec, s[48:49]
	s_cbranch_vccz .LBB0_1214
	v_mov_b32_e32 v66, v95
	v_mov_b32_e32 v67, v87
	v_mov_b32_e32 v64, v94
	v_mov_b32_e32 v65, v86
	v_pk_mul_f32 v[66:67], v[66:67], v[66:67]
	v_mov_b32_e32 v68, v93
	v_mov_b32_e32 v69, v85
	v_pk_fma_f32 v[64:65], v[64:65], v[64:65], v[66:67]
	v_mov_b32_e32 v66, v92
	v_mov_b32_e32 v67, v84
	v_pk_mul_f32 v[68:69], v[68:69], v[68:69]
	v_mov_b32_e32 v70, v89
	v_pk_fma_f32 v[66:67], v[66:67], v[66:67], v[68:69]
	v_mov_b32_e32 v68, v91
	v_mov_b32_e32 v69, v81
	v_pk_add_f32 v[64:65], v[64:65], v[66:67]
	v_mov_b32_e32 v66, v90
	v_mov_b32_e32 v67, v80
	v_pk_mul_f32 v[68:69], v[68:69], v[68:69]
	v_mov_b32_e32 v71, v83
	v_pk_fma_f32 v[66:67], v[66:67], v[66:67], v[68:69]
	v_mov_b32_e32 v68, v88
	v_mov_b32_e32 v69, v82
	v_pk_mul_f32 v[70:71], v[70:71], v[70:71]
	s_mov_b64 s[50:51], 0
	v_pk_fma_f32 v[68:69], v[68:69], v[68:69], v[70:71]
	s_nop 0
	v_pk_add_f32 v[66:67], v[66:67], v[68:69]
	s_nop 0
	v_pk_add_f32 v[64:65], v[64:65], v[66:67]
	s_nop 0
	v_add_f32_e32 v64, v64, v65
	s_nop 0
	s_nop 0
	s_nop 1
	v_mov_b32_e32 v65, v64
	s_nop 1
	v_permlane16_swap_b32_e32 v65, v64
	s_waitcnt lgkmcnt(0)
	v_add_f32_e32 v64, v64, v65
	s_nop 0
	s_nop 0
	s_nop 1
	v_mov_b32_e32 v65, v64
	s_nop 1
	v_permlane32_swap_b32_e32 v65, v64
	s_waitcnt lgkmcnt(0)
	v_add_f32_e32 v64, v64, v65
	v_fmamk_f32 v64, v64, 0x3c800000, v202
	v_rsq_f32_e32 v76, v64
	s_nop 0
	v_pk_mul_f32 v[64:65], v[94:95], v[76:77] op_sel_hi:[1,0]
	v_pk_mul_f32 v[66:67], v[92:93], v[76:77] op_sel_hi:[1,0]
	v_pk_mul_f32 v[68:69], v[90:91], v[76:77] op_sel_hi:[1,0]
	v_pk_mul_f32 v[70:71], v[88:89], v[76:77] op_sel_hi:[1,0]
	v_pk_mul_f32 v[72:73], v[86:87], v[76:77] op_sel_hi:[1,0]
	v_pk_mul_f32 v[74:75], v[84:85], v[76:77] op_sel_hi:[1,0]
	v_pk_mul_f32 v[96:97], v[80:81], v[76:77] op_sel_hi:[1,0]
	v_pk_mul_f32 v[76:77], v[82:83], v[76:77] op_sel_hi:[1,0]
	v_pk_mul_f32 v[66:67], v[156:157], v[66:67]
	v_pk_mul_f32 v[64:65], v[160:161], v[64:65]
	v_pk_mul_f32 v[70:71], v[150:151], v[70:71]
	v_pk_mul_f32 v[68:69], v[152:153], v[68:69]
	v_pk_mul_f32 v[74:75], v[162:163], v[74:75]
	v_pk_mul_f32 v[72:73], v[164:165], v[72:73]
	v_pk_mul_f32 v[78:79], v[154:155], v[76:77]
	v_pk_mul_f32 v[76:77], v[158:159], v[96:97]

; __device__ __forceinline__ f32x4 silu4(f32x4 v) { return (f32x4){silu_f(v[0]), silu_f(v[1]), silu_f(v[2]), silu_f(v[3])}; }
; __device__ __forceinline__ float sq4(f32x4 v) { return (v[0] * v[0] + v[1] * v[1]) + (v[2] * v[2] + v[3] * v[3]); }
; __device__ __forceinline__ u32x4 pack8(f32x4 a, f32x4 b) { u32x4 w; w.x = cvt_pk_bf16(a[0], a[1]); w.y = cvt_pk_bf16(a[2], a[3]); w.z = cvt_pk_bf16(b[0], b[1]); w.w = cvt_pk_bf16(b[2], b[3]); return w; }
;     __device__ __forceinline__ void operator()(const f32x4 (&acc)[2][2][4][2], const Unit& u, int wr, int wc, int fr, int fq) const {
;     ...
;                 const int row = u.pm * BM + ai * HALF + wr * 64 + m * 16 + fr;
;                 const float rstd = rs[ai][m];
;                 f32x4 v[2][2];
; #pragma unroll
;                 for (int bj = 0; bj < 2; ++bj)
; #pragma unroll
;                     for (int n = 0; n < 2; ++n) v[bj][n] = acc[ai][bj][m][n] * rstd;
;                 if (mode == 2) {
;                     float q = (sq4(v[0][0]) + sq4(v[0][1])) + (sq4(v[1][0]) + sq4(v[1][1]));
;                     q += shx(q, 16); q += shx(q, 32);
;                     const float r2 = __builtin_amdgcn_rsqf(q * (1.0f / 64.0f) + RMS_EPS);
; #pragma unroll
;                     for (int bj = 0; bj < 2; ++bj)
; #pragma unroll
;                         for (int n = 0; n < 2; ++n) v[bj][n] = v[bj][n] * r2 * wv[bj][n];
;                 } else if (mode == 1) {
; #pragma unroll
;                     for (int bj = 0; bj < 2; ++bj)
; #pragma unroll
;                         for (int n = 0; n < 2; ++n) v[bj][n] = silu4(v[bj][n]);
;                 } else {
; #pragma unroll
;                     for (int bj = 0; bj < 2; ++bj)
; #pragma unroll
;                         for (int n = 0; n < 2; ++n) v[bj][n] = v[bj][n] * sc;
;                 }
;                 bf16_t* rowp = U + (size_t)row * 2560 + lcol;
; #pragma unroll
;                 for (int bj = 0; bj < 2; ++bj) *(u32x4*)(rowp + 32 * bj) = pack8(v[bj][0], v[bj][1]);
.LBB0_1219:
	v_add_f32_e32 v80, v206, v207
	v_fmamk_f32 v80, v80, 0x3a800000, v202
	v_add_u32_e32 v81, s0, v196
	v_rsq_f32_e32 v80, v80
	v_mov_b64_e32 v[82:83], s[18:19]
	v_mad_i64_i32 v[82:83], s[50:51], v81, s12, v[82:83]
	v_lshl_add_u64 v[82:83], v[170:171], 1, v[82:83]
	v_cvt_pk_bf16_f32 v64, v64, v65
	v_cvt_pk_bf16_f32 v65, v66, v67
	v_cvt_pk_bf16_f32 v66, v68, v69
	v_cvt_pk_bf16_f32 v67, v70, v71
	global_store_dwordx4 v[82:83], v[64:67], off
	v_pk_mul_f32 v[68:69], v[54:55], v[80:81] op_sel_hi:[1,0]
	v_pk_mul_f32 v[70:71], v[52:53], v[80:81] op_sel_hi:[1,0]
	v_cvt_pk_bf16_f32 v64, v72, v73
	v_cvt_pk_bf16_f32 v65, v74, v75
	v_cvt_pk_bf16_f32 v66, v76, v77
	v_cvt_pk_bf16_f32 v67, v78, v79
	global_store_dwordx4 v[82:83], v[64:67], off offset:64
	v_pk_mul_f32 v[76:77], v[62:63], v[80:81] op_sel_hi:[1,0]
	v_pk_mul_f32 v[78:79], v[60:61], v[80:81] op_sel_hi:[1,0]
	v_pk_mul_f32 v[72:73], v[58:59], v[80:81] op_sel_hi:[1,0]
	v_pk_mul_f32 v[74:75], v[56:57], v[80:81] op_sel_hi:[1,0]
	v_pk_mul_f32 v[66:67], v[50:51], v[80:81] op_sel_hi:[1,0]
	v_pk_mul_f32 v[64:65], v[48:49], v[80:81] op_sel_hi:[1,0]
	s_mov_b64 s[50:51], -1
	s_and_b64 vcc, exec, s[48:49]
	s_cbranch_vccz .LBB0_1221
	v_mov_b32_e32 v50, v79
	v_mov_b32_e32 v51, v71
	v_mov_b32_e32 v48, v78
	v_mov_b32_e32 v49, v70
	v_pk_mul_f32 v[50:51], v[50:51], v[50:51]
	v_mov_b32_e32 v52, v77
	v_mov_b32_e32 v53, v69
	v_pk_fma_f32 v[48:49], v[48:49], v[48:49], v[50:51]
	v_mov_b32_e32 v50, v76
	v_mov_b32_e32 v51, v68
	v_pk_mul_f32 v[52:53], v[52:53], v[52:53]
	v_mov_b32_e32 v54, v73
	v_pk_fma_f32 v[50:51], v[50:51], v[50:51], v[52:53]
	v_mov_b32_e32 v52, v75
	v_mov_b32_e32 v53, v65
	v_pk_add_f32 v[48:49], v[48:49], v[50:51]
	v_mov_b32_e32 v50, v74
	v_mov_b32_e32 v51, v64
	v_pk_mul_f32 v[52:53], v[52:53], v[52:53]
	v_mov_b32_e32 v55, v67
	v_pk_fma_f32 v[50:51], v[50:51], v[50:51], v[52:53]
	v_mov_b32_e32 v52, v72
	v_mov_b32_e32 v53, v66
	v_pk_mul_f32 v[54:55], v[54:55], v[54:55]
	s_mov_b64 s[50:51], 0
	v_pk_fma_f32 v[52:53], v[52:53], v[52:53], v[54:55]
	s_nop 0
	v_pk_add_f32 v[50:51], v[50:51], v[52:53]
	s_nop 0
	v_pk_add_f32 v[48:49], v[48:49], v[50:51]
	s_nop 0
	v_add_f32_e32 v48, v48, v49
	s_nop 0
	s_nop 0
	s_nop 1
	v_mov_b32_e32 v49, v48
	s_nop 1
	v_permlane16_swap_b32_e32 v49, v48
	s_waitcnt lgkmcnt(0)
	v_add_f32_e32 v48, v48, v49
	s_nop 0
	s_nop 0
	s_nop 1
	v_mov_b32_e32 v49, v48
	s_nop 1
	v_permlane32_swap_b32_e32 v49, v48
	s_waitcnt lgkmcnt(0)
	v_add_f32_e32 v48, v48, v49
	v_fmamk_f32 v48, v48, 0x3c800000, v202
	v_rsq_f32_e32 v60, v48
	s_nop 0
	v_pk_mul_f32 v[48:49], v[78:79], v[60:61] op_sel_hi:[1,0]
	v_pk_mul_f32 v[50:51], v[76:77], v[60:61] op_sel_hi:[1,0]
	v_pk_mul_f32 v[52:53], v[74:75], v[60:61] op_sel_hi:[1,0]
	v_pk_mul_f32 v[54:55], v[72:73], v[60:61] op_sel_hi:[1,0]
	v_pk_mul_f32 v[56:57], v[70:71], v[60:61] op_sel_hi:[1,0]
	v_pk_mul_f32 v[58:59], v[68:69], v[60:61] op_sel_hi:[1,0]
	v_pk_mul_f32 v[80:81], v[64:65], v[60:61] op_sel_hi:[1,0]
	v_pk_mul_f32 v[60:61], v[66:67], v[60:61] op_sel_hi:[1,0]
	v_pk_mul_f32 v[50:51], v[156:157], v[50:51]
	v_pk_mul_f32 v[48:49], v[160:161], v[48:49]
	v_pk_mul_f32 v[54:55], v[150:151], v[54:55]
	v_pk_mul_f32 v[52:53], v[152:153], v[52:53]
	v_pk_mul_f32 v[58:59], v[162:163], v[58:59]
	v_pk_mul_f32 v[56:57], v[164:165], v[56:57]
	v_pk_mul_f32 v[62:63], v[154:155], v[60:61]
	v_pk_mul_f32 v[60:61], v[158:159], v[80:81]

; __device__ __forceinline__ f32x4 silu4(f32x4 v) { return (f32x4){silu_f(v[0]), silu_f(v[1]), silu_f(v[2]), silu_f(v[3])}; }
; __device__ __forceinline__ float sq4(f32x4 v) { return (v[0] * v[0] + v[1] * v[1]) + (v[2] * v[2] + v[3] * v[3]); }
; __device__ __forceinline__ u32x4 pack8(f32x4 a, f32x4 b) { u32x4 w; w.x = cvt_pk_bf16(a[0], a[1]); w.y = cvt_pk_bf16(a[2], a[3]); w.z = cvt_pk_bf16(b[0], b[1]); w.w = cvt_pk_bf16(b[2], b[3]); return w; }
;     __device__ __forceinline__ void operator()(const f32x4 (&acc)[2][2][4][2], const Unit& u, int wr, int wc, int fr, int fq) const {
;     ...
;                 const int row = u.pm * BM + ai * HALF + wr * 64 + m * 16 + fr;
;                 const float rstd = rs[ai][m];
;                 f32x4 v[2][2];
; #pragma unroll
;                 for (int bj = 0; bj < 2; ++bj)
; #pragma unroll
;                     for (int n = 0; n < 2; ++n) v[bj][n] = acc[ai][bj][m][n] * rstd;
;                 if (mode == 2) {
;                     float q = (sq4(v[0][0]) + sq4(v[0][1])) + (sq4(v[1][0]) + sq4(v[1][1]));
;                     q += shx(q, 16); q += shx(q, 32);
;                     const float r2 = __builtin_amdgcn_rsqf(q * (1.0f / 64.0f) + RMS_EPS);
; #pragma unroll
;                     for (int bj = 0; bj < 2; ++bj)
; #pragma unroll
;                         for (int n = 0; n < 2; ++n) v[bj][n] = v[bj][n] * r2 * wv[bj][n];
;                 } else if (mode == 1) {
; #pragma unroll
;                     for (int bj = 0; bj < 2; ++bj)
; #pragma unroll
;                         for (int n = 0; n < 2; ++n) v[bj][n] = silu4(v[bj][n]);
;                 } else {
; #pragma unroll
;                     for (int bj = 0; bj < 2; ++bj)
; #pragma unroll
;                         for (int n = 0; n < 2; ++n) v[bj][n] = v[bj][n] * sc;
;                 }
;                 bf16_t* rowp = U + (size_t)row * 2560 + lcol;
; #pragma unroll
;                 for (int bj = 0; bj < 2; ++bj) *(u32x4*)(rowp + 32 * bj) = pack8(v[bj][0], v[bj][1]);
.LBB0_1226:
	v_add_f32_e32 v64, v177, v205
	v_fmamk_f32 v64, v64, 0x3a800000, v202
	v_rsq_f32_e32 v64, v64
	v_mov_b64_e32 v[66:67], s[18:19]
	v_mad_i64_i32 v[66:67], s[50:51], v174, s12, v[66:67]
	v_lshl_add_u64 v[66:67], v[170:171], 1, v[66:67]
	v_cvt_pk_bf16_f32 v48, v48, v49
	v_cvt_pk_bf16_f32 v49, v50, v51
	v_cvt_pk_bf16_f32 v50, v52, v53
	v_cvt_pk_bf16_f32 v51, v54, v55
	global_store_dwordx4 v[66:67], v[48:51], off
	v_pk_mul_f32 v[52:53], v[38:39], v[64:65] op_sel_hi:[1,0]
	v_pk_mul_f32 v[54:55], v[36:37], v[64:65] op_sel_hi:[1,0]
	v_cvt_pk_bf16_f32 v48, v56, v57
	v_cvt_pk_bf16_f32 v49, v58, v59
	v_cvt_pk_bf16_f32 v50, v60, v61
	v_cvt_pk_bf16_f32 v51, v62, v63
	global_store_dwordx4 v[66:67], v[48:51], off offset:64
	v_pk_mul_f32 v[60:61], v[46:47], v[64:65] op_sel_hi:[1,0]
	v_pk_mul_f32 v[62:63], v[44:45], v[64:65] op_sel_hi:[1,0]
	v_pk_mul_f32 v[56:57], v[42:43], v[64:65] op_sel_hi:[1,0]
	v_pk_mul_f32 v[58:59], v[40:41], v[64:65] op_sel_hi:[1,0]
	v_pk_mul_f32 v[50:51], v[34:35], v[64:65] op_sel_hi:[1,0]
	v_pk_mul_f32 v[48:49], v[32:33], v[64:65] op_sel_hi:[1,0]
	s_mov_b64 s[50:51], -1
	s_and_b64 vcc, exec, s[48:49]
	s_cbranch_vccz .LBB0_1228
	v_mov_b32_e32 v34, v63
	v_mov_b32_e32 v35, v55
	v_mov_b32_e32 v32, v62
	v_mov_b32_e32 v33, v54
	v_pk_mul_f32 v[34:35], v[34:35], v[34:35]
	v_mov_b32_e32 v36, v61
	v_mov_b32_e32 v37, v53
	v_pk_fma_f32 v[32:33], v[32:33], v[32:33], v[34:35]
	v_mov_b32_e32 v34, v60
	v_mov_b32_e32 v35, v52
	v_pk_mul_f32 v[36:37], v[36:37], v[36:37]
	v_mov_b32_e32 v38, v57
	v_pk_fma_f32 v[34:35], v[34:35], v[34:35], v[36:37]
	v_mov_b32_e32 v36, v59
	v_mov_b32_e32 v37, v49
	v_pk_add_f32 v[32:33], v[32:33], v[34:35]
	v_mov_b32_e32 v34, v58
	v_mov_b32_e32 v35, v48
	v_pk_mul_f32 v[36:37], v[36:37], v[36:37]
	v_mov_b32_e32 v39, v51
	v_pk_fma_f32 v[34:35], v[34:35], v[34:35], v[36:37]
	v_mov_b32_e32 v36, v56
	v_mov_b32_e32 v37, v50
	v_pk_mul_f32 v[38:39], v[38:39], v[38:39]
	s_mov_b64 s[50:51], 0
	v_pk_fma_f32 v[36:37], v[36:37], v[36:37], v[38:39]
	s_nop 0
	v_pk_add_f32 v[34:35], v[34:35], v[36:37]
	s_nop 0
	v_pk_add_f32 v[32:33], v[32:33], v[34:35]
	s_nop 0
	v_add_f32_e32 v32, v32, v33
	s_nop 0
	s_nop 0
	s_nop 1
	v_mov_b32_e32 v33, v32
	s_nop 1
	v_permlane16_swap_b32_e32 v33, v32
	s_waitcnt lgkmcnt(0)
	v_add_f32_e32 v32, v32, v33
	s_nop 0
	s_nop 0
	s_nop 1
	v_mov_b32_e32 v33, v32
	s_nop 1
	v_permlane32_swap_b32_e32 v33, v32
	s_waitcnt lgkmcnt(0)
	v_add_f32_e32 v32, v32, v33
	v_fmamk_f32 v32, v32, 0x3c800000, v202
	v_rsq_f32_e32 v44, v32
	s_nop 0
	v_pk_mul_f32 v[32:33], v[62:63], v[44:45] op_sel_hi:[1,0]
	v_pk_mul_f32 v[34:35], v[60:61], v[44:45] op_sel_hi:[1,0]
	v_pk_mul_f32 v[36:37], v[58:59], v[44:45] op_sel_hi:[1,0]
	v_pk_mul_f32 v[38:39], v[56:57], v[44:45] op_sel_hi:[1,0]
	v_pk_mul_f32 v[40:41], v[54:55], v[44:45] op_sel_hi:[1,0]
	v_pk_mul_f32 v[42:43], v[52:53], v[44:45] op_sel_hi:[1,0]
	v_pk_mul_f32 v[64:65], v[48:49], v[44:45] op_sel_hi:[1,0]
	v_pk_mul_f32 v[44:45], v[50:51], v[44:45] op_sel_hi:[1,0]
	v_pk_mul_f32 v[34:35], v[156:157], v[34:35]
	v_pk_mul_f32 v[32:33], v[160:161], v[32:33]
	v_pk_mul_f32 v[38:39], v[150:151], v[38:39]
	v_pk_mul_f32 v[36:37], v[152:153], v[36:37]
	v_pk_mul_f32 v[42:43], v[162:163], v[42:43]
	v_pk_mul_f32 v[40:41], v[164:165], v[40:41]
	v_pk_mul_f32 v[46:47], v[154:155], v[44:45]
	v_pk_mul_f32 v[44:45], v[158:159], v[64:65]

; __device__ __forceinline__ f32x4 silu4(f32x4 v) { return (f32x4){silu_f(v[0]), silu_f(v[1]), silu_f(v[2]), silu_f(v[3])}; }
; __device__ __forceinline__ float sq4(f32x4 v) { return (v[0] * v[0] + v[1] * v[1]) + (v[2] * v[2] + v[3] * v[3]); }
; __device__ __forceinline__ u32x4 pack8(f32x4 a, f32x4 b) { u32x4 w; w.x = cvt_pk_bf16(a[0], a[1]); w.y = cvt_pk_bf16(a[2], a[3]); w.z = cvt_pk_bf16(b[0], b[1]); w.w = cvt_pk_bf16(b[2], b[3]); return w; }
;     __device__ __forceinline__ void operator()(const f32x4 (&acc)[2][2][4][2], const Unit& u, int wr, int wc, int fr, int fq) const {
;     ...
;                 const int row = u.pm * BM + ai * HALF + wr * 64 + m * 16 + fr;
;                 const float rstd = rs[ai][m];
;                 f32x4 v[2][2];
; #pragma unroll
;                 for (int bj = 0; bj < 2; ++bj)
; #pragma unroll
;                     for (int n = 0; n < 2; ++n) v[bj][n] = acc[ai][bj][m][n] * rstd;
;                 if (mode == 2) {
;                     float q = (sq4(v[0][0]) + sq4(v[0][1])) + (sq4(v[1][0]) + sq4(v[1][1]));
;                     q += shx(q, 16); q += shx(q, 32);
;                     const float r2 = __builtin_amdgcn_rsqf(q * (1.0f / 64.0f) + RMS_EPS);
; #pragma unroll
;                     for (int bj = 0; bj < 2; ++bj)
; #pragma unroll
;                         for (int n = 0; n < 2; ++n) v[bj][n] = v[bj][n] * r2 * wv[bj][n];
;                 } else if (mode == 1) {
; #pragma unroll
;                     for (int bj = 0; bj < 2; ++bj)
; #pragma unroll
;                         for (int n = 0; n < 2; ++n) v[bj][n] = silu4(v[bj][n]);
;                 } else {
; #pragma unroll
;                     for (int bj = 0; bj < 2; ++bj)
; #pragma unroll
;                         for (int n = 0; n < 2; ++n) v[bj][n] = v[bj][n] * sc;
;                 }
;                 bf16_t* rowp = U + (size_t)row * 2560 + lcol;
; #pragma unroll
;                 for (int bj = 0; bj < 2; ++bj) *(u32x4*)(rowp + 32 * bj) = pack8(v[bj][0], v[bj][1]);
.LBB0_1233:
	v_add_f32_e32 v48, v173, v175
	v_fmamk_f32 v48, v48, 0x3a800000, v202
	v_rsq_f32_e32 v48, v48
	v_mov_b64_e32 v[50:51], s[18:19]
	v_mad_i64_i32 v[50:51], s[50:51], v172, s12, v[50:51]
	v_lshl_add_u64 v[50:51], v[170:171], 1, v[50:51]
	v_cvt_pk_bf16_f32 v32, v32, v33
	v_cvt_pk_bf16_f32 v33, v34, v35
	v_cvt_pk_bf16_f32 v34, v36, v37
	v_cvt_pk_bf16_f32 v35, v38, v39
	global_store_dwordx4 v[50:51], v[32:35], off
	v_pk_mul_f32 v[36:37], v[22:23], v[48:49] op_sel_hi:[1,0]
	v_pk_mul_f32 v[38:39], v[20:21], v[48:49] op_sel_hi:[1,0]
	v_cvt_pk_bf16_f32 v32, v40, v41
	v_cvt_pk_bf16_f32 v33, v42, v43
	v_cvt_pk_bf16_f32 v34, v44, v45
	v_cvt_pk_bf16_f32 v35, v46, v47
	global_store_dwordx4 v[50:51], v[32:35], off offset:64
	v_pk_mul_f32 v[44:45], v[30:31], v[48:49] op_sel_hi:[1,0]
	v_pk_mul_f32 v[46:47], v[28:29], v[48:49] op_sel_hi:[1,0]
	v_pk_mul_f32 v[40:41], v[26:27], v[48:49] op_sel_hi:[1,0]
	v_pk_mul_f32 v[42:43], v[24:25], v[48:49] op_sel_hi:[1,0]
	v_pk_mul_f32 v[34:35], v[18:19], v[48:49] op_sel_hi:[1,0]
	v_pk_mul_f32 v[32:33], v[16:17], v[48:49] op_sel_hi:[1,0]
	s_mov_b64 s[50:51], -1
	s_and_b64 vcc, exec, s[48:49]
	s_cbranch_vccz .LBB0_1235
	v_mov_b32_e32 v18, v47
	v_mov_b32_e32 v19, v39
	v_mov_b32_e32 v16, v46
	v_mov_b32_e32 v17, v38
	v_pk_mul_f32 v[18:19], v[18:19], v[18:19]
	v_mov_b32_e32 v20, v45
	v_mov_b32_e32 v21, v37
	v_pk_fma_f32 v[16:17], v[16:17], v[16:17], v[18:19]
	v_mov_b32_e32 v18, v44
	v_mov_b32_e32 v19, v36
	v_pk_mul_f32 v[20:21], v[20:21], v[20:21]
	v_mov_b32_e32 v22, v41
	v_pk_fma_f32 v[18:19], v[18:19], v[18:19], v[20:21]
	v_mov_b32_e32 v20, v43
	v_mov_b32_e32 v21, v33
	v_pk_add_f32 v[16:17], v[16:17], v[18:19]
	v_mov_b32_e32 v18, v42
	v_mov_b32_e32 v19, v32
	v_pk_mul_f32 v[20:21], v[20:21], v[20:21]
	v_mov_b32_e32 v23, v35
	v_pk_fma_f32 v[18:19], v[18:19], v[18:19], v[20:21]
	v_mov_b32_e32 v20, v40
	v_mov_b32_e32 v21, v34
	v_pk_mul_f32 v[22:23], v[22:23], v[22:23]
	s_mov_b64 s[50:51], 0
	v_pk_fma_f32 v[20:21], v[20:21], v[20:21], v[22:23]
	s_nop 0
	v_pk_add_f32 v[18:19], v[18:19], v[20:21]
	s_nop 0
	v_pk_add_f32 v[16:17], v[16:17], v[18:19]
	s_nop 0
	v_add_f32_e32 v16, v16, v17
	s_nop 0
	s_nop 0
	s_nop 1
	v_mov_b32_e32 v17, v16
	s_nop 1
	v_permlane16_swap_b32_e32 v17, v16
	s_waitcnt lgkmcnt(0)
	v_add_f32_e32 v16, v16, v17
	s_nop 0
	s_nop 0
	s_nop 1
	v_mov_b32_e32 v17, v16
	s_nop 1
	v_permlane32_swap_b32_e32 v17, v16
	s_waitcnt lgkmcnt(0)
	v_add_f32_e32 v16, v16, v17
	v_fmamk_f32 v16, v16, 0x3c800000, v202
	v_rsq_f32_e32 v28, v16
	s_nop 0
	v_pk_mul_f32 v[16:17], v[46:47], v[28:29] op_sel_hi:[1,0]
	v_pk_mul_f32 v[18:19], v[44:45], v[28:29] op_sel_hi:[1,0]
	v_pk_mul_f32 v[20:21], v[42:43], v[28:29] op_sel_hi:[1,0]
	v_pk_mul_f32 v[22:23], v[40:41], v[28:29] op_sel_hi:[1,0]
	v_pk_mul_f32 v[24:25], v[38:39], v[28:29] op_sel_hi:[1,0]
	v_pk_mul_f32 v[26:27], v[36:37], v[28:29] op_sel_hi:[1,0]
	v_pk_mul_f32 v[48:49], v[32:33], v[28:29] op_sel_hi:[1,0]
	v_pk_mul_f32 v[28:29], v[34:35], v[28:29] op_sel_hi:[1,0]
	v_pk_mul_f32 v[18:19], v[156:157], v[18:19]
	v_pk_mul_f32 v[16:17], v[160:161], v[16:17]
	v_pk_mul_f32 v[22:23], v[150:151], v[22:23]
	v_pk_mul_f32 v[20:21], v[152:153], v[20:21]
	v_pk_mul_f32 v[26:27], v[162:163], v[26:27]
	v_pk_mul_f32 v[24:25], v[164:165], v[24:25]
	v_pk_mul_f32 v[30:31], v[154:155], v[28:29]
	v_pk_mul_f32 v[28:29], v[158:159], v[48:49]

; __device__ __forceinline__ f32x4 silu4(f32x4 v) { return (f32x4){silu_f(v[0]), silu_f(v[1]), silu_f(v[2]), silu_f(v[3])}; }
; __device__ __forceinline__ float sq4(f32x4 v) { return (v[0] * v[0] + v[1] * v[1]) + (v[2] * v[2] + v[3] * v[3]); }
; __device__ __forceinline__ u32x4 pack8(f32x4 a, f32x4 b) { u32x4 w; w.x = cvt_pk_bf16(a[0], a[1]); w.y = cvt_pk_bf16(a[2], a[3]); w.z = cvt_pk_bf16(b[0], b[1]); w.w = cvt_pk_bf16(b[2], b[3]); return w; }
;     __device__ __forceinline__ void operator()(const f32x4 (&acc)[2][2][4][2], const Unit& u, int wr, int wc, int fr, int fq) const {
;     ...
;                 const int row = u.pm * BM + ai * HALF + wr * 64 + m * 16 + fr;
;                 const float rstd = rs[ai][m];
;                 f32x4 v[2][2];
; #pragma unroll
;                 for (int bj = 0; bj < 2; ++bj)
; #pragma unroll
;                     for (int n = 0; n < 2; ++n) v[bj][n] = acc[ai][bj][m][n] * rstd;
;                 if (mode == 2) {
;                     float q = (sq4(v[0][0]) + sq4(v[0][1])) + (sq4(v[1][0]) + sq4(v[1][1]));
;                     q += shx(q, 16); q += shx(q, 32);
;                     const float r2 = __builtin_amdgcn_rsqf(q * (1.0f / 64.0f) + RMS_EPS);
; #pragma unroll
;                     for (int bj = 0; bj < 2; ++bj)
; #pragma unroll
;                         for (int n = 0; n < 2; ++n) v[bj][n] = v[bj][n] * r2 * wv[bj][n];
;                 } else if (mode == 1) {
; #pragma unroll
;                     for (int bj = 0; bj < 2; ++bj)
; #pragma unroll
;                         for (int n = 0; n < 2; ++n) v[bj][n] = silu4(v[bj][n]);
;                 } else {
; #pragma unroll
;                     for (int bj = 0; bj < 2; ++bj)
; #pragma unroll
;                         for (int n = 0; n < 2; ++n) v[bj][n] = v[bj][n] * sc;
;                 }
;                 bf16_t* rowp = U + (size_t)row * 2560 + lcol;
; #pragma unroll
;                 for (int bj = 0; bj < 2; ++bj) *(u32x4*)(rowp + 32 * bj) = pack8(v[bj][0], v[bj][1]);
.LBB0_1240:
	s_waitcnt lgkmcnt(0)
	v_add_f32_e32 v32, v149, v167
	v_fmamk_f32 v32, v32, 0x3a800000, v202
	v_rsq_f32_e32 v32, v32
	v_mov_b64_e32 v[34:35], s[18:19]
	v_mad_i64_i32 v[34:35], s[50:51], v166, s12, v[34:35]
	v_lshl_add_u64 v[34:35], v[170:171], 1, v[34:35]
	v_cvt_pk_bf16_f32 v16, v16, v17
	v_cvt_pk_bf16_f32 v17, v18, v19
	v_cvt_pk_bf16_f32 v18, v20, v21
	v_cvt_pk_bf16_f32 v19, v22, v23
	global_store_dwordx4 v[34:35], v[16:19], off
	v_pk_mul_f32 v[20:21], v[6:7], v[32:33] op_sel_hi:[1,0]
	v_pk_mul_f32 v[22:23], v[4:5], v[32:33] op_sel_hi:[1,0]
	v_cvt_pk_bf16_f32 v16, v24, v25
	v_cvt_pk_bf16_f32 v17, v26, v27
	v_cvt_pk_bf16_f32 v18, v28, v29
	v_cvt_pk_bf16_f32 v19, v30, v31
	global_store_dwordx4 v[34:35], v[16:19], off offset:64
	v_pk_mul_f32 v[28:29], v[14:15], v[32:33] op_sel_hi:[1,0]
	v_pk_mul_f32 v[30:31], v[12:13], v[32:33] op_sel_hi:[1,0]
	v_pk_mul_f32 v[24:25], v[10:11], v[32:33] op_sel_hi:[1,0]
	v_pk_mul_f32 v[26:27], v[8:9], v[32:33] op_sel_hi:[1,0]
	v_pk_mul_f32 v[18:19], v[2:3], v[32:33] op_sel_hi:[1,0]
	v_pk_mul_f32 v[16:17], v[0:1], v[32:33] op_sel_hi:[1,0]
	s_mov_b64 s[50:51], -1
	s_and_b64 vcc, exec, s[48:49]
	s_cbranch_vccz .LBB0_1242
	v_mov_b32_e32 v2, v31
	v_mov_b32_e32 v3, v23
	v_mov_b32_e32 v0, v30
	v_mov_b32_e32 v1, v22
	v_pk_mul_f32 v[2:3], v[2:3], v[2:3]
	v_mov_b32_e32 v4, v29
	v_mov_b32_e32 v5, v21
	v_pk_fma_f32 v[0:1], v[0:1], v[0:1], v[2:3]
	v_mov_b32_e32 v2, v28
	v_mov_b32_e32 v3, v20
	v_pk_mul_f32 v[4:5], v[4:5], v[4:5]
	v_mov_b32_e32 v6, v25
	v_pk_fma_f32 v[2:3], v[2:3], v[2:3], v[4:5]
	v_mov_b32_e32 v4, v27
	v_mov_b32_e32 v5, v17
	v_pk_add_f32 v[0:1], v[0:1], v[2:3]
	v_mov_b32_e32 v2, v26
	v_mov_b32_e32 v3, v16
	v_pk_mul_f32 v[4:5], v[4:5], v[4:5]
	v_mov_b32_e32 v7, v19
	v_pk_fma_f32 v[2:3], v[2:3], v[2:3], v[4:5]
	v_mov_b32_e32 v4, v24
	v_mov_b32_e32 v5, v18
	v_pk_mul_f32 v[6:7], v[6:7], v[6:7]
	s_mov_b64 s[50:51], 0
	v_pk_fma_f32 v[4:5], v[4:5], v[4:5], v[6:7]
	s_nop 0
	v_pk_add_f32 v[2:3], v[2:3], v[4:5]
	s_nop 0
	v_pk_add_f32 v[0:1], v[0:1], v[2:3]
	s_nop 0
	v_add_f32_e32 v0, v0, v1
	s_nop 0
	s_nop 0
	s_nop 1
	v_mov_b32_e32 v1, v0
	s_nop 1
	v_permlane16_swap_b32_e32 v1, v0
	s_waitcnt lgkmcnt(0)
	v_add_f32_e32 v0, v0, v1
	s_nop 0
	s_nop 0
	s_nop 1
	v_mov_b32_e32 v1, v0
	s_nop 1
	v_permlane32_swap_b32_e32 v1, v0
	s_waitcnt lgkmcnt(0)
	v_add_f32_e32 v0, v0, v1
	v_fmamk_f32 v0, v0, 0x3c800000, v202
	v_rsq_f32_e32 v12, v0
	s_nop 0
	v_pk_mul_f32 v[0:1], v[30:31], v[12:13] op_sel_hi:[1,0]
	v_pk_mul_f32 v[2:3], v[28:29], v[12:13] op_sel_hi:[1,0]
	v_pk_mul_f32 v[4:5], v[26:27], v[12:13] op_sel_hi:[1,0]
	v_pk_mul_f32 v[6:7], v[24:25], v[12:13] op_sel_hi:[1,0]
	v_pk_mul_f32 v[8:9], v[22:23], v[12:13] op_sel_hi:[1,0]
	v_pk_mul_f32 v[10:11], v[20:21], v[12:13] op_sel_hi:[1,0]
	v_pk_mul_f32 v[32:33], v[16:17], v[12:13] op_sel_hi:[1,0]
	v_pk_mul_f32 v[12:13], v[18:19], v[12:13] op_sel_hi:[1,0]
	v_pk_mul_f32 v[2:3], v[156:157], v[2:3]
	v_pk_mul_f32 v[0:1], v[160:161], v[0:1]
	v_pk_mul_f32 v[6:7], v[150:151], v[6:7]
	v_pk_mul_f32 v[4:5], v[152:153], v[4:5]
	v_pk_mul_f32 v[10:11], v[162:163], v[10:11]
	v_pk_mul_f32 v[8:9], v[164:165], v[8:9]
	v_pk_mul_f32 v[14:15], v[154:155], v[12:13]
	v_pk_mul_f32 v[12:13], v[158:159], v[32:33]

; __device__ __forceinline__ float sq4(f32x4 v) { return (v[0] * v[0] + v[1] * v[1]) + (v[2] * v[2] + v[3] * v[3]); }
; __device__ __forceinline__ u32x4 pack8(f32x4 a, f32x4 b) { u32x4 w; w.x = cvt_pk_bf16(a[0], a[1]); w.y = cvt_pk_bf16(a[2], a[3]); w.z = cvt_pk_bf16(b[0], b[1]); w.w = cvt_pk_bf16(b[2], b[3]); return w; }
;     __device__ __forceinline__ void operator()(const f32x4 (&acc)[2][2][4][2], const Unit& u, int wr, int wc, int fr, int fq) const {
;         const int col0 = u.pn * 256 + 32 * wc + 8 * fq;
; #pragma unroll
;         for (int ai = 0; ai < 2; ++ai) {
;             u32x4 bs[4][2];
; #pragma unroll
;             for (int m = 0; m < 4; ++m)
; #pragma unroll
;                 for (int bj = 0; bj < 2; ++bj) bs[m][bj] = *(const u32x4*)(xb + (size_t)(u.pm * BM + ai * HALF + wr * 64 + m * 16 + fr) * 1024 + col0 + 128 * bj);
; #pragma unroll
;             for (int m = 0; m < 4; ++m) {
;                 const int row = u.pm * BM + ai * HALF + wr * 64 + m * 16 + fr;
;                 float q = 0.f;
; #pragma unroll
;                 for (int bj = 0; bj < 2; ++bj) {
;                     const size_t off = (size_t)row * 1024 + col0 + 128 * bj; const u32x4 w = bs[m][bj];
;                     const f32x4 b0 = (f32x4){__builtin_bit_cast(float, w.x << 16), __builtin_bit_cast(float, w.x & 0xffff0000u), __builtin_bit_cast(float, w.y << 16), __builtin_bit_cast(float, w.y & 0xffff0000u)};
;                     const f32x4 b1 = (f32x4){__builtin_bit_cast(float, w.z << 16), __builtin_bit_cast(float, w.z & 0xffff0000u), __builtin_bit_cast(float, w.w << 16), __builtin_bit_cast(float, w.w & 0xffff0000u)};
;                     const f32x4 v0 = acc[ai][bj][m][0] + b0, v1 = acc[ai][bj][m][1] + b1;
;                     if (last) { __builtin_nontemporal_store(v0, (f32x4*)(out + off)); __builtin_nontemporal_store(v1, (f32x4*)(out + off + 4)); }
;                     else { q += sq4(v0) + sq4(v1); *(u32x4*)(xb + off) = pack8(v0, v1); }
;                 }
;                 if (!last) { q += shx(q, 16); q += shx(q, 32); if (fq == 0) ss[(size_t)row * 16 + u.pn * 4 + wc] = q; }
.LBB0_1507:
	v_lshl_or_b32 v168, s16, 8, v188
	v_lshl_add_u32 v172, s50, 8, v186
	v_ashrrev_i32_e32 v169, 31, v168
	v_lshlrev_b64 v[202:203], 1, v[168:169]
	v_ashrrev_i32_e32 v173, 31, v172
	v_lshl_add_u64 v[170:171], s[20:21], 0, v[202:203]
	v_lshlrev_b64 v[204:205], 11, v[172:173]
	v_lshl_add_u64 v[120:121], v[170:171], 0, v[204:205]
	global_load_dwordx4 v[192:195], v[120:121], off
	global_load_dwordx4 v[196:199], v[120:121], off offset:256
	v_or_b32_e32 v182, 16, v172
	v_ashrrev_i32_e32 v183, 31, v182
	v_or_b32_e32 v178, 32, v172
	v_lshlrev_b64 v[184:185], 11, v[182:183]
	v_ashrrev_i32_e32 v179, 31, v178
	v_or_b32_e32 v174, 48, v172
	v_lshl_add_u64 v[120:121], v[170:171], 0, v[184:185]
	v_lshlrev_b64 v[180:181], 11, v[178:179]
	v_ashrrev_i32_e32 v175, 31, v174
	global_load_dwordx4 v[148:151], v[120:121], off
	global_load_dwordx4 v[144:147], v[120:121], off offset:256
	v_lshl_add_u64 v[120:121], v[170:171], 0, v[180:181]
	v_lshlrev_b64 v[176:177], 11, v[174:175]
	global_load_dwordx4 v[140:143], v[120:121], off
	global_load_dwordx4 v[136:139], v[120:121], off offset:256
	v_lshl_add_u64 v[120:121], v[170:171], 0, v[176:177]
	global_load_dwordx4 v[132:135], v[120:121], off
	s_nop 0
	global_load_dwordx4 v[120:123], v[120:121], off offset:256
	s_lshl_b32 s50, s16, 2
	s_ashr_i32 s51, s50, 31
	s_waitcnt vmcnt(0)
	v_lshlrev_b32_e32 v206, 16, v192
	v_and_b32_e32 v207, 0xffff0000, v192
	v_lshlrev_b32_e32 v192, 16, v193
	v_and_b32_e32 v193, 0xffff0000, v193
	v_lshlrev_b32_e32 v208, 16, v194
	v_and_b32_e32 v209, 0xffff0000, v194
	v_lshlrev_b32_e32 v194, 16, v195
	v_and_b32_e32 v195, 0xffff0000, v195
	v_pk_add_f32 v[130:131], v[130:131], v[192:193]
	v_pk_add_f32 v[128:129], v[128:129], v[206:207]
	v_pk_add_f32 v[192:193], v[126:127], v[194:195]
	v_pk_add_f32 v[126:127], v[124:125], v[208:209]
	v_mul_f32_e32 v124, v129, v129
	v_mul_f32_e32 v125, v131, v131
	v_fmac_f32_e32 v124, v128, v128
	v_fmac_f32_e32 v125, v130, v130
	v_add_f32_e32 v124, v124, v125
	v_mul_f32_e32 v125, v127, v127
	v_mul_f32_e32 v194, v193, v193
	v_fmac_f32_e32 v125, v126, v126
	v_fmac_f32_e32 v194, v192, v192
	v_add_f32_e32 v125, v125, v194
	v_add_f32_e32 v194, v124, v125
	v_cvt_pk_bf16_f32 v124, v128, v129
	v_lshl_add_u64 v[128:129], s[20:21], 0, v[204:205]
	v_cvt_pk_bf16_f32 v125, v130, v131
	v_cvt_pk_bf16_f32 v126, v126, v127
	v_cvt_pk_bf16_f32 v127, v192, v193
	v_lshl_add_u64 v[128:129], v[128:129], 0, v[202:203]
	global_store_dwordx4 v[128:129], v[124:127], off
	v_lshlrev_b32_e32 v130, 16, v198
	v_and_b32_e32 v131, 0xffff0000, v198
	v_lshlrev_b32_e32 v124, 16, v196
	v_and_b32_e32 v125, 0xffff0000, v196
	v_lshlrev_b32_e32 v126, 16, v197
	v_and_b32_e32 v127, 0xffff0000, v197
	v_lshlrev_b32_e32 v192, 16, v199
	v_and_b32_e32 v193, 0xffff0000, v199
	v_pk_add_f32 v[118:119], v[118:119], v[126:127]
	v_pk_add_f32 v[116:117], v[116:117], v[124:125]
	v_pk_add_f32 v[124:125], v[114:115], v[192:193]
	v_pk_add_f32 v[114:115], v[112:113], v[130:131]
	v_mul_f32_e32 v112, v117, v117
	v_mul_f32_e32 v113, v119, v119
	v_fmac_f32_e32 v112, v116, v116
	v_fmac_f32_e32 v113, v118, v118
	v_add_f32_e32 v112, v112, v113
	v_mul_f32_e32 v113, v115, v115
	v_mul_f32_e32 v126, v125, v125
	v_fmac_f32_e32 v113, v114, v114
	v_fmac_f32_e32 v126, v124, v124
	v_add_f32_e32 v113, v113, v126
	v_add_f32_e32 v112, v112, v113
	v_add_f32_e32 v126, v194, v112
	v_cvt_pk_bf16_f32 v112, v116, v117
	v_cvt_pk_bf16_f32 v113, v118, v119
	v_cvt_pk_bf16_f32 v114, v114, v115
	v_cvt_pk_bf16_f32 v115, v124, v125
	global_store_dwordx4 v[128:129], v[112:115], off offset:256
	s_nop 1
	s_nop 0
	s_nop 2
	v_mov_b32_e32 v112, v126
	s_nop 1
	v_permlane16_swap_b32_e32 v112, v126
	s_waitcnt lgkmcnt(0)
	v_add_f32_e32 v112, v126, v112
	s_nop 1
	v_mov_b32_e32 v113, v112
	s_nop 1
	v_permlane32_swap_b32_e32 v113, v112
	s_and_saveexec_b64 s[52:53], s[8:9]
	s_cbranch_execz .LBB0_1509
	s_waitcnt lgkmcnt(0)
	v_add_f32_e32 v114, v112, v113
	v_lshlrev_b64 v[112:113], 6, v[172:173]
	v_lshl_add_u64 v[112:113], s[22:23], 0, v[112:113]
	v_lshl_add_u64 v[112:113], s[50:51], 2, v[112:113]
	s_lshl_b32 s16, s58, 2
	v_lshl_add_u64 v[112:113], v[112:113], 0, s[16:17]
	global_store_dword v[112:113], v114, off
.LBB0_1509:
	s_or_b64 exec, exec, s[52:53]
	v_lshlrev_b32_e32 v112, 16, v148
	s_waitcnt lgkmcnt(0)
	v_and_b32_e32 v113, 0xffff0000, v148
	v_lshlrev_b32_e32 v114, 16, v149
	v_and_b32_e32 v115, 0xffff0000, v149
	v_lshlrev_b32_e32 v116, 16, v150
	v_and_b32_e32 v117, 0xffff0000, v150
	v_lshlrev_b32_e32 v118, 16, v151
	v_and_b32_e32 v119, 0xffff0000, v151
	v_pk_add_f32 v[110:111], v[110:111], v[114:115]
	v_pk_add_f32 v[108:109], v[108:109], v[112:113]
	v_pk_add_f32 v[112:113], v[106:107], v[118:119]
	v_pk_add_f32 v[106:107], v[104:105], v[116:117]
	v_mul_f32_e32 v104, v109, v109
	v_mul_f32_e32 v105, v111, v111
	v_fmac_f32_e32 v104, v108, v108
	v_fmac_f32_e32 v105, v110, v110
	v_add_f32_e32 v104, v104, v105
	v_mul_f32_e32 v105, v107, v107
	v_mul_f32_e32 v114, v113, v113
	v_fmac_f32_e32 v105, v106, v106
	v_fmac_f32_e32 v114, v112, v112
	v_add_f32_e32 v105, v105, v114
	v_add_f32_e32 v114, v104, v105
	v_cvt_pk_bf16_f32 v104, v108, v109
	v_lshl_add_u64 v[108:109], s[20:21], 0, v[184:185]
	v_cvt_pk_bf16_f32 v105, v110, v111
	v_cvt_pk_bf16_f32 v106, v106, v107
	v_cvt_pk_bf16_f32 v107, v112, v113
	v_lshl_add_u64 v[108:109], v[168:169], 1, v[108:109]
	global_store_dwordx4 v[108:109], v[104:107], off
	v_lshlrev_b32_e32 v110, 16, v146
	v_and_b32_e32 v111, 0xffff0000, v146
	v_lshlrev_b32_e32 v104, 16, v144
	v_and_b32_e32 v105, 0xffff0000, v144
	v_lshlrev_b32_e32 v106, 16, v145
	v_and_b32_e32 v107, 0xffff0000, v145
	v_lshlrev_b32_e32 v112, 16, v147
	v_and_b32_e32 v113, 0xffff0000, v147
	v_pk_add_f32 v[102:103], v[102:103], v[106:107]
	v_pk_add_f32 v[100:101], v[100:101], v[104:105]
	v_pk_add_f32 v[104:105], v[98:99], v[112:113]
	v_pk_add_f32 v[98:99], v[96:97], v[110:111]
	v_mul_f32_e32 v96, v101, v101
	v_mul_f32_e32 v97, v103, v103
	v_fmac_f32_e32 v96, v100, v100
	v_fmac_f32_e32 v97, v102, v102
	v_add_f32_e32 v96, v96, v97
	v_mul_f32_e32 v97, v99, v99
	v_mul_f32_e32 v106, v105, v105
	v_fmac_f32_e32 v97, v98, v98
	v_fmac_f32_e32 v106, v104, v104
	v_add_f32_e32 v97, v97, v106
	v_add_f32_e32 v96, v96, v97
	v_add_f32_e32 v106, v114, v96
	v_cvt_pk_bf16_f32 v96, v100, v101
	v_cvt_pk_bf16_f32 v97, v102, v103
	v_cvt_pk_bf16_f32 v98, v98, v99
	v_cvt_pk_bf16_f32 v99, v104, v105
	global_store_dwordx4 v[108:109], v[96:99], off offset:256
	s_nop 1
	s_nop 0
	s_nop 2
	v_mov_b32_e32 v96, v106
	s_nop 1
	v_permlane16_swap_b32_e32 v96, v106
	s_waitcnt lgkmcnt(0)
	v_add_f32_e32 v96, v106, v96
	s_nop 1
	v_mov_b32_e32 v97, v96
	s_nop 1
	v_permlane32_swap_b32_e32 v97, v96
	s_and_saveexec_b64 s[52:53], s[8:9]
	s_cbranch_execz .LBB0_1511
	s_waitcnt lgkmcnt(0)
	v_add_f32_e32 v98, v96, v97
	v_lshlrev_b64 v[96:97], 6, v[182:183]
	v_lshl_add_u64 v[96:97], s[22:23], 0, v[96:97]
	v_lshl_add_u64 v[96:97], s[50:51], 2, v[96:97]
	s_lshl_b32 s16, s58, 2
	v_lshl_add_u64 v[96:97], v[96:97], 0, s[16:17]
	global_store_dword v[96:97], v98, off
; __device__ __forceinline__ float sq4(f32x4 v) { return (v[0] * v[0] + v[1] * v[1]) + (v[2] * v[2] + v[3] * v[3]); }
; __device__ __forceinline__ u32x4 pack8(f32x4 a, f32x4 b) { u32x4 w; w.x = cvt_pk_bf16(a[0], a[1]); w.y = cvt_pk_bf16(a[2], a[3]); w.z = cvt_pk_bf16(b[0], b[1]); w.w = cvt_pk_bf16(b[2], b[3]); return w; }
;     __device__ __forceinline__ void operator()(const f32x4 (&acc)[2][2][4][2], const Unit& u, int wr, int wc, int fr, int fq) const {
;     ...
;             for (int m = 0; m < 4; ++m) {
;                 const int row = u.pm * BM + ai * HALF + wr * 64 + m * 16 + fr;
;                 float q = 0.f;
; #pragma unroll
;                 for (int bj = 0; bj < 2; ++bj) {
;                     const size_t off = (size_t)row * 1024 + col0 + 128 * bj; const u32x4 w = bs[m][bj];
;                     const f32x4 b0 = (f32x4){__builtin_bit_cast(float, w.x << 16), __builtin_bit_cast(float, w.x & 0xffff0000u), __builtin_bit_cast(float, w.y << 16), __builtin_bit_cast(float, w.y & 0xffff0000u)};
;                     const f32x4 b1 = (f32x4){__builtin_bit_cast(float, w.z << 16), __builtin_bit_cast(float, w.z & 0xffff0000u), __builtin_bit_cast(float, w.w << 16), __builtin_bit_cast(float, w.w & 0xffff0000u)};
;                     const f32x4 v0 = acc[ai][bj][m][0] + b0, v1 = acc[ai][bj][m][1] + b1;
;                     if (last) { __builtin_nontemporal_store(v0, (f32x4*)(out + off)); __builtin_nontemporal_store(v1, (f32x4*)(out + off + 4)); }
;                     else { q += sq4(v0) + sq4(v1); *(u32x4*)(xb + off) = pack8(v0, v1); }
;                 }
;                 if (!last) { q += shx(q, 16); q += shx(q, 32); if (fq == 0) ss[(size_t)row * 16 + u.pn * 4 + wc] = q; }
.LBB0_1511:
	s_or_b64 exec, exec, s[52:53]
	v_lshlrev_b32_e32 v96, 16, v140
	s_waitcnt lgkmcnt(0)
	v_and_b32_e32 v97, 0xffff0000, v140
	v_lshlrev_b32_e32 v98, 16, v141
	v_and_b32_e32 v99, 0xffff0000, v141
	v_lshlrev_b32_e32 v100, 16, v142
	v_and_b32_e32 v101, 0xffff0000, v142
	v_lshlrev_b32_e32 v102, 16, v143
	v_and_b32_e32 v103, 0xffff0000, v143
	v_pk_add_f32 v[94:95], v[94:95], v[98:99]
	v_pk_add_f32 v[92:93], v[92:93], v[96:97]
	v_pk_add_f32 v[96:97], v[90:91], v[102:103]
	v_pk_add_f32 v[90:91], v[88:89], v[100:101]
	v_mul_f32_e32 v88, v93, v93
	v_mul_f32_e32 v89, v95, v95
	v_fmac_f32_e32 v88, v92, v92
	v_fmac_f32_e32 v89, v94, v94
	v_add_f32_e32 v88, v88, v89
	v_mul_f32_e32 v89, v91, v91
	v_mul_f32_e32 v98, v97, v97
	v_fmac_f32_e32 v89, v90, v90
	v_fmac_f32_e32 v98, v96, v96
	v_add_f32_e32 v89, v89, v98
	v_add_f32_e32 v98, v88, v89
	v_cvt_pk_bf16_f32 v88, v92, v93
	v_lshl_add_u64 v[92:93], s[20:21], 0, v[180:181]
	v_cvt_pk_bf16_f32 v89, v94, v95
	v_cvt_pk_bf16_f32 v90, v90, v91
	v_cvt_pk_bf16_f32 v91, v96, v97
	v_lshl_add_u64 v[92:93], v[168:169], 1, v[92:93]
	global_store_dwordx4 v[92:93], v[88:91], off
	v_lshlrev_b32_e32 v94, 16, v138
	v_and_b32_e32 v95, 0xffff0000, v138
	v_lshlrev_b32_e32 v88, 16, v136
	v_and_b32_e32 v89, 0xffff0000, v136
	v_lshlrev_b32_e32 v90, 16, v137
	v_and_b32_e32 v91, 0xffff0000, v137
	v_lshlrev_b32_e32 v96, 16, v139
	v_and_b32_e32 v97, 0xffff0000, v139
	v_pk_add_f32 v[86:87], v[86:87], v[90:91]
	v_pk_add_f32 v[84:85], v[84:85], v[88:89]
	v_pk_add_f32 v[88:89], v[82:83], v[96:97]
	v_pk_add_f32 v[82:83], v[80:81], v[94:95]
	v_mul_f32_e32 v80, v85, v85
	v_mul_f32_e32 v81, v87, v87
	v_fmac_f32_e32 v80, v84, v84
	v_fmac_f32_e32 v81, v86, v86
	v_add_f32_e32 v80, v80, v81
	v_mul_f32_e32 v81, v83, v83
	v_mul_f32_e32 v90, v89, v89
	v_fmac_f32_e32 v81, v82, v82
	v_fmac_f32_e32 v90, v88, v88
	v_add_f32_e32 v81, v81, v90
	v_add_f32_e32 v80, v80, v81
	v_add_f32_e32 v90, v98, v80
	v_cvt_pk_bf16_f32 v80, v84, v85
	v_cvt_pk_bf16_f32 v81, v86, v87
	v_cvt_pk_bf16_f32 v82, v82, v83
	v_cvt_pk_bf16_f32 v83, v88, v89
	global_store_dwordx4 v[92:93], v[80:83], off offset:256
	s_nop 1
	s_nop 0
	s_nop 2
	v_mov_b32_e32 v80, v90
	s_nop 1
	v_permlane16_swap_b32_e32 v80, v90
	s_waitcnt lgkmcnt(0)
	v_add_f32_e32 v80, v90, v80
	s_nop 1
	v_mov_b32_e32 v81, v80
	s_nop 1
	v_permlane32_swap_b32_e32 v81, v80
	s_and_saveexec_b64 s[52:53], s[8:9]
	s_cbranch_execz .LBB0_1513
	s_waitcnt lgkmcnt(0)
	v_add_f32_e32 v82, v80, v81
	v_lshlrev_b64 v[80:81], 6, v[178:179]
	v_lshl_add_u64 v[80:81], s[22:23], 0, v[80:81]
	v_lshl_add_u64 v[80:81], s[50:51], 2, v[80:81]
	s_lshl_b32 s16, s58, 2
	v_lshl_add_u64 v[80:81], v[80:81], 0, s[16:17]
	global_store_dword v[80:81], v82, off
.LBB0_1513:
	s_or_b64 exec, exec, s[52:53]
	v_lshlrev_b32_e32 v80, 16, v132
	s_waitcnt lgkmcnt(0)
	v_and_b32_e32 v81, 0xffff0000, v132
	v_lshlrev_b32_e32 v82, 16, v133
	v_and_b32_e32 v83, 0xffff0000, v133
	v_lshlrev_b32_e32 v84, 16, v134
	v_and_b32_e32 v85, 0xffff0000, v134
	v_lshlrev_b32_e32 v86, 16, v135
	v_and_b32_e32 v87, 0xffff0000, v135
	v_pk_add_f32 v[78:79], v[78:79], v[82:83]
	v_pk_add_f32 v[76:77], v[76:77], v[80:81]
	v_pk_add_f32 v[80:81], v[74:75], v[86:87]
	v_pk_add_f32 v[74:75], v[72:73], v[84:85]
	v_mul_f32_e32 v72, v77, v77
	v_mul_f32_e32 v73, v79, v79
	v_fmac_f32_e32 v72, v76, v76
	v_fmac_f32_e32 v73, v78, v78
	v_add_f32_e32 v72, v72, v73
	v_mul_f32_e32 v73, v75, v75
	v_mul_f32_e32 v82, v81, v81
	v_fmac_f32_e32 v73, v74, v74
	v_fmac_f32_e32 v82, v80, v80
	v_add_f32_e32 v73, v73, v82
	v_add_f32_e32 v82, v72, v73
	v_cvt_pk_bf16_f32 v72, v76, v77
	v_lshl_add_u64 v[76:77], s[20:21], 0, v[176:177]
	v_cvt_pk_bf16_f32 v73, v78, v79
	v_cvt_pk_bf16_f32 v74, v74, v75
	v_cvt_pk_bf16_f32 v75, v80, v81
	v_lshl_add_u64 v[76:77], v[168:169], 1, v[76:77]
	global_store_dwordx4 v[76:77], v[72:75], off
	v_lshlrev_b32_e32 v78, 16, v122
	v_and_b32_e32 v79, 0xffff0000, v122
	v_lshlrev_b32_e32 v72, 16, v120
	v_and_b32_e32 v73, 0xffff0000, v120
	v_lshlrev_b32_e32 v74, 16, v121
	v_and_b32_e32 v75, 0xffff0000, v121
	v_lshlrev_b32_e32 v80, 16, v123
	v_and_b32_e32 v81, 0xffff0000, v123
	v_pk_add_f32 v[70:71], v[70:71], v[74:75]
	v_pk_add_f32 v[68:69], v[68:69], v[72:73]
	v_pk_add_f32 v[72:73], v[66:67], v[80:81]
	v_pk_add_f32 v[66:67], v[64:65], v[78:79]
	v_mul_f32_e32 v64, v69, v69
	v_mul_f32_e32 v65, v71, v71
	v_fmac_f32_e32 v64, v68, v68
	v_fmac_f32_e32 v65, v70, v70
	v_add_f32_e32 v64, v64, v65
	v_mul_f32_e32 v65, v67, v67
	v_mul_f32_e32 v74, v73, v73
	v_fmac_f32_e32 v65, v66, v66
	v_fmac_f32_e32 v74, v72, v72
	v_add_f32_e32 v65, v65, v74
	v_add_f32_e32 v64, v64, v65
	v_add_f32_e32 v74, v82, v64
	v_cvt_pk_bf16_f32 v64, v68, v69
	v_cvt_pk_bf16_f32 v65, v70, v71
	v_cvt_pk_bf16_f32 v66, v66, v67
	v_cvt_pk_bf16_f32 v67, v72, v73
	global_store_dwordx4 v[76:77], v[64:67], off offset:256
	s_nop 1
	s_nop 0
	s_nop 2
	v_mov_b32_e32 v64, v74
	s_nop 1
	v_permlane16_swap_b32_e32 v64, v74
	s_waitcnt lgkmcnt(0)
	v_add_f32_e32 v64, v74, v64
	s_nop 1
	v_mov_b32_e32 v65, v64
	s_nop 1
	v_permlane32_swap_b32_e32 v65, v64
	s_and_saveexec_b64 s[52:53], s[8:9]
	s_cbranch_execz .LBB0_1515
	s_waitcnt lgkmcnt(0)
	v_add_f32_e32 v66, v64, v65
	v_lshlrev_b64 v[64:65], 6, v[174:175]
	v_lshl_add_u64 v[64:65], s[22:23], 0, v[64:65]
	v_lshl_add_u64 v[64:65], s[50:51], 2, v[64:65]
	s_lshl_b32 s16, s58, 2
	v_lshl_add_u64 v[64:65], v[64:65], 0, s[16:17]
	global_store_dword v[64:65], v66, off
; __device__ __forceinline__ float sq4(f32x4 v) { return (v[0] * v[0] + v[1] * v[1]) + (v[2] * v[2] + v[3] * v[3]); }
; __device__ __forceinline__ u32x4 pack8(f32x4 a, f32x4 b) { u32x4 w; w.x = cvt_pk_bf16(a[0], a[1]); w.y = cvt_pk_bf16(a[2], a[3]); w.z = cvt_pk_bf16(b[0], b[1]); w.w = cvt_pk_bf16(b[2], b[3]); return w; }
;     __device__ __forceinline__ void operator()(const f32x4 (&acc)[2][2][4][2], const Unit& u, int wr, int wc, int fr, int fq) const {
;     ...
;         for (int ai = 0; ai < 2; ++ai) {
;             u32x4 bs[4][2];
; #pragma unroll
;             for (int m = 0; m < 4; ++m)
; #pragma unroll
;                 for (int bj = 0; bj < 2; ++bj) bs[m][bj] = *(const u32x4*)(xb + (size_t)(u.pm * BM + ai * HALF + wr * 64 + m * 16 + fr) * 1024 + col0 + 128 * bj);
; #pragma unroll
;             for (int m = 0; m < 4; ++m) {
;                 const int row = u.pm * BM + ai * HALF + wr * 64 + m * 16 + fr;
;                 float q = 0.f;
; #pragma unroll
;                 for (int bj = 0; bj < 2; ++bj) {
;                     const size_t off = (size_t)row * 1024 + col0 + 128 * bj; const u32x4 w = bs[m][bj];
;                     const f32x4 b0 = (f32x4){__builtin_bit_cast(float, w.x << 16), __builtin_bit_cast(float, w.x & 0xffff0000u), __builtin_bit_cast(float, w.y << 16), __builtin_bit_cast(float, w.y & 0xffff0000u)};
;                     const f32x4 b1 = (f32x4){__builtin_bit_cast(float, w.z << 16), __builtin_bit_cast(float, w.z & 0xffff0000u), __builtin_bit_cast(float, w.w << 16), __builtin_bit_cast(float, w.w & 0xffff0000u)};
;                     const f32x4 v0 = acc[ai][bj][m][0] + b0, v1 = acc[ai][bj][m][1] + b1;
;                     if (last) { __builtin_nontemporal_store(v0, (f32x4*)(out + off)); __builtin_nontemporal_store(v1, (f32x4*)(out + off + 4)); }
;                     else { q += sq4(v0) + sq4(v1); *(u32x4*)(xb + off) = pack8(v0, v1); }
;                 }
;                 if (!last) { q += shx(q, 16); q += shx(q, 32); if (fq == 0) ss[(size_t)row * 16 + u.pn * 4 + wc] = q; }
.LBB0_1515:
	s_or_b64 exec, exec, s[52:53]
	v_add_u32_e32 v100, 0x80, v172
	v_ashrrev_i32_e32 v101, 31, v100
	v_lshlrev_b64 v[110:111], 11, v[100:101]
	s_waitcnt lgkmcnt(0)
	v_lshl_add_u64 v[64:65], v[170:171], 0, v[110:111]
	global_load_dwordx4 v[102:105], v[64:65], off
	global_load_dwordx4 v[106:109], v[64:65], off offset:256
	v_add_u32_e32 v96, 0x90, v172
	v_ashrrev_i32_e32 v97, 31, v96
	v_add_u32_e32 v92, 0xa0, v172
	v_lshlrev_b64 v[98:99], 11, v[96:97]
	v_ashrrev_i32_e32 v93, 31, v92
	v_add_u32_e32 v88, 0xb0, v172
	v_lshl_add_u64 v[64:65], v[170:171], 0, v[98:99]
	v_lshlrev_b64 v[94:95], 11, v[92:93]
	v_ashrrev_i32_e32 v89, 31, v88
	global_load_dwordx4 v[84:87], v[64:65], off
	global_load_dwordx4 v[80:83], v[64:65], off offset:256
	v_lshl_add_u64 v[64:65], v[170:171], 0, v[94:95]
	v_lshlrev_b64 v[90:91], 11, v[88:89]
	global_load_dwordx4 v[76:79], v[64:65], off
	global_load_dwordx4 v[72:75], v[64:65], off offset:256
	v_lshl_add_u64 v[64:65], v[170:171], 0, v[90:91]
	global_load_dwordx4 v[68:71], v[64:65], off
	s_nop 0
	global_load_dwordx4 v[64:67], v[64:65], off offset:256
	s_waitcnt vmcnt(7)
	v_lshlrev_b32_e32 v112, 16, v102
	v_and_b32_e32 v113, 0xffff0000, v102
	v_lshlrev_b32_e32 v102, 16, v103
	v_and_b32_e32 v103, 0xffff0000, v103
	v_lshlrev_b32_e32 v114, 16, v104
	v_and_b32_e32 v115, 0xffff0000, v104
	v_lshlrev_b32_e32 v104, 16, v105
	v_and_b32_e32 v105, 0xffff0000, v105
	v_pk_add_f32 v[62:63], v[62:63], v[102:103]
	v_pk_add_f32 v[60:61], v[60:61], v[112:113]
	v_pk_add_f32 v[102:103], v[58:59], v[104:105]
	v_pk_add_f32 v[58:59], v[56:57], v[114:115]
	v_mul_f32_e32 v56, v61, v61
	v_mul_f32_e32 v57, v63, v63
	v_fmac_f32_e32 v56, v60, v60
	v_fmac_f32_e32 v57, v62, v62
	v_add_f32_e32 v56, v56, v57
	v_mul_f32_e32 v57, v59, v59
	v_mul_f32_e32 v104, v103, v103
	v_fmac_f32_e32 v57, v58, v58
	v_fmac_f32_e32 v104, v102, v102
	v_add_f32_e32 v57, v57, v104
	v_add_f32_e32 v104, v56, v57
	v_cvt_pk_bf16_f32 v56, v60, v61
	v_lshl_add_u64 v[60:61], s[20:21], 0, v[110:111]
	v_cvt_pk_bf16_f32 v57, v62, v63
	v_cvt_pk_bf16_f32 v58, v58, v59
	v_cvt_pk_bf16_f32 v59, v102, v103
	v_lshl_add_u64 v[60:61], v[168:169], 1, v[60:61]
	global_store_dwordx4 v[60:61], v[56:59], off
	s_waitcnt vmcnt(7)
	v_lshlrev_b32_e32 v62, 16, v108
	v_and_b32_e32 v63, 0xffff0000, v108
	v_lshlrev_b32_e32 v56, 16, v106
	v_and_b32_e32 v57, 0xffff0000, v106
	v_lshlrev_b32_e32 v58, 16, v107
	v_and_b32_e32 v59, 0xffff0000, v107
	v_lshlrev_b32_e32 v102, 16, v109
	v_and_b32_e32 v103, 0xffff0000, v109
	v_pk_add_f32 v[54:55], v[54:55], v[58:59]
	v_pk_add_f32 v[52:53], v[52:53], v[56:57]
	v_pk_add_f32 v[56:57], v[50:51], v[102:103]
	v_pk_add_f32 v[50:51], v[48:49], v[62:63]
	v_mul_f32_e32 v48, v53, v53
	v_mul_f32_e32 v49, v55, v55
	v_fmac_f32_e32 v48, v52, v52
	v_fmac_f32_e32 v49, v54, v54
	v_add_f32_e32 v48, v48, v49
	v_mul_f32_e32 v49, v51, v51
	v_mul_f32_e32 v58, v57, v57
	v_fmac_f32_e32 v49, v50, v50
	v_fmac_f32_e32 v58, v56, v56
	v_add_f32_e32 v49, v49, v58
	v_add_f32_e32 v48, v48, v49
	v_add_f32_e32 v58, v104, v48
	v_cvt_pk_bf16_f32 v48, v52, v53
	v_cvt_pk_bf16_f32 v49, v54, v55
	v_cvt_pk_bf16_f32 v50, v50, v51
	v_cvt_pk_bf16_f32 v51, v56, v57
	global_store_dwordx4 v[60:61], v[48:51], off offset:256
	s_nop 1
	s_nop 0
	s_nop 2
	v_mov_b32_e32 v48, v58
	s_nop 1
	v_permlane16_swap_b32_e32 v48, v58
	s_waitcnt lgkmcnt(0)
	v_add_f32_e32 v48, v58, v48
	s_nop 1
	v_mov_b32_e32 v49, v48
	s_nop 1
	v_permlane32_swap_b32_e32 v49, v48
	s_and_saveexec_b64 s[52:53], s[8:9]
	s_cbranch_execz .LBB0_1517
	s_waitcnt lgkmcnt(0)
	v_add_f32_e32 v50, v48, v49
	v_lshlrev_b64 v[48:49], 6, v[100:101]
	v_lshl_add_u64 v[48:49], s[22:23], 0, v[48:49]
	v_lshl_add_u64 v[48:49], s[50:51], 2, v[48:49]
	s_lshl_b32 s16, s58, 2
	v_lshl_add_u64 v[48:49], v[48:49], 0, s[16:17]
	global_store_dword v[48:49], v50, off
.LBB0_1517:
	s_or_b64 exec, exec, s[52:53]
	s_waitcnt vmcnt(7)
	v_lshlrev_b32_e32 v48, 16, v84
	s_waitcnt lgkmcnt(0)
	v_and_b32_e32 v49, 0xffff0000, v84
	v_lshlrev_b32_e32 v50, 16, v85
	v_and_b32_e32 v51, 0xffff0000, v85
	v_lshlrev_b32_e32 v52, 16, v86
	v_and_b32_e32 v53, 0xffff0000, v86
	v_lshlrev_b32_e32 v54, 16, v87
	v_and_b32_e32 v55, 0xffff0000, v87
	v_pk_add_f32 v[46:47], v[46:47], v[50:51]
	v_pk_add_f32 v[44:45], v[44:45], v[48:49]
	v_pk_add_f32 v[48:49], v[42:43], v[54:55]
	v_pk_add_f32 v[42:43], v[40:41], v[52:53]
	v_mul_f32_e32 v40, v45, v45
	v_mul_f32_e32 v41, v47, v47
	v_fmac_f32_e32 v40, v44, v44
	v_fmac_f32_e32 v41, v46, v46
	v_add_f32_e32 v40, v40, v41
	v_mul_f32_e32 v41, v43, v43
	v_mul_f32_e32 v50, v49, v49
	v_fmac_f32_e32 v41, v42, v42
	v_fmac_f32_e32 v50, v48, v48
	v_add_f32_e32 v41, v41, v50
	v_add_f32_e32 v50, v40, v41
	v_cvt_pk_bf16_f32 v40, v44, v45
	v_lshl_add_u64 v[44:45], s[20:21], 0, v[98:99]
	v_cvt_pk_bf16_f32 v41, v46, v47
	v_cvt_pk_bf16_f32 v42, v42, v43
	v_cvt_pk_bf16_f32 v43, v48, v49
	v_lshl_add_u64 v[44:45], v[168:169], 1, v[44:45]
	global_store_dwordx4 v[44:45], v[40:43], off
	s_waitcnt vmcnt(7)
	v_lshlrev_b32_e32 v46, 16, v82
	v_and_b32_e32 v47, 0xffff0000, v82
	v_lshlrev_b32_e32 v40, 16, v80
	v_and_b32_e32 v41, 0xffff0000, v80
	v_lshlrev_b32_e32 v42, 16, v81
	v_and_b32_e32 v43, 0xffff0000, v81
	v_lshlrev_b32_e32 v48, 16, v83
	v_and_b32_e32 v49, 0xffff0000, v83
	v_pk_add_f32 v[38:39], v[38:39], v[42:43]
	v_pk_add_f32 v[36:37], v[36:37], v[40:41]
	v_pk_add_f32 v[40:41], v[34:35], v[48:49]
	v_pk_add_f32 v[34:35], v[32:33], v[46:47]
	v_mul_f32_e32 v32, v37, v37
	v_mul_f32_e32 v33, v39, v39
	v_fmac_f32_e32 v32, v36, v36
	v_fmac_f32_e32 v33, v38, v38
	v_add_f32_e32 v32, v32, v33
	v_mul_f32_e32 v33, v35, v35
	v_mul_f32_e32 v42, v41, v41
	v_fmac_f32_e32 v33, v34, v34
	v_fmac_f32_e32 v42, v40, v40
	v_add_f32_e32 v33, v33, v42
	v_add_f32_e32 v32, v32, v33
	v_add_f32_e32 v42, v50, v32
	v_cvt_pk_bf16_f32 v32, v36, v37
	v_cvt_pk_bf16_f32 v33, v38, v39
	v_cvt_pk_bf16_f32 v34, v34, v35
	v_cvt_pk_bf16_f32 v35, v40, v41
	global_store_dwordx4 v[44:45], v[32:35], off offset:256
	s_nop 1
	s_nop 0
	s_nop 2
	v_mov_b32_e32 v32, v42
	s_nop 1
	v_permlane16_swap_b32_e32 v32, v42
	s_waitcnt lgkmcnt(0)
	v_add_f32_e32 v32, v42, v32
	s_nop 1
	v_mov_b32_e32 v33, v32
	s_nop 1
	v_permlane32_swap_b32_e32 v33, v32
	s_and_saveexec_b64 s[52:53], s[8:9]
	s_cbranch_execz .LBB0_1519
	s_waitcnt lgkmcnt(0)
	v_add_f32_e32 v34, v32, v33
	v_lshlrev_b64 v[32:33], 6, v[96:97]
	v_lshl_add_u64 v[32:33], s[22:23], 0, v[32:33]
	v_lshl_add_u64 v[32:33], s[50:51], 2, v[32:33]
	s_lshl_b32 s16, s58, 2
	v_lshl_add_u64 v[32:33], v[32:33], 0, s[16:17]
	global_store_dword v[32:33], v34, off
; __device__ __forceinline__ float sq4(f32x4 v) { return (v[0] * v[0] + v[1] * v[1]) + (v[2] * v[2] + v[3] * v[3]); }
; __device__ __forceinline__ u32x4 pack8(f32x4 a, f32x4 b) { u32x4 w; w.x = cvt_pk_bf16(a[0], a[1]); w.y = cvt_pk_bf16(a[2], a[3]); w.z = cvt_pk_bf16(b[0], b[1]); w.w = cvt_pk_bf16(b[2], b[3]); return w; }
;     __device__ __forceinline__ void operator()(const f32x4 (&acc)[2][2][4][2], const Unit& u, int wr, int wc, int fr, int fq) const {
;     ...
;             for (int m = 0; m < 4; ++m) {
;                 const int row = u.pm * BM + ai * HALF + wr * 64 + m * 16 + fr;
;                 float q = 0.f;
; #pragma unroll
;                 for (int bj = 0; bj < 2; ++bj) {
;                     const size_t off = (size_t)row * 1024 + col0 + 128 * bj; const u32x4 w = bs[m][bj];
;                     const f32x4 b0 = (f32x4){__builtin_bit_cast(float, w.x << 16), __builtin_bit_cast(float, w.x & 0xffff0000u), __builtin_bit_cast(float, w.y << 16), __builtin_bit_cast(float, w.y & 0xffff0000u)};
;                     const f32x4 b1 = (f32x4){__builtin_bit_cast(float, w.z << 16), __builtin_bit_cast(float, w.z & 0xffff0000u), __builtin_bit_cast(float, w.w << 16), __builtin_bit_cast(float, w.w & 0xffff0000u)};
;                     const f32x4 v0 = acc[ai][bj][m][0] + b0, v1 = acc[ai][bj][m][1] + b1;
;                     if (last) { __builtin_nontemporal_store(v0, (f32x4*)(out + off)); __builtin_nontemporal_store(v1, (f32x4*)(out + off + 4)); }
;                     else { q += sq4(v0) + sq4(v1); *(u32x4*)(xb + off) = pack8(v0, v1); }
;                 }
;                 if (!last) { q += shx(q, 16); q += shx(q, 32); if (fq == 0) ss[(size_t)row * 16 + u.pn * 4 + wc] = q; }
.LBB0_1519:
	s_or_b64 exec, exec, s[52:53]
	s_waitcnt vmcnt(7)
	v_lshlrev_b32_e32 v32, 16, v76
	s_waitcnt lgkmcnt(0)
	v_and_b32_e32 v33, 0xffff0000, v76
	v_lshlrev_b32_e32 v34, 16, v77
	v_and_b32_e32 v35, 0xffff0000, v77
	v_lshlrev_b32_e32 v36, 16, v78
	v_and_b32_e32 v37, 0xffff0000, v78
	v_lshlrev_b32_e32 v38, 16, v79
	v_and_b32_e32 v39, 0xffff0000, v79
	v_pk_add_f32 v[30:31], v[30:31], v[34:35]
	v_pk_add_f32 v[28:29], v[28:29], v[32:33]
	v_pk_add_f32 v[32:33], v[26:27], v[38:39]
	v_pk_add_f32 v[26:27], v[24:25], v[36:37]
	v_mul_f32_e32 v24, v29, v29
	v_mul_f32_e32 v25, v31, v31
	v_fmac_f32_e32 v24, v28, v28
	v_fmac_f32_e32 v25, v30, v30
	v_add_f32_e32 v24, v24, v25
	v_mul_f32_e32 v25, v27, v27
	v_mul_f32_e32 v34, v33, v33
	v_fmac_f32_e32 v25, v26, v26
	v_fmac_f32_e32 v34, v32, v32
	v_add_f32_e32 v25, v25, v34
	v_add_f32_e32 v34, v24, v25
	v_cvt_pk_bf16_f32 v24, v28, v29
	v_lshl_add_u64 v[28:29], s[20:21], 0, v[94:95]
	v_cvt_pk_bf16_f32 v25, v30, v31
	v_cvt_pk_bf16_f32 v26, v26, v27
	v_cvt_pk_bf16_f32 v27, v32, v33
	v_lshl_add_u64 v[28:29], v[168:169], 1, v[28:29]
	global_store_dwordx4 v[28:29], v[24:27], off
	s_waitcnt vmcnt(7)
	v_lshlrev_b32_e32 v30, 16, v74
	v_and_b32_e32 v31, 0xffff0000, v74
	v_lshlrev_b32_e32 v24, 16, v72
	v_and_b32_e32 v25, 0xffff0000, v72
	v_lshlrev_b32_e32 v26, 16, v73
	v_and_b32_e32 v27, 0xffff0000, v73
	v_lshlrev_b32_e32 v32, 16, v75
	v_and_b32_e32 v33, 0xffff0000, v75
	v_pk_add_f32 v[22:23], v[22:23], v[26:27]
	v_pk_add_f32 v[20:21], v[20:21], v[24:25]
	v_pk_add_f32 v[24:25], v[18:19], v[32:33]
	v_pk_add_f32 v[18:19], v[16:17], v[30:31]
	v_mul_f32_e32 v16, v21, v21
	v_mul_f32_e32 v17, v23, v23
	v_fmac_f32_e32 v16, v20, v20
	v_fmac_f32_e32 v17, v22, v22
	v_add_f32_e32 v16, v16, v17
	v_mul_f32_e32 v17, v19, v19
	v_mul_f32_e32 v26, v25, v25
	v_fmac_f32_e32 v17, v18, v18
	v_fmac_f32_e32 v26, v24, v24
	v_add_f32_e32 v17, v17, v26
	v_add_f32_e32 v16, v16, v17
	v_add_f32_e32 v26, v34, v16
	v_cvt_pk_bf16_f32 v16, v20, v21
	v_cvt_pk_bf16_f32 v17, v22, v23
	v_cvt_pk_bf16_f32 v18, v18, v19
	v_cvt_pk_bf16_f32 v19, v24, v25
	global_store_dwordx4 v[28:29], v[16:19], off offset:256
	s_nop 1
	s_nop 0
	s_nop 2
	v_mov_b32_e32 v16, v26
	s_nop 1
	v_permlane16_swap_b32_e32 v16, v26
	s_waitcnt lgkmcnt(0)
	v_add_f32_e32 v16, v26, v16
	s_nop 1
	v_mov_b32_e32 v17, v16
	s_nop 1
	v_permlane32_swap_b32_e32 v17, v16
	s_and_saveexec_b64 s[52:53], s[8:9]
	s_cbranch_execz .LBB0_1521
	s_waitcnt lgkmcnt(0)
	v_add_f32_e32 v18, v16, v17
	v_lshlrev_b64 v[16:17], 6, v[92:93]
	v_lshl_add_u64 v[16:17], s[22:23], 0, v[16:17]
	v_lshl_add_u64 v[16:17], s[50:51], 2, v[16:17]
	s_lshl_b32 s16, s58, 2
	v_lshl_add_u64 v[16:17], v[16:17], 0, s[16:17]
	global_store_dword v[16:17], v18, off
.LBB0_1521:
	s_or_b64 exec, exec, s[52:53]
	s_waitcnt vmcnt(7)
	v_lshlrev_b32_e32 v16, 16, v68
	s_waitcnt lgkmcnt(0)
	v_and_b32_e32 v17, 0xffff0000, v68
	v_lshlrev_b32_e32 v18, 16, v69
	v_and_b32_e32 v19, 0xffff0000, v69
	v_lshlrev_b32_e32 v20, 16, v70
	v_and_b32_e32 v21, 0xffff0000, v70
	v_lshlrev_b32_e32 v22, 16, v71
	v_and_b32_e32 v23, 0xffff0000, v71
	v_pk_add_f32 v[14:15], v[14:15], v[18:19]
	v_pk_add_f32 v[12:13], v[12:13], v[16:17]
	v_pk_add_f32 v[16:17], v[10:11], v[22:23]
	v_pk_add_f32 v[10:11], v[8:9], v[20:21]
	v_mul_f32_e32 v8, v13, v13
	v_mul_f32_e32 v9, v15, v15
	v_fmac_f32_e32 v8, v12, v12
	v_fmac_f32_e32 v9, v14, v14
	v_add_f32_e32 v8, v8, v9
	v_mul_f32_e32 v9, v11, v11
	v_mul_f32_e32 v18, v17, v17
	v_fmac_f32_e32 v9, v10, v10
	v_fmac_f32_e32 v18, v16, v16
	v_add_f32_e32 v9, v9, v18
	v_add_f32_e32 v18, v8, v9
	v_cvt_pk_bf16_f32 v8, v12, v13
	v_lshl_add_u64 v[12:13], s[20:21], 0, v[90:91]
	v_cvt_pk_bf16_f32 v9, v14, v15
	v_cvt_pk_bf16_f32 v10, v10, v11
	v_cvt_pk_bf16_f32 v11, v16, v17
	v_lshl_add_u64 v[12:13], v[168:169], 1, v[12:13]
	global_store_dwordx4 v[12:13], v[8:11], off
	s_waitcnt vmcnt(7)
	v_lshlrev_b32_e32 v14, 16, v66
	v_and_b32_e32 v15, 0xffff0000, v66
	v_lshlrev_b32_e32 v8, 16, v64
	v_and_b32_e32 v9, 0xffff0000, v64
	v_lshlrev_b32_e32 v10, 16, v65
	v_and_b32_e32 v11, 0xffff0000, v65
	v_lshlrev_b32_e32 v16, 16, v67
	v_and_b32_e32 v17, 0xffff0000, v67
	v_pk_add_f32 v[6:7], v[6:7], v[10:11]
	v_pk_add_f32 v[4:5], v[4:5], v[8:9]
	v_pk_add_f32 v[8:9], v[2:3], v[16:17]
	v_pk_add_f32 v[2:3], v[0:1], v[14:15]
	v_mul_f32_e32 v0, v5, v5
	v_mul_f32_e32 v1, v7, v7
	v_fmac_f32_e32 v0, v4, v4
	v_fmac_f32_e32 v1, v6, v6
	v_add_f32_e32 v0, v0, v1
	v_mul_f32_e32 v1, v3, v3
	v_mul_f32_e32 v10, v9, v9
	v_fmac_f32_e32 v1, v2, v2
	v_fmac_f32_e32 v10, v8, v8
	v_add_f32_e32 v1, v1, v10
	v_add_f32_e32 v0, v0, v1
	v_add_f32_e32 v10, v18, v0
	v_cvt_pk_bf16_f32 v0, v4, v5
	v_cvt_pk_bf16_f32 v1, v6, v7
	v_cvt_pk_bf16_f32 v2, v2, v3
	v_cvt_pk_bf16_f32 v3, v8, v9
	global_store_dwordx4 v[12:13], v[0:3], off offset:256
	s_nop 1
	s_nop 0
	s_nop 2
	v_mov_b32_e32 v0, v10
	s_nop 1
	v_permlane16_swap_b32_e32 v0, v10
	s_waitcnt lgkmcnt(0)
	v_add_f32_e32 v0, v10, v0
	s_nop 1
	v_mov_b32_e32 v1, v0
	s_nop 1
	v_permlane32_swap_b32_e32 v1, v0
	s_and_saveexec_b64 s[52:53], s[8:9]
	s_cbranch_execz .LBB0_1523
	s_waitcnt lgkmcnt(0)
	v_add_f32_e32 v2, v0, v1
	v_lshlrev_b64 v[0:1], 6, v[88:89]
	v_lshl_add_u64 v[0:1], s[22:23], 0, v[0:1]
	v_lshl_add_u64 v[0:1], s[50:51], 2, v[0:1]
	s_lshl_b32 s16, s58, 2
	v_lshl_add_u64 v[0:1], v[0:1], 0, s[16:17]
	global_store_dword v[0:1], v2, off

; __device__ __forceinline__ float row_part(const float* ss, int row, int fq) { const f32x4 a = ((const f32x4*)(ss + (size_t)row * 16))[fq]; return (a[0] + a[1]) + (a[2] + a[3]); }
; __device__ __forceinline__ float row_finish(float t) { t += shx(t, 16); t += shx(t, 32); return __builtin_amdgcn_rsqf(t * (1.0f / 1024.0f) + RMS_EPS); }
;     __device__ __forceinline__ void operator()(const f32x4 (&acc)[2][2][4][2], const Unit& u, int wr, int wc, int fr, int fq) const {
;     ...
;         float rs[2][4];
; #pragma unroll
;         for (int ai = 0; ai < 2; ++ai)
; #pragma unroll
;             for (int m = 0; m < 4; ++m) rs[ai][m] = row_part(ss, u.pm * BM + ai * HALF + wr * 64 + m * 16 + fr, fq);
; #pragma unroll
;         for (int ai = 0; ai < 2; ++ai)
; #pragma unroll
;             for (int m = 0; m < 4; ++m) rs[ai][m] = row_finish(rs[ai][m]);
.LBB0_1591:
	v_lshl_add_u32 v170, s44, 8, v153
	v_ashrrev_i32_e32 v171, 31, v170
	v_or_b32_e32 v166, 16, v170
	v_lshlrev_b64 v[146:147], 6, v[170:171]
	v_ashrrev_i32_e32 v167, 31, v166
	v_lshl_add_u64 v[146:147], v[136:137], 0, v[146:147]
	v_lshlrev_b64 v[148:149], 6, v[166:167]
	v_lshl_add_u64 v[148:149], v[136:137], 0, v[148:149]
	ds_read_b128 v[176:179], v239
	ds_read_b128 v[180:183], v239 offset:1024
	v_or_b32_e32 v162, 32, v170
	v_ashrrev_i32_e32 v163, 31, v162
	v_or_b32_e32 v158, 48, v170
	v_lshlrev_b64 v[146:147], 6, v[162:163]
	v_ashrrev_i32_e32 v159, 31, v158
	v_lshl_add_u64 v[146:147], v[136:137], 0, v[146:147]
	v_lshlrev_b64 v[148:149], 6, v[158:159]
	v_lshl_add_u64 v[148:149], v[136:137], 0, v[148:149]
	ds_read_b128 v[184:187], v239 offset:2048
	ds_read_b128 v[188:191], v239 offset:3072
	v_add_u32_e32 v154, 0x80, v170
	v_ashrrev_i32_e32 v155, 31, v154
	v_add_u32_e32 v150, 0x90, v170
	v_lshlrev_b64 v[146:147], 6, v[154:155]
	v_ashrrev_i32_e32 v151, 31, v150
	v_lshl_add_u64 v[146:147], v[136:137], 0, v[146:147]
	v_lshlrev_b64 v[148:149], 6, v[150:151]
	v_lshl_add_u64 v[148:149], v[136:137], 0, v[148:149]
	ds_read_b128 v[192:195], v239 offset:8192
	ds_read_b128 v[196:199], v239 offset:9216
	v_add_u32_e32 v148, 0xa0, v170
	v_ashrrev_i32_e32 v149, 31, v148
	v_lshlrev_b64 v[146:147], 6, v[148:149]
	v_lshl_add_u64 v[146:147], v[136:137], 0, v[146:147]
	ds_read_b128 v[202:205], v239 offset:10240
	v_add_u32_e32 v146, 0xb0, v170
	v_ashrrev_i32_e32 v147, 31, v146
	v_lshlrev_b64 v[206:207], 6, v[146:147]
	v_lshl_add_u64 v[206:207], v[136:137], 0, v[206:207]
	ds_read_b128 v[206:209], v239 offset:11264
	s_nop 0
	s_nop 3
	s_andn2_b64 vcc, exec, s[8:9]
	s_nop 3
	s_mov_b64 s[8:9], -1
	s_waitcnt lgkmcnt(0)
	v_mov_b32_e32 v210, v177
	v_mov_b32_e32 v211, v178
	v_mov_b32_e32 v177, v179
	v_pk_add_f32 v[176:177], v[210:211], v[176:177]
	v_mov_b32_e32 v178, v181
	v_add_f32_e32 v152, v176, v177
	v_mov_b32_e32 v179, v182
	v_mov_b32_e32 v181, v183
	v_mov_b32_e32 v147, v152
	s_nop 1
	v_permlane16_swap_b32_e32 v147, v152
	v_pk_add_f32 v[176:177], v[178:179], v[180:181]
	v_mov_b32_e32 v182, v185
	v_add_f32_e32 v155, v176, v177
	v_mov_b32_e32 v151, v155
	s_nop 1
	v_permlane16_swap_b32_e32 v151, v155
	s_waitcnt lgkmcnt(0)
	v_add_f32_e32 v147, v152, v147
	s_nop 0
	v_mov_b32_e32 v149, v147
	s_nop 1
	v_permlane32_swap_b32_e32 v149, v147
	s_waitcnt lgkmcnt(0)
	v_add_f32_e32 v151, v155, v151
	s_nop 1
	v_mov_b32_e32 v152, v151
	s_nop 1
	v_permlane32_swap_b32_e32 v152, v151
	s_waitcnt lgkmcnt(0)
	v_add_f32_e32 v147, v147, v149
	s_nop 0
	v_mov_b32_e32 v183, v186
	v_mov_b32_e32 v185, v187
	v_pk_add_f32 v[178:179], v[182:183], v[184:185]
	v_fmamk_f32 v147, v147, 0x3a800000, v175
	s_nop 0
	v_add_f32_e32 v156, v178, v179
	v_rsq_f32_e32 v176, v147
	s_waitcnt lgkmcnt(0)
	v_add_f32_e32 v147, v151, v152
	s_nop 2
	v_mov_b32_e32 v186, v189
	v_mov_b32_e32 v187, v190
	v_mov_b32_e32 v189, v191
	v_mov_b32_e32 v149, v156
	s_nop 1
	v_permlane16_swap_b32_e32 v149, v156
	v_pk_add_f32 v[180:181], v[186:187], v[188:189]
	s_nop 0
	v_add_f32_e32 v159, v180, v181
	s_nop 0
	v_mov_b32_e32 v152, v159
	s_nop 1
	v_permlane16_swap_b32_e32 v152, v159
	s_waitcnt lgkmcnt(0)
	v_add_f32_e32 v149, v156, v149
	s_nop 2
	v_mov_b32_e32 v151, v149
	s_nop 1
	v_permlane32_swap_b32_e32 v151, v149
	s_nop 0
	s_waitcnt lgkmcnt(0)
	v_add_f32_e32 v152, v159, v152
	s_nop 0
	v_mov_b32_e32 v156, v152
	s_nop 1
	v_permlane32_swap_b32_e32 v156, v152
	v_fmamk_f32 v147, v147, 0x3a800000, v175
	v_rsq_f32_e32 v174, v147
	s_waitcnt lgkmcnt(0)
	v_add_f32_e32 v147, v149, v151
	s_nop 0
	v_mov_b32_e32 v190, v193
	v_mov_b32_e32 v191, v194
	v_mov_b32_e32 v193, v195
	v_fmamk_f32 v147, v147, 0x3a800000, v175
	v_pk_add_f32 v[182:183], v[190:191], v[192:193]
	v_rsq_f32_e32 v172, v147
	s_waitcnt lgkmcnt(0)
	v_add_f32_e32 v147, v152, v156
	s_nop 2
	v_mov_b32_e32 v194, v197
	v_mov_b32_e32 v195, v198
	v_mov_b32_e32 v197, v199
	v_add_f32_e32 v160, v182, v183
	s_nop 0
	v_pk_add_f32 v[184:185], v[194:195], v[196:197]
	v_mov_b32_e32 v149, v160
	s_nop 1
	v_permlane16_swap_b32_e32 v149, v160
	s_nop 0
	v_add_f32_e32 v163, v184, v185
	s_nop 0
	v_mov_b32_e32 v152, v163
	s_nop 1
	v_permlane16_swap_b32_e32 v152, v163
	s_nop 1
	s_waitcnt lgkmcnt(0)
	v_add_f32_e32 v149, v160, v149
	s_nop 0
	v_mov_b32_e32 v151, v149
	s_nop 1
	v_permlane32_swap_b32_e32 v151, v149
	s_nop 0
	s_waitcnt lgkmcnt(0)
	v_add_f32_e32 v152, v163, v152
	s_nop 0
	v_mov_b32_e32 v156, v152
	s_nop 1
	v_permlane32_swap_b32_e32 v156, v152
	v_fmamk_f32 v147, v147, 0x3a800000, v175
	v_rsq_f32_e32 v168, v147
	s_waitcnt lgkmcnt(0)
	v_add_f32_e32 v147, v149, v151
	v_fmamk_f32 v147, v147, 0x3a800000, v175
	v_rsq_f32_e32 v164, v147
	s_waitcnt lgkmcnt(0)
	v_add_f32_e32 v147, v152, v156
	s_nop 2
	v_mov_b32_e32 v198, v203
	v_mov_b32_e32 v199, v204
	v_mov_b32_e32 v203, v205
	v_mov_b32_e32 v204, v207
	v_mov_b32_e32 v205, v208
	v_mov_b32_e32 v207, v209
	v_pk_add_f32 v[188:189], v[204:205], v[206:207]
	s_nop 0
	v_pk_add_f32 v[186:187], v[198:199], v[202:203]
	v_add_f32_e32 v155, v188, v189
	s_nop 1
	v_add_f32_e32 v167, v186, v187
	s_nop 0
	v_mov_b32_e32 v152, v155
	s_nop 1
	v_permlane16_swap_b32_e32 v152, v155
	v_mov_b32_e32 v149, v167
	s_nop 1
	v_permlane16_swap_b32_e32 v149, v167
	s_nop 1
	v_fmamk_f32 v147, v147, 0x3a800000, v175
	s_waitcnt lgkmcnt(0)
	v_add_f32_e32 v152, v155, v152
	s_nop 0
	s_waitcnt lgkmcnt(0)
	v_add_f32_e32 v149, v167, v149
	v_mov_b32_e32 v151, v149
	s_nop 1
	v_permlane32_swap_b32_e32 v151, v149
	s_nop 1
	v_mov_b32_e32 v155, v152
	s_nop 1
	v_permlane32_swap_b32_e32 v155, v152
	v_rsq_f32_e32 v160, v147
	s_waitcnt lgkmcnt(0)
; __device__ __forceinline__ f32x4 silu4(f32x4 v) { return (f32x4){silu_f(v[0]), silu_f(v[1]), silu_f(v[2]), silu_f(v[3])}; }
; __device__ __forceinline__ u32x4 pack8(f32x4 a, f32x4 b) { u32x4 w; w.x = cvt_pk_bf16(a[0], a[1]); w.y = cvt_pk_bf16(a[2], a[3]); w.z = cvt_pk_bf16(b[0], b[1]); w.w = cvt_pk_bf16(b[2], b[3]); return w; }
;     __device__ __forceinline__ void operator()(const f32x4 (&acc)[2][2][4][2], const Unit& u, int wr, int wc, int fr, int fq) const {
;     ...
; #pragma unroll
;         for (int ai = 0; ai < 2; ++ai)
; #pragma unroll
;             for (int m = 0; m < 4; ++m) {
;                 const int row = u.pm * BM + ai * HALF + wr * 64 + m * 16 + fr;
;                 const float rstd = rs[ai][m];
;                 const f32x4 a0 = silu4(acc[ai][0][m][0] * rstd) * (acc[ai][1][m][0] * rstd);
;                 const f32x4 a1 = silu4(acc[ai][0][m][1] * rstd) * (acc[ai][1][m][1] * rstd);
;                 *(u32x4*)(ACT + (size_t)row * 2816 + col0) = pack8(a0, a1);
;             }
	v_add_f32_e32 v147, v149, v151
	v_fmamk_f32 v147, v147, 0x3a800000, v175
	v_rsq_f32_e32 v156, v147
	s_waitcnt lgkmcnt(0)
	v_add_f32_e32 v147, v152, v155
	v_fmamk_f32 v147, v147, 0x3a800000, v175
	v_pk_mul_f32 v[124:125], v[124:125], v[176:177] op_sel_hi:[1,0]
	v_rsq_f32_e32 v152, v147
	v_mul_f32_e32 v147, 0xbfb8aa3b, v124
	v_exp_f32_e32 v147, v147
	v_mul_f32_e32 v149, 0xbfb8aa3b, v125
	v_exp_f32_e32 v149, v149
	v_pk_mul_f32 v[126:127], v[126:127], v[176:177] op_sel_hi:[1,0]
	v_add_f32_e32 v147, 1.0, v147
	v_rcp_f32_e32 v178, v147
	v_add_f32_e32 v147, 1.0, v149
	v_mul_f32_e32 v149, 0xbfb8aa3b, v126
	v_exp_f32_e32 v149, v149
	v_mul_f32_e32 v151, 0xbfb8aa3b, v127
	v_exp_f32_e32 v151, v151
	v_rcp_f32_e32 v179, v147
	v_add_f32_e32 v147, 1.0, v149
	v_rcp_f32_e32 v180, v147
	v_add_f32_e32 v147, 1.0, v151
	v_pk_mul_f32 v[120:121], v[120:121], v[176:177] op_sel_hi:[1,0]
	v_rcp_f32_e32 v181, v147
	v_mul_f32_e32 v147, 0xbfb8aa3b, v120
	v_exp_f32_e32 v147, v147
	v_mul_f32_e32 v149, 0xbfb8aa3b, v121
	v_exp_f32_e32 v149, v149
	v_pk_mul_f32 v[122:123], v[122:123], v[176:177] op_sel_hi:[1,0]
	v_add_f32_e32 v147, 1.0, v147
	v_pk_mul_f32 v[124:125], v[124:125], v[178:179]
	v_rcp_f32_e32 v178, v147
	v_add_f32_e32 v147, 1.0, v149
	v_mul_f32_e32 v149, 0xbfb8aa3b, v122
	v_exp_f32_e32 v149, v149
	v_mul_f32_e32 v151, 0xbfb8aa3b, v123
	v_exp_f32_e32 v151, v151
	v_rcp_f32_e32 v179, v147
	v_add_f32_e32 v147, 1.0, v149
	v_pk_mul_f32 v[126:127], v[126:127], v[180:181]
	v_rcp_f32_e32 v180, v147
	v_add_f32_e32 v147, 1.0, v151
	v_rcp_f32_e32 v181, v147
	v_pk_mul_f32 v[116:117], v[116:117], v[176:177] op_sel_hi:[1,0]
	v_pk_mul_f32 v[118:119], v[118:119], v[176:177] op_sel_hi:[1,0]
	v_pk_mul_f32 v[120:121], v[120:121], v[178:179]
	v_pk_mul_f32 v[112:113], v[112:113], v[176:177] op_sel_hi:[1,0]
	v_lshl_or_b32 v182, s61, 7, v161
	v_pk_mul_f32 v[118:119], v[118:119], v[126:127]
	v_pk_mul_f32 v[116:117], v[116:117], v[124:125]
	v_pk_mul_f32 v[122:123], v[122:123], v[180:181]
	v_pk_mul_f32 v[114:115], v[114:115], v[176:177] op_sel_hi:[1,0]
	v_pk_mul_f32 v[112:113], v[112:113], v[120:121]
	v_ashrrev_i32_e32 v183, 31, v182
	v_pk_mul_f32 v[114:115], v[114:115], v[122:123]
	v_cvt_pk_bf16_f32 v116, v116, v117
	v_cvt_pk_bf16_f32 v117, v118, v119
	v_cvt_pk_bf16_f32 v118, v112, v113
	v_mov_b64_e32 v[112:113], s[16:17]
	v_cvt_pk_bf16_f32 v119, v114, v115
	v_mad_i64_i32 v[120:121], s[46:47], v170, s60, v[112:113]
	v_lshlrev_b64 v[114:115], 1, v[182:183]
	v_pk_mul_f32 v[108:109], v[108:109], v[174:175] op_sel_hi:[1,0]
	v_pk_mul_f32 v[110:111], v[110:111], v[174:175] op_sel_hi:[1,0]
	v_mul_f32_e32 v122, 0xbfb8aa3b, v108
	v_mul_f32_e32 v123, 0xbfb8aa3b, v109
	v_lshl_add_u64 v[120:121], v[120:121], 0, v[114:115]
	v_pk_mul_f32 v[104:105], v[104:105], v[174:175] op_sel_hi:[1,0]
	v_pk_mul_f32 v[106:107], v[106:107], v[174:175] op_sel_hi:[1,0]
	v_exp_f32_e32 v122, v122
	v_exp_f32_e32 v123, v123
	v_mul_f32_e32 v124, 0xbfb8aa3b, v110
	v_mul_f32_e32 v125, 0xbfb8aa3b, v111
	global_store_dwordx4 v[120:121], v[116:119], off
	v_exp_f32_e32 v124, v124
	v_exp_f32_e32 v125, v125
	v_mul_f32_e32 v116, 0xbfb8aa3b, v104
	v_mul_f32_e32 v117, 0xbfb8aa3b, v105
	v_mul_f32_e32 v118, 0xbfb8aa3b, v106
	v_mul_f32_e32 v119, 0xbfb8aa3b, v107
	v_exp_f32_e32 v116, v116
	v_exp_f32_e32 v117, v117
	v_exp_f32_e32 v118, v118
	v_exp_f32_e32 v119, v119
	v_add_f32_e32 v122, 1.0, v122
	v_add_f32_e32 v123, 1.0, v123
	v_rcp_f32_e32 v122, v122
	v_rcp_f32_e32 v123, v123
	v_add_f32_e32 v124, 1.0, v124
	v_add_f32_e32 v125, 1.0, v125
	v_add_f32_e32 v116, 1.0, v116
	v_add_f32_e32 v117, 1.0, v117
	v_add_f32_e32 v118, 1.0, v118
	v_add_f32_e32 v119, 1.0, v119
	v_rcp_f32_e32 v124, v124
	v_rcp_f32_e32 v125, v125
	v_rcp_f32_e32 v116, v116
	v_rcp_f32_e32 v117, v117
	v_rcp_f32_e32 v118, v118
	v_rcp_f32_e32 v119, v119
	v_pk_mul_f32 v[108:109], v[108:109], v[122:123]
	v_pk_mul_f32 v[100:101], v[100:101], v[174:175] op_sel_hi:[1,0]
	v_pk_mul_f32 v[110:111], v[110:111], v[124:125]
	v_pk_mul_f32 v[102:103], v[102:103], v[174:175] op_sel_hi:[1,0]
	v_pk_mul_f32 v[100:101], v[100:101], v[108:109]
	v_pk_mul_f32 v[104:105], v[104:105], v[116:117]
	v_pk_mul_f32 v[106:107], v[106:107], v[118:119]
	v_pk_mul_f32 v[96:97], v[96:97], v[174:175] op_sel_hi:[1,0]
	v_pk_mul_f32 v[98:99], v[98:99], v[174:175] op_sel_hi:[1,0]
	v_pk_mul_f32 v[102:103], v[102:103], v[110:111]
	v_pk_mul_f32 v[106:107], v[98:99], v[106:107]
	v_pk_mul_f32 v[98:99], v[96:97], v[104:105]
	v_cvt_pk_bf16_f32 v96, v100, v101
	v_mad_i64_i32 v[100:101], s[46:47], v166, s60, v[112:113]
	v_pk_mul_f32 v[92:93], v[92:93], v[172:173] op_sel_hi:[1,0]
	v_cvt_pk_bf16_f32 v97, v102, v103
	v_cvt_pk_bf16_f32 v98, v98, v99
	v_cvt_pk_bf16_f32 v99, v106, v107
	v_pk_mul_f32 v[94:95], v[94:95], v[172:173] op_sel_hi:[1,0]
	v_mul_f32_e32 v102, 0xbfb8aa3b, v92
	v_mul_f32_e32 v103, 0xbfb8aa3b, v93
	v_lshl_add_u64 v[100:101], v[100:101], 0, v[114:115]
	v_pk_mul_f32 v[88:89], v[88:89], v[172:173] op_sel_hi:[1,0]
	v_pk_mul_f32 v[90:91], v[90:91], v[172:173] op_sel_hi:[1,0]
	v_exp_f32_e32 v102, v102
	v_exp_f32_e32 v103, v103
	v_mul_f32_e32 v104, 0xbfb8aa3b, v94
	v_mul_f32_e32 v105, 0xbfb8aa3b, v95
	global_store_dwordx4 v[100:101], v[96:99], off
	v_exp_f32_e32 v104, v104
	v_exp_f32_e32 v105, v105
	v_mul_f32_e32 v96, 0xbfb8aa3b, v88
	v_mul_f32_e32 v97, 0xbfb8aa3b, v89
	v_mul_f32_e32 v98, 0xbfb8aa3b, v90
	v_mul_f32_e32 v99, 0xbfb8aa3b, v91
	v_exp_f32_e32 v96, v96
	v_exp_f32_e32 v97, v97
	v_exp_f32_e32 v98, v98
	v_exp_f32_e32 v99, v99
	v_add_f32_e32 v102, 1.0, v102
	v_add_f32_e32 v103, 1.0, v103
	v_rcp_f32_e32 v102, v102
	v_rcp_f32_e32 v103, v103
	v_add_f32_e32 v104, 1.0, v104
	v_add_f32_e32 v105, 1.0, v105
; __device__ __forceinline__ f32x4 silu4(f32x4 v) { return (f32x4){silu_f(v[0]), silu_f(v[1]), silu_f(v[2]), silu_f(v[3])}; }
; __device__ __forceinline__ u32x4 pack8(f32x4 a, f32x4 b) { u32x4 w; w.x = cvt_pk_bf16(a[0], a[1]); w.y = cvt_pk_bf16(a[2], a[3]); w.z = cvt_pk_bf16(b[0], b[1]); w.w = cvt_pk_bf16(b[2], b[3]); return w; }
;     __device__ __forceinline__ void operator()(const f32x4 (&acc)[2][2][4][2], const Unit& u, int wr, int wc, int fr, int fq) const {
;     ...
; #pragma unroll
;         for (int ai = 0; ai < 2; ++ai)
; #pragma unroll
;             for (int m = 0; m < 4; ++m) {
;                 const int row = u.pm * BM + ai * HALF + wr * 64 + m * 16 + fr;
;                 const float rstd = rs[ai][m];
;                 const f32x4 a0 = silu4(acc[ai][0][m][0] * rstd) * (acc[ai][1][m][0] * rstd);
;                 const f32x4 a1 = silu4(acc[ai][0][m][1] * rstd) * (acc[ai][1][m][1] * rstd);
;                 *(u32x4*)(ACT + (size_t)row * 2816 + col0) = pack8(a0, a1);
;             }
	v_add_f32_e32 v96, 1.0, v96
	v_add_f32_e32 v97, 1.0, v97
	v_add_f32_e32 v98, 1.0, v98
	v_add_f32_e32 v99, 1.0, v99
	v_rcp_f32_e32 v104, v104
	v_rcp_f32_e32 v105, v105
	v_rcp_f32_e32 v96, v96
	v_rcp_f32_e32 v97, v97
	v_rcp_f32_e32 v98, v98
	v_rcp_f32_e32 v99, v99
	v_pk_mul_f32 v[92:93], v[92:93], v[102:103]
	v_pk_mul_f32 v[84:85], v[84:85], v[172:173] op_sel_hi:[1,0]
	v_pk_mul_f32 v[94:95], v[94:95], v[104:105]
	v_pk_mul_f32 v[86:87], v[86:87], v[172:173] op_sel_hi:[1,0]
	v_pk_mul_f32 v[84:85], v[84:85], v[92:93]
	v_pk_mul_f32 v[88:89], v[88:89], v[96:97]
	v_pk_mul_f32 v[90:91], v[90:91], v[98:99]
	v_pk_mul_f32 v[80:81], v[80:81], v[172:173] op_sel_hi:[1,0]
	v_pk_mul_f32 v[82:83], v[82:83], v[172:173] op_sel_hi:[1,0]
	v_pk_mul_f32 v[86:87], v[86:87], v[94:95]
	v_pk_mul_f32 v[90:91], v[82:83], v[90:91]
	v_pk_mul_f32 v[82:83], v[80:81], v[88:89]
	v_cvt_pk_bf16_f32 v80, v84, v85
	v_mad_i64_i32 v[84:85], s[46:47], v162, s60, v[112:113]
	v_pk_mul_f32 v[76:77], v[76:77], v[168:169] op_sel_hi:[1,0]
	v_cvt_pk_bf16_f32 v81, v86, v87
	v_cvt_pk_bf16_f32 v82, v82, v83
	v_cvt_pk_bf16_f32 v83, v90, v91
	v_pk_mul_f32 v[78:79], v[78:79], v[168:169] op_sel_hi:[1,0]
	v_mul_f32_e32 v86, 0xbfb8aa3b, v76
	v_mul_f32_e32 v87, 0xbfb8aa3b, v77
	v_lshl_add_u64 v[84:85], v[84:85], 0, v[114:115]
	v_pk_mul_f32 v[72:73], v[72:73], v[168:169] op_sel_hi:[1,0]
	v_pk_mul_f32 v[74:75], v[74:75], v[168:169] op_sel_hi:[1,0]
	v_exp_f32_e32 v86, v86
	v_exp_f32_e32 v87, v87
	v_mul_f32_e32 v88, 0xbfb8aa3b, v78
	v_mul_f32_e32 v89, 0xbfb8aa3b, v79
	global_store_dwordx4 v[84:85], v[80:83], off
	v_exp_f32_e32 v88, v88
	v_exp_f32_e32 v89, v89
	v_mul_f32_e32 v80, 0xbfb8aa3b, v72
	v_mul_f32_e32 v81, 0xbfb8aa3b, v73
	v_mul_f32_e32 v82, 0xbfb8aa3b, v74
	v_mul_f32_e32 v83, 0xbfb8aa3b, v75
	v_exp_f32_e32 v80, v80
	v_exp_f32_e32 v81, v81
	v_exp_f32_e32 v82, v82
	v_exp_f32_e32 v83, v83
	v_add_f32_e32 v86, 1.0, v86
	v_add_f32_e32 v87, 1.0, v87
	v_rcp_f32_e32 v86, v86
	v_rcp_f32_e32 v87, v87
	v_add_f32_e32 v88, 1.0, v88
	v_add_f32_e32 v89, 1.0, v89
	v_add_f32_e32 v80, 1.0, v80
	v_add_f32_e32 v81, 1.0, v81
	v_add_f32_e32 v82, 1.0, v82
	v_add_f32_e32 v83, 1.0, v83
	v_rcp_f32_e32 v88, v88
	v_rcp_f32_e32 v89, v89
	v_rcp_f32_e32 v80, v80
	v_rcp_f32_e32 v81, v81
	v_rcp_f32_e32 v82, v82
	v_rcp_f32_e32 v83, v83
	v_pk_mul_f32 v[76:77], v[76:77], v[86:87]
	v_pk_mul_f32 v[68:69], v[68:69], v[168:169] op_sel_hi:[1,0]
	v_pk_mul_f32 v[78:79], v[78:79], v[88:89]
	v_pk_mul_f32 v[70:71], v[70:71], v[168:169] op_sel_hi:[1,0]
	v_pk_mul_f32 v[68:69], v[68:69], v[76:77]
	v_pk_mul_f32 v[72:73], v[72:73], v[80:81]
	v_pk_mul_f32 v[74:75], v[74:75], v[82:83]
	v_pk_mul_f32 v[64:65], v[64:65], v[168:169] op_sel_hi:[1,0]
	v_pk_mul_f32 v[66:67], v[66:67], v[168:169] op_sel_hi:[1,0]
	v_pk_mul_f32 v[70:71], v[70:71], v[78:79]
	v_pk_mul_f32 v[74:75], v[66:67], v[74:75]
	v_pk_mul_f32 v[66:67], v[64:65], v[72:73]
	v_cvt_pk_bf16_f32 v64, v68, v69
	v_mad_i64_i32 v[68:69], s[46:47], v158, s60, v[112:113]
	v_pk_mul_f32 v[60:61], v[60:61], v[164:165] op_sel_hi:[1,0]
	v_cvt_pk_bf16_f32 v65, v70, v71
	v_cvt_pk_bf16_f32 v66, v66, v67
	v_cvt_pk_bf16_f32 v67, v74, v75
	v_pk_mul_f32 v[62:63], v[62:63], v[164:165] op_sel_hi:[1,0]
	v_mul_f32_e32 v70, 0xbfb8aa3b, v60
	v_mul_f32_e32 v71, 0xbfb8aa3b, v61
	v_lshl_add_u64 v[68:69], v[68:69], 0, v[114:115]
	v_pk_mul_f32 v[56:57], v[56:57], v[164:165] op_sel_hi:[1,0]
	v_pk_mul_f32 v[58:59], v[58:59], v[164:165] op_sel_hi:[1,0]
	v_exp_f32_e32 v70, v70
	v_exp_f32_e32 v71, v71
	v_mul_f32_e32 v72, 0xbfb8aa3b, v62
	v_mul_f32_e32 v73, 0xbfb8aa3b, v63
	global_store_dwordx4 v[68:69], v[64:67], off
	v_exp_f32_e32 v72, v72
	v_exp_f32_e32 v73, v73
	v_mul_f32_e32 v64, 0xbfb8aa3b, v56
	v_mul_f32_e32 v65, 0xbfb8aa3b, v57
	v_mul_f32_e32 v66, 0xbfb8aa3b, v58
	v_mul_f32_e32 v67, 0xbfb8aa3b, v59
	v_exp_f32_e32 v64, v64
	v_exp_f32_e32 v65, v65
	v_exp_f32_e32 v66, v66
	v_exp_f32_e32 v67, v67
	v_add_f32_e32 v70, 1.0, v70
	v_add_f32_e32 v71, 1.0, v71
	v_rcp_f32_e32 v70, v70
	v_rcp_f32_e32 v71, v71
	v_add_f32_e32 v72, 1.0, v72
	v_add_f32_e32 v73, 1.0, v73
	v_add_f32_e32 v64, 1.0, v64
	v_add_f32_e32 v65, 1.0, v65
	v_add_f32_e32 v66, 1.0, v66
	v_add_f32_e32 v67, 1.0, v67
	v_rcp_f32_e32 v72, v72
	v_rcp_f32_e32 v73, v73
	v_rcp_f32_e32 v64, v64
	v_rcp_f32_e32 v65, v65
	v_rcp_f32_e32 v66, v66
	v_rcp_f32_e32 v67, v67
	v_pk_mul_f32 v[60:61], v[60:61], v[70:71]
	v_pk_mul_f32 v[52:53], v[52:53], v[164:165] op_sel_hi:[1,0]
	v_pk_mul_f32 v[62:63], v[62:63], v[72:73]
	v_pk_mul_f32 v[54:55], v[54:55], v[164:165] op_sel_hi:[1,0]
	v_pk_mul_f32 v[52:53], v[52:53], v[60:61]
	v_pk_mul_f32 v[56:57], v[56:57], v[64:65]
	v_pk_mul_f32 v[58:59], v[58:59], v[66:67]
	v_pk_mul_f32 v[48:49], v[48:49], v[164:165] op_sel_hi:[1,0]
	v_pk_mul_f32 v[50:51], v[50:51], v[164:165] op_sel_hi:[1,0]
	v_pk_mul_f32 v[54:55], v[54:55], v[62:63]
	v_pk_mul_f32 v[58:59], v[50:51], v[58:59]
	v_pk_mul_f32 v[50:51], v[48:49], v[56:57]
	v_cvt_pk_bf16_f32 v48, v52, v53
	v_mad_i64_i32 v[52:53], s[46:47], v154, s60, v[112:113]
	v_pk_mul_f32 v[44:45], v[44:45], v[160:161] op_sel_hi:[1,0]
	v_cvt_pk_bf16_f32 v49, v54, v55
	v_cvt_pk_bf16_f32 v50, v50, v51
	v_cvt_pk_bf16_f32 v51, v58, v59
	v_pk_mul_f32 v[46:47], v[46:47], v[160:161] op_sel_hi:[1,0]
	v_mul_f32_e32 v54, 0xbfb8aa3b, v44
	v_mul_f32_e32 v55, 0xbfb8aa3b, v45
	v_lshl_add_u64 v[52:53], v[52:53], 0, v[114:115]
	v_pk_mul_f32 v[40:41], v[40:41], v[160:161] op_sel_hi:[1,0]
	v_pk_mul_f32 v[42:43], v[42:43], v[160:161] op_sel_hi:[1,0]
	v_exp_f32_e32 v54, v54
	v_exp_f32_e32 v55, v55
	v_mul_f32_e32 v56, 0xbfb8aa3b, v46
	v_mul_f32_e32 v57, 0xbfb8aa3b, v47
	global_store_dwordx4 v[52:53], v[48:51], off
	v_exp_f32_e32 v56, v56
; __device__ __forceinline__ f32x4 silu4(f32x4 v) { return (f32x4){silu_f(v[0]), silu_f(v[1]), silu_f(v[2]), silu_f(v[3])}; }
; __device__ __forceinline__ u32x4 pack8(f32x4 a, f32x4 b) { u32x4 w; w.x = cvt_pk_bf16(a[0], a[1]); w.y = cvt_pk_bf16(a[2], a[3]); w.z = cvt_pk_bf16(b[0], b[1]); w.w = cvt_pk_bf16(b[2], b[3]); return w; }
; #define PG8_BAR __builtin_amdgcn_s_barrier()
;     __device__ __forceinline__ void operator()(const f32x4 (&acc)[2][2][4][2], const Unit& u, int wr, int wc, int fr, int fq) const {
;     ...
; #pragma unroll
;         for (int ai = 0; ai < 2; ++ai)
; #pragma unroll
;             for (int m = 0; m < 4; ++m) {
;                 const int row = u.pm * BM + ai * HALF + wr * 64 + m * 16 + fr;
;                 const float rstd = rs[ai][m];
;                 const f32x4 a0 = silu4(acc[ai][0][m][0] * rstd) * (acc[ai][1][m][0] * rstd);
;                 const f32x4 a1 = silu4(acc[ai][0][m][1] * rstd) * (acc[ai][1][m][1] * rstd);
;                 *(u32x4*)(ACT + (size_t)row * 2816 + col0) = pack8(a0, a1);
;             }
; template <class Epi, class Sched, bool ALIGN_EPI = false, bool SP2 = false>
; __device__ __forceinline__ void gemm_phase(PG8_LAS unsigned char* lds, const Gemm g, const Sched& S, const Epi& E, int tid_in) {
;     ...
;         if (!has_next) break;
; #pragma unroll
;         for (int a = 0; a < 2; ++a)
; #pragma unroll
;             for (int b = 0; b < 2; ++b)
; #pragma unroll
;                 for (int m = 0; m < 4; ++m)
; #pragma unroll
;                     for (int n = 0; n < 2; ++n) acc[a][b][m][n] = (f32x4){0.f, 0.f, 0.f, 0.f};
;         cur = nxt; cA = nA; cB = nB; ++ui;
;         if constexpr (ALIGN_EPI) { if (wr == 1) PG8_BAR; }
;     }
	v_exp_f32_e32 v57, v57
	v_mul_f32_e32 v48, 0xbfb8aa3b, v40
	v_mul_f32_e32 v49, 0xbfb8aa3b, v41
	v_mul_f32_e32 v50, 0xbfb8aa3b, v42
	v_mul_f32_e32 v51, 0xbfb8aa3b, v43
	v_exp_f32_e32 v48, v48
	v_exp_f32_e32 v49, v49
	v_exp_f32_e32 v50, v50
	v_exp_f32_e32 v51, v51
	v_add_f32_e32 v54, 1.0, v54
	v_add_f32_e32 v55, 1.0, v55
	v_rcp_f32_e32 v54, v54
	v_rcp_f32_e32 v55, v55
	v_add_f32_e32 v56, 1.0, v56
	v_add_f32_e32 v57, 1.0, v57
	v_add_f32_e32 v48, 1.0, v48
	v_add_f32_e32 v49, 1.0, v49
	v_add_f32_e32 v50, 1.0, v50
	v_add_f32_e32 v51, 1.0, v51
	v_rcp_f32_e32 v56, v56
	v_rcp_f32_e32 v57, v57
	v_rcp_f32_e32 v48, v48
	v_rcp_f32_e32 v49, v49
	v_rcp_f32_e32 v50, v50
	v_rcp_f32_e32 v51, v51
	v_pk_mul_f32 v[44:45], v[44:45], v[54:55]
	v_pk_mul_f32 v[36:37], v[36:37], v[160:161] op_sel_hi:[1,0]
	v_pk_mul_f32 v[46:47], v[46:47], v[56:57]
	v_pk_mul_f32 v[38:39], v[38:39], v[160:161] op_sel_hi:[1,0]
	v_pk_mul_f32 v[36:37], v[36:37], v[44:45]
	v_pk_mul_f32 v[40:41], v[40:41], v[48:49]
	v_pk_mul_f32 v[42:43], v[42:43], v[50:51]
	v_pk_mul_f32 v[32:33], v[32:33], v[160:161] op_sel_hi:[1,0]
	v_pk_mul_f32 v[34:35], v[34:35], v[160:161] op_sel_hi:[1,0]
	v_pk_mul_f32 v[38:39], v[38:39], v[46:47]
	v_pk_mul_f32 v[42:43], v[34:35], v[42:43]
	v_pk_mul_f32 v[34:35], v[32:33], v[40:41]
	v_cvt_pk_bf16_f32 v32, v36, v37
	v_mad_i64_i32 v[36:37], s[46:47], v150, s60, v[112:113]
	v_pk_mul_f32 v[28:29], v[28:29], v[156:157] op_sel_hi:[1,0]
	v_cvt_pk_bf16_f32 v33, v38, v39
	v_cvt_pk_bf16_f32 v34, v34, v35
	v_cvt_pk_bf16_f32 v35, v42, v43
	v_pk_mul_f32 v[30:31], v[30:31], v[156:157] op_sel_hi:[1,0]
	v_mul_f32_e32 v38, 0xbfb8aa3b, v28
	v_mul_f32_e32 v39, 0xbfb8aa3b, v29
	v_lshl_add_u64 v[36:37], v[36:37], 0, v[114:115]
	v_pk_mul_f32 v[24:25], v[24:25], v[156:157] op_sel_hi:[1,0]
	v_pk_mul_f32 v[26:27], v[26:27], v[156:157] op_sel_hi:[1,0]
	v_exp_f32_e32 v38, v38
	v_exp_f32_e32 v39, v39
	v_mul_f32_e32 v40, 0xbfb8aa3b, v30
	v_mul_f32_e32 v41, 0xbfb8aa3b, v31
	global_store_dwordx4 v[36:37], v[32:35], off
	v_exp_f32_e32 v40, v40
	v_exp_f32_e32 v41, v41
	v_mul_f32_e32 v32, 0xbfb8aa3b, v24
	v_mul_f32_e32 v33, 0xbfb8aa3b, v25
	v_mul_f32_e32 v34, 0xbfb8aa3b, v26
	v_mul_f32_e32 v35, 0xbfb8aa3b, v27
	v_exp_f32_e32 v32, v32
	v_exp_f32_e32 v33, v33
	v_exp_f32_e32 v34, v34
	v_exp_f32_e32 v35, v35
	v_add_f32_e32 v38, 1.0, v38
	v_add_f32_e32 v39, 1.0, v39
	v_rcp_f32_e32 v38, v38
	v_rcp_f32_e32 v39, v39
	v_add_f32_e32 v40, 1.0, v40
	v_add_f32_e32 v41, 1.0, v41
	v_add_f32_e32 v32, 1.0, v32
	v_add_f32_e32 v33, 1.0, v33
	v_add_f32_e32 v34, 1.0, v34
	v_add_f32_e32 v35, 1.0, v35
	v_rcp_f32_e32 v40, v40
	v_rcp_f32_e32 v41, v41
	v_rcp_f32_e32 v32, v32
	v_rcp_f32_e32 v33, v33
	v_rcp_f32_e32 v34, v34
	v_rcp_f32_e32 v35, v35
	v_pk_mul_f32 v[28:29], v[28:29], v[38:39]
	v_pk_mul_f32 v[20:21], v[20:21], v[156:157] op_sel_hi:[1,0]
	v_pk_mul_f32 v[30:31], v[30:31], v[40:41]
	v_pk_mul_f32 v[22:23], v[22:23], v[156:157] op_sel_hi:[1,0]
	v_pk_mul_f32 v[20:21], v[20:21], v[28:29]
	v_pk_mul_f32 v[24:25], v[24:25], v[32:33]
	v_pk_mul_f32 v[26:27], v[26:27], v[34:35]
	v_pk_mul_f32 v[16:17], v[16:17], v[156:157] op_sel_hi:[1,0]
	v_pk_mul_f32 v[18:19], v[18:19], v[156:157] op_sel_hi:[1,0]
	v_pk_mul_f32 v[22:23], v[22:23], v[30:31]
	v_pk_mul_f32 v[26:27], v[18:19], v[26:27]
	v_pk_mul_f32 v[18:19], v[16:17], v[24:25]
	v_cvt_pk_bf16_f32 v16, v20, v21
	v_mad_i64_i32 v[20:21], s[46:47], v148, s60, v[112:113]
	v_pk_mul_f32 v[12:13], v[12:13], v[152:153] op_sel_hi:[1,0]
	v_cvt_pk_bf16_f32 v17, v22, v23
	v_cvt_pk_bf16_f32 v18, v18, v19
	v_cvt_pk_bf16_f32 v19, v26, v27
	v_lshl_add_u64 v[20:21], v[20:21], 0, v[114:115]
	v_mul_f32_e32 v22, 0xbfb8aa3b, v12
	v_mul_f32_e32 v23, 0xbfb8aa3b, v13
	v_pk_mul_f32 v[8:9], v[8:9], v[152:153] op_sel_hi:[1,0]
	v_pk_mul_f32 v[10:11], v[10:11], v[152:153] op_sel_hi:[1,0]
	v_exp_f32_e32 v22, v22
	v_exp_f32_e32 v23, v23
	global_store_dwordx4 v[20:21], v[16:19], off
	v_pk_mul_f32 v[14:15], v[14:15], v[152:153] op_sel_hi:[1,0]
	v_add_f32_e32 v22, 1.0, v22
	v_mul_f32_e32 v16, 0xbfb8aa3b, v8
	v_mul_f32_e32 v17, 0xbfb8aa3b, v9
	v_mul_f32_e32 v18, 0xbfb8aa3b, v10
	v_mul_f32_e32 v19, 0xbfb8aa3b, v11
	v_exp_f32_e32 v16, v16
	v_exp_f32_e32 v17, v17
	v_exp_f32_e32 v18, v18
	v_exp_f32_e32 v19, v19
	v_mul_f32_e32 v24, 0xbfb8aa3b, v14
	v_mul_f32_e32 v25, 0xbfb8aa3b, v15
	v_exp_f32_e32 v24, v24
	v_exp_f32_e32 v25, v25
	v_add_f32_e32 v23, 1.0, v23
	v_rcp_f32_e32 v22, v22
	v_rcp_f32_e32 v23, v23
	v_add_f32_e32 v16, 1.0, v16
	v_add_f32_e32 v17, 1.0, v17
	v_add_f32_e32 v18, 1.0, v18
	v_add_f32_e32 v19, 1.0, v19
	v_rcp_f32_e32 v16, v16
	v_rcp_f32_e32 v17, v17
	v_rcp_f32_e32 v18, v18
	v_rcp_f32_e32 v19, v19
	v_add_f32_e32 v24, 1.0, v24
	v_add_f32_e32 v25, 1.0, v25
	v_rcp_f32_e32 v24, v24
	v_rcp_f32_e32 v25, v25
	v_pk_mul_f32 v[12:13], v[12:13], v[22:23]
	v_pk_mul_f32 v[4:5], v[4:5], v[152:153] op_sel_hi:[1,0]
	v_pk_mul_f32 v[8:9], v[8:9], v[16:17]
	v_pk_mul_f32 v[4:5], v[4:5], v[12:13]
	v_pk_mul_f32 v[10:11], v[10:11], v[18:19]
	v_pk_mul_f32 v[0:1], v[0:1], v[152:153] op_sel_hi:[1,0]
	v_pk_mul_f32 v[2:3], v[2:3], v[152:153] op_sel_hi:[1,0]
	v_pk_mul_f32 v[14:15], v[14:15], v[24:25]
	v_pk_mul_f32 v[10:11], v[2:3], v[10:11]
	v_pk_mul_f32 v[2:3], v[0:1], v[8:9]
	v_cvt_pk_bf16_f32 v0, v4, v5
	v_mad_i64_i32 v[4:5], s[46:47], v146, s60, v[112:113]
	v_pk_mul_f32 v[6:7], v[6:7], v[152:153] op_sel_hi:[1,0]
	v_lshl_add_u64 v[4:5], v[4:5], 0, v[114:115]
	v_pk_mul_f32 v[6:7], v[6:7], v[14:15]
	s_nop 0
	v_cvt_pk_bf16_f32 v1, v6, v7
	v_cvt_pk_bf16_f32 v2, v2, v3
	v_cvt_pk_bf16_f32 v3, v10, v11
	global_store_dwordx4 v[4:5], v[0:3], off
	s_cbranch_vccnz .LBB0_1584
	s_andn2_b64 vcc, exec, s[14:15]
	s_cbranch_vccnz .LBB0_1583
	s_barrier
	s_branch .LBB0_1583

; __device__ __forceinline__ float sq4(f32x4 v) { return (v[0] * v[0] + v[1] * v[1]) + (v[2] * v[2] + v[3] * v[3]); }
; __device__ __forceinline__ u32x4 pack8(f32x4 a, f32x4 b) { u32x4 w; w.x = cvt_pk_bf16(a[0], a[1]); w.y = cvt_pk_bf16(a[2], a[3]); w.z = cvt_pk_bf16(b[0], b[1]); w.w = cvt_pk_bf16(b[2], b[3]); return w; }
;     __device__ __forceinline__ void operator()(const f32x4 (&acc)[2][2][4][2], const Unit& u, int wr, int wc, int fr, int fq) const {
;     ...
;         for (int ai = 0; ai < 2; ++ai) {
;             u32x4 bs[4][2];
; #pragma unroll
;             for (int m = 0; m < 4; ++m)
; #pragma unroll
;                 for (int bj = 0; bj < 2; ++bj) bs[m][bj] = *(const u32x4*)(xb + (size_t)(u.pm * BM + ai * HALF + wr * 64 + m * 16 + fr) * 1024 + col0 + 128 * bj);
; #pragma unroll
;             for (int m = 0; m < 4; ++m) {
;                 const int row = u.pm * BM + ai * HALF + wr * 64 + m * 16 + fr;
;                 float q = 0.f;
; #pragma unroll
;                 for (int bj = 0; bj < 2; ++bj) {
;                     const size_t off = (size_t)row * 1024 + col0 + 128 * bj; const u32x4 w = bs[m][bj];
;                     const f32x4 b0 = (f32x4){__builtin_bit_cast(float, w.x << 16), __builtin_bit_cast(float, w.x & 0xffff0000u), __builtin_bit_cast(float, w.y << 16), __builtin_bit_cast(float, w.y & 0xffff0000u)};
;                     const f32x4 b1 = (f32x4){__builtin_bit_cast(float, w.z << 16), __builtin_bit_cast(float, w.z & 0xffff0000u), __builtin_bit_cast(float, w.w << 16), __builtin_bit_cast(float, w.w & 0xffff0000u)};
;                     const f32x4 v0 = acc[ai][bj][m][0] + b0, v1 = acc[ai][bj][m][1] + b1;
;                     if (last) { __builtin_nontemporal_store(v0, (f32x4*)(out + off)); __builtin_nontemporal_store(v1, (f32x4*)(out + off + 4)); }
;                     else { q += sq4(v0) + sq4(v1); *(u32x4*)(xb + off) = pack8(v0, v1); }
;                 }
;                 if (!last) { q += shx(q, 16); q += shx(q, 32); if (fq == 0) ss[(size_t)row * 16 + u.pn * 4 + wc] = q; }
.LBB0_1673:
	v_lshl_or_b32 v168, s18, 8, v188
	v_lshl_add_u32 v172, s65, 8, v186
	v_ashrrev_i32_e32 v169, 31, v168
	v_lshlrev_b64 v[202:203], 1, v[168:169]
	v_ashrrev_i32_e32 v173, 31, v172
	v_lshl_add_u64 v[170:171], s[22:23], 0, v[202:203]
	v_lshlrev_b64 v[204:205], 11, v[172:173]
	v_lshl_add_u64 v[120:121], v[170:171], 0, v[204:205]
	global_load_dwordx4 v[192:195], v[120:121], off
	global_load_dwordx4 v[196:199], v[120:121], off offset:256
	v_or_b32_e32 v182, 16, v172
	v_ashrrev_i32_e32 v183, 31, v182
	v_or_b32_e32 v178, 32, v172
	v_lshlrev_b64 v[184:185], 11, v[182:183]
	v_ashrrev_i32_e32 v179, 31, v178
	v_or_b32_e32 v174, 48, v172
	v_lshl_add_u64 v[120:121], v[170:171], 0, v[184:185]
	v_lshlrev_b64 v[180:181], 11, v[178:179]
	v_ashrrev_i32_e32 v175, 31, v174
	global_load_dwordx4 v[148:151], v[120:121], off
	global_load_dwordx4 v[144:147], v[120:121], off offset:256
	v_lshl_add_u64 v[120:121], v[170:171], 0, v[180:181]
	v_lshlrev_b64 v[176:177], 11, v[174:175]
	global_load_dwordx4 v[140:143], v[120:121], off
	global_load_dwordx4 v[136:139], v[120:121], off offset:256
	v_lshl_add_u64 v[120:121], v[170:171], 0, v[176:177]
	global_load_dwordx4 v[132:135], v[120:121], off
	s_nop 0
	global_load_dwordx4 v[120:123], v[120:121], off offset:256
	s_lshl_b32 s46, s18, 2
	s_ashr_i32 s47, s46, 31
	s_waitcnt vmcnt(0)
	v_lshlrev_b32_e32 v206, 16, v192
	v_and_b32_e32 v207, 0xffff0000, v192
	v_lshlrev_b32_e32 v192, 16, v193
	v_and_b32_e32 v193, 0xffff0000, v193
	v_lshlrev_b32_e32 v208, 16, v194
	v_and_b32_e32 v209, 0xffff0000, v194
	v_lshlrev_b32_e32 v194, 16, v195
	v_and_b32_e32 v195, 0xffff0000, v195
	v_pk_add_f32 v[130:131], v[130:131], v[192:193]
	v_pk_add_f32 v[128:129], v[128:129], v[206:207]
	v_pk_add_f32 v[192:193], v[126:127], v[194:195]
	v_pk_add_f32 v[126:127], v[124:125], v[208:209]
	v_mul_f32_e32 v124, v129, v129
	v_mul_f32_e32 v125, v131, v131
	v_fmac_f32_e32 v124, v128, v128
	v_fmac_f32_e32 v125, v130, v130
	v_add_f32_e32 v124, v124, v125
	v_mul_f32_e32 v125, v127, v127
	v_mul_f32_e32 v194, v193, v193
	v_fmac_f32_e32 v125, v126, v126
	v_fmac_f32_e32 v194, v192, v192
	v_add_f32_e32 v125, v125, v194
	v_add_f32_e32 v194, v124, v125
	v_cvt_pk_bf16_f32 v124, v128, v129
	v_lshl_add_u64 v[128:129], s[22:23], 0, v[204:205]
	v_cvt_pk_bf16_f32 v125, v130, v131
	v_cvt_pk_bf16_f32 v126, v126, v127
	v_cvt_pk_bf16_f32 v127, v192, v193
	v_lshl_add_u64 v[128:129], v[128:129], 0, v[202:203]
	global_store_dwordx4 v[128:129], v[124:127], off
	v_lshlrev_b32_e32 v130, 16, v198
	v_and_b32_e32 v131, 0xffff0000, v198
	v_lshlrev_b32_e32 v124, 16, v196
	v_and_b32_e32 v125, 0xffff0000, v196
	v_lshlrev_b32_e32 v126, 16, v197
	v_and_b32_e32 v127, 0xffff0000, v197
	v_lshlrev_b32_e32 v192, 16, v199
	v_and_b32_e32 v193, 0xffff0000, v199
	v_pk_add_f32 v[118:119], v[118:119], v[126:127]
	v_pk_add_f32 v[116:117], v[116:117], v[124:125]
	v_pk_add_f32 v[124:125], v[114:115], v[192:193]
	v_pk_add_f32 v[114:115], v[112:113], v[130:131]
	v_mul_f32_e32 v112, v117, v117
	v_mul_f32_e32 v113, v119, v119
	v_fmac_f32_e32 v112, v116, v116
	v_fmac_f32_e32 v113, v118, v118
	v_add_f32_e32 v112, v112, v113
	v_mul_f32_e32 v113, v115, v115
	v_mul_f32_e32 v126, v125, v125
	v_fmac_f32_e32 v113, v114, v114
	v_fmac_f32_e32 v126, v124, v124
	v_add_f32_e32 v113, v113, v126
	v_add_f32_e32 v112, v112, v113
	v_add_f32_e32 v126, v194, v112
	v_cvt_pk_bf16_f32 v112, v116, v117
	v_cvt_pk_bf16_f32 v113, v118, v119
	v_cvt_pk_bf16_f32 v114, v114, v115
	v_cvt_pk_bf16_f32 v115, v124, v125
	global_store_dwordx4 v[128:129], v[112:115], off offset:256
	s_nop 1
	s_nop 0
	s_nop 2
	v_mov_b32_e32 v112, v126
	s_nop 1
	v_permlane16_swap_b32_e32 v112, v126
	s_waitcnt lgkmcnt(0)
	v_add_f32_e32 v112, v126, v112
	s_nop 1
	v_mov_b32_e32 v113, v112
	s_nop 1
	v_permlane32_swap_b32_e32 v113, v112
	s_and_saveexec_b64 s[48:49], s[8:9]
	s_cbranch_execz .LBB0_1675
	s_waitcnt lgkmcnt(0)
	v_add_f32_e32 v114, v112, v113
	v_lshlrev_b64 v[112:113], 6, v[172:173]
	v_lshl_add_u64 v[112:113], s[24:25], 0, v[112:113]
	v_lshl_add_u64 v[112:113], s[46:47], 2, v[112:113]
	s_lshl_b32 s18, s54, 2
	v_lshl_add_u64 v[112:113], v[112:113], 0, s[18:19]
	global_store_dword v[112:113], v114, off
.LBB0_1675:
	s_or_b64 exec, exec, s[48:49]
	v_lshlrev_b32_e32 v112, 16, v148
	s_waitcnt lgkmcnt(0)
	v_and_b32_e32 v113, 0xffff0000, v148
	v_lshlrev_b32_e32 v114, 16, v149
	v_and_b32_e32 v115, 0xffff0000, v149
	v_lshlrev_b32_e32 v116, 16, v150
	v_and_b32_e32 v117, 0xffff0000, v150
	v_lshlrev_b32_e32 v118, 16, v151
	v_and_b32_e32 v119, 0xffff0000, v151
	v_pk_add_f32 v[110:111], v[110:111], v[114:115]
	v_pk_add_f32 v[108:109], v[108:109], v[112:113]
	v_pk_add_f32 v[112:113], v[106:107], v[118:119]
	v_pk_add_f32 v[106:107], v[104:105], v[116:117]
	v_mul_f32_e32 v104, v109, v109
	v_mul_f32_e32 v105, v111, v111
	v_fmac_f32_e32 v104, v108, v108
	v_fmac_f32_e32 v105, v110, v110
	v_add_f32_e32 v104, v104, v105
	v_mul_f32_e32 v105, v107, v107
	v_mul_f32_e32 v114, v113, v113
	v_fmac_f32_e32 v105, v106, v106
	v_fmac_f32_e32 v114, v112, v112
	v_add_f32_e32 v105, v105, v114
	v_add_f32_e32 v114, v104, v105
	v_cvt_pk_bf16_f32 v104, v108, v109
	v_lshl_add_u64 v[108:109], s[22:23], 0, v[184:185]
	v_cvt_pk_bf16_f32 v105, v110, v111
	v_cvt_pk_bf16_f32 v106, v106, v107
	v_cvt_pk_bf16_f32 v107, v112, v113
	v_lshl_add_u64 v[108:109], v[168:169], 1, v[108:109]
	global_store_dwordx4 v[108:109], v[104:107], off
	v_lshlrev_b32_e32 v110, 16, v146
	v_and_b32_e32 v111, 0xffff0000, v146
	v_lshlrev_b32_e32 v104, 16, v144
	v_and_b32_e32 v105, 0xffff0000, v144
	v_lshlrev_b32_e32 v106, 16, v145
	v_and_b32_e32 v107, 0xffff0000, v145
	v_lshlrev_b32_e32 v112, 16, v147
	v_and_b32_e32 v113, 0xffff0000, v147
	v_pk_add_f32 v[102:103], v[102:103], v[106:107]
	v_pk_add_f32 v[100:101], v[100:101], v[104:105]
	v_pk_add_f32 v[104:105], v[98:99], v[112:113]
	v_pk_add_f32 v[98:99], v[96:97], v[110:111]
	v_mul_f32_e32 v96, v101, v101
	v_mul_f32_e32 v97, v103, v103
	v_fmac_f32_e32 v96, v100, v100
	v_fmac_f32_e32 v97, v102, v102
	v_add_f32_e32 v96, v96, v97
	v_mul_f32_e32 v97, v99, v99
	v_mul_f32_e32 v106, v105, v105
	v_fmac_f32_e32 v97, v98, v98
	v_fmac_f32_e32 v106, v104, v104
	v_add_f32_e32 v97, v97, v106
	v_add_f32_e32 v96, v96, v97
	v_add_f32_e32 v106, v114, v96
	v_cvt_pk_bf16_f32 v96, v100, v101
	v_cvt_pk_bf16_f32 v97, v102, v103
	v_cvt_pk_bf16_f32 v98, v98, v99
	v_cvt_pk_bf16_f32 v99, v104, v105
	global_store_dwordx4 v[108:109], v[96:99], off offset:256
	s_nop 1
	s_nop 0
	s_nop 2
	v_mov_b32_e32 v96, v106
	s_nop 1
	v_permlane16_swap_b32_e32 v96, v106
	s_waitcnt lgkmcnt(0)
	v_add_f32_e32 v96, v106, v96
	s_nop 1
	v_mov_b32_e32 v97, v96
	s_nop 1
	v_permlane32_swap_b32_e32 v97, v96
	s_and_saveexec_b64 s[48:49], s[8:9]
	s_cbranch_execz .LBB0_1677
	s_waitcnt lgkmcnt(0)
	v_add_f32_e32 v98, v96, v97
	v_lshlrev_b64 v[96:97], 6, v[182:183]
	v_lshl_add_u64 v[96:97], s[24:25], 0, v[96:97]
	v_lshl_add_u64 v[96:97], s[46:47], 2, v[96:97]
	s_lshl_b32 s18, s54, 2
	v_lshl_add_u64 v[96:97], v[96:97], 0, s[18:19]
	global_store_dword v[96:97], v98, off
; __device__ __forceinline__ float sq4(f32x4 v) { return (v[0] * v[0] + v[1] * v[1]) + (v[2] * v[2] + v[3] * v[3]); }
; __device__ __forceinline__ u32x4 pack8(f32x4 a, f32x4 b) { u32x4 w; w.x = cvt_pk_bf16(a[0], a[1]); w.y = cvt_pk_bf16(a[2], a[3]); w.z = cvt_pk_bf16(b[0], b[1]); w.w = cvt_pk_bf16(b[2], b[3]); return w; }
;     __device__ __forceinline__ void operator()(const f32x4 (&acc)[2][2][4][2], const Unit& u, int wr, int wc, int fr, int fq) const {
;     ...
;             for (int m = 0; m < 4; ++m) {
;                 const int row = u.pm * BM + ai * HALF + wr * 64 + m * 16 + fr;
;                 float q = 0.f;
; #pragma unroll
;                 for (int bj = 0; bj < 2; ++bj) {
;                     const size_t off = (size_t)row * 1024 + col0 + 128 * bj; const u32x4 w = bs[m][bj];
;                     const f32x4 b0 = (f32x4){__builtin_bit_cast(float, w.x << 16), __builtin_bit_cast(float, w.x & 0xffff0000u), __builtin_bit_cast(float, w.y << 16), __builtin_bit_cast(float, w.y & 0xffff0000u)};
;                     const f32x4 b1 = (f32x4){__builtin_bit_cast(float, w.z << 16), __builtin_bit_cast(float, w.z & 0xffff0000u), __builtin_bit_cast(float, w.w << 16), __builtin_bit_cast(float, w.w & 0xffff0000u)};
;                     const f32x4 v0 = acc[ai][bj][m][0] + b0, v1 = acc[ai][bj][m][1] + b1;
;                     if (last) { __builtin_nontemporal_store(v0, (f32x4*)(out + off)); __builtin_nontemporal_store(v1, (f32x4*)(out + off + 4)); }
;                     else { q += sq4(v0) + sq4(v1); *(u32x4*)(xb + off) = pack8(v0, v1); }
;                 }
;                 if (!last) { q += shx(q, 16); q += shx(q, 32); if (fq == 0) ss[(size_t)row * 16 + u.pn * 4 + wc] = q; }
.LBB0_1677:
	s_or_b64 exec, exec, s[48:49]
	v_lshlrev_b32_e32 v96, 16, v140
	s_waitcnt lgkmcnt(0)
	v_and_b32_e32 v97, 0xffff0000, v140
	v_lshlrev_b32_e32 v98, 16, v141
	v_and_b32_e32 v99, 0xffff0000, v141
	v_lshlrev_b32_e32 v100, 16, v142
	v_and_b32_e32 v101, 0xffff0000, v142
	v_lshlrev_b32_e32 v102, 16, v143
	v_and_b32_e32 v103, 0xffff0000, v143
	v_pk_add_f32 v[94:95], v[94:95], v[98:99]
	v_pk_add_f32 v[92:93], v[92:93], v[96:97]
	v_pk_add_f32 v[96:97], v[90:91], v[102:103]
	v_pk_add_f32 v[90:91], v[88:89], v[100:101]
	v_mul_f32_e32 v88, v93, v93
	v_mul_f32_e32 v89, v95, v95
	v_fmac_f32_e32 v88, v92, v92
	v_fmac_f32_e32 v89, v94, v94
	v_add_f32_e32 v88, v88, v89
	v_mul_f32_e32 v89, v91, v91
	v_mul_f32_e32 v98, v97, v97
	v_fmac_f32_e32 v89, v90, v90
	v_fmac_f32_e32 v98, v96, v96
	v_add_f32_e32 v89, v89, v98
	v_add_f32_e32 v98, v88, v89
	v_cvt_pk_bf16_f32 v88, v92, v93
	v_lshl_add_u64 v[92:93], s[22:23], 0, v[180:181]
	v_cvt_pk_bf16_f32 v89, v94, v95
	v_cvt_pk_bf16_f32 v90, v90, v91
	v_cvt_pk_bf16_f32 v91, v96, v97
	v_lshl_add_u64 v[92:93], v[168:169], 1, v[92:93]
	global_store_dwordx4 v[92:93], v[88:91], off
	v_lshlrev_b32_e32 v94, 16, v138
	v_and_b32_e32 v95, 0xffff0000, v138
	v_lshlrev_b32_e32 v88, 16, v136
	v_and_b32_e32 v89, 0xffff0000, v136
	v_lshlrev_b32_e32 v90, 16, v137
	v_and_b32_e32 v91, 0xffff0000, v137
	v_lshlrev_b32_e32 v96, 16, v139
	v_and_b32_e32 v97, 0xffff0000, v139
	v_pk_add_f32 v[86:87], v[86:87], v[90:91]
	v_pk_add_f32 v[84:85], v[84:85], v[88:89]
	v_pk_add_f32 v[88:89], v[82:83], v[96:97]
	v_pk_add_f32 v[82:83], v[80:81], v[94:95]
	v_mul_f32_e32 v80, v85, v85
	v_mul_f32_e32 v81, v87, v87
	v_fmac_f32_e32 v80, v84, v84
	v_fmac_f32_e32 v81, v86, v86
	v_add_f32_e32 v80, v80, v81
	v_mul_f32_e32 v81, v83, v83
	v_mul_f32_e32 v90, v89, v89
	v_fmac_f32_e32 v81, v82, v82
	v_fmac_f32_e32 v90, v88, v88
	v_add_f32_e32 v81, v81, v90
	v_add_f32_e32 v80, v80, v81
	v_add_f32_e32 v90, v98, v80
	v_cvt_pk_bf16_f32 v80, v84, v85
	v_cvt_pk_bf16_f32 v81, v86, v87
	v_cvt_pk_bf16_f32 v82, v82, v83
	v_cvt_pk_bf16_f32 v83, v88, v89
	global_store_dwordx4 v[92:93], v[80:83], off offset:256
	s_nop 1
	s_nop 0
	s_nop 2
	v_mov_b32_e32 v80, v90
	s_nop 1
	v_permlane16_swap_b32_e32 v80, v90
	s_waitcnt lgkmcnt(0)
	v_add_f32_e32 v80, v90, v80
	s_nop 1
	v_mov_b32_e32 v81, v80
	s_nop 1
	v_permlane32_swap_b32_e32 v81, v80
	s_and_saveexec_b64 s[48:49], s[8:9]
	s_cbranch_execz .LBB0_1679
	s_waitcnt lgkmcnt(0)
	v_add_f32_e32 v82, v80, v81
	v_lshlrev_b64 v[80:81], 6, v[178:179]
	v_lshl_add_u64 v[80:81], s[24:25], 0, v[80:81]
	v_lshl_add_u64 v[80:81], s[46:47], 2, v[80:81]
	s_lshl_b32 s18, s54, 2
	v_lshl_add_u64 v[80:81], v[80:81], 0, s[18:19]
	global_store_dword v[80:81], v82, off
.LBB0_1679:
	s_or_b64 exec, exec, s[48:49]
	v_lshlrev_b32_e32 v80, 16, v132
	s_waitcnt lgkmcnt(0)
	v_and_b32_e32 v81, 0xffff0000, v132
	v_lshlrev_b32_e32 v82, 16, v133
	v_and_b32_e32 v83, 0xffff0000, v133
	v_lshlrev_b32_e32 v84, 16, v134
	v_and_b32_e32 v85, 0xffff0000, v134
	v_lshlrev_b32_e32 v86, 16, v135
	v_and_b32_e32 v87, 0xffff0000, v135
	v_pk_add_f32 v[78:79], v[78:79], v[82:83]
	v_pk_add_f32 v[76:77], v[76:77], v[80:81]
	v_pk_add_f32 v[80:81], v[74:75], v[86:87]
	v_pk_add_f32 v[74:75], v[72:73], v[84:85]
	v_mul_f32_e32 v72, v77, v77
	v_mul_f32_e32 v73, v79, v79
	v_fmac_f32_e32 v72, v76, v76
	v_fmac_f32_e32 v73, v78, v78
	v_add_f32_e32 v72, v72, v73
	v_mul_f32_e32 v73, v75, v75
	v_mul_f32_e32 v82, v81, v81
	v_fmac_f32_e32 v73, v74, v74
	v_fmac_f32_e32 v82, v80, v80
	v_add_f32_e32 v73, v73, v82
	v_add_f32_e32 v82, v72, v73
	v_cvt_pk_bf16_f32 v72, v76, v77
	v_lshl_add_u64 v[76:77], s[22:23], 0, v[176:177]
	v_cvt_pk_bf16_f32 v73, v78, v79
	v_cvt_pk_bf16_f32 v74, v74, v75
	v_cvt_pk_bf16_f32 v75, v80, v81
	v_lshl_add_u64 v[76:77], v[168:169], 1, v[76:77]
	global_store_dwordx4 v[76:77], v[72:75], off
	v_lshlrev_b32_e32 v78, 16, v122
	v_and_b32_e32 v79, 0xffff0000, v122
	v_lshlrev_b32_e32 v72, 16, v120
	v_and_b32_e32 v73, 0xffff0000, v120
	v_lshlrev_b32_e32 v74, 16, v121
	v_and_b32_e32 v75, 0xffff0000, v121
	v_lshlrev_b32_e32 v80, 16, v123
	v_and_b32_e32 v81, 0xffff0000, v123
	v_pk_add_f32 v[70:71], v[70:71], v[74:75]
	v_pk_add_f32 v[68:69], v[68:69], v[72:73]
	v_pk_add_f32 v[72:73], v[66:67], v[80:81]
	v_pk_add_f32 v[66:67], v[64:65], v[78:79]
	v_mul_f32_e32 v64, v69, v69
	v_mul_f32_e32 v65, v71, v71
	v_fmac_f32_e32 v64, v68, v68
	v_fmac_f32_e32 v65, v70, v70
	v_add_f32_e32 v64, v64, v65
	v_mul_f32_e32 v65, v67, v67
	v_mul_f32_e32 v74, v73, v73
	v_fmac_f32_e32 v65, v66, v66
	v_fmac_f32_e32 v74, v72, v72
	v_add_f32_e32 v65, v65, v74
	v_add_f32_e32 v64, v64, v65
	v_add_f32_e32 v74, v82, v64
	v_cvt_pk_bf16_f32 v64, v68, v69
	v_cvt_pk_bf16_f32 v65, v70, v71
	v_cvt_pk_bf16_f32 v66, v66, v67
	v_cvt_pk_bf16_f32 v67, v72, v73
	global_store_dwordx4 v[76:77], v[64:67], off offset:256
	s_nop 1
	s_nop 0
	s_nop 2
	v_mov_b32_e32 v64, v74
	s_nop 1
	v_permlane16_swap_b32_e32 v64, v74
	s_waitcnt lgkmcnt(0)
	v_add_f32_e32 v64, v74, v64
	s_nop 1
	v_mov_b32_e32 v65, v64
	s_nop 1
	v_permlane32_swap_b32_e32 v65, v64
	s_and_saveexec_b64 s[48:49], s[8:9]
	s_cbranch_execz .LBB0_1681
	s_waitcnt lgkmcnt(0)
	v_add_f32_e32 v66, v64, v65
	v_lshlrev_b64 v[64:65], 6, v[174:175]
	v_lshl_add_u64 v[64:65], s[24:25], 0, v[64:65]
	v_lshl_add_u64 v[64:65], s[46:47], 2, v[64:65]
	s_lshl_b32 s18, s54, 2
	v_lshl_add_u64 v[64:65], v[64:65], 0, s[18:19]
	global_store_dword v[64:65], v66, off
; __device__ __forceinline__ float sq4(f32x4 v) { return (v[0] * v[0] + v[1] * v[1]) + (v[2] * v[2] + v[3] * v[3]); }
; __device__ __forceinline__ u32x4 pack8(f32x4 a, f32x4 b) { u32x4 w; w.x = cvt_pk_bf16(a[0], a[1]); w.y = cvt_pk_bf16(a[2], a[3]); w.z = cvt_pk_bf16(b[0], b[1]); w.w = cvt_pk_bf16(b[2], b[3]); return w; }
;     __device__ __forceinline__ void operator()(const f32x4 (&acc)[2][2][4][2], const Unit& u, int wr, int wc, int fr, int fq) const {
;     ...
;         for (int ai = 0; ai < 2; ++ai) {
;             u32x4 bs[4][2];
; #pragma unroll
;             for (int m = 0; m < 4; ++m)
; #pragma unroll
;                 for (int bj = 0; bj < 2; ++bj) bs[m][bj] = *(const u32x4*)(xb + (size_t)(u.pm * BM + ai * HALF + wr * 64 + m * 16 + fr) * 1024 + col0 + 128 * bj);
; #pragma unroll
;             for (int m = 0; m < 4; ++m) {
;                 const int row = u.pm * BM + ai * HALF + wr * 64 + m * 16 + fr;
;                 float q = 0.f;
; #pragma unroll
;                 for (int bj = 0; bj < 2; ++bj) {
;                     const size_t off = (size_t)row * 1024 + col0 + 128 * bj; const u32x4 w = bs[m][bj];
;                     const f32x4 b0 = (f32x4){__builtin_bit_cast(float, w.x << 16), __builtin_bit_cast(float, w.x & 0xffff0000u), __builtin_bit_cast(float, w.y << 16), __builtin_bit_cast(float, w.y & 0xffff0000u)};
;                     const f32x4 b1 = (f32x4){__builtin_bit_cast(float, w.z << 16), __builtin_bit_cast(float, w.z & 0xffff0000u), __builtin_bit_cast(float, w.w << 16), __builtin_bit_cast(float, w.w & 0xffff0000u)};
;                     const f32x4 v0 = acc[ai][bj][m][0] + b0, v1 = acc[ai][bj][m][1] + b1;
;                     if (last) { __builtin_nontemporal_store(v0, (f32x4*)(out + off)); __builtin_nontemporal_store(v1, (f32x4*)(out + off + 4)); }
;                     else { q += sq4(v0) + sq4(v1); *(u32x4*)(xb + off) = pack8(v0, v1); }
;                 }
;                 if (!last) { q += shx(q, 16); q += shx(q, 32); if (fq == 0) ss[(size_t)row * 16 + u.pn * 4 + wc] = q; }
.LBB0_1681:
	s_or_b64 exec, exec, s[48:49]
	v_add_u32_e32 v100, 0x80, v172
	v_ashrrev_i32_e32 v101, 31, v100
	v_lshlrev_b64 v[110:111], 11, v[100:101]
	s_waitcnt lgkmcnt(0)
	v_lshl_add_u64 v[64:65], v[170:171], 0, v[110:111]
	global_load_dwordx4 v[102:105], v[64:65], off
	global_load_dwordx4 v[106:109], v[64:65], off offset:256
	v_add_u32_e32 v96, 0x90, v172
	v_ashrrev_i32_e32 v97, 31, v96
	v_add_u32_e32 v92, 0xa0, v172
	v_lshlrev_b64 v[98:99], 11, v[96:97]
	v_ashrrev_i32_e32 v93, 31, v92
	v_add_u32_e32 v88, 0xb0, v172
	v_lshl_add_u64 v[64:65], v[170:171], 0, v[98:99]
	v_lshlrev_b64 v[94:95], 11, v[92:93]
	v_ashrrev_i32_e32 v89, 31, v88
	global_load_dwordx4 v[84:87], v[64:65], off
	global_load_dwordx4 v[80:83], v[64:65], off offset:256
	v_lshl_add_u64 v[64:65], v[170:171], 0, v[94:95]
	v_lshlrev_b64 v[90:91], 11, v[88:89]
	global_load_dwordx4 v[76:79], v[64:65], off
	global_load_dwordx4 v[72:75], v[64:65], off offset:256
	v_lshl_add_u64 v[64:65], v[170:171], 0, v[90:91]
	global_load_dwordx4 v[68:71], v[64:65], off
	s_nop 0
	global_load_dwordx4 v[64:67], v[64:65], off offset:256
	s_waitcnt vmcnt(7)
	v_lshlrev_b32_e32 v112, 16, v102
	v_and_b32_e32 v113, 0xffff0000, v102
	v_lshlrev_b32_e32 v102, 16, v103
	v_and_b32_e32 v103, 0xffff0000, v103
	v_lshlrev_b32_e32 v114, 16, v104
	v_and_b32_e32 v115, 0xffff0000, v104
	v_lshlrev_b32_e32 v104, 16, v105
	v_and_b32_e32 v105, 0xffff0000, v105
	v_pk_add_f32 v[62:63], v[62:63], v[102:103]
	v_pk_add_f32 v[60:61], v[60:61], v[112:113]
	v_pk_add_f32 v[102:103], v[58:59], v[104:105]
	v_pk_add_f32 v[58:59], v[56:57], v[114:115]
	v_mul_f32_e32 v56, v61, v61
	v_mul_f32_e32 v57, v63, v63
	v_fmac_f32_e32 v56, v60, v60
	v_fmac_f32_e32 v57, v62, v62
	v_add_f32_e32 v56, v56, v57
	v_mul_f32_e32 v57, v59, v59
	v_mul_f32_e32 v104, v103, v103
	v_fmac_f32_e32 v57, v58, v58
	v_fmac_f32_e32 v104, v102, v102
	v_add_f32_e32 v57, v57, v104
	v_add_f32_e32 v104, v56, v57
	v_cvt_pk_bf16_f32 v56, v60, v61
	v_lshl_add_u64 v[60:61], s[22:23], 0, v[110:111]
	v_cvt_pk_bf16_f32 v57, v62, v63
	v_cvt_pk_bf16_f32 v58, v58, v59
	v_cvt_pk_bf16_f32 v59, v102, v103
	v_lshl_add_u64 v[60:61], v[168:169], 1, v[60:61]
	global_store_dwordx4 v[60:61], v[56:59], off
	s_waitcnt vmcnt(7)
	v_lshlrev_b32_e32 v62, 16, v108
	v_and_b32_e32 v63, 0xffff0000, v108
	v_lshlrev_b32_e32 v56, 16, v106
	v_and_b32_e32 v57, 0xffff0000, v106
	v_lshlrev_b32_e32 v58, 16, v107
	v_and_b32_e32 v59, 0xffff0000, v107
	v_lshlrev_b32_e32 v102, 16, v109
	v_and_b32_e32 v103, 0xffff0000, v109
	v_pk_add_f32 v[54:55], v[54:55], v[58:59]
	v_pk_add_f32 v[52:53], v[52:53], v[56:57]
	v_pk_add_f32 v[56:57], v[50:51], v[102:103]
	v_pk_add_f32 v[50:51], v[48:49], v[62:63]
	v_mul_f32_e32 v48, v53, v53
	v_mul_f32_e32 v49, v55, v55
	v_fmac_f32_e32 v48, v52, v52
	v_fmac_f32_e32 v49, v54, v54
	v_add_f32_e32 v48, v48, v49
	v_mul_f32_e32 v49, v51, v51
	v_mul_f32_e32 v58, v57, v57
	v_fmac_f32_e32 v49, v50, v50
	v_fmac_f32_e32 v58, v56, v56
	v_add_f32_e32 v49, v49, v58
	v_add_f32_e32 v48, v48, v49
	v_add_f32_e32 v58, v104, v48
	v_cvt_pk_bf16_f32 v48, v52, v53
	v_cvt_pk_bf16_f32 v49, v54, v55
	v_cvt_pk_bf16_f32 v50, v50, v51
	v_cvt_pk_bf16_f32 v51, v56, v57
	global_store_dwordx4 v[60:61], v[48:51], off offset:256
	s_nop 1
	s_nop 0
	s_nop 2
	v_mov_b32_e32 v48, v58
	s_nop 1
	v_permlane16_swap_b32_e32 v48, v58
	s_waitcnt lgkmcnt(0)
	v_add_f32_e32 v48, v58, v48
	s_nop 1
	v_mov_b32_e32 v49, v48
	s_nop 1
	v_permlane32_swap_b32_e32 v49, v48
	s_and_saveexec_b64 s[48:49], s[8:9]
	s_cbranch_execz .LBB0_1683
	s_waitcnt lgkmcnt(0)
	v_add_f32_e32 v50, v48, v49
	v_lshlrev_b64 v[48:49], 6, v[100:101]
	v_lshl_add_u64 v[48:49], s[24:25], 0, v[48:49]
	v_lshl_add_u64 v[48:49], s[46:47], 2, v[48:49]
	s_lshl_b32 s18, s54, 2
	v_lshl_add_u64 v[48:49], v[48:49], 0, s[18:19]
	global_store_dword v[48:49], v50, off
.LBB0_1683:
	s_or_b64 exec, exec, s[48:49]
	s_waitcnt vmcnt(7)
	v_lshlrev_b32_e32 v48, 16, v84
	s_waitcnt lgkmcnt(0)
	v_and_b32_e32 v49, 0xffff0000, v84
	v_lshlrev_b32_e32 v50, 16, v85
	v_and_b32_e32 v51, 0xffff0000, v85
	v_lshlrev_b32_e32 v52, 16, v86
	v_and_b32_e32 v53, 0xffff0000, v86
	v_lshlrev_b32_e32 v54, 16, v87
	v_and_b32_e32 v55, 0xffff0000, v87
	v_pk_add_f32 v[46:47], v[46:47], v[50:51]
	v_pk_add_f32 v[44:45], v[44:45], v[48:49]
	v_pk_add_f32 v[48:49], v[42:43], v[54:55]
	v_pk_add_f32 v[42:43], v[40:41], v[52:53]
	v_mul_f32_e32 v40, v45, v45
	v_mul_f32_e32 v41, v47, v47
	v_fmac_f32_e32 v40, v44, v44
	v_fmac_f32_e32 v41, v46, v46
	v_add_f32_e32 v40, v40, v41
	v_mul_f32_e32 v41, v43, v43
	v_mul_f32_e32 v50, v49, v49
	v_fmac_f32_e32 v41, v42, v42
	v_fmac_f32_e32 v50, v48, v48
	v_add_f32_e32 v41, v41, v50
	v_add_f32_e32 v50, v40, v41
	v_cvt_pk_bf16_f32 v40, v44, v45
	v_lshl_add_u64 v[44:45], s[22:23], 0, v[98:99]
	v_cvt_pk_bf16_f32 v41, v46, v47
	v_cvt_pk_bf16_f32 v42, v42, v43
	v_cvt_pk_bf16_f32 v43, v48, v49
	v_lshl_add_u64 v[44:45], v[168:169], 1, v[44:45]
	global_store_dwordx4 v[44:45], v[40:43], off
	s_waitcnt vmcnt(7)
	v_lshlrev_b32_e32 v46, 16, v82
	v_and_b32_e32 v47, 0xffff0000, v82
	v_lshlrev_b32_e32 v40, 16, v80
	v_and_b32_e32 v41, 0xffff0000, v80
	v_lshlrev_b32_e32 v42, 16, v81
	v_and_b32_e32 v43, 0xffff0000, v81
	v_lshlrev_b32_e32 v48, 16, v83
	v_and_b32_e32 v49, 0xffff0000, v83
	v_pk_add_f32 v[38:39], v[38:39], v[42:43]
	v_pk_add_f32 v[36:37], v[36:37], v[40:41]
	v_pk_add_f32 v[40:41], v[34:35], v[48:49]
	v_pk_add_f32 v[34:35], v[32:33], v[46:47]
	v_mul_f32_e32 v32, v37, v37
	v_mul_f32_e32 v33, v39, v39
	v_fmac_f32_e32 v32, v36, v36
	v_fmac_f32_e32 v33, v38, v38
	v_add_f32_e32 v32, v32, v33
	v_mul_f32_e32 v33, v35, v35
	v_mul_f32_e32 v42, v41, v41
	v_fmac_f32_e32 v33, v34, v34
	v_fmac_f32_e32 v42, v40, v40
	v_add_f32_e32 v33, v33, v42
	v_add_f32_e32 v32, v32, v33
	v_add_f32_e32 v42, v50, v32
	v_cvt_pk_bf16_f32 v32, v36, v37
	v_cvt_pk_bf16_f32 v33, v38, v39
	v_cvt_pk_bf16_f32 v34, v34, v35
	v_cvt_pk_bf16_f32 v35, v40, v41
	global_store_dwordx4 v[44:45], v[32:35], off offset:256
	s_nop 1
	s_nop 0
	s_nop 2
	v_mov_b32_e32 v32, v42
	s_nop 1
	v_permlane16_swap_b32_e32 v32, v42
	s_waitcnt lgkmcnt(0)
	v_add_f32_e32 v32, v42, v32
	s_nop 1
	v_mov_b32_e32 v33, v32
	s_nop 1
	v_permlane32_swap_b32_e32 v33, v32
	s_and_saveexec_b64 s[48:49], s[8:9]
	s_cbranch_execz .LBB0_1685
	s_waitcnt lgkmcnt(0)
	v_add_f32_e32 v34, v32, v33
	v_lshlrev_b64 v[32:33], 6, v[96:97]
	v_lshl_add_u64 v[32:33], s[24:25], 0, v[32:33]
	v_lshl_add_u64 v[32:33], s[46:47], 2, v[32:33]
	s_lshl_b32 s18, s54, 2
	v_lshl_add_u64 v[32:33], v[32:33], 0, s[18:19]
	global_store_dword v[32:33], v34, off
; __device__ __forceinline__ float sq4(f32x4 v) { return (v[0] * v[0] + v[1] * v[1]) + (v[2] * v[2] + v[3] * v[3]); }
; __device__ __forceinline__ u32x4 pack8(f32x4 a, f32x4 b) { u32x4 w; w.x = cvt_pk_bf16(a[0], a[1]); w.y = cvt_pk_bf16(a[2], a[3]); w.z = cvt_pk_bf16(b[0], b[1]); w.w = cvt_pk_bf16(b[2], b[3]); return w; }
;     __device__ __forceinline__ void operator()(const f32x4 (&acc)[2][2][4][2], const Unit& u, int wr, int wc, int fr, int fq) const {
;     ...
;             for (int m = 0; m < 4; ++m) {
;                 const int row = u.pm * BM + ai * HALF + wr * 64 + m * 16 + fr;
;                 float q = 0.f;
; #pragma unroll
;                 for (int bj = 0; bj < 2; ++bj) {
;                     const size_t off = (size_t)row * 1024 + col0 + 128 * bj; const u32x4 w = bs[m][bj];
;                     const f32x4 b0 = (f32x4){__builtin_bit_cast(float, w.x << 16), __builtin_bit_cast(float, w.x & 0xffff0000u), __builtin_bit_cast(float, w.y << 16), __builtin_bit_cast(float, w.y & 0xffff0000u)};
;                     const f32x4 b1 = (f32x4){__builtin_bit_cast(float, w.z << 16), __builtin_bit_cast(float, w.z & 0xffff0000u), __builtin_bit_cast(float, w.w << 16), __builtin_bit_cast(float, w.w & 0xffff0000u)};
;                     const f32x4 v0 = acc[ai][bj][m][0] + b0, v1 = acc[ai][bj][m][1] + b1;
;                     if (last) { __builtin_nontemporal_store(v0, (f32x4*)(out + off)); __builtin_nontemporal_store(v1, (f32x4*)(out + off + 4)); }
;                     else { q += sq4(v0) + sq4(v1); *(u32x4*)(xb + off) = pack8(v0, v1); }
;                 }
;                 if (!last) { q += shx(q, 16); q += shx(q, 32); if (fq == 0) ss[(size_t)row * 16 + u.pn * 4 + wc] = q; }
.LBB0_1685:
	s_or_b64 exec, exec, s[48:49]
	s_waitcnt vmcnt(7)
	v_lshlrev_b32_e32 v32, 16, v76
	s_waitcnt lgkmcnt(0)
	v_and_b32_e32 v33, 0xffff0000, v76
	v_lshlrev_b32_e32 v34, 16, v77
	v_and_b32_e32 v35, 0xffff0000, v77
	v_lshlrev_b32_e32 v36, 16, v78
	v_and_b32_e32 v37, 0xffff0000, v78
	v_lshlrev_b32_e32 v38, 16, v79
	v_and_b32_e32 v39, 0xffff0000, v79
	v_pk_add_f32 v[30:31], v[30:31], v[34:35]
	v_pk_add_f32 v[28:29], v[28:29], v[32:33]
	v_pk_add_f32 v[32:33], v[26:27], v[38:39]
	v_pk_add_f32 v[26:27], v[24:25], v[36:37]
	v_mul_f32_e32 v24, v29, v29
	v_mul_f32_e32 v25, v31, v31
	v_fmac_f32_e32 v24, v28, v28
	v_fmac_f32_e32 v25, v30, v30
	v_add_f32_e32 v24, v24, v25
	v_mul_f32_e32 v25, v27, v27
	v_mul_f32_e32 v34, v33, v33
	v_fmac_f32_e32 v25, v26, v26
	v_fmac_f32_e32 v34, v32, v32
	v_add_f32_e32 v25, v25, v34
	v_add_f32_e32 v34, v24, v25
	v_cvt_pk_bf16_f32 v24, v28, v29
	v_lshl_add_u64 v[28:29], s[22:23], 0, v[94:95]
	v_cvt_pk_bf16_f32 v25, v30, v31
	v_cvt_pk_bf16_f32 v26, v26, v27
	v_cvt_pk_bf16_f32 v27, v32, v33
	v_lshl_add_u64 v[28:29], v[168:169], 1, v[28:29]
	global_store_dwordx4 v[28:29], v[24:27], off
	s_waitcnt vmcnt(7)
	v_lshlrev_b32_e32 v30, 16, v74
	v_and_b32_e32 v31, 0xffff0000, v74
	v_lshlrev_b32_e32 v24, 16, v72
	v_and_b32_e32 v25, 0xffff0000, v72
	v_lshlrev_b32_e32 v26, 16, v73
	v_and_b32_e32 v27, 0xffff0000, v73
	v_lshlrev_b32_e32 v32, 16, v75
	v_and_b32_e32 v33, 0xffff0000, v75
	v_pk_add_f32 v[22:23], v[22:23], v[26:27]
	v_pk_add_f32 v[20:21], v[20:21], v[24:25]
	v_pk_add_f32 v[24:25], v[18:19], v[32:33]
	v_pk_add_f32 v[18:19], v[16:17], v[30:31]
	v_mul_f32_e32 v16, v21, v21
	v_mul_f32_e32 v17, v23, v23
	v_fmac_f32_e32 v16, v20, v20
	v_fmac_f32_e32 v17, v22, v22
	v_add_f32_e32 v16, v16, v17
	v_mul_f32_e32 v17, v19, v19
	v_mul_f32_e32 v26, v25, v25
	v_fmac_f32_e32 v17, v18, v18
	v_fmac_f32_e32 v26, v24, v24
	v_add_f32_e32 v17, v17, v26
	v_add_f32_e32 v16, v16, v17
	v_add_f32_e32 v26, v34, v16
	v_cvt_pk_bf16_f32 v16, v20, v21
	v_cvt_pk_bf16_f32 v17, v22, v23
	v_cvt_pk_bf16_f32 v18, v18, v19
	v_cvt_pk_bf16_f32 v19, v24, v25
	global_store_dwordx4 v[28:29], v[16:19], off offset:256
	s_nop 1
	s_nop 0
	s_nop 2
	v_mov_b32_e32 v16, v26
	s_nop 1
	v_permlane16_swap_b32_e32 v16, v26
	s_waitcnt lgkmcnt(0)
	v_add_f32_e32 v16, v26, v16
	s_nop 1
	v_mov_b32_e32 v17, v16
	s_nop 1
	v_permlane32_swap_b32_e32 v17, v16
	s_and_saveexec_b64 s[48:49], s[8:9]
	s_cbranch_execz .LBB0_1687
	s_waitcnt lgkmcnt(0)
	v_add_f32_e32 v18, v16, v17
	v_lshlrev_b64 v[16:17], 6, v[92:93]
	v_lshl_add_u64 v[16:17], s[24:25], 0, v[16:17]
	v_lshl_add_u64 v[16:17], s[46:47], 2, v[16:17]
	s_lshl_b32 s18, s54, 2
	v_lshl_add_u64 v[16:17], v[16:17], 0, s[18:19]
	global_store_dword v[16:17], v18, off
.LBB0_1687:
	s_or_b64 exec, exec, s[48:49]
	s_waitcnt vmcnt(7)
	v_lshlrev_b32_e32 v16, 16, v68
	s_waitcnt lgkmcnt(0)
	v_and_b32_e32 v17, 0xffff0000, v68
	v_lshlrev_b32_e32 v18, 16, v69
	v_and_b32_e32 v19, 0xffff0000, v69
	v_lshlrev_b32_e32 v20, 16, v70
	v_and_b32_e32 v21, 0xffff0000, v70
	v_lshlrev_b32_e32 v22, 16, v71
	v_and_b32_e32 v23, 0xffff0000, v71
	v_pk_add_f32 v[14:15], v[14:15], v[18:19]
	v_pk_add_f32 v[12:13], v[12:13], v[16:17]
	v_pk_add_f32 v[16:17], v[10:11], v[22:23]
	v_pk_add_f32 v[10:11], v[8:9], v[20:21]
	v_mul_f32_e32 v8, v13, v13
	v_mul_f32_e32 v9, v15, v15
	v_fmac_f32_e32 v8, v12, v12
	v_fmac_f32_e32 v9, v14, v14
	v_add_f32_e32 v8, v8, v9
	v_mul_f32_e32 v9, v11, v11
	v_mul_f32_e32 v18, v17, v17
	v_fmac_f32_e32 v9, v10, v10
	v_fmac_f32_e32 v18, v16, v16
	v_add_f32_e32 v9, v9, v18
	v_add_f32_e32 v18, v8, v9
	v_cvt_pk_bf16_f32 v8, v12, v13
	v_lshl_add_u64 v[12:13], s[22:23], 0, v[90:91]
	v_cvt_pk_bf16_f32 v9, v14, v15
	v_cvt_pk_bf16_f32 v10, v10, v11
	v_cvt_pk_bf16_f32 v11, v16, v17
	v_lshl_add_u64 v[12:13], v[168:169], 1, v[12:13]
	global_store_dwordx4 v[12:13], v[8:11], off
	s_waitcnt vmcnt(7)
	v_lshlrev_b32_e32 v14, 16, v66
	v_and_b32_e32 v15, 0xffff0000, v66
	v_lshlrev_b32_e32 v8, 16, v64
	v_and_b32_e32 v9, 0xffff0000, v64
	v_lshlrev_b32_e32 v10, 16, v65
	v_and_b32_e32 v11, 0xffff0000, v65
	v_lshlrev_b32_e32 v16, 16, v67
	v_and_b32_e32 v17, 0xffff0000, v67
	v_pk_add_f32 v[6:7], v[6:7], v[10:11]
	v_pk_add_f32 v[4:5], v[4:5], v[8:9]
	v_pk_add_f32 v[8:9], v[2:3], v[16:17]
	v_pk_add_f32 v[2:3], v[0:1], v[14:15]
	v_mul_f32_e32 v0, v5, v5
	v_mul_f32_e32 v1, v7, v7
	v_fmac_f32_e32 v0, v4, v4
	v_fmac_f32_e32 v1, v6, v6
	v_add_f32_e32 v0, v0, v1
	v_mul_f32_e32 v1, v3, v3
	v_mul_f32_e32 v10, v9, v9
	v_fmac_f32_e32 v1, v2, v2
	v_fmac_f32_e32 v10, v8, v8
	v_add_f32_e32 v1, v1, v10
	v_add_f32_e32 v0, v0, v1
	v_add_f32_e32 v10, v18, v0
	v_cvt_pk_bf16_f32 v0, v4, v5
	v_cvt_pk_bf16_f32 v1, v6, v7
	v_cvt_pk_bf16_f32 v2, v2, v3
	v_cvt_pk_bf16_f32 v3, v8, v9
	global_store_dwordx4 v[12:13], v[0:3], off offset:256
	s_nop 1
	s_nop 0
	s_nop 2
	v_mov_b32_e32 v0, v10
	s_nop 1
	v_permlane16_swap_b32_e32 v0, v10
	s_waitcnt lgkmcnt(0)
	v_add_f32_e32 v0, v10, v0
	s_nop 1
	v_mov_b32_e32 v1, v0
	s_nop 1
	v_permlane32_swap_b32_e32 v1, v0
	s_and_saveexec_b64 s[48:49], s[8:9]
	s_cbranch_execz .LBB0_1689
	s_waitcnt lgkmcnt(0)
	v_add_f32_e32 v2, v0, v1
	v_lshlrev_b64 v[0:1], 6, v[88:89]
	v_lshl_add_u64 v[0:1], s[24:25], 0, v[0:1]
	v_lshl_add_u64 v[0:1], s[46:47], 2, v[0:1]
	s_lshl_b32 s18, s54, 2
	v_lshl_add_u64 v[0:1], v[0:1], 0, s[18:19]
	global_store_dword v[0:1], v2, off

; __device__ __forceinline__ float row_part(const float* ss, int row, int fq) { const f32x4 a = ((const f32x4*)(ss + (size_t)row * 16))[fq]; return (a[0] + a[1]) + (a[2] + a[3]); }
; __device__ __forceinline__ float row_finish(float t) { t += shx(t, 16); t += shx(t, 32); return __builtin_amdgcn_rsqf(t * (1.0f / 1024.0f) + RMS_EPS); }
;     __device__ __forceinline__ void operator()(const f32x4 (&acc)[2][2][4][2], const Unit& u, int wr, int wc, int fr, int fq) const {
;         const int g = u.pn * 4 + wc;
;         int mode = 0; const float* w = mqw; float sc = 1.f, nsc = 1.f;
;         if (g >= 36) { mode = 2; w = mqw; nsc = qscale; }
;         else if (diff) { if (g < 12) { mode = 2; w = qw; nsc = qscale; } else if (g < 24) { mode = 2; w = kw; } }
;         else { if (g >= 6 && g < 12) sc = 0.125f; else if (g >= 24) mode = 1; }
;         f32x4 wv[2][2];
; #pragma unroll
;         for (int bj = 0; bj < 2; ++bj)
; #pragma unroll
;             for (int n = 0; n < 2; ++n) wv[bj][n] = *(const f32x4*)(w + 32 * bj + 8 * fq + 4 * n) * nsc;
;         const int lcol = u.pn * 256 + 64 * wc + 8 * fq;
;         float rs[2][4];
; #pragma unroll
;         for (int ai = 0; ai < 2; ++ai)
; #pragma unroll
;             for (int m = 0; m < 4; ++m) rs[ai][m] = row_part(ss, u.pm * BM + ai * HALF + wr * 64 + m * 16 + fr, fq);
; #pragma unroll
;         for (int ai = 0; ai < 2; ++ai)
; #pragma unroll
;             for (int m = 0; m < 4; ++m) rs[ai][m] = row_finish(rs[ai][m]);
.LBB0_1759:
	s_lshl_b32 s4, s8, 2
	s_or_b32 s5, s4, s60
	s_cmp_lt_u32 s4, 24
	s_cselect_b32 s9, s57, s59
	s_cselect_b32 s23, s56, s58
	s_cmp_lt_i32 s5, 12
	s_cselect_b32 s23, s54, s23
	s_cselect_b32 s9, s55, s9
	s_sub_i32 s4, s4, 36
	s_cmp_lt_u32 s4, 0xffffffe8
	s_cselect_b64 vcc, -1, 0
	s_cmp_gt_i32 s5, 35
	s_cselect_b32 s49, s59, s9
	s_cselect_b32 s48, s58, s23
	global_load_dwordx4 v[148:151], v183, s[48:49] offset:16
	global_load_dwordx4 v[154:157], v183, s[48:49]
	global_load_dwordx4 v[162:165], v183, s[48:49] offset:144
	global_load_dwordx4 v[166:169], v183, s[48:49] offset:128
	s_cmp_lt_u32 s4, -12
	v_cndmask_b32_e32 v170, 1.0, v185, vcc
	s_cselect_b64 s[46:47], -1, 0
	s_lshl_b32 s23, s44, 8
	s_cmp_gt_u32 s4, -13
	s_waitcnt vmcnt(0)
	v_pk_mul_f32 v[146:147], v[170:171], v[150:151] op_sel_hi:[0,1]
	v_pk_mul_f32 v[152:153], v[170:171], v[156:157] op_sel_hi:[0,1]
	v_pk_mul_f32 v[156:157], v[170:171], v[154:155] op_sel_hi:[0,1]
	v_pk_mul_f32 v[148:149], v[170:171], v[148:149] op_sel_hi:[0,1]
	v_pk_mul_f32 v[158:159], v[170:171], v[168:169] op_sel_hi:[0,1]
	v_pk_mul_f32 v[160:161], v[170:171], v[166:167] op_sel_hi:[0,1]
	v_pk_mul_f32 v[150:151], v[170:171], v[164:165] op_sel_hi:[0,1]
	v_pk_mul_f32 v[154:155], v[170:171], v[162:163] op_sel_hi:[0,1]
	v_add_u32_e32 v170, s23, v174
	v_ashrrev_i32_e32 v171, 31, v170
	v_lshlrev_b64 v[162:163], 6, v[170:171]
	v_lshl_add_u64 v[162:163], v[136:137], 0, v[162:163]
	ds_read_b128 v[162:165], v239
	v_add_u32_e32 v168, 0x80, v170
	v_ashrrev_i32_e32 v169, 31, v168
	s_waitcnt lgkmcnt(0)
	v_mov_b32_e32 v166, v163
	v_mov_b32_e32 v167, v164
	v_mov_b32_e32 v163, v165
	v_pk_add_f32 v[162:163], v[166:167], v[162:163]
	v_add_u32_e32 v166, 0x90, v170
	v_add_f32_e32 v171, v162, v163
	v_or_b32_e32 v162, 16, v170
	v_ashrrev_i32_e32 v163, 31, v162
	v_lshlrev_b64 v[162:163], 6, v[162:163]
	v_lshl_add_u64 v[162:163], v[136:137], 0, v[162:163]
	ds_read_b128 v[162:165], v239 offset:1024
	v_ashrrev_i32_e32 v167, 31, v166
	s_waitcnt lgkmcnt(0)
	v_add_f32_e32 v162, v162, v163
	v_add_f32_e32 v163, v164, v165
	v_add_f32_e32 v190, v162, v163
	v_or_b32_e32 v162, 32, v170
	v_ashrrev_i32_e32 v163, 31, v162
	v_lshlrev_b64 v[162:163], 6, v[162:163]
	v_lshl_add_u64 v[162:163], v[136:137], 0, v[162:163]
	ds_read_b128 v[162:165], v239 offset:2048
	s_waitcnt lgkmcnt(0)
	v_add_f32_e32 v162, v162, v163
	v_add_f32_e32 v163, v164, v165
	v_add_f32_e32 v191, v162, v163
	v_or_b32_e32 v162, 48, v170
	v_ashrrev_i32_e32 v163, 31, v162
	v_lshlrev_b64 v[162:163], 6, v[162:163]
	v_lshl_add_u64 v[162:163], v[136:137], 0, v[162:163]
	ds_read_b128 v[162:165], v239 offset:3072
	s_waitcnt lgkmcnt(0)
	v_add_f32_e32 v162, v162, v163
	v_add_f32_e32 v163, v164, v165
	v_add_f32_e32 v195, v162, v163
	v_lshlrev_b64 v[162:163], 6, v[168:169]
	v_lshl_add_u64 v[162:163], v[136:137], 0, v[162:163]
	ds_read_b128 v[162:165], v239 offset:8192
	s_waitcnt lgkmcnt(0)
	v_add_f32_e32 v162, v162, v163
	v_add_f32_e32 v163, v164, v165
	v_add_f32_e32 v169, v162, v163
	v_lshlrev_b64 v[162:163], 6, v[166:167]
	v_lshl_add_u64 v[162:163], v[136:137], 0, v[162:163]
	ds_read_b128 v[162:165], v239 offset:9216
	s_waitcnt lgkmcnt(0)
	v_add_f32_e32 v162, v162, v163
	v_add_f32_e32 v163, v164, v165
	v_add_u32_e32 v164, 0xa0, v170
	v_ashrrev_i32_e32 v165, 31, v164
	v_add_f32_e32 v167, v162, v163
	v_lshlrev_b64 v[162:163], 6, v[164:165]
	v_lshl_add_u64 v[162:163], v[136:137], 0, v[162:163]
	ds_read_b128 v[186:189], v239 offset:10240
	s_waitcnt lgkmcnt(0)
	v_add_f32_e32 v162, v186, v187
	v_add_f32_e32 v163, v188, v189
	v_add_f32_e32 v165, v162, v163
	v_add_u32_e32 v162, 0xb0, v170
	v_ashrrev_i32_e32 v163, 31, v162
	v_lshlrev_b64 v[172:173], 6, v[162:163]
	v_lshl_add_u64 v[172:173], v[136:137], 0, v[172:173]
	ds_read_b128 v[186:189], v239 offset:11264
	s_waitcnt lgkmcnt(0)
	v_add_f32_e32 v163, v186, v187
	v_add_f32_e32 v172, v188, v189
	v_add_f32_e32 v163, v163, v172
	s_nop 0
	s_nop 0
	s_nop 1
	v_mov_b32_e32 v172, v171
	s_nop 1
	v_permlane16_swap_b32_e32 v172, v171
	s_waitcnt lgkmcnt(0)
	v_add_f32_e32 v171, v171, v172
	s_nop 0
	s_nop 0
	s_nop 1
	v_mov_b32_e32 v172, v171
	s_nop 1
	v_permlane32_swap_b32_e32 v172, v171
	s_waitcnt lgkmcnt(0)
	v_add_f32_e32 v171, v171, v172
	v_fmamk_f32 v171, v171, 0x3a800000, v184
	v_rsq_f32_e32 v196, v171
	s_nop 0
	v_pk_mul_f32 v[126:127], v[126:127], v[196:197] op_sel_hi:[1,0]
	s_nop 1
	v_mov_b32_e32 v171, v190
	s_nop 1
	v_permlane16_swap_b32_e32 v171, v190
	v_pk_mul_f32 v[124:125], v[124:125], v[196:197] op_sel_hi:[1,0]
	v_pk_mul_f32 v[122:123], v[122:123], v[196:197] op_sel_hi:[1,0]
	v_pk_mul_f32 v[172:173], v[120:121], v[196:197] op_sel_hi:[1,0]
	v_pk_mul_f32 v[118:119], v[118:119], v[196:197] op_sel_hi:[1,0]
	s_waitcnt lgkmcnt(0)
	v_add_f32_e32 v193, v190, v171
	s_nop 0
	v_pk_mul_f32 v[116:117], v[116:117], v[196:197] op_sel_hi:[1,0]
	s_nop 1
	v_mov_b32_e32 v194, v193
	s_nop 1
	v_permlane32_swap_b32_e32 v194, v193
	s_nop 0
	v_pk_mul_f32 v[114:115], v[114:115], v[196:197] op_sel_hi:[1,0]
	s_nop 1
	v_mov_b32_e32 v171, v191
	s_nop 1
	v_permlane16_swap_b32_e32 v171, v191
	v_pk_mul_f32 v[120:121], v[112:113], v[196:197] op_sel_hi:[1,0]
	s_waitcnt lgkmcnt(0)
	v_add_f32_e32 v191, v191, v171
	s_nop 0
	s_nop 0
	s_nop 1
	v_mov_b32_e32 v192, v191
	s_nop 1
	v_permlane32_swap_b32_e32 v192, v191
	s_nop 0
	s_nop 0
	s_nop 1
	v_mov_b32_e32 v171, v195
	s_nop 1
	v_permlane16_swap_b32_e32 v171, v195
	s_waitcnt lgkmcnt(0)
	v_add_f32_e32 v189, v195, v171
	s_nop 0
	s_nop 0
	s_nop 1
	v_mov_b32_e32 v190, v189
	s_nop 1
	v_permlane32_swap_b32_e32 v190, v189
	s_nop 0
	s_nop 0
	s_nop 1
	v_mov_b32_e32 v171, v169
	s_nop 1
	v_permlane16_swap_b32_e32 v171, v169
	s_waitcnt lgkmcnt(0)
	v_add_f32_e32 v187, v169, v171
	s_nop 0
	s_nop 0
	s_nop 1
	v_mov_b32_e32 v188, v187
	s_nop 1
	v_permlane32_swap_b32_e32 v188, v187
	s_nop 0
	s_nop 0
	s_nop 1
	v_mov_b32_e32 v169, v167
	s_nop 1
	v_permlane16_swap_b32_e32 v169, v167
	s_waitcnt lgkmcnt(0)
	v_add_f32_e32 v171, v167, v169
	s_nop 0
	s_nop 0
	s_nop 1
	v_mov_b32_e32 v186, v171
	s_nop 1
	v_permlane32_swap_b32_e32 v186, v171
	s_nop 0
	s_nop 0
	s_nop 1
	v_mov_b32_e32 v167, v165
	s_nop 1
	v_permlane16_swap_b32_e32 v167, v165
	s_waitcnt lgkmcnt(0)
	v_add_f32_e32 v167, v165, v167
	s_nop 0
	s_nop 0
	s_nop 1
	v_mov_b32_e32 v169, v167
	s_nop 1
	v_permlane32_swap_b32_e32 v169, v167
	s_nop 0
	s_nop 0
	s_nop 1
	v_mov_b32_e32 v165, v163
	s_nop 1
	v_permlane16_swap_b32_e32 v165, v163
	s_waitcnt lgkmcnt(0)
	v_add_f32_e32 v163, v163, v165
	s_nop 0
	s_nop 0
	s_nop 1
	v_mov_b32_e32 v165, v163
	s_nop 1
	v_permlane32_swap_b32_e32 v165, v163
	s_cbranch_scc1 .LBB0_1761
; __device__ __forceinline__ f32x4 silu4(f32x4 v) { return (f32x4){silu_f(v[0]), silu_f(v[1]), silu_f(v[2]), silu_f(v[3])}; }
; __device__ __forceinline__ float sq4(f32x4 v) { return (v[0] * v[0] + v[1] * v[1]) + (v[2] * v[2] + v[3] * v[3]); }
; __device__ __forceinline__ u32x4 pack8(f32x4 a, f32x4 b) { u32x4 w; w.x = cvt_pk_bf16(a[0], a[1]); w.y = cvt_pk_bf16(a[2], a[3]); w.z = cvt_pk_bf16(b[0], b[1]); w.w = cvt_pk_bf16(b[2], b[3]); return w; }
;     __device__ __forceinline__ void operator()(const f32x4 (&acc)[2][2][4][2], const Unit& u, int wr, int wc, int fr, int fq) const {
;     ...
;                 const int row = u.pm * BM + ai * HALF + wr * 64 + m * 16 + fr;
;                 const float rstd = rs[ai][m];
;                 f32x4 v[2][2];
; #pragma unroll
;                 for (int bj = 0; bj < 2; ++bj)
; #pragma unroll
;                     for (int n = 0; n < 2; ++n) v[bj][n] = acc[ai][bj][m][n] * rstd;
;                 if (mode == 2) {
;                     float q = (sq4(v[0][0]) + sq4(v[0][1])) + (sq4(v[1][0]) + sq4(v[1][1]));
;                     q += shx(q, 16); q += shx(q, 32);
;                     const float r2 = __builtin_amdgcn_rsqf(q * (1.0f / 64.0f) + RMS_EPS);
; #pragma unroll
;                     for (int bj = 0; bj < 2; ++bj)
; #pragma unroll
;                         for (int n = 0; n < 2; ++n) v[bj][n] = v[bj][n] * r2 * wv[bj][n];
;                 } else if (mode == 1) {
; #pragma unroll
;                     for (int bj = 0; bj < 2; ++bj)
; #pragma unroll
;                         for (int n = 0; n < 2; ++n) v[bj][n] = silu4(v[bj][n]);
;                 } else {
; #pragma unroll
;                     for (int bj = 0; bj < 2; ++bj)
; #pragma unroll
;                         for (int n = 0; n < 2; ++n) v[bj][n] = v[bj][n] * sc;
;                 }
;                 bf16_t* rowp = U + (size_t)row * 2560 + lcol;
; #pragma unroll
;                 for (int bj = 0; bj < 2; ++bj) *(u32x4*)(rowp + 32 * bj) = pack8(v[bj][0], v[bj][1]);
	v_mov_b32_e32 v196, v125
	v_mov_b32_e32 v197, v117
	v_mov_b32_e32 v112, v124
	v_mov_b32_e32 v113, v116
	v_pk_mul_f32 v[196:197], v[196:197], v[196:197]
	v_mov_b32_e32 v198, v127
	v_mov_b32_e32 v199, v119
	v_pk_fma_f32 v[112:113], v[112:113], v[112:113], v[196:197]
	v_mov_b32_e32 v196, v126
	v_mov_b32_e32 v197, v118
	v_pk_mul_f32 v[198:199], v[198:199], v[198:199]
	v_mov_b32_e32 v202, v123
	v_pk_fma_f32 v[196:197], v[196:197], v[196:197], v[198:199]
	v_mov_b32_e32 v198, v173
	v_mov_b32_e32 v199, v121
	v_pk_add_f32 v[112:113], v[112:113], v[196:197]
	v_mov_b32_e32 v196, v172
	v_mov_b32_e32 v197, v120
	v_pk_mul_f32 v[198:199], v[198:199], v[198:199]
	v_mov_b32_e32 v203, v115
	v_pk_fma_f32 v[196:197], v[196:197], v[196:197], v[198:199]
	v_mov_b32_e32 v198, v122
	v_mov_b32_e32 v199, v114
	v_pk_mul_f32 v[202:203], v[202:203], v[202:203]
	s_nop 0
	v_pk_fma_f32 v[198:199], v[198:199], v[198:199], v[202:203]
	s_nop 0
	v_pk_add_f32 v[196:197], v[196:197], v[198:199]
	s_nop 0
	v_pk_add_f32 v[112:113], v[112:113], v[196:197]
	s_nop 0
	v_add_f32_e32 v112, v112, v113
	s_nop 0
	s_nop 0
	s_nop 1
	v_mov_b32_e32 v113, v112
	s_nop 1
	v_permlane16_swap_b32_e32 v113, v112
	s_waitcnt lgkmcnt(0)
	v_add_f32_e32 v112, v112, v113
	s_nop 0
	s_nop 0
	s_nop 1
	v_mov_b32_e32 v113, v112
	s_nop 1
	v_permlane32_swap_b32_e32 v113, v112
	s_waitcnt lgkmcnt(0)
	v_add_f32_e32 v112, v112, v113
	v_fmamk_f32 v112, v112, 0x3c800000, v184
	v_rsq_f32_e32 v112, v112
	s_nop 0
	v_pk_mul_f32 v[124:125], v[124:125], v[112:113] op_sel_hi:[1,0]
	v_pk_mul_f32 v[126:127], v[126:127], v[112:113] op_sel_hi:[1,0]
	v_pk_mul_f32 v[172:173], v[172:173], v[112:113] op_sel_hi:[1,0]
	v_pk_mul_f32 v[122:123], v[122:123], v[112:113] op_sel_hi:[1,0]
	v_pk_mul_f32 v[116:117], v[116:117], v[112:113] op_sel_hi:[1,0]
	v_pk_mul_f32 v[118:119], v[118:119], v[112:113] op_sel_hi:[1,0]
	v_pk_mul_f32 v[120:121], v[120:121], v[112:113] op_sel_hi:[1,0]
	v_pk_mul_f32 v[112:113], v[114:115], v[112:113] op_sel_hi:[1,0]
	v_pk_mul_f32 v[126:127], v[152:153], v[126:127]
	v_pk_mul_f32 v[124:125], v[156:157], v[124:125]
	v_pk_mul_f32 v[122:123], v[146:147], v[122:123]
	v_pk_mul_f32 v[172:173], v[148:149], v[172:173]
	v_pk_mul_f32 v[118:119], v[158:159], v[118:119]
	v_pk_mul_f32 v[116:117], v[160:161], v[116:117]
	v_pk_mul_f32 v[114:115], v[150:151], v[112:113]
	v_pk_mul_f32 v[120:121], v[154:155], v[120:121]
.LBB0_1761:
	v_add_f32_e32 v112, v193, v194
	v_fmamk_f32 v112, v112, 0x3a800000, v184
	v_rsq_f32_e32 v194, v112
	v_lshl_or_b32 v112, s8, 8, v179
	v_mov_b64_e32 v[196:197], s[20:21]
	v_ashrrev_i32_e32 v113, 31, v112
	v_mad_i64_i32 v[196:197], s[8:9], v170, s68, v[196:197]
	v_lshl_add_u64 v[196:197], v[112:113], 1, v[196:197]
	v_cvt_pk_bf16_f32 v124, v124, v125
	v_cvt_pk_bf16_f32 v125, v126, v127
	v_cvt_pk_bf16_f32 v126, v172, v173
	v_cvt_pk_bf16_f32 v127, v122, v123
	global_store_dwordx4 v[196:197], v[124:127], off
	v_cvt_pk_bf16_f32 v116, v116, v117
	v_cvt_pk_bf16_f32 v117, v118, v119
	v_cvt_pk_bf16_f32 v118, v120, v121
	v_cvt_pk_bf16_f32 v119, v114, v115
	v_cndmask_b32_e64 v114, 0, 1, s[46:47]
	v_pk_mul_f32 v[110:111], v[110:111], v[194:195] op_sel_hi:[1,0]
	v_pk_mul_f32 v[108:109], v[108:109], v[194:195] op_sel_hi:[1,0]
	v_pk_mul_f32 v[106:107], v[106:107], v[194:195] op_sel_hi:[1,0]
	v_pk_mul_f32 v[104:105], v[104:105], v[194:195] op_sel_hi:[1,0]
	v_pk_mul_f32 v[102:103], v[102:103], v[194:195] op_sel_hi:[1,0]
	v_pk_mul_f32 v[100:101], v[100:101], v[194:195] op_sel_hi:[1,0]
	v_pk_mul_f32 v[98:99], v[98:99], v[194:195] op_sel_hi:[1,0]
	v_cmp_ne_u32_e64 s[8:9], 1, v114
	s_andn2_b64 vcc, exec, s[46:47]
	v_pk_mul_f32 v[96:97], v[96:97], v[194:195] op_sel_hi:[1,0]
	global_store_dwordx4 v[196:197], v[116:119], off offset:64
	s_cbranch_vccnz .LBB0_1763
	s_nop 0
	v_mov_b32_e32 v116, v109
	v_mov_b32_e32 v117, v101
	v_mov_b32_e32 v114, v108
	v_mov_b32_e32 v115, v100
	v_pk_mul_f32 v[116:117], v[116:117], v[116:117]
	v_mov_b32_e32 v118, v111
	v_mov_b32_e32 v119, v103
	v_pk_fma_f32 v[114:115], v[114:115], v[114:115], v[116:117]
	v_mov_b32_e32 v116, v110
	v_mov_b32_e32 v117, v102
	v_pk_mul_f32 v[118:119], v[118:119], v[118:119]
	v_mov_b32_e32 v120, v107
	v_pk_fma_f32 v[116:117], v[116:117], v[116:117], v[118:119]
	v_mov_b32_e32 v118, v105
	v_mov_b32_e32 v119, v97
	v_pk_add_f32 v[114:115], v[114:115], v[116:117]
	v_mov_b32_e32 v116, v104
	v_mov_b32_e32 v117, v96
	v_pk_mul_f32 v[118:119], v[118:119], v[118:119]
	v_mov_b32_e32 v121, v99
	v_pk_fma_f32 v[116:117], v[116:117], v[116:117], v[118:119]
	v_mov_b32_e32 v118, v106
	v_mov_b32_e32 v119, v98
	v_pk_mul_f32 v[120:121], v[120:121], v[120:121]
	s_nop 0
	v_pk_fma_f32 v[118:119], v[118:119], v[118:119], v[120:121]
	s_nop 0
	v_pk_add_f32 v[116:117], v[116:117], v[118:119]
	s_nop 0
	v_pk_add_f32 v[114:115], v[114:115], v[116:117]
	s_nop 0
	v_add_f32_e32 v114, v114, v115
	s_nop 0
	s_nop 0
	s_nop 1
	v_mov_b32_e32 v115, v114
	s_nop 1
	v_permlane16_swap_b32_e32 v115, v114
	s_waitcnt lgkmcnt(0)
	v_add_f32_e32 v114, v114, v115
	s_nop 0
	s_nop 0
	s_nop 1
	v_mov_b32_e32 v115, v114
	s_nop 1
	v_permlane32_swap_b32_e32 v115, v114
	s_waitcnt lgkmcnt(0)
	v_add_f32_e32 v114, v114, v115
	v_fmamk_f32 v114, v114, 0x3c800000, v184
	v_rsq_f32_e32 v114, v114
	s_nop 0
	v_pk_mul_f32 v[108:109], v[108:109], v[114:115] op_sel_hi:[1,0]
	v_pk_mul_f32 v[110:111], v[110:111], v[114:115] op_sel_hi:[1,0]
	v_pk_mul_f32 v[104:105], v[104:105], v[114:115] op_sel_hi:[1,0]
	v_pk_mul_f32 v[106:107], v[106:107], v[114:115] op_sel_hi:[1,0]
	v_pk_mul_f32 v[100:101], v[100:101], v[114:115] op_sel_hi:[1,0]
	v_pk_mul_f32 v[102:103], v[102:103], v[114:115] op_sel_hi:[1,0]
	v_pk_mul_f32 v[96:97], v[96:97], v[114:115] op_sel_hi:[1,0]
	v_pk_mul_f32 v[98:99], v[98:99], v[114:115] op_sel_hi:[1,0]
	v_pk_mul_f32 v[110:111], v[152:153], v[110:111]
	v_pk_mul_f32 v[108:109], v[156:157], v[108:109]
	v_pk_mul_f32 v[106:107], v[146:147], v[106:107]
	v_pk_mul_f32 v[104:105], v[148:149], v[104:105]
	v_pk_mul_f32 v[102:103], v[158:159], v[102:103]
	v_pk_mul_f32 v[100:101], v[160:161], v[100:101]
	v_pk_mul_f32 v[98:99], v[150:151], v[98:99]
	v_pk_mul_f32 v[96:97], v[154:155], v[96:97]
; __device__ __forceinline__ f32x4 silu4(f32x4 v) { return (f32x4){silu_f(v[0]), silu_f(v[1]), silu_f(v[2]), silu_f(v[3])}; }
; __device__ __forceinline__ float sq4(f32x4 v) { return (v[0] * v[0] + v[1] * v[1]) + (v[2] * v[2] + v[3] * v[3]); }
; __device__ __forceinline__ u32x4 pack8(f32x4 a, f32x4 b) { u32x4 w; w.x = cvt_pk_bf16(a[0], a[1]); w.y = cvt_pk_bf16(a[2], a[3]); w.z = cvt_pk_bf16(b[0], b[1]); w.w = cvt_pk_bf16(b[2], b[3]); return w; }
;     __device__ __forceinline__ void operator()(const f32x4 (&acc)[2][2][4][2], const Unit& u, int wr, int wc, int fr, int fq) const {
;     ...
;                 const int row = u.pm * BM + ai * HALF + wr * 64 + m * 16 + fr;
;                 const float rstd = rs[ai][m];
;                 f32x4 v[2][2];
; #pragma unroll
;                 for (int bj = 0; bj < 2; ++bj)
; #pragma unroll
;                     for (int n = 0; n < 2; ++n) v[bj][n] = acc[ai][bj][m][n] * rstd;
;                 if (mode == 2) {
;                     float q = (sq4(v[0][0]) + sq4(v[0][1])) + (sq4(v[1][0]) + sq4(v[1][1]));
;                     q += shx(q, 16); q += shx(q, 32);
;                     const float r2 = __builtin_amdgcn_rsqf(q * (1.0f / 64.0f) + RMS_EPS);
; #pragma unroll
;                     for (int bj = 0; bj < 2; ++bj)
; #pragma unroll
;                         for (int n = 0; n < 2; ++n) v[bj][n] = v[bj][n] * r2 * wv[bj][n];
;                 } else if (mode == 1) {
; #pragma unroll
;                     for (int bj = 0; bj < 2; ++bj)
; #pragma unroll
;                         for (int n = 0; n < 2; ++n) v[bj][n] = silu4(v[bj][n]);
;                 } else {
; #pragma unroll
;                     for (int bj = 0; bj < 2; ++bj)
; #pragma unroll
;                         for (int n = 0; n < 2; ++n) v[bj][n] = v[bj][n] * sc;
;                 }
;                 bf16_t* rowp = U + (size_t)row * 2560 + lcol;
; #pragma unroll
;                 for (int bj = 0; bj < 2; ++bj) *(u32x4*)(rowp + 32 * bj) = pack8(v[bj][0], v[bj][1]);
.LBB0_1763:
	v_add_f32_e32 v114, v191, v192
	v_fmamk_f32 v114, v114, 0x3a800000, v184
	v_rsq_f32_e32 v114, v114
	v_add_u32_e32 v115, s23, v176
	v_mov_b64_e32 v[116:117], s[20:21]
	v_mad_i64_i32 v[116:117], s[46:47], v115, s68, v[116:117]
	v_lshl_add_u64 v[116:117], v[112:113], 1, v[116:117]
	v_pk_mul_f32 v[94:95], v[94:95], v[114:115] op_sel_hi:[1,0]
	v_pk_mul_f32 v[92:93], v[92:93], v[114:115] op_sel_hi:[1,0]
	v_pk_mul_f32 v[90:91], v[90:91], v[114:115] op_sel_hi:[1,0]
	v_pk_mul_f32 v[88:89], v[88:89], v[114:115] op_sel_hi:[1,0]
	v_pk_mul_f32 v[86:87], v[86:87], v[114:115] op_sel_hi:[1,0]
	v_pk_mul_f32 v[84:85], v[84:85], v[114:115] op_sel_hi:[1,0]
	v_pk_mul_f32 v[82:83], v[82:83], v[114:115] op_sel_hi:[1,0]
	s_and_b64 vcc, exec, s[8:9]
	v_pk_mul_f32 v[80:81], v[80:81], v[114:115] op_sel_hi:[1,0]
	v_cvt_pk_bf16_f32 v108, v108, v109
	v_cvt_pk_bf16_f32 v109, v110, v111
	v_cvt_pk_bf16_f32 v110, v104, v105
	v_cvt_pk_bf16_f32 v111, v106, v107
	global_store_dwordx4 v[116:117], v[108:111], off
	v_cvt_pk_bf16_f32 v100, v100, v101
	v_cvt_pk_bf16_f32 v101, v102, v103
	v_cvt_pk_bf16_f32 v102, v96, v97
	v_cvt_pk_bf16_f32 v103, v98, v99
	global_store_dwordx4 v[116:117], v[100:103], off offset:64
	s_cbranch_vccnz .LBB0_1765
	v_mov_b32_e32 v98, v93
	v_mov_b32_e32 v99, v85
	v_mov_b32_e32 v96, v92
	v_mov_b32_e32 v97, v84
	v_pk_mul_f32 v[98:99], v[98:99], v[98:99]
	v_mov_b32_e32 v100, v95
	v_mov_b32_e32 v101, v87
	v_pk_fma_f32 v[96:97], v[96:97], v[96:97], v[98:99]
	v_mov_b32_e32 v98, v94
	v_mov_b32_e32 v99, v86
	v_pk_mul_f32 v[100:101], v[100:101], v[100:101]
	v_mov_b32_e32 v102, v91
	v_pk_fma_f32 v[98:99], v[98:99], v[98:99], v[100:101]
	v_mov_b32_e32 v100, v89
	v_mov_b32_e32 v101, v81
	v_pk_add_f32 v[96:97], v[96:97], v[98:99]
	v_mov_b32_e32 v98, v88
	v_mov_b32_e32 v99, v80
	v_pk_mul_f32 v[100:101], v[100:101], v[100:101]
	v_mov_b32_e32 v103, v83
	v_pk_fma_f32 v[98:99], v[98:99], v[98:99], v[100:101]
	v_mov_b32_e32 v100, v90
	v_mov_b32_e32 v101, v82
	v_pk_mul_f32 v[102:103], v[102:103], v[102:103]
	s_nop 0
	v_pk_fma_f32 v[100:101], v[100:101], v[100:101], v[102:103]
	s_nop 0
	v_pk_add_f32 v[98:99], v[98:99], v[100:101]
	s_nop 0
	v_pk_add_f32 v[96:97], v[96:97], v[98:99]
	s_nop 0
	v_add_f32_e32 v96, v96, v97
	s_nop 0
	s_nop 0
	s_nop 1
	v_mov_b32_e32 v97, v96
	s_nop 1
	v_permlane16_swap_b32_e32 v97, v96
	s_waitcnt lgkmcnt(0)
	v_add_f32_e32 v96, v96, v97
	s_nop 0
	s_nop 0
	s_nop 1
	v_mov_b32_e32 v97, v96
	s_nop 1
	v_permlane32_swap_b32_e32 v97, v96
	s_waitcnt lgkmcnt(0)
	v_add_f32_e32 v96, v96, v97
	v_fmamk_f32 v96, v96, 0x3c800000, v184
	v_rsq_f32_e32 v96, v96
	s_nop 0
	v_pk_mul_f32 v[92:93], v[92:93], v[96:97] op_sel_hi:[1,0]
	v_pk_mul_f32 v[94:95], v[94:95], v[96:97] op_sel_hi:[1,0]
	v_pk_mul_f32 v[88:89], v[88:89], v[96:97] op_sel_hi:[1,0]
	v_pk_mul_f32 v[90:91], v[90:91], v[96:97] op_sel_hi:[1,0]
	v_pk_mul_f32 v[84:85], v[84:85], v[96:97] op_sel_hi:[1,0]
	v_pk_mul_f32 v[86:87], v[86:87], v[96:97] op_sel_hi:[1,0]
	v_pk_mul_f32 v[80:81], v[80:81], v[96:97] op_sel_hi:[1,0]
	v_pk_mul_f32 v[82:83], v[82:83], v[96:97] op_sel_hi:[1,0]
	v_pk_mul_f32 v[94:95], v[152:153], v[94:95]
	v_pk_mul_f32 v[92:93], v[156:157], v[92:93]
	v_pk_mul_f32 v[90:91], v[146:147], v[90:91]
	v_pk_mul_f32 v[88:89], v[148:149], v[88:89]
	v_pk_mul_f32 v[86:87], v[158:159], v[86:87]
	v_pk_mul_f32 v[84:85], v[160:161], v[84:85]
	v_pk_mul_f32 v[82:83], v[150:151], v[82:83]
	v_pk_mul_f32 v[80:81], v[154:155], v[80:81]
.LBB0_1765:
	v_add_f32_e32 v96, v189, v190
	v_fmamk_f32 v96, v96, 0x3a800000, v184
	v_rsq_f32_e32 v96, v96
	v_add_u32_e32 v97, s23, v177
	v_mov_b64_e32 v[98:99], s[20:21]
	v_mad_i64_i32 v[98:99], s[46:47], v97, s68, v[98:99]
	v_lshl_add_u64 v[98:99], v[112:113], 1, v[98:99]
	v_pk_mul_f32 v[78:79], v[78:79], v[96:97] op_sel_hi:[1,0]
	v_pk_mul_f32 v[76:77], v[76:77], v[96:97] op_sel_hi:[1,0]
	v_pk_mul_f32 v[74:75], v[74:75], v[96:97] op_sel_hi:[1,0]
	v_pk_mul_f32 v[72:73], v[72:73], v[96:97] op_sel_hi:[1,0]
	v_pk_mul_f32 v[70:71], v[70:71], v[96:97] op_sel_hi:[1,0]
	v_pk_mul_f32 v[68:69], v[68:69], v[96:97] op_sel_hi:[1,0]
	v_pk_mul_f32 v[66:67], v[66:67], v[96:97] op_sel_hi:[1,0]
	s_and_b64 vcc, exec, s[8:9]
	v_pk_mul_f32 v[64:65], v[64:65], v[96:97] op_sel_hi:[1,0]
	v_cvt_pk_bf16_f32 v92, v92, v93
	v_cvt_pk_bf16_f32 v93, v94, v95
	v_cvt_pk_bf16_f32 v94, v88, v89
	v_cvt_pk_bf16_f32 v95, v90, v91
	global_store_dwordx4 v[98:99], v[92:95], off
	v_cvt_pk_bf16_f32 v84, v84, v85
	v_cvt_pk_bf16_f32 v85, v86, v87
	v_cvt_pk_bf16_f32 v86, v80, v81
	v_cvt_pk_bf16_f32 v87, v82, v83
	global_store_dwordx4 v[98:99], v[84:87], off offset:64
	s_cbranch_vccnz .LBB0_1767
	v_mov_b32_e32 v82, v77
	v_mov_b32_e32 v83, v69
	v_mov_b32_e32 v80, v76
	v_mov_b32_e32 v81, v68
	v_pk_mul_f32 v[82:83], v[82:83], v[82:83]
	v_mov_b32_e32 v84, v79
	v_mov_b32_e32 v85, v71
	v_pk_fma_f32 v[80:81], v[80:81], v[80:81], v[82:83]
	v_mov_b32_e32 v82, v78
	v_mov_b32_e32 v83, v70
	v_pk_mul_f32 v[84:85], v[84:85], v[84:85]
	v_mov_b32_e32 v86, v75
	v_pk_fma_f32 v[82:83], v[82:83], v[82:83], v[84:85]
	v_mov_b32_e32 v84, v73
	v_mov_b32_e32 v85, v65
	v_pk_add_f32 v[80:81], v[80:81], v[82:83]
	v_mov_b32_e32 v82, v72
	v_mov_b32_e32 v83, v64
	v_pk_mul_f32 v[84:85], v[84:85], v[84:85]
	v_mov_b32_e32 v87, v67
	v_pk_fma_f32 v[82:83], v[82:83], v[82:83], v[84:85]
	v_mov_b32_e32 v84, v74
	v_mov_b32_e32 v85, v66
	v_pk_mul_f32 v[86:87], v[86:87], v[86:87]
	s_nop 0
	v_pk_fma_f32 v[84:85], v[84:85], v[84:85], v[86:87]
	s_nop 0
	v_pk_add_f32 v[82:83], v[82:83], v[84:85]
	s_nop 0
	v_pk_add_f32 v[80:81], v[80:81], v[82:83]
	s_nop 0
	v_add_f32_e32 v80, v80, v81
	s_nop 0
	s_nop 0
	s_nop 1
	v_mov_b32_e32 v81, v80
	s_nop 1
	v_permlane16_swap_b32_e32 v81, v80
	s_waitcnt lgkmcnt(0)
	v_add_f32_e32 v80, v80, v81
	s_nop 0
	s_nop 0
	s_nop 1
	v_mov_b32_e32 v81, v80
	s_nop 1
	v_permlane32_swap_b32_e32 v81, v80
	s_waitcnt lgkmcnt(0)
	v_add_f32_e32 v80, v80, v81
	v_fmamk_f32 v80, v80, 0x3c800000, v184
	v_rsq_f32_e32 v80, v80
	s_nop 0
	v_pk_mul_f32 v[76:77], v[76:77], v[80:81] op_sel_hi:[1,0]
	v_pk_mul_f32 v[78:79], v[78:79], v[80:81] op_sel_hi:[1,0]
	v_pk_mul_f32 v[72:73], v[72:73], v[80:81] op_sel_hi:[1,0]
	v_pk_mul_f32 v[74:75], v[74:75], v[80:81] op_sel_hi:[1,0]
	v_pk_mul_f32 v[68:69], v[68:69], v[80:81] op_sel_hi:[1,0]
	v_pk_mul_f32 v[70:71], v[70:71], v[80:81] op_sel_hi:[1,0]
	v_pk_mul_f32 v[64:65], v[64:65], v[80:81] op_sel_hi:[1,0]
	v_pk_mul_f32 v[66:67], v[66:67], v[80:81] op_sel_hi:[1,0]
	v_pk_mul_f32 v[78:79], v[152:153], v[78:79]
	v_pk_mul_f32 v[76:77], v[156:157], v[76:77]
	v_pk_mul_f32 v[74:75], v[146:147], v[74:75]
	v_pk_mul_f32 v[72:73], v[148:149], v[72:73]
	v_pk_mul_f32 v[70:71], v[158:159], v[70:71]
	v_pk_mul_f32 v[68:69], v[160:161], v[68:69]
	v_pk_mul_f32 v[66:67], v[150:151], v[66:67]
	v_pk_mul_f32 v[64:65], v[154:155], v[64:65]
; __device__ __forceinline__ f32x4 silu4(f32x4 v) { return (f32x4){silu_f(v[0]), silu_f(v[1]), silu_f(v[2]), silu_f(v[3])}; }
; __device__ __forceinline__ float sq4(f32x4 v) { return (v[0] * v[0] + v[1] * v[1]) + (v[2] * v[2] + v[3] * v[3]); }
; __device__ __forceinline__ u32x4 pack8(f32x4 a, f32x4 b) { u32x4 w; w.x = cvt_pk_bf16(a[0], a[1]); w.y = cvt_pk_bf16(a[2], a[3]); w.z = cvt_pk_bf16(b[0], b[1]); w.w = cvt_pk_bf16(b[2], b[3]); return w; }
;     __device__ __forceinline__ void operator()(const f32x4 (&acc)[2][2][4][2], const Unit& u, int wr, int wc, int fr, int fq) const {
;     ...
;                 const int row = u.pm * BM + ai * HALF + wr * 64 + m * 16 + fr;
;                 const float rstd = rs[ai][m];
;                 f32x4 v[2][2];
; #pragma unroll
;                 for (int bj = 0; bj < 2; ++bj)
; #pragma unroll
;                     for (int n = 0; n < 2; ++n) v[bj][n] = acc[ai][bj][m][n] * rstd;
;                 if (mode == 2) {
;                     float q = (sq4(v[0][0]) + sq4(v[0][1])) + (sq4(v[1][0]) + sq4(v[1][1]));
;                     q += shx(q, 16); q += shx(q, 32);
;                     const float r2 = __builtin_amdgcn_rsqf(q * (1.0f / 64.0f) + RMS_EPS);
; #pragma unroll
;                     for (int bj = 0; bj < 2; ++bj)
; #pragma unroll
;                         for (int n = 0; n < 2; ++n) v[bj][n] = v[bj][n] * r2 * wv[bj][n];
;                 } else if (mode == 1) {
; #pragma unroll
;                     for (int bj = 0; bj < 2; ++bj)
; #pragma unroll
;                         for (int n = 0; n < 2; ++n) v[bj][n] = silu4(v[bj][n]);
;                 } else {
; #pragma unroll
;                     for (int bj = 0; bj < 2; ++bj)
; #pragma unroll
;                         for (int n = 0; n < 2; ++n) v[bj][n] = v[bj][n] * sc;
;                 }
;                 bf16_t* rowp = U + (size_t)row * 2560 + lcol;
; #pragma unroll
;                 for (int bj = 0; bj < 2; ++bj) *(u32x4*)(rowp + 32 * bj) = pack8(v[bj][0], v[bj][1]);
.LBB0_1767:
	v_add_f32_e32 v80, v187, v188
	v_fmamk_f32 v80, v80, 0x3a800000, v184
	v_rsq_f32_e32 v80, v80
	v_add_u32_e32 v81, s23, v178
	v_mov_b64_e32 v[82:83], s[20:21]
	v_mad_i64_i32 v[82:83], s[46:47], v81, s68, v[82:83]
	v_lshl_add_u64 v[82:83], v[112:113], 1, v[82:83]
	v_pk_mul_f32 v[62:63], v[62:63], v[80:81] op_sel_hi:[1,0]
	v_pk_mul_f32 v[60:61], v[60:61], v[80:81] op_sel_hi:[1,0]
	v_pk_mul_f32 v[58:59], v[58:59], v[80:81] op_sel_hi:[1,0]
	v_pk_mul_f32 v[56:57], v[56:57], v[80:81] op_sel_hi:[1,0]
	v_pk_mul_f32 v[54:55], v[54:55], v[80:81] op_sel_hi:[1,0]
	v_pk_mul_f32 v[52:53], v[52:53], v[80:81] op_sel_hi:[1,0]
	v_pk_mul_f32 v[50:51], v[50:51], v[80:81] op_sel_hi:[1,0]
	s_and_b64 vcc, exec, s[8:9]
	v_pk_mul_f32 v[48:49], v[48:49], v[80:81] op_sel_hi:[1,0]
	v_cvt_pk_bf16_f32 v76, v76, v77
	v_cvt_pk_bf16_f32 v77, v78, v79
	v_cvt_pk_bf16_f32 v78, v72, v73
	v_cvt_pk_bf16_f32 v79, v74, v75
	global_store_dwordx4 v[82:83], v[76:79], off
	v_cvt_pk_bf16_f32 v68, v68, v69
	v_cvt_pk_bf16_f32 v69, v70, v71
	v_cvt_pk_bf16_f32 v70, v64, v65
	v_cvt_pk_bf16_f32 v71, v66, v67
	global_store_dwordx4 v[82:83], v[68:71], off offset:64
	s_cbranch_vccnz .LBB0_1769
	v_mov_b32_e32 v66, v61
	v_mov_b32_e32 v67, v53
	v_mov_b32_e32 v64, v60
	v_mov_b32_e32 v65, v52
	v_pk_mul_f32 v[66:67], v[66:67], v[66:67]
	v_mov_b32_e32 v68, v63
	v_mov_b32_e32 v69, v55
	v_pk_fma_f32 v[64:65], v[64:65], v[64:65], v[66:67]
	v_mov_b32_e32 v66, v62
	v_mov_b32_e32 v67, v54
	v_pk_mul_f32 v[68:69], v[68:69], v[68:69]
	v_mov_b32_e32 v70, v59
	v_pk_fma_f32 v[66:67], v[66:67], v[66:67], v[68:69]
	v_mov_b32_e32 v68, v57
	v_mov_b32_e32 v69, v49
	v_pk_add_f32 v[64:65], v[64:65], v[66:67]
	v_mov_b32_e32 v66, v56
	v_mov_b32_e32 v67, v48
	v_pk_mul_f32 v[68:69], v[68:69], v[68:69]
	v_mov_b32_e32 v71, v51
	v_pk_fma_f32 v[66:67], v[66:67], v[66:67], v[68:69]
	v_mov_b32_e32 v68, v58
	v_mov_b32_e32 v69, v50
	v_pk_mul_f32 v[70:71], v[70:71], v[70:71]
	s_nop 0
	v_pk_fma_f32 v[68:69], v[68:69], v[68:69], v[70:71]
	s_nop 0
	v_pk_add_f32 v[66:67], v[66:67], v[68:69]
	s_nop 0
	v_pk_add_f32 v[64:65], v[64:65], v[66:67]
	s_nop 0
	v_add_f32_e32 v64, v64, v65
	s_nop 0
	s_nop 0
	s_nop 1
	v_mov_b32_e32 v65, v64
	s_nop 1
	v_permlane16_swap_b32_e32 v65, v64
	s_waitcnt lgkmcnt(0)
	v_add_f32_e32 v64, v64, v65
	s_nop 0
	s_nop 0
	s_nop 1
	v_mov_b32_e32 v65, v64
	s_nop 1
	v_permlane32_swap_b32_e32 v65, v64
	s_waitcnt lgkmcnt(0)
	v_add_f32_e32 v64, v64, v65
	v_fmamk_f32 v64, v64, 0x3c800000, v184
	v_rsq_f32_e32 v64, v64
	s_nop 0
	v_pk_mul_f32 v[60:61], v[60:61], v[64:65] op_sel_hi:[1,0]
	v_pk_mul_f32 v[62:63], v[62:63], v[64:65] op_sel_hi:[1,0]
	v_pk_mul_f32 v[56:57], v[56:57], v[64:65] op_sel_hi:[1,0]
	v_pk_mul_f32 v[58:59], v[58:59], v[64:65] op_sel_hi:[1,0]
	v_pk_mul_f32 v[52:53], v[52:53], v[64:65] op_sel_hi:[1,0]
	v_pk_mul_f32 v[54:55], v[54:55], v[64:65] op_sel_hi:[1,0]
	v_pk_mul_f32 v[48:49], v[48:49], v[64:65] op_sel_hi:[1,0]
	v_pk_mul_f32 v[50:51], v[50:51], v[64:65] op_sel_hi:[1,0]
	v_pk_mul_f32 v[62:63], v[152:153], v[62:63]
	v_pk_mul_f32 v[60:61], v[156:157], v[60:61]
	v_pk_mul_f32 v[58:59], v[146:147], v[58:59]
	v_pk_mul_f32 v[56:57], v[148:149], v[56:57]
	v_pk_mul_f32 v[54:55], v[158:159], v[54:55]
	v_pk_mul_f32 v[52:53], v[160:161], v[52:53]
	v_pk_mul_f32 v[50:51], v[150:151], v[50:51]
	v_pk_mul_f32 v[48:49], v[154:155], v[48:49]
.LBB0_1769:
	v_add_f32_e32 v64, v171, v186
	v_fmamk_f32 v64, v64, 0x3a800000, v184
	v_rsq_f32_e32 v64, v64
	v_mov_b64_e32 v[66:67], s[20:21]
	v_mad_i64_i32 v[66:67], s[46:47], v168, s68, v[66:67]
	v_lshl_add_u64 v[66:67], v[112:113], 1, v[66:67]
	v_pk_mul_f32 v[46:47], v[46:47], v[64:65] op_sel_hi:[1,0]
	v_pk_mul_f32 v[44:45], v[44:45], v[64:65] op_sel_hi:[1,0]
	v_pk_mul_f32 v[42:43], v[42:43], v[64:65] op_sel_hi:[1,0]
	v_pk_mul_f32 v[40:41], v[40:41], v[64:65] op_sel_hi:[1,0]
	v_pk_mul_f32 v[38:39], v[38:39], v[64:65] op_sel_hi:[1,0]
	v_pk_mul_f32 v[36:37], v[36:37], v[64:65] op_sel_hi:[1,0]
	v_pk_mul_f32 v[34:35], v[34:35], v[64:65] op_sel_hi:[1,0]
	s_and_b64 vcc, exec, s[8:9]
	v_pk_mul_f32 v[32:33], v[32:33], v[64:65] op_sel_hi:[1,0]
	v_cvt_pk_bf16_f32 v60, v60, v61
	v_cvt_pk_bf16_f32 v61, v62, v63
	v_cvt_pk_bf16_f32 v62, v56, v57
	v_cvt_pk_bf16_f32 v63, v58, v59
	global_store_dwordx4 v[66:67], v[60:63], off
	v_cvt_pk_bf16_f32 v52, v52, v53
	v_cvt_pk_bf16_f32 v53, v54, v55
	v_cvt_pk_bf16_f32 v54, v48, v49
	v_cvt_pk_bf16_f32 v55, v50, v51
	global_store_dwordx4 v[66:67], v[52:55], off offset:64
	s_cbranch_vccnz .LBB0_1771
	v_mov_b32_e32 v50, v45
	v_mov_b32_e32 v51, v37
	v_mov_b32_e32 v48, v44
	v_mov_b32_e32 v49, v36
	v_pk_mul_f32 v[50:51], v[50:51], v[50:51]
	v_mov_b32_e32 v52, v47
	v_mov_b32_e32 v53, v39
	v_pk_fma_f32 v[48:49], v[48:49], v[48:49], v[50:51]
	v_mov_b32_e32 v50, v46
	v_mov_b32_e32 v51, v38
	v_pk_mul_f32 v[52:53], v[52:53], v[52:53]
	v_mov_b32_e32 v54, v43
	v_pk_fma_f32 v[50:51], v[50:51], v[50:51], v[52:53]
	v_mov_b32_e32 v52, v41
	v_mov_b32_e32 v53, v33
	v_pk_add_f32 v[48:49], v[48:49], v[50:51]
	v_mov_b32_e32 v50, v40
	v_mov_b32_e32 v51, v32
	v_pk_mul_f32 v[52:53], v[52:53], v[52:53]
	v_mov_b32_e32 v55, v35
	v_pk_fma_f32 v[50:51], v[50:51], v[50:51], v[52:53]
	v_mov_b32_e32 v52, v42
	v_mov_b32_e32 v53, v34
	v_pk_mul_f32 v[54:55], v[54:55], v[54:55]
	s_nop 0
	v_pk_fma_f32 v[52:53], v[52:53], v[52:53], v[54:55]
	s_nop 0
	v_pk_add_f32 v[50:51], v[50:51], v[52:53]
	s_nop 0
	v_pk_add_f32 v[48:49], v[48:49], v[50:51]
	s_nop 0
	v_add_f32_e32 v48, v48, v49
	s_nop 0
	s_nop 0
	s_nop 1
	v_mov_b32_e32 v49, v48
	s_nop 1
	v_permlane16_swap_b32_e32 v49, v48
	s_waitcnt lgkmcnt(0)
	v_add_f32_e32 v48, v48, v49
	s_nop 0
	s_nop 0
	s_nop 1
	v_mov_b32_e32 v49, v48
	s_nop 1
	v_permlane32_swap_b32_e32 v49, v48
	s_waitcnt lgkmcnt(0)
	v_add_f32_e32 v48, v48, v49
	v_fmamk_f32 v48, v48, 0x3c800000, v184
	v_rsq_f32_e32 v48, v48
	s_nop 0
	v_pk_mul_f32 v[44:45], v[44:45], v[48:49] op_sel_hi:[1,0]
	v_pk_mul_f32 v[46:47], v[46:47], v[48:49] op_sel_hi:[1,0]
	v_pk_mul_f32 v[40:41], v[40:41], v[48:49] op_sel_hi:[1,0]
	v_pk_mul_f32 v[42:43], v[42:43], v[48:49] op_sel_hi:[1,0]
	v_pk_mul_f32 v[36:37], v[36:37], v[48:49] op_sel_hi:[1,0]
	v_pk_mul_f32 v[38:39], v[38:39], v[48:49] op_sel_hi:[1,0]
	v_pk_mul_f32 v[32:33], v[32:33], v[48:49] op_sel_hi:[1,0]
	v_pk_mul_f32 v[34:35], v[34:35], v[48:49] op_sel_hi:[1,0]
	v_pk_mul_f32 v[46:47], v[152:153], v[46:47]
	v_pk_mul_f32 v[44:45], v[156:157], v[44:45]
	v_pk_mul_f32 v[42:43], v[146:147], v[42:43]
	v_pk_mul_f32 v[40:41], v[148:149], v[40:41]
	v_pk_mul_f32 v[38:39], v[158:159], v[38:39]
	v_pk_mul_f32 v[36:37], v[160:161], v[36:37]
	v_pk_mul_f32 v[34:35], v[150:151], v[34:35]
	v_pk_mul_f32 v[32:33], v[154:155], v[32:33]
; __device__ __forceinline__ f32x4 silu4(f32x4 v) { return (f32x4){silu_f(v[0]), silu_f(v[1]), silu_f(v[2]), silu_f(v[3])}; }
; __device__ __forceinline__ float sq4(f32x4 v) { return (v[0] * v[0] + v[1] * v[1]) + (v[2] * v[2] + v[3] * v[3]); }
; __device__ __forceinline__ u32x4 pack8(f32x4 a, f32x4 b) { u32x4 w; w.x = cvt_pk_bf16(a[0], a[1]); w.y = cvt_pk_bf16(a[2], a[3]); w.z = cvt_pk_bf16(b[0], b[1]); w.w = cvt_pk_bf16(b[2], b[3]); return w; }
;     __device__ __forceinline__ void operator()(const f32x4 (&acc)[2][2][4][2], const Unit& u, int wr, int wc, int fr, int fq) const {
;     ...
;                 const int row = u.pm * BM + ai * HALF + wr * 64 + m * 16 + fr;
;                 const float rstd = rs[ai][m];
;                 f32x4 v[2][2];
; #pragma unroll
;                 for (int bj = 0; bj < 2; ++bj)
; #pragma unroll
;                     for (int n = 0; n < 2; ++n) v[bj][n] = acc[ai][bj][m][n] * rstd;
;                 if (mode == 2) {
;                     float q = (sq4(v[0][0]) + sq4(v[0][1])) + (sq4(v[1][0]) + sq4(v[1][1]));
;                     q += shx(q, 16); q += shx(q, 32);
;                     const float r2 = __builtin_amdgcn_rsqf(q * (1.0f / 64.0f) + RMS_EPS);
; #pragma unroll
;                     for (int bj = 0; bj < 2; ++bj)
; #pragma unroll
;                         for (int n = 0; n < 2; ++n) v[bj][n] = v[bj][n] * r2 * wv[bj][n];
;                 } else if (mode == 1) {
; #pragma unroll
;                     for (int bj = 0; bj < 2; ++bj)
; #pragma unroll
;                         for (int n = 0; n < 2; ++n) v[bj][n] = silu4(v[bj][n]);
;                 } else {
; #pragma unroll
;                     for (int bj = 0; bj < 2; ++bj)
; #pragma unroll
;                         for (int n = 0; n < 2; ++n) v[bj][n] = v[bj][n] * sc;
;                 }
;                 bf16_t* rowp = U + (size_t)row * 2560 + lcol;
; #pragma unroll
;                 for (int bj = 0; bj < 2; ++bj) *(u32x4*)(rowp + 32 * bj) = pack8(v[bj][0], v[bj][1]);
.LBB0_1771:
	v_add_f32_e32 v48, v167, v169
	v_fmamk_f32 v48, v48, 0x3a800000, v184
	v_rsq_f32_e32 v48, v48
	v_mov_b64_e32 v[50:51], s[20:21]
	v_mad_i64_i32 v[50:51], s[46:47], v166, s68, v[50:51]
	v_lshl_add_u64 v[50:51], v[112:113], 1, v[50:51]
	v_pk_mul_f32 v[30:31], v[30:31], v[48:49] op_sel_hi:[1,0]
	v_pk_mul_f32 v[28:29], v[28:29], v[48:49] op_sel_hi:[1,0]
	v_pk_mul_f32 v[26:27], v[26:27], v[48:49] op_sel_hi:[1,0]
	v_pk_mul_f32 v[24:25], v[24:25], v[48:49] op_sel_hi:[1,0]
	v_pk_mul_f32 v[22:23], v[22:23], v[48:49] op_sel_hi:[1,0]
	v_pk_mul_f32 v[20:21], v[20:21], v[48:49] op_sel_hi:[1,0]
	v_pk_mul_f32 v[18:19], v[18:19], v[48:49] op_sel_hi:[1,0]
	s_and_b64 vcc, exec, s[8:9]
	v_pk_mul_f32 v[16:17], v[16:17], v[48:49] op_sel_hi:[1,0]
	v_cvt_pk_bf16_f32 v44, v44, v45
	v_cvt_pk_bf16_f32 v45, v46, v47
	v_cvt_pk_bf16_f32 v46, v40, v41
	v_cvt_pk_bf16_f32 v47, v42, v43
	global_store_dwordx4 v[50:51], v[44:47], off
	v_cvt_pk_bf16_f32 v36, v36, v37
	v_cvt_pk_bf16_f32 v37, v38, v39
	v_cvt_pk_bf16_f32 v38, v32, v33
	v_cvt_pk_bf16_f32 v39, v34, v35
	global_store_dwordx4 v[50:51], v[36:39], off offset:64
	s_cbranch_vccnz .LBB0_1773
	v_mov_b32_e32 v34, v29
	v_mov_b32_e32 v35, v21
	v_mov_b32_e32 v32, v28
	v_mov_b32_e32 v33, v20
	v_pk_mul_f32 v[34:35], v[34:35], v[34:35]
	v_mov_b32_e32 v36, v31
	v_mov_b32_e32 v37, v23
	v_pk_fma_f32 v[32:33], v[32:33], v[32:33], v[34:35]
	v_mov_b32_e32 v34, v30
	v_mov_b32_e32 v35, v22
	v_pk_mul_f32 v[36:37], v[36:37], v[36:37]
	v_mov_b32_e32 v38, v27
	v_pk_fma_f32 v[34:35], v[34:35], v[34:35], v[36:37]
	v_mov_b32_e32 v36, v25
	v_mov_b32_e32 v37, v17
	v_pk_add_f32 v[32:33], v[32:33], v[34:35]
	v_mov_b32_e32 v34, v24
	v_mov_b32_e32 v35, v16
	v_pk_mul_f32 v[36:37], v[36:37], v[36:37]
	v_mov_b32_e32 v39, v19
	v_pk_fma_f32 v[34:35], v[34:35], v[34:35], v[36:37]
	v_mov_b32_e32 v36, v26
	v_mov_b32_e32 v37, v18
	v_pk_mul_f32 v[38:39], v[38:39], v[38:39]
	s_nop 0
	v_pk_fma_f32 v[36:37], v[36:37], v[36:37], v[38:39]
	s_nop 0
	v_pk_add_f32 v[34:35], v[34:35], v[36:37]
	s_nop 0
	v_pk_add_f32 v[32:33], v[32:33], v[34:35]
	s_nop 0
	v_add_f32_e32 v32, v32, v33
	s_nop 0
	s_nop 0
	s_nop 1
	v_mov_b32_e32 v33, v32
	s_nop 1
	v_permlane16_swap_b32_e32 v33, v32
	s_waitcnt lgkmcnt(0)
	v_add_f32_e32 v32, v32, v33
	s_nop 0
	s_nop 0
	s_nop 1
	v_mov_b32_e32 v33, v32
	s_nop 1
	v_permlane32_swap_b32_e32 v33, v32
	s_waitcnt lgkmcnt(0)
	v_add_f32_e32 v32, v32, v33
	v_fmamk_f32 v32, v32, 0x3c800000, v184
	v_rsq_f32_e32 v32, v32
	s_nop 0
	v_pk_mul_f32 v[28:29], v[28:29], v[32:33] op_sel_hi:[1,0]
	v_pk_mul_f32 v[30:31], v[30:31], v[32:33] op_sel_hi:[1,0]
	v_pk_mul_f32 v[24:25], v[24:25], v[32:33] op_sel_hi:[1,0]
	v_pk_mul_f32 v[26:27], v[26:27], v[32:33] op_sel_hi:[1,0]
	v_pk_mul_f32 v[20:21], v[20:21], v[32:33] op_sel_hi:[1,0]
	v_pk_mul_f32 v[22:23], v[22:23], v[32:33] op_sel_hi:[1,0]
	v_pk_mul_f32 v[16:17], v[16:17], v[32:33] op_sel_hi:[1,0]
	v_pk_mul_f32 v[18:19], v[18:19], v[32:33] op_sel_hi:[1,0]
	v_pk_mul_f32 v[30:31], v[152:153], v[30:31]
	v_pk_mul_f32 v[28:29], v[156:157], v[28:29]
	v_pk_mul_f32 v[26:27], v[146:147], v[26:27]
	v_pk_mul_f32 v[24:25], v[148:149], v[24:25]
	v_pk_mul_f32 v[22:23], v[158:159], v[22:23]
	v_pk_mul_f32 v[20:21], v[160:161], v[20:21]
	v_pk_mul_f32 v[18:19], v[150:151], v[18:19]
	v_pk_mul_f32 v[16:17], v[154:155], v[16:17]
.LBB0_1773:
	s_waitcnt lgkmcnt(0)
	v_add_f32_e32 v32, v163, v165
	v_fmamk_f32 v32, v32, 0x3a800000, v184
	v_rsq_f32_e32 v32, v32
	v_mov_b64_e32 v[34:35], s[20:21]
	v_mad_i64_i32 v[34:35], s[46:47], v164, s68, v[34:35]
	v_lshl_add_u64 v[34:35], v[112:113], 1, v[34:35]
	v_pk_mul_f32 v[14:15], v[14:15], v[32:33] op_sel_hi:[1,0]
	v_pk_mul_f32 v[12:13], v[12:13], v[32:33] op_sel_hi:[1,0]
	v_pk_mul_f32 v[10:11], v[10:11], v[32:33] op_sel_hi:[1,0]
	v_pk_mul_f32 v[8:9], v[8:9], v[32:33] op_sel_hi:[1,0]
	v_pk_mul_f32 v[6:7], v[6:7], v[32:33] op_sel_hi:[1,0]
	v_pk_mul_f32 v[4:5], v[4:5], v[32:33] op_sel_hi:[1,0]
	v_pk_mul_f32 v[2:3], v[2:3], v[32:33] op_sel_hi:[1,0]
	s_and_b64 vcc, exec, s[8:9]
	v_pk_mul_f32 v[0:1], v[0:1], v[32:33] op_sel_hi:[1,0]
	v_cvt_pk_bf16_f32 v28, v28, v29
	v_cvt_pk_bf16_f32 v29, v30, v31
	v_cvt_pk_bf16_f32 v30, v24, v25
	v_cvt_pk_bf16_f32 v31, v26, v27
	global_store_dwordx4 v[34:35], v[28:31], off
	v_cvt_pk_bf16_f32 v20, v20, v21
	v_cvt_pk_bf16_f32 v21, v22, v23
	v_cvt_pk_bf16_f32 v22, v16, v17
	v_cvt_pk_bf16_f32 v23, v18, v19
	global_store_dwordx4 v[34:35], v[20:23], off offset:64
	s_cbranch_vccnz .LBB0_1775
	v_mov_b32_e32 v18, v13
	v_mov_b32_e32 v19, v5
	v_mov_b32_e32 v16, v12
	v_mov_b32_e32 v17, v4
	v_pk_mul_f32 v[18:19], v[18:19], v[18:19]
	v_mov_b32_e32 v20, v15
	v_mov_b32_e32 v21, v7
	v_pk_fma_f32 v[16:17], v[16:17], v[16:17], v[18:19]
	v_mov_b32_e32 v18, v14
	v_mov_b32_e32 v19, v6
	v_pk_mul_f32 v[20:21], v[20:21], v[20:21]
	v_mov_b32_e32 v22, v11
	v_pk_fma_f32 v[18:19], v[18:19], v[18:19], v[20:21]
	v_mov_b32_e32 v20, v9
	v_mov_b32_e32 v21, v1
	v_pk_add_f32 v[16:17], v[16:17], v[18:19]
	v_mov_b32_e32 v18, v8
	v_mov_b32_e32 v19, v0
	v_pk_mul_f32 v[20:21], v[20:21], v[20:21]
	v_mov_b32_e32 v23, v3
	v_pk_fma_f32 v[18:19], v[18:19], v[18:19], v[20:21]
	v_mov_b32_e32 v20, v10
	v_mov_b32_e32 v21, v2
	v_pk_mul_f32 v[22:23], v[22:23], v[22:23]
	s_nop 0
	v_pk_fma_f32 v[20:21], v[20:21], v[20:21], v[22:23]
	s_nop 0
	v_pk_add_f32 v[18:19], v[18:19], v[20:21]
	s_nop 0
	v_pk_add_f32 v[16:17], v[16:17], v[18:19]
	s_nop 0
	v_add_f32_e32 v16, v16, v17
	s_nop 0
	s_nop 0
	s_nop 1
	v_mov_b32_e32 v17, v16
	s_nop 1
	v_permlane16_swap_b32_e32 v17, v16
	s_waitcnt lgkmcnt(0)
	v_add_f32_e32 v16, v16, v17
	s_nop 0
	s_nop 0
	s_nop 1
	v_mov_b32_e32 v17, v16
	s_nop 1
	v_permlane32_swap_b32_e32 v17, v16
	s_waitcnt lgkmcnt(0)
	v_add_f32_e32 v16, v16, v17
	v_fmamk_f32 v16, v16, 0x3c800000, v184
	v_rsq_f32_e32 v16, v16
	s_nop 0
	v_pk_mul_f32 v[12:13], v[12:13], v[16:17] op_sel_hi:[1,0]
	v_pk_mul_f32 v[14:15], v[14:15], v[16:17] op_sel_hi:[1,0]
	v_pk_mul_f32 v[8:9], v[8:9], v[16:17] op_sel_hi:[1,0]
	v_pk_mul_f32 v[10:11], v[10:11], v[16:17] op_sel_hi:[1,0]
	v_pk_mul_f32 v[4:5], v[4:5], v[16:17] op_sel_hi:[1,0]
	v_pk_mul_f32 v[6:7], v[6:7], v[16:17] op_sel_hi:[1,0]
	v_pk_mul_f32 v[0:1], v[0:1], v[16:17] op_sel_hi:[1,0]
	v_pk_mul_f32 v[2:3], v[2:3], v[16:17] op_sel_hi:[1,0]
	v_pk_mul_f32 v[14:15], v[152:153], v[14:15]
	v_pk_mul_f32 v[12:13], v[156:157], v[12:13]
	v_pk_mul_f32 v[10:11], v[146:147], v[10:11]
	v_pk_mul_f32 v[8:9], v[148:149], v[8:9]
	v_pk_mul_f32 v[6:7], v[158:159], v[6:7]
	v_pk_mul_f32 v[4:5], v[160:161], v[4:5]
	v_pk_mul_f32 v[2:3], v[150:151], v[2:3]
	v_pk_mul_f32 v[0:1], v[154:155], v[0:1]

; __device__ __forceinline__ float sq4(f32x4 v) { return (v[0] * v[0] + v[1] * v[1]) + (v[2] * v[2] + v[3] * v[3]); }
; __device__ __forceinline__ u32x4 pack8(f32x4 a, f32x4 b) { u32x4 w; w.x = cvt_pk_bf16(a[0], a[1]); w.y = cvt_pk_bf16(a[2], a[3]); w.z = cvt_pk_bf16(b[0], b[1]); w.w = cvt_pk_bf16(b[2], b[3]); return w; }
;     __device__ __forceinline__ void operator()(const f32x4 (&acc)[2][2][4][2], const Unit& u, int wr, int wc, int fr, int fq) const {
;     ...
;             for (int m = 0; m < 4; ++m) {
;                 const int row = u.pm * BM + ai * HALF + wr * 64 + m * 16 + fr;
;                 float q = 0.f;
; #pragma unroll
;                 for (int bj = 0; bj < 2; ++bj) {
;                     const size_t off = (size_t)row * 1024 + col0 + 128 * bj; const u32x4 w = bs[m][bj];
;                     const f32x4 b0 = (f32x4){__builtin_bit_cast(float, w.x << 16), __builtin_bit_cast(float, w.x & 0xffff0000u), __builtin_bit_cast(float, w.y << 16), __builtin_bit_cast(float, w.y & 0xffff0000u)};
;                     const f32x4 b1 = (f32x4){__builtin_bit_cast(float, w.z << 16), __builtin_bit_cast(float, w.z & 0xffff0000u), __builtin_bit_cast(float, w.w << 16), __builtin_bit_cast(float, w.w & 0xffff0000u)};
;                     const f32x4 v0 = acc[ai][bj][m][0] + b0, v1 = acc[ai][bj][m][1] + b1;
;                     if (last) { __builtin_nontemporal_store(v0, (f32x4*)(out + off)); __builtin_nontemporal_store(v1, (f32x4*)(out + off + 4)); }
;                     else { q += sq4(v0) + sq4(v1); *(u32x4*)(xb + off) = pack8(v0, v1); }
;                 }
;                 if (!last) { q += shx(q, 16); q += shx(q, 32); if (fq == 0) ss[(size_t)row * 16 + u.pn * 4 + wc] = q; }
.LBB0_1961:
	s_or_b64 exec, exec, s[40:41]
	v_lshlrev_b32_e32 v112, 16, v148
	s_waitcnt lgkmcnt(0)
	v_and_b32_e32 v113, 0xffff0000, v148
	v_lshlrev_b32_e32 v114, 16, v149
	v_and_b32_e32 v115, 0xffff0000, v149
	v_lshlrev_b32_e32 v116, 16, v150
	v_and_b32_e32 v117, 0xffff0000, v150
	v_lshlrev_b32_e32 v118, 16, v151
	v_and_b32_e32 v119, 0xffff0000, v151
	v_pk_add_f32 v[110:111], v[110:111], v[114:115]
	v_pk_add_f32 v[108:109], v[108:109], v[112:113]
	v_pk_add_f32 v[112:113], v[106:107], v[118:119]
	v_pk_add_f32 v[106:107], v[104:105], v[116:117]
	v_mul_f32_e32 v104, v109, v109
	v_mul_f32_e32 v105, v111, v111
	v_fmac_f32_e32 v104, v108, v108
	v_fmac_f32_e32 v105, v110, v110
	v_add_f32_e32 v104, v104, v105
	v_mul_f32_e32 v105, v107, v107
	v_mul_f32_e32 v114, v113, v113
	v_fmac_f32_e32 v105, v106, v106
	v_fmac_f32_e32 v114, v112, v112
	v_add_f32_e32 v105, v105, v114
	v_add_f32_e32 v114, v104, v105
	v_cvt_pk_bf16_f32 v104, v108, v109
	v_lshl_add_u64 v[108:109], s[16:17], 0, v[184:185]
	v_cvt_pk_bf16_f32 v105, v110, v111
	v_cvt_pk_bf16_f32 v106, v106, v107
	v_cvt_pk_bf16_f32 v107, v112, v113
	v_lshl_add_u64 v[108:109], v[168:169], 1, v[108:109]
	global_store_dwordx4 v[108:109], v[104:107], off
	v_lshlrev_b32_e32 v110, 16, v146
	v_and_b32_e32 v111, 0xffff0000, v146
	v_lshlrev_b32_e32 v104, 16, v144
	v_and_b32_e32 v105, 0xffff0000, v144
	v_lshlrev_b32_e32 v106, 16, v145
	v_and_b32_e32 v107, 0xffff0000, v145
	v_lshlrev_b32_e32 v112, 16, v147
	v_and_b32_e32 v113, 0xffff0000, v147
	v_pk_add_f32 v[102:103], v[102:103], v[106:107]
	v_pk_add_f32 v[100:101], v[100:101], v[104:105]
	v_pk_add_f32 v[104:105], v[98:99], v[112:113]
	v_pk_add_f32 v[98:99], v[96:97], v[110:111]
	v_mul_f32_e32 v96, v101, v101
	v_mul_f32_e32 v97, v103, v103
	v_fmac_f32_e32 v96, v100, v100
	v_fmac_f32_e32 v97, v102, v102
	v_add_f32_e32 v96, v96, v97
	v_mul_f32_e32 v97, v99, v99
	v_mul_f32_e32 v106, v105, v105
	v_fmac_f32_e32 v97, v98, v98
	v_fmac_f32_e32 v106, v104, v104
	v_add_f32_e32 v97, v97, v106
	v_add_f32_e32 v96, v96, v97
	v_add_f32_e32 v106, v114, v96
	v_cvt_pk_bf16_f32 v96, v100, v101
	v_cvt_pk_bf16_f32 v97, v102, v103
	v_cvt_pk_bf16_f32 v98, v98, v99
	v_cvt_pk_bf16_f32 v99, v104, v105
	global_store_dwordx4 v[108:109], v[96:99], off offset:256
	s_nop 1
	s_nop 0
	s_nop 2
	v_mov_b32_e32 v96, v106
	s_nop 1
	v_permlane16_swap_b32_e32 v96, v106
	s_waitcnt lgkmcnt(0)
	v_add_f32_e32 v96, v106, v96
	s_nop 1
	v_mov_b32_e32 v97, v96
	s_nop 1
	v_permlane32_swap_b32_e32 v97, v96
	s_and_saveexec_b64 s[40:41], s[6:7]
	s_cbranch_execz .LBB0_1963
	s_waitcnt lgkmcnt(0)
	v_add_f32_e32 v98, v96, v97
	v_lshlrev_b64 v[96:97], 6, v[182:183]
	v_lshl_add_u64 v[96:97], s[18:19], 0, v[96:97]
	v_lshl_add_u64 v[96:97], s[38:39], 2, v[96:97]
	s_lshl_b32 s10, s33, 2
	v_lshl_add_u64 v[96:97], v[96:97], 0, s[10:11]
	global_store_dword v[96:97], v98, off
; __device__ __forceinline__ float sq4(f32x4 v) { return (v[0] * v[0] + v[1] * v[1]) + (v[2] * v[2] + v[3] * v[3]); }
; __device__ __forceinline__ u32x4 pack8(f32x4 a, f32x4 b) { u32x4 w; w.x = cvt_pk_bf16(a[0], a[1]); w.y = cvt_pk_bf16(a[2], a[3]); w.z = cvt_pk_bf16(b[0], b[1]); w.w = cvt_pk_bf16(b[2], b[3]); return w; }
;     __device__ __forceinline__ void operator()(const f32x4 (&acc)[2][2][4][2], const Unit& u, int wr, int wc, int fr, int fq) const {
;     ...
;             for (int m = 0; m < 4; ++m) {
;                 const int row = u.pm * BM + ai * HALF + wr * 64 + m * 16 + fr;
;                 float q = 0.f;
; #pragma unroll
;                 for (int bj = 0; bj < 2; ++bj) {
;                     const size_t off = (size_t)row * 1024 + col0 + 128 * bj; const u32x4 w = bs[m][bj];
;                     const f32x4 b0 = (f32x4){__builtin_bit_cast(float, w.x << 16), __builtin_bit_cast(float, w.x & 0xffff0000u), __builtin_bit_cast(float, w.y << 16), __builtin_bit_cast(float, w.y & 0xffff0000u)};
;                     const f32x4 b1 = (f32x4){__builtin_bit_cast(float, w.z << 16), __builtin_bit_cast(float, w.z & 0xffff0000u), __builtin_bit_cast(float, w.w << 16), __builtin_bit_cast(float, w.w & 0xffff0000u)};
;                     const f32x4 v0 = acc[ai][bj][m][0] + b0, v1 = acc[ai][bj][m][1] + b1;
;                     if (last) { __builtin_nontemporal_store(v0, (f32x4*)(out + off)); __builtin_nontemporal_store(v1, (f32x4*)(out + off + 4)); }
;                     else { q += sq4(v0) + sq4(v1); *(u32x4*)(xb + off) = pack8(v0, v1); }
;                 }
;                 if (!last) { q += shx(q, 16); q += shx(q, 32); if (fq == 0) ss[(size_t)row * 16 + u.pn * 4 + wc] = q; }
.LBB0_1963:
	s_or_b64 exec, exec, s[40:41]
	v_lshlrev_b32_e32 v96, 16, v140
	s_waitcnt lgkmcnt(0)
	v_and_b32_e32 v97, 0xffff0000, v140
	v_lshlrev_b32_e32 v98, 16, v141
	v_and_b32_e32 v99, 0xffff0000, v141
	v_lshlrev_b32_e32 v100, 16, v142
	v_and_b32_e32 v101, 0xffff0000, v142
	v_lshlrev_b32_e32 v102, 16, v143
	v_and_b32_e32 v103, 0xffff0000, v143
	v_pk_add_f32 v[94:95], v[94:95], v[98:99]
	v_pk_add_f32 v[92:93], v[92:93], v[96:97]
	v_pk_add_f32 v[96:97], v[90:91], v[102:103]
	v_pk_add_f32 v[90:91], v[88:89], v[100:101]
	v_mul_f32_e32 v88, v93, v93
	v_mul_f32_e32 v89, v95, v95
	v_fmac_f32_e32 v88, v92, v92
	v_fmac_f32_e32 v89, v94, v94
	v_add_f32_e32 v88, v88, v89
	v_mul_f32_e32 v89, v91, v91
	v_mul_f32_e32 v98, v97, v97
	v_fmac_f32_e32 v89, v90, v90
	v_fmac_f32_e32 v98, v96, v96
	v_add_f32_e32 v89, v89, v98
	v_add_f32_e32 v98, v88, v89
	v_cvt_pk_bf16_f32 v88, v92, v93
	v_lshl_add_u64 v[92:93], s[16:17], 0, v[180:181]
	v_cvt_pk_bf16_f32 v89, v94, v95
	v_cvt_pk_bf16_f32 v90, v90, v91
	v_cvt_pk_bf16_f32 v91, v96, v97
	v_lshl_add_u64 v[92:93], v[168:169], 1, v[92:93]
	global_store_dwordx4 v[92:93], v[88:91], off
	v_lshlrev_b32_e32 v94, 16, v138
	v_and_b32_e32 v95, 0xffff0000, v138
	v_lshlrev_b32_e32 v88, 16, v136
	v_and_b32_e32 v89, 0xffff0000, v136
	v_lshlrev_b32_e32 v90, 16, v137
	v_and_b32_e32 v91, 0xffff0000, v137
	v_lshlrev_b32_e32 v96, 16, v139
	v_and_b32_e32 v97, 0xffff0000, v139
	v_pk_add_f32 v[86:87], v[86:87], v[90:91]
	v_pk_add_f32 v[84:85], v[84:85], v[88:89]
	v_pk_add_f32 v[88:89], v[82:83], v[96:97]
	v_pk_add_f32 v[82:83], v[80:81], v[94:95]
	v_mul_f32_e32 v80, v85, v85
	v_mul_f32_e32 v81, v87, v87
	v_fmac_f32_e32 v80, v84, v84
	v_fmac_f32_e32 v81, v86, v86
	v_add_f32_e32 v80, v80, v81
	v_mul_f32_e32 v81, v83, v83
	v_mul_f32_e32 v90, v89, v89
	v_fmac_f32_e32 v81, v82, v82
	v_fmac_f32_e32 v90, v88, v88
	v_add_f32_e32 v81, v81, v90
	v_add_f32_e32 v80, v80, v81
	v_add_f32_e32 v90, v98, v80
	v_cvt_pk_bf16_f32 v80, v84, v85
	v_cvt_pk_bf16_f32 v81, v86, v87
	v_cvt_pk_bf16_f32 v82, v82, v83
	v_cvt_pk_bf16_f32 v83, v88, v89
	global_store_dwordx4 v[92:93], v[80:83], off offset:256
	s_nop 1
	s_nop 0
	s_nop 2
	v_mov_b32_e32 v80, v90
	s_nop 1
	v_permlane16_swap_b32_e32 v80, v90
	s_waitcnt lgkmcnt(0)
	v_add_f32_e32 v80, v90, v80
	s_nop 1
	v_mov_b32_e32 v81, v80
	s_nop 1
	v_permlane32_swap_b32_e32 v81, v80
	s_and_saveexec_b64 s[40:41], s[6:7]
	s_cbranch_execz .LBB0_1965
	s_waitcnt lgkmcnt(0)
	v_add_f32_e32 v82, v80, v81
	v_lshlrev_b64 v[80:81], 6, v[178:179]
	v_lshl_add_u64 v[80:81], s[18:19], 0, v[80:81]
	v_lshl_add_u64 v[80:81], s[38:39], 2, v[80:81]
	s_lshl_b32 s10, s33, 2
	v_lshl_add_u64 v[80:81], v[80:81], 0, s[10:11]
	global_store_dword v[80:81], v82, off
.LBB0_1965:
	s_or_b64 exec, exec, s[40:41]
	v_lshlrev_b32_e32 v80, 16, v132
	s_waitcnt lgkmcnt(0)
	v_and_b32_e32 v81, 0xffff0000, v132
	v_lshlrev_b32_e32 v82, 16, v133
	v_and_b32_e32 v83, 0xffff0000, v133
	v_lshlrev_b32_e32 v84, 16, v134
	v_and_b32_e32 v85, 0xffff0000, v134
	v_lshlrev_b32_e32 v86, 16, v135
	v_and_b32_e32 v87, 0xffff0000, v135
	v_pk_add_f32 v[78:79], v[78:79], v[82:83]
	v_pk_add_f32 v[76:77], v[76:77], v[80:81]
	v_pk_add_f32 v[80:81], v[74:75], v[86:87]
	v_pk_add_f32 v[74:75], v[72:73], v[84:85]
	v_mul_f32_e32 v72, v77, v77
	v_mul_f32_e32 v73, v79, v79
	v_fmac_f32_e32 v72, v76, v76
	v_fmac_f32_e32 v73, v78, v78
	v_add_f32_e32 v72, v72, v73
	v_mul_f32_e32 v73, v75, v75
	v_mul_f32_e32 v82, v81, v81
	v_fmac_f32_e32 v73, v74, v74
	v_fmac_f32_e32 v82, v80, v80
	v_add_f32_e32 v73, v73, v82
	v_add_f32_e32 v82, v72, v73
	v_cvt_pk_bf16_f32 v72, v76, v77
	v_lshl_add_u64 v[76:77], s[16:17], 0, v[176:177]
	v_cvt_pk_bf16_f32 v73, v78, v79
	v_cvt_pk_bf16_f32 v74, v74, v75
	v_cvt_pk_bf16_f32 v75, v80, v81
	v_lshl_add_u64 v[76:77], v[168:169], 1, v[76:77]
	global_store_dwordx4 v[76:77], v[72:75], off
	v_lshlrev_b32_e32 v78, 16, v130
	v_and_b32_e32 v79, 0xffff0000, v130
	v_lshlrev_b32_e32 v72, 16, v128
	v_and_b32_e32 v73, 0xffff0000, v128
	v_lshlrev_b32_e32 v74, 16, v129
	v_and_b32_e32 v75, 0xffff0000, v129
	v_lshlrev_b32_e32 v80, 16, v131
	v_and_b32_e32 v81, 0xffff0000, v131
	v_pk_add_f32 v[70:71], v[70:71], v[74:75]
	v_pk_add_f32 v[68:69], v[68:69], v[72:73]
	v_pk_add_f32 v[72:73], v[66:67], v[80:81]
	v_pk_add_f32 v[66:67], v[64:65], v[78:79]
	v_mul_f32_e32 v64, v69, v69
	v_mul_f32_e32 v65, v71, v71
	v_fmac_f32_e32 v64, v68, v68
	v_fmac_f32_e32 v65, v70, v70
	v_add_f32_e32 v64, v64, v65
	v_mul_f32_e32 v65, v67, v67
	v_mul_f32_e32 v74, v73, v73
	v_fmac_f32_e32 v65, v66, v66
	v_fmac_f32_e32 v74, v72, v72
	v_add_f32_e32 v65, v65, v74
	v_add_f32_e32 v64, v64, v65
	v_add_f32_e32 v74, v82, v64
	v_cvt_pk_bf16_f32 v64, v68, v69
	v_cvt_pk_bf16_f32 v65, v70, v71
	v_cvt_pk_bf16_f32 v66, v66, v67
	v_cvt_pk_bf16_f32 v67, v72, v73
	global_store_dwordx4 v[76:77], v[64:67], off offset:256
	s_nop 1
	s_nop 0
	s_nop 2
	v_mov_b32_e32 v64, v74
	s_nop 1
	v_permlane16_swap_b32_e32 v64, v74
	s_waitcnt lgkmcnt(0)
	v_add_f32_e32 v64, v74, v64
	s_nop 1
	v_mov_b32_e32 v65, v64
	s_nop 1
	v_permlane32_swap_b32_e32 v65, v64
	s_and_saveexec_b64 s[40:41], s[6:7]
	s_cbranch_execz .LBB0_1967
	s_waitcnt lgkmcnt(0)
	v_add_f32_e32 v66, v64, v65
	v_lshlrev_b64 v[64:65], 6, v[174:175]
	v_lshl_add_u64 v[64:65], s[18:19], 0, v[64:65]
	v_lshl_add_u64 v[64:65], s[38:39], 2, v[64:65]
	s_lshl_b32 s10, s33, 2
	v_lshl_add_u64 v[64:65], v[64:65], 0, s[10:11]
	global_store_dword v[64:65], v66, off

; __device__ __forceinline__ float sq4(f32x4 v) { return (v[0] * v[0] + v[1] * v[1]) + (v[2] * v[2] + v[3] * v[3]); }
; __device__ __forceinline__ u32x4 pack8(f32x4 a, f32x4 b) { u32x4 w; w.x = cvt_pk_bf16(a[0], a[1]); w.y = cvt_pk_bf16(a[2], a[3]); w.z = cvt_pk_bf16(b[0], b[1]); w.w = cvt_pk_bf16(b[2], b[3]); return w; }
;     __device__ __forceinline__ void operator()(const f32x4 (&acc)[2][2][4][2], const Unit& u, int wr, int wc, int fr, int fq) const {
;     ...
;             for (int m = 0; m < 4; ++m) {
;                 const int row = u.pm * BM + ai * HALF + wr * 64 + m * 16 + fr;
;                 float q = 0.f;
; #pragma unroll
;                 for (int bj = 0; bj < 2; ++bj) {
;                     const size_t off = (size_t)row * 1024 + col0 + 128 * bj; const u32x4 w = bs[m][bj];
;                     const f32x4 b0 = (f32x4){__builtin_bit_cast(float, w.x << 16), __builtin_bit_cast(float, w.x & 0xffff0000u), __builtin_bit_cast(float, w.y << 16), __builtin_bit_cast(float, w.y & 0xffff0000u)};
;                     const f32x4 b1 = (f32x4){__builtin_bit_cast(float, w.z << 16), __builtin_bit_cast(float, w.z & 0xffff0000u), __builtin_bit_cast(float, w.w << 16), __builtin_bit_cast(float, w.w & 0xffff0000u)};
;                     const f32x4 v0 = acc[ai][bj][m][0] + b0, v1 = acc[ai][bj][m][1] + b1;
;                     if (last) { __builtin_nontemporal_store(v0, (f32x4*)(out + off)); __builtin_nontemporal_store(v1, (f32x4*)(out + off + 4)); }
;                     else { q += sq4(v0) + sq4(v1); *(u32x4*)(xb + off) = pack8(v0, v1); }
;                 }
;                 if (!last) { q += shx(q, 16); q += shx(q, 32); if (fq == 0) ss[(size_t)row * 16 + u.pn * 4 + wc] = q; }
.LBB0_1969:
	s_or_b64 exec, exec, s[40:41]
	s_waitcnt vmcnt(7)
	v_lshlrev_b32_e32 v48, 16, v84
	s_waitcnt lgkmcnt(0)
	v_and_b32_e32 v49, 0xffff0000, v84
	v_lshlrev_b32_e32 v50, 16, v85
	v_and_b32_e32 v51, 0xffff0000, v85
	v_lshlrev_b32_e32 v52, 16, v86
	v_and_b32_e32 v53, 0xffff0000, v86
	v_lshlrev_b32_e32 v54, 16, v87
	v_and_b32_e32 v55, 0xffff0000, v87
	v_pk_add_f32 v[46:47], v[46:47], v[50:51]
	v_pk_add_f32 v[44:45], v[44:45], v[48:49]
	v_pk_add_f32 v[48:49], v[42:43], v[54:55]
	v_pk_add_f32 v[42:43], v[40:41], v[52:53]
	v_mul_f32_e32 v40, v45, v45
	v_mul_f32_e32 v41, v47, v47
	v_fmac_f32_e32 v40, v44, v44
	v_fmac_f32_e32 v41, v46, v46
	v_add_f32_e32 v40, v40, v41
	v_mul_f32_e32 v41, v43, v43
	v_mul_f32_e32 v50, v49, v49
	v_fmac_f32_e32 v41, v42, v42
	v_fmac_f32_e32 v50, v48, v48
	v_add_f32_e32 v41, v41, v50
	v_add_f32_e32 v50, v40, v41
	v_cvt_pk_bf16_f32 v40, v44, v45
	v_lshl_add_u64 v[44:45], s[16:17], 0, v[98:99]
	v_cvt_pk_bf16_f32 v41, v46, v47
	v_cvt_pk_bf16_f32 v42, v42, v43
	v_cvt_pk_bf16_f32 v43, v48, v49
	v_lshl_add_u64 v[44:45], v[168:169], 1, v[44:45]
	global_store_dwordx4 v[44:45], v[40:43], off
	s_waitcnt vmcnt(7)
	v_lshlrev_b32_e32 v46, 16, v82
	v_and_b32_e32 v47, 0xffff0000, v82
	v_lshlrev_b32_e32 v40, 16, v80
	v_and_b32_e32 v41, 0xffff0000, v80
	v_lshlrev_b32_e32 v42, 16, v81
	v_and_b32_e32 v43, 0xffff0000, v81
	v_lshlrev_b32_e32 v48, 16, v83
	v_and_b32_e32 v49, 0xffff0000, v83
	v_pk_add_f32 v[38:39], v[38:39], v[42:43]
	v_pk_add_f32 v[36:37], v[36:37], v[40:41]
	v_pk_add_f32 v[40:41], v[34:35], v[48:49]
	v_pk_add_f32 v[34:35], v[32:33], v[46:47]
	v_mul_f32_e32 v32, v37, v37
	v_mul_f32_e32 v33, v39, v39
	v_fmac_f32_e32 v32, v36, v36
	v_fmac_f32_e32 v33, v38, v38
	v_add_f32_e32 v32, v32, v33
	v_mul_f32_e32 v33, v35, v35
	v_mul_f32_e32 v42, v41, v41
	v_fmac_f32_e32 v33, v34, v34
	v_fmac_f32_e32 v42, v40, v40
	v_add_f32_e32 v33, v33, v42
	v_add_f32_e32 v32, v32, v33
	v_add_f32_e32 v42, v50, v32
	v_cvt_pk_bf16_f32 v32, v36, v37
	v_cvt_pk_bf16_f32 v33, v38, v39
	v_cvt_pk_bf16_f32 v34, v34, v35
	v_cvt_pk_bf16_f32 v35, v40, v41
	global_store_dwordx4 v[44:45], v[32:35], off offset:256
	s_nop 1
	s_nop 0
	s_nop 2
	v_mov_b32_e32 v32, v42
	s_nop 1
	v_permlane16_swap_b32_e32 v32, v42
	s_waitcnt lgkmcnt(0)
	v_add_f32_e32 v32, v42, v32
	s_nop 1
	v_mov_b32_e32 v33, v32
	s_nop 1
	v_permlane32_swap_b32_e32 v33, v32
	s_and_saveexec_b64 s[40:41], s[6:7]
	s_cbranch_execz .LBB0_1971
	s_waitcnt lgkmcnt(0)
	v_add_f32_e32 v34, v32, v33
	v_lshlrev_b64 v[32:33], 6, v[96:97]
	v_lshl_add_u64 v[32:33], s[18:19], 0, v[32:33]
	v_lshl_add_u64 v[32:33], s[38:39], 2, v[32:33]
	s_lshl_b32 s10, s33, 2
	v_lshl_add_u64 v[32:33], v[32:33], 0, s[10:11]
	global_store_dword v[32:33], v34, off
; __device__ __forceinline__ float sq4(f32x4 v) { return (v[0] * v[0] + v[1] * v[1]) + (v[2] * v[2] + v[3] * v[3]); }
; __device__ __forceinline__ u32x4 pack8(f32x4 a, f32x4 b) { u32x4 w; w.x = cvt_pk_bf16(a[0], a[1]); w.y = cvt_pk_bf16(a[2], a[3]); w.z = cvt_pk_bf16(b[0], b[1]); w.w = cvt_pk_bf16(b[2], b[3]); return w; }
;     __device__ __forceinline__ void operator()(const f32x4 (&acc)[2][2][4][2], const Unit& u, int wr, int wc, int fr, int fq) const {
;     ...
;             for (int m = 0; m < 4; ++m) {
;                 const int row = u.pm * BM + ai * HALF + wr * 64 + m * 16 + fr;
;                 float q = 0.f;
; #pragma unroll
;                 for (int bj = 0; bj < 2; ++bj) {
;                     const size_t off = (size_t)row * 1024 + col0 + 128 * bj; const u32x4 w = bs[m][bj];
;                     const f32x4 b0 = (f32x4){__builtin_bit_cast(float, w.x << 16), __builtin_bit_cast(float, w.x & 0xffff0000u), __builtin_bit_cast(float, w.y << 16), __builtin_bit_cast(float, w.y & 0xffff0000u)};
;                     const f32x4 b1 = (f32x4){__builtin_bit_cast(float, w.z << 16), __builtin_bit_cast(float, w.z & 0xffff0000u), __builtin_bit_cast(float, w.w << 16), __builtin_bit_cast(float, w.w & 0xffff0000u)};
;                     const f32x4 v0 = acc[ai][bj][m][0] + b0, v1 = acc[ai][bj][m][1] + b1;
;                     if (last) { __builtin_nontemporal_store(v0, (f32x4*)(out + off)); __builtin_nontemporal_store(v1, (f32x4*)(out + off + 4)); }
;                     else { q += sq4(v0) + sq4(v1); *(u32x4*)(xb + off) = pack8(v0, v1); }
;                 }
;                 if (!last) { q += shx(q, 16); q += shx(q, 32); if (fq == 0) ss[(size_t)row * 16 + u.pn * 4 + wc] = q; }
.LBB0_1971:
	s_or_b64 exec, exec, s[40:41]
	s_waitcnt vmcnt(7)
	v_lshlrev_b32_e32 v32, 16, v76
	s_waitcnt lgkmcnt(0)
	v_and_b32_e32 v33, 0xffff0000, v76
	v_lshlrev_b32_e32 v34, 16, v77
	v_and_b32_e32 v35, 0xffff0000, v77
	v_lshlrev_b32_e32 v36, 16, v78
	v_and_b32_e32 v37, 0xffff0000, v78
	v_lshlrev_b32_e32 v38, 16, v79
	v_and_b32_e32 v39, 0xffff0000, v79
	v_pk_add_f32 v[30:31], v[30:31], v[34:35]
	v_pk_add_f32 v[28:29], v[28:29], v[32:33]
	v_pk_add_f32 v[32:33], v[26:27], v[38:39]
	v_pk_add_f32 v[26:27], v[24:25], v[36:37]
	v_mul_f32_e32 v24, v29, v29
	v_mul_f32_e32 v25, v31, v31
	v_fmac_f32_e32 v24, v28, v28
	v_fmac_f32_e32 v25, v30, v30
	v_add_f32_e32 v24, v24, v25
	v_mul_f32_e32 v25, v27, v27
	v_mul_f32_e32 v34, v33, v33
	v_fmac_f32_e32 v25, v26, v26
	v_fmac_f32_e32 v34, v32, v32
	v_add_f32_e32 v25, v25, v34
	v_add_f32_e32 v34, v24, v25
	v_cvt_pk_bf16_f32 v24, v28, v29
	v_lshl_add_u64 v[28:29], s[16:17], 0, v[94:95]
	v_cvt_pk_bf16_f32 v25, v30, v31
	v_cvt_pk_bf16_f32 v26, v26, v27
	v_cvt_pk_bf16_f32 v27, v32, v33
	v_lshl_add_u64 v[28:29], v[168:169], 1, v[28:29]
	global_store_dwordx4 v[28:29], v[24:27], off
	s_waitcnt vmcnt(7)
	v_lshlrev_b32_e32 v30, 16, v74
	v_and_b32_e32 v31, 0xffff0000, v74
	v_lshlrev_b32_e32 v24, 16, v72
	v_and_b32_e32 v25, 0xffff0000, v72
	v_lshlrev_b32_e32 v26, 16, v73
	v_and_b32_e32 v27, 0xffff0000, v73
	v_lshlrev_b32_e32 v32, 16, v75
	v_and_b32_e32 v33, 0xffff0000, v75
	v_pk_add_f32 v[22:23], v[22:23], v[26:27]
	v_pk_add_f32 v[20:21], v[20:21], v[24:25]
	v_pk_add_f32 v[24:25], v[18:19], v[32:33]
	v_pk_add_f32 v[18:19], v[16:17], v[30:31]
	v_mul_f32_e32 v16, v21, v21
	v_mul_f32_e32 v17, v23, v23
	v_fmac_f32_e32 v16, v20, v20
	v_fmac_f32_e32 v17, v22, v22
	v_add_f32_e32 v16, v16, v17
	v_mul_f32_e32 v17, v19, v19
	v_mul_f32_e32 v26, v25, v25
	v_fmac_f32_e32 v17, v18, v18
	v_fmac_f32_e32 v26, v24, v24
	v_add_f32_e32 v17, v17, v26
	v_add_f32_e32 v16, v16, v17
	v_add_f32_e32 v26, v34, v16
	v_cvt_pk_bf16_f32 v16, v20, v21
	v_cvt_pk_bf16_f32 v17, v22, v23
	v_cvt_pk_bf16_f32 v18, v18, v19
	v_cvt_pk_bf16_f32 v19, v24, v25
	global_store_dwordx4 v[28:29], v[16:19], off offset:256
	s_nop 1
	s_nop 0
	s_nop 2
	v_mov_b32_e32 v16, v26
	s_nop 1
	v_permlane16_swap_b32_e32 v16, v26
	s_waitcnt lgkmcnt(0)
	v_add_f32_e32 v16, v26, v16
	s_nop 1
	v_mov_b32_e32 v17, v16
	s_nop 1
	v_permlane32_swap_b32_e32 v17, v16
	s_and_saveexec_b64 s[40:41], s[6:7]
	s_cbranch_execz .LBB0_1973
	s_waitcnt lgkmcnt(0)
	v_add_f32_e32 v18, v16, v17
	v_lshlrev_b64 v[16:17], 6, v[92:93]
	v_lshl_add_u64 v[16:17], s[18:19], 0, v[16:17]
	v_lshl_add_u64 v[16:17], s[38:39], 2, v[16:17]
	s_lshl_b32 s10, s33, 2
	v_lshl_add_u64 v[16:17], v[16:17], 0, s[10:11]
	global_store_dword v[16:17], v18, off
.LBB0_1973:
	s_or_b64 exec, exec, s[40:41]
	s_waitcnt vmcnt(7)
	v_lshlrev_b32_e32 v16, 16, v68
	s_waitcnt lgkmcnt(0)
	v_and_b32_e32 v17, 0xffff0000, v68
	v_lshlrev_b32_e32 v18, 16, v69
	v_and_b32_e32 v19, 0xffff0000, v69
	v_lshlrev_b32_e32 v20, 16, v70
	v_and_b32_e32 v21, 0xffff0000, v70
	v_lshlrev_b32_e32 v22, 16, v71
	v_and_b32_e32 v23, 0xffff0000, v71
	v_pk_add_f32 v[14:15], v[14:15], v[18:19]
	v_pk_add_f32 v[12:13], v[12:13], v[16:17]
	v_pk_add_f32 v[16:17], v[10:11], v[22:23]
	v_pk_add_f32 v[10:11], v[8:9], v[20:21]
	v_mul_f32_e32 v8, v13, v13
	v_mul_f32_e32 v9, v15, v15
	v_fmac_f32_e32 v8, v12, v12
	v_fmac_f32_e32 v9, v14, v14
	v_add_f32_e32 v8, v8, v9
	v_mul_f32_e32 v9, v11, v11
	v_mul_f32_e32 v18, v17, v17
	v_fmac_f32_e32 v9, v10, v10
	v_fmac_f32_e32 v18, v16, v16
	v_add_f32_e32 v9, v9, v18
	v_add_f32_e32 v18, v8, v9
	v_cvt_pk_bf16_f32 v8, v12, v13
	v_lshl_add_u64 v[12:13], s[16:17], 0, v[90:91]
	v_cvt_pk_bf16_f32 v9, v14, v15
	v_cvt_pk_bf16_f32 v10, v10, v11
	v_cvt_pk_bf16_f32 v11, v16, v17
	v_lshl_add_u64 v[12:13], v[168:169], 1, v[12:13]
	global_store_dwordx4 v[12:13], v[8:11], off
	s_waitcnt vmcnt(7)
	v_lshlrev_b32_e32 v14, 16, v66
	v_and_b32_e32 v15, 0xffff0000, v66
	v_lshlrev_b32_e32 v8, 16, v64
	v_and_b32_e32 v9, 0xffff0000, v64
	v_lshlrev_b32_e32 v10, 16, v65
	v_and_b32_e32 v11, 0xffff0000, v65
	v_lshlrev_b32_e32 v16, 16, v67
	v_and_b32_e32 v17, 0xffff0000, v67
	v_pk_add_f32 v[6:7], v[6:7], v[10:11]
	v_pk_add_f32 v[4:5], v[4:5], v[8:9]
	v_pk_add_f32 v[8:9], v[2:3], v[16:17]
	v_pk_add_f32 v[2:3], v[0:1], v[14:15]
	v_mul_f32_e32 v0, v5, v5
	v_mul_f32_e32 v1, v7, v7
	v_fmac_f32_e32 v0, v4, v4
	v_fmac_f32_e32 v1, v6, v6
	v_add_f32_e32 v0, v0, v1
	v_mul_f32_e32 v1, v3, v3
	v_mul_f32_e32 v10, v9, v9
	v_fmac_f32_e32 v1, v2, v2
	v_fmac_f32_e32 v10, v8, v8
	v_add_f32_e32 v1, v1, v10
	v_add_f32_e32 v0, v0, v1
	v_add_f32_e32 v10, v18, v0
	v_cvt_pk_bf16_f32 v0, v4, v5
	v_cvt_pk_bf16_f32 v1, v6, v7
	v_cvt_pk_bf16_f32 v2, v2, v3
	v_cvt_pk_bf16_f32 v3, v8, v9
	global_store_dwordx4 v[12:13], v[0:3], off offset:256
	s_nop 1
	s_nop 0
	s_nop 2
	v_mov_b32_e32 v0, v10
	s_nop 1
	v_permlane16_swap_b32_e32 v0, v10
	s_waitcnt lgkmcnt(0)
	v_add_f32_e32 v0, v10, v0
	s_nop 1
	v_mov_b32_e32 v1, v0
	s_nop 1
	v_permlane32_swap_b32_e32 v1, v0
	s_and_saveexec_b64 s[40:41], s[6:7]
	s_cbranch_execz .LBB0_1975
	s_waitcnt lgkmcnt(0)
	v_add_f32_e32 v2, v0, v1
	v_lshlrev_b64 v[0:1], 6, v[88:89]
	v_lshl_add_u64 v[0:1], s[18:19], 0, v[0:1]
	v_lshl_add_u64 v[0:1], s[38:39], 2, v[0:1]
	s_lshl_b32 s10, s33, 2
	v_lshl_add_u64 v[0:1], v[0:1], 0, s[10:11]
	global_store_dword v[0:1], v2, off

; __device__ __forceinline__ float row_part(const float* ss, int row, int fq) { const f32x4 a = ((const f32x4*)(ss + (size_t)row * 16))[fq]; return (a[0] + a[1]) + (a[2] + a[3]); }
; __device__ __forceinline__ float row_finish(float t) { t += shx(t, 16); t += shx(t, 32); return __builtin_amdgcn_rsqf(t * (1.0f / 1024.0f) + RMS_EPS); }
;     __device__ __forceinline__ void operator()(const f32x4 (&acc)[2][2][4][2], const Unit& u, int wr, int wc, int fr, int fq) const {
;     ...
;         float rs[2][4];
; #pragma unroll
;         for (int ai = 0; ai < 2; ++ai)
; #pragma unroll
;             for (int m = 0; m < 4; ++m) rs[ai][m] = row_part(ss, u.pm * BM + ai * HALF + wr * 64 + m * 16 + fr, fq);
; #pragma unroll
;         for (int ai = 0; ai < 2; ++ai)
; #pragma unroll
;             for (int m = 0; m < 4; ++m) rs[ai][m] = row_finish(rs[ai][m]);
.LBB0_2043:
	v_lshl_add_u32 v170, s24, 8, v153
	v_ashrrev_i32_e32 v171, 31, v170
	v_or_b32_e32 v166, 16, v170
	v_lshlrev_b64 v[146:147], 6, v[170:171]
	v_ashrrev_i32_e32 v167, 31, v166
	v_lshl_add_u64 v[146:147], v[136:137], 0, v[146:147]
	v_lshlrev_b64 v[148:149], 6, v[166:167]
	v_lshl_add_u64 v[148:149], v[136:137], 0, v[148:149]
	ds_read_b128 v[176:179], v239
	ds_read_b128 v[180:183], v239 offset:1024
	v_or_b32_e32 v162, 32, v170
	v_ashrrev_i32_e32 v163, 31, v162
	v_or_b32_e32 v158, 48, v170
	v_lshlrev_b64 v[146:147], 6, v[162:163]
	v_ashrrev_i32_e32 v159, 31, v158
	v_lshl_add_u64 v[146:147], v[136:137], 0, v[146:147]
	v_lshlrev_b64 v[148:149], 6, v[158:159]
	v_lshl_add_u64 v[148:149], v[136:137], 0, v[148:149]
	ds_read_b128 v[184:187], v239 offset:2048
	ds_read_b128 v[188:191], v239 offset:3072
	v_add_u32_e32 v154, 0x80, v170
	v_ashrrev_i32_e32 v155, 31, v154
	v_add_u32_e32 v150, 0x90, v170
	v_lshlrev_b64 v[146:147], 6, v[154:155]
	v_ashrrev_i32_e32 v151, 31, v150
	v_lshl_add_u64 v[146:147], v[136:137], 0, v[146:147]
	v_lshlrev_b64 v[148:149], 6, v[150:151]
	v_lshl_add_u64 v[148:149], v[136:137], 0, v[148:149]
	ds_read_b128 v[192:195], v239 offset:8192
	ds_read_b128 v[196:199], v239 offset:9216
	v_add_u32_e32 v148, 0xa0, v170
	v_ashrrev_i32_e32 v149, 31, v148
	v_lshlrev_b64 v[146:147], 6, v[148:149]
	v_lshl_add_u64 v[146:147], v[136:137], 0, v[146:147]
	ds_read_b128 v[202:205], v239 offset:10240
	v_add_u32_e32 v146, 0xb0, v170
	v_ashrrev_i32_e32 v147, 31, v146
	v_lshlrev_b64 v[206:207], 6, v[146:147]
	v_lshl_add_u64 v[206:207], v[136:137], 0, v[206:207]
	ds_read_b128 v[206:209], v239 offset:11264
	s_nop 0
	s_nop 3
	s_andn2_b64 vcc, exec, s[6:7]
	s_nop 3
	s_mov_b64 s[6:7], -1
	s_waitcnt lgkmcnt(0)
	v_mov_b32_e32 v210, v177
	v_mov_b32_e32 v211, v178
	v_mov_b32_e32 v177, v179
	v_pk_add_f32 v[176:177], v[210:211], v[176:177]
	v_mov_b32_e32 v178, v181
	v_add_f32_e32 v152, v176, v177
	v_mov_b32_e32 v179, v182
	v_mov_b32_e32 v181, v183
	v_mov_b32_e32 v147, v152
	s_nop 1
	v_permlane16_swap_b32_e32 v147, v152
	v_pk_add_f32 v[176:177], v[178:179], v[180:181]
	v_mov_b32_e32 v182, v185
	v_add_f32_e32 v155, v176, v177
	v_mov_b32_e32 v151, v155
	s_nop 1
	v_permlane16_swap_b32_e32 v151, v155
	s_waitcnt lgkmcnt(0)
	v_add_f32_e32 v147, v152, v147
	s_nop 0
	v_mov_b32_e32 v149, v147
	s_nop 1
	v_permlane32_swap_b32_e32 v149, v147
	s_waitcnt lgkmcnt(0)
	v_add_f32_e32 v151, v155, v151
	s_nop 1
	v_mov_b32_e32 v152, v151
	s_nop 1
	v_permlane32_swap_b32_e32 v152, v151
	s_waitcnt lgkmcnt(0)
	v_add_f32_e32 v147, v147, v149
	s_nop 0
	v_mov_b32_e32 v183, v186
	v_mov_b32_e32 v185, v187
	v_pk_add_f32 v[178:179], v[182:183], v[184:185]
	v_fmamk_f32 v147, v147, 0x3a800000, v175
	s_nop 0
	v_add_f32_e32 v156, v178, v179
	v_rsq_f32_e32 v176, v147
	s_waitcnt lgkmcnt(0)
	v_add_f32_e32 v147, v151, v152
	s_nop 2
	v_mov_b32_e32 v186, v189
	v_mov_b32_e32 v187, v190
	v_mov_b32_e32 v189, v191
	v_mov_b32_e32 v149, v156
	s_nop 1
	v_permlane16_swap_b32_e32 v149, v156
	v_pk_add_f32 v[180:181], v[186:187], v[188:189]
	s_nop 0
	v_add_f32_e32 v159, v180, v181
	s_nop 0
	v_mov_b32_e32 v152, v159
	s_nop 1
	v_permlane16_swap_b32_e32 v152, v159
	s_waitcnt lgkmcnt(0)
	v_add_f32_e32 v149, v156, v149
	s_nop 2
	v_mov_b32_e32 v151, v149
	s_nop 1
	v_permlane32_swap_b32_e32 v151, v149
	s_nop 0
	s_waitcnt lgkmcnt(0)
	v_add_f32_e32 v152, v159, v152
	s_nop 0
	v_mov_b32_e32 v156, v152
	s_nop 1
	v_permlane32_swap_b32_e32 v156, v152
	v_fmamk_f32 v147, v147, 0x3a800000, v175
	v_rsq_f32_e32 v174, v147
	s_waitcnt lgkmcnt(0)
	v_add_f32_e32 v147, v149, v151
	s_nop 0
	v_mov_b32_e32 v190, v193
	v_mov_b32_e32 v191, v194
	v_mov_b32_e32 v193, v195
	v_fmamk_f32 v147, v147, 0x3a800000, v175
	v_pk_add_f32 v[182:183], v[190:191], v[192:193]
	v_rsq_f32_e32 v172, v147
	s_waitcnt lgkmcnt(0)
	v_add_f32_e32 v147, v152, v156
	s_nop 2
	v_mov_b32_e32 v194, v197
	v_mov_b32_e32 v195, v198
	v_mov_b32_e32 v197, v199
	v_add_f32_e32 v160, v182, v183
	s_nop 0
	v_pk_add_f32 v[184:185], v[194:195], v[196:197]
	v_mov_b32_e32 v149, v160
	s_nop 1
	v_permlane16_swap_b32_e32 v149, v160
	s_nop 0
	v_add_f32_e32 v163, v184, v185
	s_nop 0
	v_mov_b32_e32 v152, v163
	s_nop 1
	v_permlane16_swap_b32_e32 v152, v163
	s_nop 1
	s_waitcnt lgkmcnt(0)
	v_add_f32_e32 v149, v160, v149
	s_nop 0
	v_mov_b32_e32 v151, v149
	s_nop 1
	v_permlane32_swap_b32_e32 v151, v149
	s_nop 0
	s_waitcnt lgkmcnt(0)
	v_add_f32_e32 v152, v163, v152
	s_nop 0
	v_mov_b32_e32 v156, v152
	s_nop 1
	v_permlane32_swap_b32_e32 v156, v152
	v_fmamk_f32 v147, v147, 0x3a800000, v175
	v_rsq_f32_e32 v168, v147
	s_waitcnt lgkmcnt(0)
	v_add_f32_e32 v147, v149, v151
	v_fmamk_f32 v147, v147, 0x3a800000, v175
	v_rsq_f32_e32 v164, v147
	s_waitcnt lgkmcnt(0)
	v_add_f32_e32 v147, v152, v156
	s_nop 2
	v_mov_b32_e32 v198, v203
	v_mov_b32_e32 v199, v204
	v_mov_b32_e32 v203, v205
	v_mov_b32_e32 v204, v207
	v_mov_b32_e32 v205, v208
	v_mov_b32_e32 v207, v209
	v_pk_add_f32 v[188:189], v[204:205], v[206:207]
	s_nop 0
	v_pk_add_f32 v[186:187], v[198:199], v[202:203]
	v_add_f32_e32 v155, v188, v189
	s_nop 1
	v_add_f32_e32 v167, v186, v187
	s_nop 0
	v_mov_b32_e32 v152, v155
	s_nop 1
	v_permlane16_swap_b32_e32 v152, v155
	v_mov_b32_e32 v149, v167
	s_nop 1
	v_permlane16_swap_b32_e32 v149, v167
	s_nop 1
	v_fmamk_f32 v147, v147, 0x3a800000, v175
	s_waitcnt lgkmcnt(0)
	v_add_f32_e32 v152, v155, v152
	s_nop 0
	s_waitcnt lgkmcnt(0)
	v_add_f32_e32 v149, v167, v149
	v_mov_b32_e32 v151, v149
	s_nop 1
	v_permlane32_swap_b32_e32 v151, v149
	s_nop 1
	v_mov_b32_e32 v155, v152
	s_nop 1
	v_permlane32_swap_b32_e32 v155, v152
	v_rsq_f32_e32 v160, v147
	s_waitcnt lgkmcnt(0)
; __device__ __forceinline__ f32x4 silu4(f32x4 v) { return (f32x4){silu_f(v[0]), silu_f(v[1]), silu_f(v[2]), silu_f(v[3])}; }
; __device__ __forceinline__ u32x4 pack8(f32x4 a, f32x4 b) { u32x4 w; w.x = cvt_pk_bf16(a[0], a[1]); w.y = cvt_pk_bf16(a[2], a[3]); w.z = cvt_pk_bf16(b[0], b[1]); w.w = cvt_pk_bf16(b[2], b[3]); return w; }
;     __device__ __forceinline__ void operator()(const f32x4 (&acc)[2][2][4][2], const Unit& u, int wr, int wc, int fr, int fq) const {
;     ...
; #pragma unroll
;         for (int ai = 0; ai < 2; ++ai)
; #pragma unroll
;             for (int m = 0; m < 4; ++m) {
;                 const int row = u.pm * BM + ai * HALF + wr * 64 + m * 16 + fr;
;                 const float rstd = rs[ai][m];
;                 const f32x4 a0 = silu4(acc[ai][0][m][0] * rstd) * (acc[ai][1][m][0] * rstd);
;                 const f32x4 a1 = silu4(acc[ai][0][m][1] * rstd) * (acc[ai][1][m][1] * rstd);
;                 *(u32x4*)(ACT + (size_t)row * 2816 + col0) = pack8(a0, a1);
;             }
	v_add_f32_e32 v147, v149, v151
	v_fmamk_f32 v147, v147, 0x3a800000, v175
	v_rsq_f32_e32 v156, v147
	s_waitcnt lgkmcnt(0)
	v_add_f32_e32 v147, v152, v155
	v_fmamk_f32 v147, v147, 0x3a800000, v175
	v_pk_mul_f32 v[124:125], v[124:125], v[176:177] op_sel_hi:[1,0]
	v_rsq_f32_e32 v152, v147
	v_mul_f32_e32 v147, 0xbfb8aa3b, v124
	v_exp_f32_e32 v147, v147
	v_mul_f32_e32 v149, 0xbfb8aa3b, v125
	v_exp_f32_e32 v149, v149
	v_pk_mul_f32 v[126:127], v[126:127], v[176:177] op_sel_hi:[1,0]
	v_add_f32_e32 v147, 1.0, v147
	v_rcp_f32_e32 v178, v147
	v_add_f32_e32 v147, 1.0, v149
	v_mul_f32_e32 v149, 0xbfb8aa3b, v126
	v_exp_f32_e32 v149, v149
	v_mul_f32_e32 v151, 0xbfb8aa3b, v127
	v_exp_f32_e32 v151, v151
	v_rcp_f32_e32 v179, v147
	v_add_f32_e32 v147, 1.0, v149
	v_rcp_f32_e32 v180, v147
	v_add_f32_e32 v147, 1.0, v151
	v_pk_mul_f32 v[120:121], v[120:121], v[176:177] op_sel_hi:[1,0]
	v_rcp_f32_e32 v181, v147
	v_mul_f32_e32 v147, 0xbfb8aa3b, v120
	v_exp_f32_e32 v147, v147
	v_mul_f32_e32 v149, 0xbfb8aa3b, v121
	v_exp_f32_e32 v149, v149
	v_pk_mul_f32 v[122:123], v[122:123], v[176:177] op_sel_hi:[1,0]
	v_add_f32_e32 v147, 1.0, v147
	v_pk_mul_f32 v[124:125], v[124:125], v[178:179]
	v_rcp_f32_e32 v178, v147
	v_add_f32_e32 v147, 1.0, v149
	v_mul_f32_e32 v149, 0xbfb8aa3b, v122
	v_exp_f32_e32 v149, v149
	v_mul_f32_e32 v151, 0xbfb8aa3b, v123
	v_exp_f32_e32 v151, v151
	v_rcp_f32_e32 v179, v147
	v_add_f32_e32 v147, 1.0, v149
	v_pk_mul_f32 v[126:127], v[126:127], v[180:181]
	v_rcp_f32_e32 v180, v147
	v_add_f32_e32 v147, 1.0, v151
	v_rcp_f32_e32 v181, v147
	v_pk_mul_f32 v[116:117], v[116:117], v[176:177] op_sel_hi:[1,0]
	v_pk_mul_f32 v[118:119], v[118:119], v[176:177] op_sel_hi:[1,0]
	v_pk_mul_f32 v[120:121], v[120:121], v[178:179]
	v_pk_mul_f32 v[112:113], v[112:113], v[176:177] op_sel_hi:[1,0]
	v_lshl_or_b32 v182, s48, 7, v161
	v_pk_mul_f32 v[118:119], v[118:119], v[126:127]
	v_pk_mul_f32 v[116:117], v[116:117], v[124:125]
	v_pk_mul_f32 v[122:123], v[122:123], v[180:181]
	v_pk_mul_f32 v[114:115], v[114:115], v[176:177] op_sel_hi:[1,0]
	v_pk_mul_f32 v[112:113], v[112:113], v[120:121]
	v_ashrrev_i32_e32 v183, 31, v182
	v_pk_mul_f32 v[114:115], v[114:115], v[122:123]
	v_cvt_pk_bf16_f32 v116, v116, v117
	v_cvt_pk_bf16_f32 v117, v118, v119
	v_cvt_pk_bf16_f32 v118, v112, v113
	v_mov_b64_e32 v[112:113], s[10:11]
	v_cvt_pk_bf16_f32 v119, v114, v115
	v_mad_i64_i32 v[120:121], s[26:27], v170, s47, v[112:113]
	v_lshlrev_b64 v[114:115], 1, v[182:183]
	v_pk_mul_f32 v[108:109], v[108:109], v[174:175] op_sel_hi:[1,0]
	v_pk_mul_f32 v[110:111], v[110:111], v[174:175] op_sel_hi:[1,0]
	v_mul_f32_e32 v122, 0xbfb8aa3b, v108
	v_mul_f32_e32 v123, 0xbfb8aa3b, v109
	v_lshl_add_u64 v[120:121], v[120:121], 0, v[114:115]
	v_pk_mul_f32 v[104:105], v[104:105], v[174:175] op_sel_hi:[1,0]
	v_pk_mul_f32 v[106:107], v[106:107], v[174:175] op_sel_hi:[1,0]
	v_exp_f32_e32 v122, v122
	v_exp_f32_e32 v123, v123
	v_mul_f32_e32 v124, 0xbfb8aa3b, v110
	v_mul_f32_e32 v125, 0xbfb8aa3b, v111
	global_store_dwordx4 v[120:121], v[116:119], off
	v_exp_f32_e32 v124, v124
	v_exp_f32_e32 v125, v125
	v_mul_f32_e32 v116, 0xbfb8aa3b, v104
	v_mul_f32_e32 v117, 0xbfb8aa3b, v105
	v_mul_f32_e32 v118, 0xbfb8aa3b, v106
	v_mul_f32_e32 v119, 0xbfb8aa3b, v107
	v_exp_f32_e32 v116, v116
	v_exp_f32_e32 v117, v117
	v_exp_f32_e32 v118, v118
	v_exp_f32_e32 v119, v119
	v_add_f32_e32 v122, 1.0, v122
	v_add_f32_e32 v123, 1.0, v123
	v_rcp_f32_e32 v122, v122
	v_rcp_f32_e32 v123, v123
	v_add_f32_e32 v124, 1.0, v124
	v_add_f32_e32 v125, 1.0, v125
	v_add_f32_e32 v116, 1.0, v116
	v_add_f32_e32 v117, 1.0, v117
	v_add_f32_e32 v118, 1.0, v118
	v_add_f32_e32 v119, 1.0, v119
	v_rcp_f32_e32 v124, v124
	v_rcp_f32_e32 v125, v125
	v_rcp_f32_e32 v116, v116
	v_rcp_f32_e32 v117, v117
	v_rcp_f32_e32 v118, v118
	v_rcp_f32_e32 v119, v119
	v_pk_mul_f32 v[108:109], v[108:109], v[122:123]
	v_pk_mul_f32 v[100:101], v[100:101], v[174:175] op_sel_hi:[1,0]
	v_pk_mul_f32 v[110:111], v[110:111], v[124:125]
	v_pk_mul_f32 v[102:103], v[102:103], v[174:175] op_sel_hi:[1,0]
	v_pk_mul_f32 v[100:101], v[100:101], v[108:109]
	v_pk_mul_f32 v[104:105], v[104:105], v[116:117]
	v_pk_mul_f32 v[106:107], v[106:107], v[118:119]
	v_pk_mul_f32 v[96:97], v[96:97], v[174:175] op_sel_hi:[1,0]
	v_pk_mul_f32 v[98:99], v[98:99], v[174:175] op_sel_hi:[1,0]
	v_pk_mul_f32 v[102:103], v[102:103], v[110:111]
	v_pk_mul_f32 v[106:107], v[98:99], v[106:107]
	v_pk_mul_f32 v[98:99], v[96:97], v[104:105]
	v_cvt_pk_bf16_f32 v96, v100, v101
	v_mad_i64_i32 v[100:101], s[26:27], v166, s47, v[112:113]
	v_pk_mul_f32 v[92:93], v[92:93], v[172:173] op_sel_hi:[1,0]
	v_cvt_pk_bf16_f32 v97, v102, v103
	v_cvt_pk_bf16_f32 v98, v98, v99
	v_cvt_pk_bf16_f32 v99, v106, v107
	v_pk_mul_f32 v[94:95], v[94:95], v[172:173] op_sel_hi:[1,0]
	v_mul_f32_e32 v102, 0xbfb8aa3b, v92
	v_mul_f32_e32 v103, 0xbfb8aa3b, v93
	v_lshl_add_u64 v[100:101], v[100:101], 0, v[114:115]
	v_pk_mul_f32 v[88:89], v[88:89], v[172:173] op_sel_hi:[1,0]
	v_pk_mul_f32 v[90:91], v[90:91], v[172:173] op_sel_hi:[1,0]
	v_exp_f32_e32 v102, v102
	v_exp_f32_e32 v103, v103
	v_mul_f32_e32 v104, 0xbfb8aa3b, v94
	v_mul_f32_e32 v105, 0xbfb8aa3b, v95
	global_store_dwordx4 v[100:101], v[96:99], off
	v_exp_f32_e32 v104, v104
	v_exp_f32_e32 v105, v105
	v_mul_f32_e32 v96, 0xbfb8aa3b, v88
	v_mul_f32_e32 v97, 0xbfb8aa3b, v89
	v_mul_f32_e32 v98, 0xbfb8aa3b, v90
	v_mul_f32_e32 v99, 0xbfb8aa3b, v91
	v_exp_f32_e32 v96, v96
	v_exp_f32_e32 v97, v97
	v_exp_f32_e32 v98, v98
	v_exp_f32_e32 v99, v99
	v_add_f32_e32 v102, 1.0, v102
	v_add_f32_e32 v103, 1.0, v103
	v_rcp_f32_e32 v102, v102
	v_rcp_f32_e32 v103, v103
	v_add_f32_e32 v104, 1.0, v104
	v_add_f32_e32 v105, 1.0, v105
; __device__ __forceinline__ u32x4 pack8(f32x4 a, f32x4 b) { u32x4 w; w.x = cvt_pk_bf16(a[0], a[1]); w.y = cvt_pk_bf16(a[2], a[3]); w.z = cvt_pk_bf16(b[0], b[1]); w.w = cvt_pk_bf16(b[2], b[3]); return w; }
; __device__ __forceinline__ float silu_f(float v) { return v * __builtin_amdgcn_rcpf(1.0f + __builtin_amdgcn_exp2f(v * -1.4426950408889634f)); }
; __device__ __forceinline__ f32x4 silu4(f32x4 v) { return (f32x4){silu_f(v[0]), silu_f(v[1]), silu_f(v[2]), silu_f(v[3])}; }
;     __device__ __forceinline__ void operator()(const f32x4 (&acc)[2][2][4][2], const Unit& u, int wr, int wc, int fr, int fq) const {
;     ...
; #pragma unroll
;         for (int ai = 0; ai < 2; ++ai)
; #pragma unroll
;             for (int m = 0; m < 4; ++m) {
;                 const int row = u.pm * BM + ai * HALF + wr * 64 + m * 16 + fr;
;                 const float rstd = rs[ai][m];
;                 const f32x4 a0 = silu4(acc[ai][0][m][0] * rstd) * (acc[ai][1][m][0] * rstd);
;                 const f32x4 a1 = silu4(acc[ai][0][m][1] * rstd) * (acc[ai][1][m][1] * rstd);
;                 *(u32x4*)(ACT + (size_t)row * 2816 + col0) = pack8(a0, a1);
;             }
	v_add_f32_e32 v96, 1.0, v96
	v_add_f32_e32 v97, 1.0, v97
	v_add_f32_e32 v98, 1.0, v98
	v_add_f32_e32 v99, 1.0, v99
	v_rcp_f32_e32 v104, v104
	v_rcp_f32_e32 v105, v105
	v_rcp_f32_e32 v96, v96
	v_rcp_f32_e32 v97, v97
	v_rcp_f32_e32 v98, v98
	v_rcp_f32_e32 v99, v99
	v_pk_mul_f32 v[92:93], v[92:93], v[102:103]
	v_pk_mul_f32 v[84:85], v[84:85], v[172:173] op_sel_hi:[1,0]
	v_pk_mul_f32 v[94:95], v[94:95], v[104:105]
	v_pk_mul_f32 v[86:87], v[86:87], v[172:173] op_sel_hi:[1,0]
	v_pk_mul_f32 v[84:85], v[84:85], v[92:93]
	v_pk_mul_f32 v[88:89], v[88:89], v[96:97]
	v_pk_mul_f32 v[90:91], v[90:91], v[98:99]
	v_pk_mul_f32 v[80:81], v[80:81], v[172:173] op_sel_hi:[1,0]
	v_pk_mul_f32 v[82:83], v[82:83], v[172:173] op_sel_hi:[1,0]
	v_pk_mul_f32 v[86:87], v[86:87], v[94:95]
	v_pk_mul_f32 v[90:91], v[82:83], v[90:91]
	v_pk_mul_f32 v[82:83], v[80:81], v[88:89]
	v_cvt_pk_bf16_f32 v80, v84, v85
	v_mad_i64_i32 v[84:85], s[26:27], v162, s47, v[112:113]
	v_pk_mul_f32 v[76:77], v[76:77], v[168:169] op_sel_hi:[1,0]
	v_cvt_pk_bf16_f32 v81, v86, v87
	v_cvt_pk_bf16_f32 v82, v82, v83
	v_cvt_pk_bf16_f32 v83, v90, v91
	v_pk_mul_f32 v[78:79], v[78:79], v[168:169] op_sel_hi:[1,0]
	v_mul_f32_e32 v86, 0xbfb8aa3b, v76
	v_mul_f32_e32 v87, 0xbfb8aa3b, v77
	v_lshl_add_u64 v[84:85], v[84:85], 0, v[114:115]
	v_pk_mul_f32 v[72:73], v[72:73], v[168:169] op_sel_hi:[1,0]
	v_pk_mul_f32 v[74:75], v[74:75], v[168:169] op_sel_hi:[1,0]
	v_exp_f32_e32 v86, v86
	v_exp_f32_e32 v87, v87
	v_mul_f32_e32 v88, 0xbfb8aa3b, v78
	v_mul_f32_e32 v89, 0xbfb8aa3b, v79
	global_store_dwordx4 v[84:85], v[80:83], off
	v_exp_f32_e32 v88, v88
	v_exp_f32_e32 v89, v89
	v_mul_f32_e32 v80, 0xbfb8aa3b, v72
	v_mul_f32_e32 v81, 0xbfb8aa3b, v73
	v_mul_f32_e32 v82, 0xbfb8aa3b, v74
	v_mul_f32_e32 v83, 0xbfb8aa3b, v75
	v_exp_f32_e32 v80, v80
	v_exp_f32_e32 v81, v81
	v_exp_f32_e32 v82, v82
	v_exp_f32_e32 v83, v83
	v_add_f32_e32 v86, 1.0, v86
	v_add_f32_e32 v87, 1.0, v87
	v_rcp_f32_e32 v86, v86
	v_rcp_f32_e32 v87, v87
	v_add_f32_e32 v88, 1.0, v88
	v_add_f32_e32 v89, 1.0, v89
	v_add_f32_e32 v80, 1.0, v80
	v_add_f32_e32 v81, 1.0, v81
	v_add_f32_e32 v82, 1.0, v82
	v_add_f32_e32 v83, 1.0, v83
	v_rcp_f32_e32 v88, v88
	v_rcp_f32_e32 v89, v89
	v_rcp_f32_e32 v80, v80
	v_rcp_f32_e32 v81, v81
	v_rcp_f32_e32 v82, v82
	v_rcp_f32_e32 v83, v83
	v_pk_mul_f32 v[76:77], v[76:77], v[86:87]
	v_pk_mul_f32 v[68:69], v[68:69], v[168:169] op_sel_hi:[1,0]
	v_pk_mul_f32 v[78:79], v[78:79], v[88:89]
	v_pk_mul_f32 v[70:71], v[70:71], v[168:169] op_sel_hi:[1,0]
	v_pk_mul_f32 v[68:69], v[68:69], v[76:77]
	v_pk_mul_f32 v[72:73], v[72:73], v[80:81]
	v_pk_mul_f32 v[74:75], v[74:75], v[82:83]
	v_pk_mul_f32 v[64:65], v[64:65], v[168:169] op_sel_hi:[1,0]
	v_pk_mul_f32 v[66:67], v[66:67], v[168:169] op_sel_hi:[1,0]
	v_pk_mul_f32 v[70:71], v[70:71], v[78:79]
	v_pk_mul_f32 v[74:75], v[66:67], v[74:75]
	v_pk_mul_f32 v[66:67], v[64:65], v[72:73]
	v_cvt_pk_bf16_f32 v64, v68, v69
	v_mad_i64_i32 v[68:69], s[26:27], v158, s47, v[112:113]
	v_pk_mul_f32 v[60:61], v[60:61], v[164:165] op_sel_hi:[1,0]
	v_cvt_pk_bf16_f32 v65, v70, v71
	v_cvt_pk_bf16_f32 v66, v66, v67
	v_cvt_pk_bf16_f32 v67, v74, v75
	v_pk_mul_f32 v[62:63], v[62:63], v[164:165] op_sel_hi:[1,0]
	v_mul_f32_e32 v70, 0xbfb8aa3b, v60
	v_mul_f32_e32 v71, 0xbfb8aa3b, v61
	v_lshl_add_u64 v[68:69], v[68:69], 0, v[114:115]
	v_pk_mul_f32 v[56:57], v[56:57], v[164:165] op_sel_hi:[1,0]
	v_pk_mul_f32 v[58:59], v[58:59], v[164:165] op_sel_hi:[1,0]
	v_exp_f32_e32 v70, v70
	v_exp_f32_e32 v71, v71
	v_mul_f32_e32 v72, 0xbfb8aa3b, v62
	v_mul_f32_e32 v73, 0xbfb8aa3b, v63
	global_store_dwordx4 v[68:69], v[64:67], off
	v_exp_f32_e32 v72, v72
	v_exp_f32_e32 v73, v73
	v_mul_f32_e32 v64, 0xbfb8aa3b, v56
	v_mul_f32_e32 v65, 0xbfb8aa3b, v57
	v_mul_f32_e32 v66, 0xbfb8aa3b, v58
	v_mul_f32_e32 v67, 0xbfb8aa3b, v59
	v_exp_f32_e32 v64, v64
	v_exp_f32_e32 v65, v65
	v_exp_f32_e32 v66, v66
	v_exp_f32_e32 v67, v67
	v_add_f32_e32 v70, 1.0, v70
	v_add_f32_e32 v71, 1.0, v71
	v_rcp_f32_e32 v70, v70
	v_rcp_f32_e32 v71, v71
	v_add_f32_e32 v72, 1.0, v72
	v_add_f32_e32 v73, 1.0, v73
	v_add_f32_e32 v64, 1.0, v64
	v_add_f32_e32 v65, 1.0, v65
	v_add_f32_e32 v66, 1.0, v66
	v_add_f32_e32 v67, 1.0, v67
	v_rcp_f32_e32 v72, v72
	v_rcp_f32_e32 v73, v73
	v_rcp_f32_e32 v64, v64
	v_rcp_f32_e32 v65, v65
	v_rcp_f32_e32 v66, v66
	v_rcp_f32_e32 v67, v67
	v_pk_mul_f32 v[60:61], v[60:61], v[70:71]
	v_pk_mul_f32 v[52:53], v[52:53], v[164:165] op_sel_hi:[1,0]
	v_pk_mul_f32 v[62:63], v[62:63], v[72:73]
	v_pk_mul_f32 v[54:55], v[54:55], v[164:165] op_sel_hi:[1,0]
	v_pk_mul_f32 v[52:53], v[52:53], v[60:61]
	v_pk_mul_f32 v[56:57], v[56:57], v[64:65]
	v_pk_mul_f32 v[58:59], v[58:59], v[66:67]
	v_pk_mul_f32 v[48:49], v[48:49], v[164:165] op_sel_hi:[1,0]
	v_pk_mul_f32 v[50:51], v[50:51], v[164:165] op_sel_hi:[1,0]
	v_pk_mul_f32 v[54:55], v[54:55], v[62:63]
	v_pk_mul_f32 v[58:59], v[50:51], v[58:59]
	v_pk_mul_f32 v[50:51], v[48:49], v[56:57]
	v_cvt_pk_bf16_f32 v48, v52, v53
	v_mad_i64_i32 v[52:53], s[26:27], v154, s47, v[112:113]
	v_pk_mul_f32 v[44:45], v[44:45], v[160:161] op_sel_hi:[1,0]
	v_cvt_pk_bf16_f32 v49, v54, v55
	v_cvt_pk_bf16_f32 v50, v50, v51
	v_cvt_pk_bf16_f32 v51, v58, v59
	v_pk_mul_f32 v[46:47], v[46:47], v[160:161] op_sel_hi:[1,0]
	v_mul_f32_e32 v54, 0xbfb8aa3b, v44
	v_mul_f32_e32 v55, 0xbfb8aa3b, v45
	v_lshl_add_u64 v[52:53], v[52:53], 0, v[114:115]
	v_pk_mul_f32 v[40:41], v[40:41], v[160:161] op_sel_hi:[1,0]
	v_pk_mul_f32 v[42:43], v[42:43], v[160:161] op_sel_hi:[1,0]
	v_exp_f32_e32 v54, v54
	v_exp_f32_e32 v55, v55
	v_mul_f32_e32 v56, 0xbfb8aa3b, v46
	v_mul_f32_e32 v57, 0xbfb8aa3b, v47
	global_store_dwordx4 v[52:53], v[48:51], off
	v_exp_f32_e32 v56, v56
; __device__ __forceinline__ f32x4 silu4(f32x4 v) { return (f32x4){silu_f(v[0]), silu_f(v[1]), silu_f(v[2]), silu_f(v[3])}; }
; __device__ __forceinline__ u32x4 pack8(f32x4 a, f32x4 b) { u32x4 w; w.x = cvt_pk_bf16(a[0], a[1]); w.y = cvt_pk_bf16(a[2], a[3]); w.z = cvt_pk_bf16(b[0], b[1]); w.w = cvt_pk_bf16(b[2], b[3]); return w; }
; #define PG8_BAR __builtin_amdgcn_s_barrier()
;     __device__ __forceinline__ void operator()(const f32x4 (&acc)[2][2][4][2], const Unit& u, int wr, int wc, int fr, int fq) const {
;     ...
;         for (int ai = 0; ai < 2; ++ai)
; #pragma unroll
;             for (int m = 0; m < 4; ++m) {
;                 const int row = u.pm * BM + ai * HALF + wr * 64 + m * 16 + fr;
;                 const float rstd = rs[ai][m];
;                 const f32x4 a0 = silu4(acc[ai][0][m][0] * rstd) * (acc[ai][1][m][0] * rstd);
;                 const f32x4 a1 = silu4(acc[ai][0][m][1] * rstd) * (acc[ai][1][m][1] * rstd);
;                 *(u32x4*)(ACT + (size_t)row * 2816 + col0) = pack8(a0, a1);
;             }
; template <class Epi, class Sched, bool ALIGN_EPI = false, bool SP2 = false>
; __device__ __forceinline__ void gemm_phase(PG8_LAS unsigned char* lds, const Gemm g, const Sched& S, const Epi& E, int tid_in) {
;     ...
;         if (!has_next) break;
; #pragma unroll
;         for (int a = 0; a < 2; ++a)
; #pragma unroll
;             for (int b = 0; b < 2; ++b)
; #pragma unroll
;                 for (int m = 0; m < 4; ++m)
; #pragma unroll
;                     for (int n = 0; n < 2; ++n) acc[a][b][m][n] = (f32x4){0.f, 0.f, 0.f, 0.f};
;         cur = nxt; cA = nA; cB = nB; ++ui;
;         if constexpr (ALIGN_EPI) { if (wr == 1) PG8_BAR; }
	v_exp_f32_e32 v57, v57
	v_mul_f32_e32 v48, 0xbfb8aa3b, v40
	v_mul_f32_e32 v49, 0xbfb8aa3b, v41
	v_mul_f32_e32 v50, 0xbfb8aa3b, v42
	v_mul_f32_e32 v51, 0xbfb8aa3b, v43
	v_exp_f32_e32 v48, v48
	v_exp_f32_e32 v49, v49
	v_exp_f32_e32 v50, v50
	v_exp_f32_e32 v51, v51
	v_add_f32_e32 v54, 1.0, v54
	v_add_f32_e32 v55, 1.0, v55
	v_rcp_f32_e32 v54, v54
	v_rcp_f32_e32 v55, v55
	v_add_f32_e32 v56, 1.0, v56
	v_add_f32_e32 v57, 1.0, v57
	v_add_f32_e32 v48, 1.0, v48
	v_add_f32_e32 v49, 1.0, v49
	v_add_f32_e32 v50, 1.0, v50
	v_add_f32_e32 v51, 1.0, v51
	v_rcp_f32_e32 v56, v56
	v_rcp_f32_e32 v57, v57
	v_rcp_f32_e32 v48, v48
	v_rcp_f32_e32 v49, v49
	v_rcp_f32_e32 v50, v50
	v_rcp_f32_e32 v51, v51
	v_pk_mul_f32 v[44:45], v[44:45], v[54:55]
	v_pk_mul_f32 v[36:37], v[36:37], v[160:161] op_sel_hi:[1,0]
	v_pk_mul_f32 v[46:47], v[46:47], v[56:57]
	v_pk_mul_f32 v[38:39], v[38:39], v[160:161] op_sel_hi:[1,0]
	v_pk_mul_f32 v[36:37], v[36:37], v[44:45]
	v_pk_mul_f32 v[40:41], v[40:41], v[48:49]
	v_pk_mul_f32 v[42:43], v[42:43], v[50:51]
	v_pk_mul_f32 v[32:33], v[32:33], v[160:161] op_sel_hi:[1,0]
	v_pk_mul_f32 v[34:35], v[34:35], v[160:161] op_sel_hi:[1,0]
	v_pk_mul_f32 v[38:39], v[38:39], v[46:47]
	v_pk_mul_f32 v[42:43], v[34:35], v[42:43]
	v_pk_mul_f32 v[34:35], v[32:33], v[40:41]
	v_cvt_pk_bf16_f32 v32, v36, v37
	v_mad_i64_i32 v[36:37], s[26:27], v150, s47, v[112:113]
	v_pk_mul_f32 v[28:29], v[28:29], v[156:157] op_sel_hi:[1,0]
	v_cvt_pk_bf16_f32 v33, v38, v39
	v_cvt_pk_bf16_f32 v34, v34, v35
	v_cvt_pk_bf16_f32 v35, v42, v43
	v_pk_mul_f32 v[30:31], v[30:31], v[156:157] op_sel_hi:[1,0]
	v_mul_f32_e32 v38, 0xbfb8aa3b, v28
	v_mul_f32_e32 v39, 0xbfb8aa3b, v29
	v_lshl_add_u64 v[36:37], v[36:37], 0, v[114:115]
	v_pk_mul_f32 v[24:25], v[24:25], v[156:157] op_sel_hi:[1,0]
	v_pk_mul_f32 v[26:27], v[26:27], v[156:157] op_sel_hi:[1,0]
	v_exp_f32_e32 v38, v38
	v_exp_f32_e32 v39, v39
	v_mul_f32_e32 v40, 0xbfb8aa3b, v30
	v_mul_f32_e32 v41, 0xbfb8aa3b, v31
	global_store_dwordx4 v[36:37], v[32:35], off
	v_exp_f32_e32 v40, v40
	v_exp_f32_e32 v41, v41
	v_mul_f32_e32 v32, 0xbfb8aa3b, v24
	v_mul_f32_e32 v33, 0xbfb8aa3b, v25
	v_mul_f32_e32 v34, 0xbfb8aa3b, v26
	v_mul_f32_e32 v35, 0xbfb8aa3b, v27
	v_exp_f32_e32 v32, v32
	v_exp_f32_e32 v33, v33
	v_exp_f32_e32 v34, v34
	v_exp_f32_e32 v35, v35
	v_add_f32_e32 v38, 1.0, v38
	v_add_f32_e32 v39, 1.0, v39
	v_rcp_f32_e32 v38, v38
	v_rcp_f32_e32 v39, v39
	v_add_f32_e32 v40, 1.0, v40
	v_add_f32_e32 v41, 1.0, v41
	v_add_f32_e32 v32, 1.0, v32
	v_add_f32_e32 v33, 1.0, v33
	v_add_f32_e32 v34, 1.0, v34
	v_add_f32_e32 v35, 1.0, v35
	v_rcp_f32_e32 v40, v40
	v_rcp_f32_e32 v41, v41
	v_rcp_f32_e32 v32, v32
	v_rcp_f32_e32 v33, v33
	v_rcp_f32_e32 v34, v34
	v_rcp_f32_e32 v35, v35
	v_pk_mul_f32 v[28:29], v[28:29], v[38:39]
	v_pk_mul_f32 v[20:21], v[20:21], v[156:157] op_sel_hi:[1,0]
	v_pk_mul_f32 v[30:31], v[30:31], v[40:41]
	v_pk_mul_f32 v[22:23], v[22:23], v[156:157] op_sel_hi:[1,0]
	v_pk_mul_f32 v[20:21], v[20:21], v[28:29]
	v_pk_mul_f32 v[24:25], v[24:25], v[32:33]
	v_pk_mul_f32 v[26:27], v[26:27], v[34:35]
	v_pk_mul_f32 v[16:17], v[16:17], v[156:157] op_sel_hi:[1,0]
	v_pk_mul_f32 v[18:19], v[18:19], v[156:157] op_sel_hi:[1,0]
	v_pk_mul_f32 v[22:23], v[22:23], v[30:31]
	v_pk_mul_f32 v[26:27], v[18:19], v[26:27]
	v_pk_mul_f32 v[18:19], v[16:17], v[24:25]
	v_cvt_pk_bf16_f32 v16, v20, v21
	v_mad_i64_i32 v[20:21], s[26:27], v148, s47, v[112:113]
	v_pk_mul_f32 v[12:13], v[12:13], v[152:153] op_sel_hi:[1,0]
	v_cvt_pk_bf16_f32 v17, v22, v23
	v_cvt_pk_bf16_f32 v18, v18, v19
	v_cvt_pk_bf16_f32 v19, v26, v27
	v_lshl_add_u64 v[20:21], v[20:21], 0, v[114:115]
	v_mul_f32_e32 v22, 0xbfb8aa3b, v12
	v_mul_f32_e32 v23, 0xbfb8aa3b, v13
	v_pk_mul_f32 v[8:9], v[8:9], v[152:153] op_sel_hi:[1,0]
	v_pk_mul_f32 v[10:11], v[10:11], v[152:153] op_sel_hi:[1,0]
	v_exp_f32_e32 v22, v22
	v_exp_f32_e32 v23, v23
	global_store_dwordx4 v[20:21], v[16:19], off
	v_pk_mul_f32 v[14:15], v[14:15], v[152:153] op_sel_hi:[1,0]
	v_add_f32_e32 v22, 1.0, v22
	v_mul_f32_e32 v16, 0xbfb8aa3b, v8
	v_mul_f32_e32 v17, 0xbfb8aa3b, v9
	v_mul_f32_e32 v18, 0xbfb8aa3b, v10
	v_mul_f32_e32 v19, 0xbfb8aa3b, v11
	v_exp_f32_e32 v16, v16
	v_exp_f32_e32 v17, v17
	v_exp_f32_e32 v18, v18
	v_exp_f32_e32 v19, v19
	v_mul_f32_e32 v24, 0xbfb8aa3b, v14
	v_mul_f32_e32 v25, 0xbfb8aa3b, v15
	v_exp_f32_e32 v24, v24
	v_exp_f32_e32 v25, v25
	v_add_f32_e32 v23, 1.0, v23
	v_rcp_f32_e32 v22, v22
	v_rcp_f32_e32 v23, v23
	v_add_f32_e32 v16, 1.0, v16
	v_add_f32_e32 v17, 1.0, v17
	v_add_f32_e32 v18, 1.0, v18
	v_add_f32_e32 v19, 1.0, v19
	v_rcp_f32_e32 v16, v16
	v_rcp_f32_e32 v17, v17
	v_rcp_f32_e32 v18, v18
	v_rcp_f32_e32 v19, v19
	v_add_f32_e32 v24, 1.0, v24
	v_add_f32_e32 v25, 1.0, v25
	v_rcp_f32_e32 v24, v24
	v_rcp_f32_e32 v25, v25
	v_pk_mul_f32 v[12:13], v[12:13], v[22:23]
	v_pk_mul_f32 v[4:5], v[4:5], v[152:153] op_sel_hi:[1,0]
	v_pk_mul_f32 v[8:9], v[8:9], v[16:17]
	v_pk_mul_f32 v[4:5], v[4:5], v[12:13]
	v_pk_mul_f32 v[10:11], v[10:11], v[18:19]
	v_pk_mul_f32 v[0:1], v[0:1], v[152:153] op_sel_hi:[1,0]
	v_pk_mul_f32 v[2:3], v[2:3], v[152:153] op_sel_hi:[1,0]
	v_pk_mul_f32 v[14:15], v[14:15], v[24:25]
	v_pk_mul_f32 v[10:11], v[2:3], v[10:11]
	v_pk_mul_f32 v[2:3], v[0:1], v[8:9]
	v_cvt_pk_bf16_f32 v0, v4, v5
	v_mad_i64_i32 v[4:5], s[26:27], v146, s47, v[112:113]
	v_pk_mul_f32 v[6:7], v[6:7], v[152:153] op_sel_hi:[1,0]
	v_lshl_add_u64 v[4:5], v[4:5], 0, v[114:115]
	v_pk_mul_f32 v[6:7], v[6:7], v[14:15]
	s_nop 0
	v_cvt_pk_bf16_f32 v1, v6, v7
	v_cvt_pk_bf16_f32 v2, v2, v3
	v_cvt_pk_bf16_f32 v3, v10, v11
	global_store_dwordx4 v[4:5], v[0:3], off
	s_cbranch_vccnz .LBB0_2036
	s_andn2_b64 vcc, exec, s[8:9]
	s_cbranch_vccnz .LBB0_2035
	s_barrier
	s_branch .LBB0_2035
